# GEMM K loops: post-barrier lgkmcnt(0) in front of each MFMA cluster replaced by counted per-MFMA waits (wait moved to first consumer)
# baseline (speedup 1.0000x reference)
; #define PG8_STAGE(bufoff, gbase, voff) do { _Pragma("unroll") for (int _i = 0; _i < 2; ++_i) \
;         __builtin_amdgcn_global_load_lds((const unsigned*)((const char*)(gbase) + (voff)[_i]), (LAS unsigned*)(lds + (bufoff) + ldsw + _i * 8192), 16, 0, 0); } while (0)
; #define PG8_LDA(dst, b, h) do { _Pragma("unroll") for (int m = 0; m < 4; ++m) _Pragma("unroll") for (int k = 0; k < 2; ++k) dst[m][k] = *(const LAS bf16x8*)(lds + PG8_SA(b, h) + aoff + m * 2048 + k * 1024); } while (0)
; #define PG8_LDB(dst, b, h) do { _Pragma("unroll") for (int n = 0; n < 2; ++n) _Pragma("unroll") for (int k = 0; k < 2; ++k) dst[n][k] = *(const LAS bf16x8*)(lds + PG8_SB(b, h) + boff + n * 2048 + k * 1024); } while (0)
; #define PG8_WAIT_V(n) asm volatile("s_waitcnt vmcnt(" #n ")" ::: "memory")
; #define PG8_WAIT_L(n) asm volatile("s_waitcnt lgkmcnt(" #n ")" ::: "memory")
; #define PG8_BAR __builtin_amdgcn_s_barrier()
; #define PG8_SCHED __builtin_amdgcn_sched_barrier(0)
; template <class Epi>
; __device__ __forceinline__ void gemm_phase(LAS unsigned char* lds, const Gemm g, const StaticOrder& S, const Epi& E) {
;     ...
;         const bool has_next = S.next(ui + 1, nxt);
;         const char* nA = has_next ? (const char*)g.A + (size_t)nxt.pm * tstepA : cA; const char* nB = has_next ? (const char*)g.Bt + (size_t)nxt.pn * tstepB : cB;
;         for (int t = 0; t < nt; t += 2) {
;             const bool last = (t == nt - 2);
;             const char* a1 = cA + (size_t)(t + 1) * kstep;
;             const char* a2 = last ? nA : cA + (size_t)(t + 2) * kstep; const char* b2 = last ? nB : cB + (size_t)(t + 2) * kstep;
;             const char* a3 = a2 + kstep; const char* b3 = b2 + kstep;
;             if (last) E.pre(cur, wr, fr, epre);
;             PG8_LDB(B0, 0, 0); PG8_SCHED; PG8_LDA(At, 0, 0); PG8_STAGE(PG8_SA(1, 1), a1 + hstepA, voffA);
;             PG8_WAIT_L(8); PG8_BAR; PG8_WAIT_L(0); PG8_MMA(0, 0, At, B0); PG8_BAR; PG8_SCHED;
;             PG8_LDB(B1, 0, 1); PG8_STAGE(PG8_SB(0, 0), b2, voffB);
;             PG8_BAR; PG8_WAIT_L(0); PG8_MMA(0, 1, At, B1); PG8_BAR;
;             PG8_LDA(At, 0, 1); PG8_STAGE(PG8_SA(0, 0), a2, voffA);
;             PG8_BAR; PG8_WAIT_L(0); PG8_MMA(1, 0, At, B0); PG8_BAR; PG8_SCHED;
;             PG8_STAGE(PG8_SB(0, 1), b2 + hstepB, voffB);
;             PG8_WAIT_V(6); PG8_BAR; PG8_MMA(1, 1, At, B1); PG8_BAR;
.LBB0_204:
	s_ashr_i32 s13, s12, 31
	v_cmp_lt_i64_e32 vcc, s[14:15], v[142:143]
	s_lshl_b64 s[14:15], s[12:13], 19
	s_add_u32 s14, s76, s14
	s_addc_u32 s15, s77, s15
	s_and_b64 s[16:17], vcc, exec
	s_cselect_b32 s13, s15, s21
	s_cselect_b32 s19, s14, s20
	s_ashr_i32 s11, s10, 31
	s_lshl_b64 s[16:17], s[10:11], 19
	s_add_u32 s16, s74, s16
	s_addc_u32 s17, s75, s17
	s_and_b64 s[24:25], vcc, exec
	s_cselect_b32 s11, s17, s23
	s_cselect_b32 s44, s16, s22
	s_add_u32 s20, s20, 0x40080
	s_addc_u32 s21, s21, 0
	s_add_u32 s45, s22, 0x100
	s_addc_u32 s46, s23, 0
	s_mov_b32 s47, -2
	s_waitcnt lgkmcnt(0)
	ds_read_b128 v[146:149], v170
	ds_read_b128 v[154:157], v170 offset:1024
	ds_read_b128 v[158:161], v170 offset:2048
	ds_read_b128 v[162:165], v170 offset:3072
	s_add_u32 s22, s20, 0xfffc0080
	s_addc_u32 s23, s21, -1
	s_cmp_eq_u32 s47, 12
	s_cselect_b32 s25, s13, s23
	s_cselect_b32 s24, s19, s22
	s_cselect_b32 s23, s11, s46
	s_cselect_b32 s22, s44, s45
	v_lshl_add_u64 v[150:151], s[20:21], 0, v[138:139]
	s_add_i32 m0, s30, 0xc000
	ds_read_b128 v[174:177], v171
	ds_read_b128 v[178:181], v171 offset:1024
	ds_read_b128 v[182:185], v171 offset:2048
	ds_read_b128 v[186:189], v171 offset:3072
	ds_read_b128 v[190:193], v171 offset:4096
	ds_read_b128 v[194:197], v171 offset:5120
	ds_read_b128 v[198:201], v171 offset:6144
	ds_read_b128 v[202:205], v171 offset:7168
	global_load_lds_dwordx4 v[150:151], off
	v_lshl_add_u64 v[150:151], s[20:21], 0, v[140:141]
	s_add_i32 m0, s30, 0xe000
	s_nop 0
	global_load_lds_dwordx4 v[150:151], off
	s_waitcnt lgkmcnt(8)
	s_barrier
	s_waitcnt lgkmcnt(7)
	v_mfma_f32_16x16x32_bf16 v[76:79], v[146:149], v[174:177], 0
	v_mfma_f32_16x16x32_bf16 v[64:67], v[158:161], v[174:177], 0
	s_waitcnt lgkmcnt(5)
	v_mfma_f32_16x16x32_bf16 v[60:63], v[146:149], v[182:185], 0
	v_mfma_f32_16x16x32_bf16 v[56:59], v[158:161], v[182:185], 0
	s_waitcnt lgkmcnt(3)
	v_mfma_f32_16x16x32_bf16 v[48:51], v[146:149], v[190:193], 0
	v_mfma_f32_16x16x32_bf16 v[40:43], v[158:161], v[190:193], 0
	s_waitcnt lgkmcnt(1)
	v_mfma_f32_16x16x32_bf16 v[36:39], v[146:149], v[198:201], 0
	v_mfma_f32_16x16x32_bf16 v[32:35], v[158:161], v[198:201], 0
	v_mfma_f32_16x16x32_bf16 v[76:79], v[154:157], v[178:181], v[76:79]
	v_mfma_f32_16x16x32_bf16 v[64:67], v[162:165], v[178:181], v[64:67]
	v_mfma_f32_16x16x32_bf16 v[60:63], v[154:157], v[186:189], v[60:63]
	v_mfma_f32_16x16x32_bf16 v[56:59], v[162:165], v[186:189], v[56:59]
	v_mfma_f32_16x16x32_bf16 v[48:51], v[154:157], v[194:197], v[48:51]
	v_mfma_f32_16x16x32_bf16 v[40:43], v[162:165], v[194:197], v[40:43]
	s_waitcnt lgkmcnt(0)
	v_mfma_f32_16x16x32_bf16 v[36:39], v[154:157], v[202:205], v[36:39]
	v_mfma_f32_16x16x32_bf16 v[32:35], v[162:165], v[202:205], v[32:35]
	s_barrier
	s_add_i32 s48, s39, s27
	v_lshl_add_u64 v[150:151], s[22:23], 0, v[132:133]
	s_mov_b32 m0, s48
	ds_read_b128 v[206:209], v172
	ds_read_b128 v[210:213], v172 offset:1024
	ds_read_b128 v[214:217], v172 offset:2048
	ds_read_b128 v[218:221], v172 offset:3072
	global_load_lds_dwordx4 v[150:151], off
	v_lshl_add_u64 v[166:167], s[22:23], 0, v[128:129]
	s_add_i32 m0, s48, 0x2000
	s_nop 0
	global_load_lds_dwordx4 v[166:167], off
	s_barrier
	s_waitcnt lgkmcnt(3)
	v_mfma_f32_16x16x32_bf16 v[124:127], v[206:209], v[174:177], 0
	s_waitcnt lgkmcnt(1)
	v_mfma_f32_16x16x32_bf16 v[120:123], v[214:217], v[174:177], 0
	v_mfma_f32_16x16x32_bf16 v[116:119], v[206:209], v[182:185], 0
	v_mfma_f32_16x16x32_bf16 v[112:115], v[214:217], v[182:185], 0
	v_mfma_f32_16x16x32_bf16 v[108:111], v[206:209], v[190:193], 0
	v_mfma_f32_16x16x32_bf16 v[104:107], v[214:217], v[190:193], 0
	v_mfma_f32_16x16x32_bf16 v[100:103], v[206:209], v[198:201], 0
	v_mfma_f32_16x16x32_bf16 v[96:99], v[214:217], v[198:201], 0
	v_mfma_f32_16x16x32_bf16 v[124:127], v[210:213], v[178:181], v[124:127]
	s_waitcnt lgkmcnt(0)
	v_mfma_f32_16x16x32_bf16 v[120:123], v[218:221], v[178:181], v[120:123]
	v_mfma_f32_16x16x32_bf16 v[116:119], v[210:213], v[186:189], v[116:119]
	v_mfma_f32_16x16x32_bf16 v[112:115], v[218:221], v[186:189], v[112:115]
	v_mfma_f32_16x16x32_bf16 v[108:111], v[210:213], v[194:197], v[108:111]
	v_mfma_f32_16x16x32_bf16 v[104:107], v[218:221], v[194:197], v[104:107]
	v_mfma_f32_16x16x32_bf16 v[100:103], v[210:213], v[202:205], v[100:103]
	v_mfma_f32_16x16x32_bf16 v[96:99], v[218:221], v[202:205], v[96:99]
	s_mov_b32 m0, s30
	v_lshl_add_u64 v[222:223], s[24:25], 0, v[134:135]
	s_barrier
	ds_read_b128 v[174:177], v171 offset:16384
	ds_read_b128 v[178:181], v171 offset:17408
	ds_read_b128 v[182:185], v171 offset:18432
	ds_read_b128 v[186:189], v171 offset:19456
	ds_read_b128 v[190:193], v171 offset:20480
	ds_read_b128 v[194:197], v171 offset:21504
	ds_read_b128 v[198:201], v171 offset:22528
	ds_read_b128 v[202:205], v171 offset:23552
	global_load_lds_dwordx4 v[222:223], off
	v_lshl_add_u64 v[224:225], s[24:25], 0, v[130:131]
	s_mov_b32 m0, s31
	s_nop 0
	global_load_lds_dwordx4 v[224:225], off
	s_barrier
	s_waitcnt lgkmcnt(7)
	v_mfma_f32_16x16x32_bf16 v[28:31], v[146:149], v[174:177], 0
	v_mfma_f32_16x16x32_bf16 v[24:27], v[158:161], v[174:177], 0
	s_waitcnt lgkmcnt(5)
	v_mfma_f32_16x16x32_bf16 v[20:23], v[146:149], v[182:185], 0
	v_mfma_f32_16x16x32_bf16 v[16:19], v[158:161], v[182:185], 0
	s_waitcnt lgkmcnt(3)
	v_mfma_f32_16x16x32_bf16 v[12:15], v[146:149], v[190:193], 0
	v_mfma_f32_16x16x32_bf16 v[8:11], v[158:161], v[190:193], 0
	s_waitcnt lgkmcnt(1)
	v_mfma_f32_16x16x32_bf16 v[4:7], v[146:149], v[198:201], 0
	v_mfma_f32_16x16x32_bf16 v[0:3], v[158:161], v[198:201], 0
	v_mfma_f32_16x16x32_bf16 v[28:31], v[154:157], v[178:181], v[28:31]
	v_mfma_f32_16x16x32_bf16 v[24:27], v[162:165], v[178:181], v[24:27]
	v_mfma_f32_16x16x32_bf16 v[20:23], v[154:157], v[186:189], v[20:23]
	v_mfma_f32_16x16x32_bf16 v[16:19], v[162:165], v[186:189], v[16:19]
	v_mfma_f32_16x16x32_bf16 v[12:15], v[154:157], v[194:197], v[12:15]
	v_mfma_f32_16x16x32_bf16 v[8:11], v[162:165], v[194:197], v[8:11]
	s_waitcnt lgkmcnt(0)
	v_mfma_f32_16x16x32_bf16 v[4:7], v[154:157], v[202:205], v[4:7]
	v_mfma_f32_16x16x32_bf16 v[0:3], v[162:165], v[202:205], v[0:3]
	s_barrier
; #define PG8_STAGE(bufoff, gbase, voff) do { _Pragma("unroll") for (int _i = 0; _i < 2; ++_i) \
;         __builtin_amdgcn_global_load_lds((const unsigned*)((const char*)(gbase) + (voff)[_i]), (LAS unsigned*)(lds + (bufoff) + ldsw + _i * 8192), 16, 0, 0); } while (0)
; #define PG8_LDA(dst, b, h) do { _Pragma("unroll") for (int m = 0; m < 4; ++m) _Pragma("unroll") for (int k = 0; k < 2; ++k) dst[m][k] = *(const LAS bf16x8*)(lds + PG8_SA(b, h) + aoff + m * 2048 + k * 1024); } while (0)
; #define PG8_LDB(dst, b, h) do { _Pragma("unroll") for (int n = 0; n < 2; ++n) _Pragma("unroll") for (int k = 0; k < 2; ++k) dst[n][k] = *(const LAS bf16x8*)(lds + PG8_SB(b, h) + boff + n * 2048 + k * 1024); } while (0)
; #define PG8_MMA(ai, bj, At, Bt) do { __builtin_amdgcn_s_setprio(1); _Pragma("unroll") for (int m = 0; m < 4; ++m) _Pragma("unroll") for (int n = 0; n < 2; ++n) _Pragma("unroll") for (int k = 0; k < 2; ++k) \
;         acc[ai][bj][m][n] = __builtin_amdgcn_mfma_f32_16x16x32_bf16(Bt[n][k], At[m][k], acc[ai][bj][m][n], 0, 0, 0); __builtin_amdgcn_s_setprio(0); } while (0)
; #define PG8_WAIT_V(n) asm volatile("s_waitcnt vmcnt(" #n ")" ::: "memory")
; #define PG8_WAIT_L(n) asm volatile("s_waitcnt lgkmcnt(" #n ")" ::: "memory")
; #define PG8_BAR __builtin_amdgcn_s_barrier()
; #define PG8_SCHED __builtin_amdgcn_sched_barrier(0)
; template <class Epi>
; __device__ __forceinline__ void gemm_phase(LAS unsigned char* lds, const Gemm g, const StaticOrder& S, const Epi& E) {
;     ...
;             PG8_STAGE(PG8_SB(0, 1), b2 + hstepB, voffB);
;             PG8_WAIT_V(6); PG8_BAR; PG8_MMA(1, 1, At, B1); PG8_BAR;
;             PG8_LDB(B0, 1, 0); PG8_SCHED; PG8_LDA(At, 1, 0); PG8_STAGE(PG8_SA(0, 1), a2 + hstepA, voffA);
;             PG8_WAIT_L(8); PG8_BAR; PG8_WAIT_L(0); PG8_MMA(0, 0, At, B0); PG8_BAR; PG8_SCHED;
;             PG8_LDB(B1, 1, 1); PG8_STAGE(PG8_SB(1, 0), b3, voffB);
;             PG8_BAR; PG8_WAIT_L(0); PG8_MMA(0, 1, At, B1); PG8_BAR;
;             PG8_LDA(At, 1, 1); PG8_STAGE(PG8_SA(1, 0), a3, voffA);
;             PG8_BAR; PG8_WAIT_L(0); PG8_MMA(1, 0, At, B0); PG8_BAR; PG8_SCHED;
;             PG8_STAGE(PG8_SB(1, 1), b3 + hstepB, voffB);
;             PG8_WAIT_V(6); PG8_BAR; PG8_MMA(1, 1, At, B1); PG8_BAR;
	s_add_u32 s48, s22, 0x40000
	s_addc_u32 s49, s23, 0
	s_add_i32 s50, s40, s27
	v_lshl_add_u64 v[146:147], s[48:49], 0, v[132:133]
	s_mov_b32 m0, s50
	s_nop 0
	global_load_lds_dwordx4 v[146:147], off
	v_lshl_add_u64 v[146:147], s[48:49], 0, v[128:129]
	s_add_i32 m0, s50, 0x2000
	s_nop 0
	global_load_lds_dwordx4 v[146:147], off
	s_waitcnt vmcnt(6)
	s_barrier
	v_mfma_f32_16x16x32_bf16 v[92:95], v[206:209], v[174:177], 0
	v_mfma_f32_16x16x32_bf16 v[88:91], v[214:217], v[174:177], 0
	v_mfma_f32_16x16x32_bf16 v[84:87], v[206:209], v[182:185], 0
	v_mfma_f32_16x16x32_bf16 v[80:83], v[214:217], v[182:185], 0
	v_mfma_f32_16x16x32_bf16 v[72:75], v[206:209], v[190:193], 0
	v_mfma_f32_16x16x32_bf16 v[68:71], v[214:217], v[190:193], 0
	v_mfma_f32_16x16x32_bf16 v[52:55], v[206:209], v[198:201], 0
	v_mfma_f32_16x16x32_bf16 v[44:47], v[214:217], v[198:201], 0
	v_mfma_f32_16x16x32_bf16 v[92:95], v[210:213], v[178:181], v[92:95]
	v_mfma_f32_16x16x32_bf16 v[88:91], v[218:221], v[178:181], v[88:91]
	v_mfma_f32_16x16x32_bf16 v[84:87], v[210:213], v[186:189], v[84:87]
	v_mfma_f32_16x16x32_bf16 v[80:83], v[218:221], v[186:189], v[80:83]
	v_mfma_f32_16x16x32_bf16 v[72:75], v[210:213], v[194:197], v[72:75]
	v_mfma_f32_16x16x32_bf16 v[68:71], v[218:221], v[194:197], v[68:71]
	v_mfma_f32_16x16x32_bf16 v[52:55], v[210:213], v[202:205], v[52:55]
	v_mfma_f32_16x16x32_bf16 v[44:47], v[218:221], v[202:205], v[44:47]
	s_add_i32 s48, 0, 0x18000
	v_add_u32_e32 v162, s48, v168
	s_barrier
	ds_read_b128 v[146:149], v162
	ds_read_b128 v[154:157], v162 offset:1024
	ds_read_b128 v[158:161], v162 offset:2048
	ds_read_b128 v[162:165], v162 offset:3072
	s_add_u32 s24, s24, 0x40000
	s_addc_u32 s25, s25, 0
	s_mov_b32 m0, s33
	v_lshl_add_u64 v[206:207], s[24:25], 0, v[134:135]
	ds_read_b128 v[174:177], v171 offset:32768
	ds_read_b128 v[178:181], v171 offset:33792
	ds_read_b128 v[182:185], v171 offset:34816
	ds_read_b128 v[186:189], v171 offset:35840
	ds_read_b128 v[190:193], v171 offset:36864
	ds_read_b128 v[194:197], v171 offset:37888
	ds_read_b128 v[198:201], v171 offset:38912
	ds_read_b128 v[202:205], v171 offset:39936
	global_load_lds_dwordx4 v[206:207], off
	v_lshl_add_u64 v[206:207], s[24:25], 0, v[130:131]
	s_mov_b32 m0, s34
	s_nop 0
	global_load_lds_dwordx4 v[206:207], off
	s_waitcnt lgkmcnt(8)
	s_barrier
	s_waitcnt lgkmcnt(7)
	v_mfma_f32_16x16x32_bf16 v[76:79], v[146:149], v[174:177], v[76:79]
	v_mfma_f32_16x16x32_bf16 v[64:67], v[158:161], v[174:177], v[64:67]
	s_waitcnt lgkmcnt(5)
	v_mfma_f32_16x16x32_bf16 v[60:63], v[146:149], v[182:185], v[60:63]
	v_mfma_f32_16x16x32_bf16 v[56:59], v[158:161], v[182:185], v[56:59]
	s_waitcnt lgkmcnt(3)
	v_mfma_f32_16x16x32_bf16 v[48:51], v[146:149], v[190:193], v[48:51]
	v_mfma_f32_16x16x32_bf16 v[40:43], v[158:161], v[190:193], v[40:43]
	s_waitcnt lgkmcnt(1)
	v_mfma_f32_16x16x32_bf16 v[36:39], v[146:149], v[198:201], v[36:39]
	v_mfma_f32_16x16x32_bf16 v[32:35], v[158:161], v[198:201], v[32:35]
	v_mfma_f32_16x16x32_bf16 v[76:79], v[154:157], v[178:181], v[76:79]
	v_mfma_f32_16x16x32_bf16 v[64:67], v[162:165], v[178:181], v[64:67]
	v_mfma_f32_16x16x32_bf16 v[60:63], v[154:157], v[186:189], v[60:63]
	v_mfma_f32_16x16x32_bf16 v[56:59], v[162:165], v[186:189], v[56:59]
	v_mfma_f32_16x16x32_bf16 v[48:51], v[154:157], v[194:197], v[48:51]
	v_mfma_f32_16x16x32_bf16 v[40:43], v[162:165], v[194:197], v[40:43]
	s_waitcnt lgkmcnt(0)
	v_mfma_f32_16x16x32_bf16 v[36:39], v[154:157], v[202:205], v[36:39]
	v_mfma_f32_16x16x32_bf16 v[32:35], v[162:165], v[202:205], v[32:35]
	s_barrier
	s_add_i32 s24, 0, 0x1c000
	s_add_i32 s25, s48, s27
	v_add_u32_e32 v218, s24, v168
	v_lshl_add_u64 v[150:151], v[150:151], 0, s[6:7]
	s_mov_b32 m0, s25
	ds_read_b128 v[206:209], v218
	ds_read_b128 v[210:213], v218 offset:1024
	ds_read_b128 v[214:217], v218 offset:2048
	ds_read_b128 v[218:221], v218 offset:3072
	global_load_lds_dwordx4 v[150:151], off
	v_lshl_add_u64 v[150:151], v[166:167], 0, s[6:7]
	s_add_i32 m0, s25, 0x2000
	s_nop 0
	global_load_lds_dwordx4 v[150:151], off
	s_barrier
	s_waitcnt lgkmcnt(3)
	v_mfma_f32_16x16x32_bf16 v[124:127], v[206:209], v[174:177], v[124:127]
	s_waitcnt lgkmcnt(1)
	v_mfma_f32_16x16x32_bf16 v[120:123], v[214:217], v[174:177], v[120:123]
	v_mfma_f32_16x16x32_bf16 v[116:119], v[206:209], v[182:185], v[116:119]
	v_mfma_f32_16x16x32_bf16 v[112:115], v[214:217], v[182:185], v[112:115]
	v_mfma_f32_16x16x32_bf16 v[108:111], v[206:209], v[190:193], v[108:111]
	v_mfma_f32_16x16x32_bf16 v[104:107], v[214:217], v[190:193], v[104:107]
	v_mfma_f32_16x16x32_bf16 v[100:103], v[206:209], v[198:201], v[100:103]
	v_mfma_f32_16x16x32_bf16 v[96:99], v[214:217], v[198:201], v[96:99]
	v_mfma_f32_16x16x32_bf16 v[124:127], v[210:213], v[178:181], v[124:127]
	s_waitcnt lgkmcnt(0)
	v_mfma_f32_16x16x32_bf16 v[120:123], v[218:221], v[178:181], v[120:123]
	v_mfma_f32_16x16x32_bf16 v[116:119], v[210:213], v[186:189], v[116:119]
	v_mfma_f32_16x16x32_bf16 v[112:115], v[218:221], v[186:189], v[112:115]
	v_mfma_f32_16x16x32_bf16 v[108:111], v[210:213], v[194:197], v[108:111]
	v_mfma_f32_16x16x32_bf16 v[104:107], v[218:221], v[194:197], v[104:107]
	v_mfma_f32_16x16x32_bf16 v[100:103], v[210:213], v[202:205], v[100:103]
	v_mfma_f32_16x16x32_bf16 v[96:99], v[218:221], v[202:205], v[96:99]
	s_mov_b32 m0, s36
	v_lshl_add_u64 v[150:151], v[222:223], 0, s[6:7]
	s_barrier
	ds_read_b128 v[174:177], v171 offset:49152
	ds_read_b128 v[178:181], v171 offset:50176
	ds_read_b128 v[182:185], v171 offset:51200
	ds_read_b128 v[186:189], v171 offset:52224
	ds_read_b128 v[190:193], v171 offset:53248
	ds_read_b128 v[194:197], v171 offset:54272
	ds_read_b128 v[198:201], v171 offset:55296
	ds_read_b128 v[202:205], v171 offset:56320
	global_load_lds_dwordx4 v[150:151], off
	v_lshl_add_u64 v[150:151], v[224:225], 0, s[6:7]
	s_mov_b32 m0, s37
	s_nop 0
	global_load_lds_dwordx4 v[150:151], off
	s_barrier
; #define PG8_STAGE(bufoff, gbase, voff) do { _Pragma("unroll") for (int _i = 0; _i < 2; ++_i) \
;         __builtin_amdgcn_global_load_lds((const unsigned*)((const char*)(gbase) + (voff)[_i]), (LAS unsigned*)(lds + (bufoff) + ldsw + _i * 8192), 16, 0, 0); } while (0)
; #define PG8_LDA(dst, b, h) do { _Pragma("unroll") for (int m = 0; m < 4; ++m) _Pragma("unroll") for (int k = 0; k < 2; ++k) dst[m][k] = *(const LAS bf16x8*)(lds + PG8_SA(b, h) + aoff + m * 2048 + k * 1024); } while (0)
; #define PG8_LDB(dst, b, h) do { _Pragma("unroll") for (int n = 0; n < 2; ++n) _Pragma("unroll") for (int k = 0; k < 2; ++k) dst[n][k] = *(const LAS bf16x8*)(lds + PG8_SB(b, h) + boff + n * 2048 + k * 1024); } while (0)
; #define PG8_MMA(ai, bj, At, Bt) do { __builtin_amdgcn_s_setprio(1); _Pragma("unroll") for (int m = 0; m < 4; ++m) _Pragma("unroll") for (int n = 0; n < 2; ++n) _Pragma("unroll") for (int k = 0; k < 2; ++k) \
;         acc[ai][bj][m][n] = __builtin_amdgcn_mfma_f32_16x16x32_bf16(Bt[n][k], At[m][k], acc[ai][bj][m][n], 0, 0, 0); __builtin_amdgcn_s_setprio(0); } while (0)
; #define PG8_WAIT_V(n) asm volatile("s_waitcnt vmcnt(" #n ")" ::: "memory")
; #define PG8_BAR __builtin_amdgcn_s_barrier()
; template <class Epi>
; __device__ __forceinline__ void gemm_phase(LAS unsigned char* lds, const Gemm g, const StaticOrder& S, const Epi& E) {
;     ...
;         const bool has_next = S.next(ui + 1, nxt);
;         const char* nA = has_next ? (const char*)g.A + (size_t)nxt.pm * tstepA : cA; const char* nB = has_next ? (const char*)g.Bt + (size_t)nxt.pn * tstepB : cB;
;         for (int t = 0; t < nt; t += 2) {
;             const bool last = (t == nt - 2);
;             const char* a1 = cA + (size_t)(t + 1) * kstep;
;             const char* a2 = last ? nA : cA + (size_t)(t + 2) * kstep; const char* b2 = last ? nB : cB + (size_t)(t + 2) * kstep;
;             const char* a3 = a2 + kstep; const char* b3 = b2 + kstep;
;             if (last) E.pre(cur, wr, fr, epre);
;             PG8_LDB(B0, 0, 0); PG8_SCHED; PG8_LDA(At, 0, 0); PG8_STAGE(PG8_SA(1, 1), a1 + hstepA, voffA);
;             PG8_WAIT_L(8); PG8_BAR; PG8_WAIT_L(0); PG8_MMA(0, 0, At, B0); PG8_BAR; PG8_SCHED;
;             PG8_LDB(B1, 0, 1); PG8_STAGE(PG8_SB(0, 0), b2, voffB);
;             PG8_BAR; PG8_WAIT_L(0); PG8_MMA(0, 1, At, B1); PG8_BAR;
;     ...
;             PG8_WAIT_V(6); PG8_BAR; PG8_MMA(1, 1, At, B1); PG8_BAR;
	s_waitcnt lgkmcnt(7)
	v_mfma_f32_16x16x32_bf16 v[28:31], v[146:149], v[174:177], v[28:31]
	v_mfma_f32_16x16x32_bf16 v[24:27], v[158:161], v[174:177], v[24:27]
	s_waitcnt lgkmcnt(5)
	v_mfma_f32_16x16x32_bf16 v[20:23], v[146:149], v[182:185], v[20:23]
	v_mfma_f32_16x16x32_bf16 v[16:19], v[158:161], v[182:185], v[16:19]
	s_waitcnt lgkmcnt(3)
	v_mfma_f32_16x16x32_bf16 v[12:15], v[146:149], v[190:193], v[12:15]
	v_mfma_f32_16x16x32_bf16 v[8:11], v[158:161], v[190:193], v[8:11]
	s_waitcnt lgkmcnt(1)
	v_mfma_f32_16x16x32_bf16 v[4:7], v[146:149], v[198:201], v[4:7]
	v_mfma_f32_16x16x32_bf16 v[0:3], v[158:161], v[198:201], v[0:3]
	v_mfma_f32_16x16x32_bf16 v[28:31], v[154:157], v[178:181], v[28:31]
	v_mfma_f32_16x16x32_bf16 v[24:27], v[162:165], v[178:181], v[24:27]
	v_mfma_f32_16x16x32_bf16 v[20:23], v[154:157], v[186:189], v[20:23]
	v_mfma_f32_16x16x32_bf16 v[16:19], v[162:165], v[186:189], v[16:19]
	v_mfma_f32_16x16x32_bf16 v[12:15], v[154:157], v[194:197], v[12:15]
	v_mfma_f32_16x16x32_bf16 v[8:11], v[162:165], v[194:197], v[8:11]
	s_waitcnt lgkmcnt(0)
	v_mfma_f32_16x16x32_bf16 v[4:7], v[154:157], v[202:205], v[4:7]
	v_mfma_f32_16x16x32_bf16 v[0:3], v[162:165], v[202:205], v[0:3]
	s_barrier
	s_add_u32 s22, s22, 0x40080
	s_addc_u32 s23, s23, 0
	s_add_i32 s24, s24, s27
	v_lshl_add_u64 v[146:147], s[22:23], 0, v[132:133]
	s_mov_b32 m0, s24
	s_nop 0
	global_load_lds_dwordx4 v[146:147], off
	v_lshl_add_u64 v[146:147], s[22:23], 0, v[128:129]
	s_add_i32 m0, s24, 0x2000
	s_nop 0
	global_load_lds_dwordx4 v[146:147], off
	s_waitcnt vmcnt(6)
	s_barrier
	v_mfma_f32_16x16x32_bf16 v[92:95], v[206:209], v[174:177], v[92:95]
	v_mfma_f32_16x16x32_bf16 v[88:91], v[214:217], v[174:177], v[88:91]
	v_mfma_f32_16x16x32_bf16 v[84:87], v[206:209], v[182:185], v[84:87]
	v_mfma_f32_16x16x32_bf16 v[80:83], v[214:217], v[182:185], v[80:83]
	v_mfma_f32_16x16x32_bf16 v[72:75], v[206:209], v[190:193], v[72:75]
	v_mfma_f32_16x16x32_bf16 v[68:71], v[214:217], v[190:193], v[68:71]
	v_mfma_f32_16x16x32_bf16 v[52:55], v[206:209], v[198:201], v[52:55]
	v_mfma_f32_16x16x32_bf16 v[44:47], v[214:217], v[198:201], v[44:47]
	v_mfma_f32_16x16x32_bf16 v[92:95], v[210:213], v[178:181], v[92:95]
	v_mfma_f32_16x16x32_bf16 v[88:91], v[218:221], v[178:181], v[88:91]
	v_mfma_f32_16x16x32_bf16 v[84:87], v[210:213], v[186:189], v[84:87]
	v_mfma_f32_16x16x32_bf16 v[80:83], v[218:221], v[186:189], v[80:83]
	v_mfma_f32_16x16x32_bf16 v[72:75], v[210:213], v[194:197], v[72:75]
	v_mfma_f32_16x16x32_bf16 v[68:71], v[218:221], v[194:197], v[68:71]
	v_mfma_f32_16x16x32_bf16 v[52:55], v[210:213], v[202:205], v[52:55]
	v_mfma_f32_16x16x32_bf16 v[44:47], v[218:221], v[202:205], v[44:47]
	s_add_i32 s47, s47, 2
	s_add_u32 s20, s20, 0x100
	s_addc_u32 s21, s21, 0
	s_add_u32 s45, s45, 0x100
	s_addc_u32 s46, s46, 0
	s_cmp_gt_u32 s47, 13
	s_barrier
.LBB0_205:
	ds_read_b128 v[146:149], v170
	ds_read_b128 v[154:157], v170 offset:1024
	ds_read_b128 v[158:161], v170 offset:2048
	ds_read_b128 v[162:165], v170 offset:3072
	s_add_u32 s22, s20, 0xfffc0080
	s_addc_u32 s23, s21, -1
	s_cmp_eq_u32 s47, 12
	s_cselect_b32 s25, s13, s23
	s_cselect_b32 s24, s19, s22
	s_cselect_b32 s23, s11, s46
	s_cselect_b32 s22, s44, s45
	v_lshl_add_u64 v[150:151], s[20:21], 0, v[138:139]
	s_add_i32 m0, s30, 0xc000
	ds_read_b128 v[174:177], v171
	ds_read_b128 v[178:181], v171 offset:1024
	ds_read_b128 v[182:185], v171 offset:2048
	ds_read_b128 v[186:189], v171 offset:3072
	ds_read_b128 v[190:193], v171 offset:4096
	ds_read_b128 v[194:197], v171 offset:5120
	ds_read_b128 v[198:201], v171 offset:6144
	ds_read_b128 v[202:205], v171 offset:7168
	global_load_lds_dwordx4 v[150:151], off
	v_lshl_add_u64 v[150:151], s[20:21], 0, v[140:141]
	s_add_i32 m0, s30, 0xe000
	s_nop 0
	global_load_lds_dwordx4 v[150:151], off
	s_waitcnt lgkmcnt(8)
	s_barrier
	s_waitcnt lgkmcnt(7)
	v_mfma_f32_16x16x32_bf16 v[76:79], v[146:149], v[174:177], v[76:79]
	v_mfma_f32_16x16x32_bf16 v[64:67], v[158:161], v[174:177], v[64:67]
	s_waitcnt lgkmcnt(5)
	v_mfma_f32_16x16x32_bf16 v[60:63], v[146:149], v[182:185], v[60:63]
	v_mfma_f32_16x16x32_bf16 v[56:59], v[158:161], v[182:185], v[56:59]
	s_waitcnt lgkmcnt(3)
	v_mfma_f32_16x16x32_bf16 v[48:51], v[146:149], v[190:193], v[48:51]
	v_mfma_f32_16x16x32_bf16 v[40:43], v[158:161], v[190:193], v[40:43]
	s_waitcnt lgkmcnt(1)
	v_mfma_f32_16x16x32_bf16 v[36:39], v[146:149], v[198:201], v[36:39]
	v_mfma_f32_16x16x32_bf16 v[32:35], v[158:161], v[198:201], v[32:35]
	v_mfma_f32_16x16x32_bf16 v[76:79], v[154:157], v[178:181], v[76:79]
	v_mfma_f32_16x16x32_bf16 v[64:67], v[162:165], v[178:181], v[64:67]
	v_mfma_f32_16x16x32_bf16 v[60:63], v[154:157], v[186:189], v[60:63]
	v_mfma_f32_16x16x32_bf16 v[56:59], v[162:165], v[186:189], v[56:59]
	v_mfma_f32_16x16x32_bf16 v[48:51], v[154:157], v[194:197], v[48:51]
	v_mfma_f32_16x16x32_bf16 v[40:43], v[162:165], v[194:197], v[40:43]
	s_waitcnt lgkmcnt(0)
	v_mfma_f32_16x16x32_bf16 v[36:39], v[154:157], v[202:205], v[36:39]
	v_mfma_f32_16x16x32_bf16 v[32:35], v[162:165], v[202:205], v[32:35]
	s_barrier
	s_add_i32 s48, s39, s27
	v_lshl_add_u64 v[150:151], s[22:23], 0, v[132:133]
	s_mov_b32 m0, s48
	ds_read_b128 v[206:209], v172
	ds_read_b128 v[210:213], v172 offset:1024
	ds_read_b128 v[214:217], v172 offset:2048
	ds_read_b128 v[218:221], v172 offset:3072
	global_load_lds_dwordx4 v[150:151], off
	v_lshl_add_u64 v[166:167], s[22:23], 0, v[128:129]
	s_add_i32 m0, s48, 0x2000
	s_nop 0
	global_load_lds_dwordx4 v[166:167], off
	s_barrier
; #define PG8_STAGE(bufoff, gbase, voff) do { _Pragma("unroll") for (int _i = 0; _i < 2; ++_i) \
;         __builtin_amdgcn_global_load_lds((const unsigned*)((const char*)(gbase) + (voff)[_i]), (LAS unsigned*)(lds + (bufoff) + ldsw + _i * 8192), 16, 0, 0); } while (0)
; #define PG8_LDA(dst, b, h) do { _Pragma("unroll") for (int m = 0; m < 4; ++m) _Pragma("unroll") for (int k = 0; k < 2; ++k) dst[m][k] = *(const LAS bf16x8*)(lds + PG8_SA(b, h) + aoff + m * 2048 + k * 1024); } while (0)
; #define PG8_LDB(dst, b, h) do { _Pragma("unroll") for (int n = 0; n < 2; ++n) _Pragma("unroll") for (int k = 0; k < 2; ++k) dst[n][k] = *(const LAS bf16x8*)(lds + PG8_SB(b, h) + boff + n * 2048 + k * 1024); } while (0)
; #define PG8_MMA(ai, bj, At, Bt) do { __builtin_amdgcn_s_setprio(1); _Pragma("unroll") for (int m = 0; m < 4; ++m) _Pragma("unroll") for (int n = 0; n < 2; ++n) _Pragma("unroll") for (int k = 0; k < 2; ++k) \
;         acc[ai][bj][m][n] = __builtin_amdgcn_mfma_f32_16x16x32_bf16(Bt[n][k], At[m][k], acc[ai][bj][m][n], 0, 0, 0); __builtin_amdgcn_s_setprio(0); } while (0)
; #define PG8_WAIT_V(n) asm volatile("s_waitcnt vmcnt(" #n ")" ::: "memory")
; #define PG8_WAIT_L(n) asm volatile("s_waitcnt lgkmcnt(" #n ")" ::: "memory")
; #define PG8_BAR __builtin_amdgcn_s_barrier()
; #define PG8_SCHED __builtin_amdgcn_sched_barrier(0)
; template <class Epi>
; __device__ __forceinline__ void gemm_phase(LAS unsigned char* lds, const Gemm g, const StaticOrder& S, const Epi& E) {
;     ...
;             PG8_BAR; PG8_WAIT_L(0); PG8_MMA(0, 1, At, B1); PG8_BAR;
;             PG8_LDA(At, 0, 1); PG8_STAGE(PG8_SA(0, 0), a2, voffA);
;             PG8_BAR; PG8_WAIT_L(0); PG8_MMA(1, 0, At, B0); PG8_BAR; PG8_SCHED;
;             PG8_STAGE(PG8_SB(0, 1), b2 + hstepB, voffB);
;             PG8_WAIT_V(6); PG8_BAR; PG8_MMA(1, 1, At, B1); PG8_BAR;
;             PG8_LDB(B0, 1, 0); PG8_SCHED; PG8_LDA(At, 1, 0); PG8_STAGE(PG8_SA(0, 1), a2 + hstepA, voffA);
;             PG8_WAIT_L(8); PG8_BAR; PG8_WAIT_L(0); PG8_MMA(0, 0, At, B0); PG8_BAR; PG8_SCHED;
	s_waitcnt lgkmcnt(3)
	v_mfma_f32_16x16x32_bf16 v[124:127], v[206:209], v[174:177], v[124:127]
	s_waitcnt lgkmcnt(1)
	v_mfma_f32_16x16x32_bf16 v[120:123], v[214:217], v[174:177], v[120:123]
	v_mfma_f32_16x16x32_bf16 v[116:119], v[206:209], v[182:185], v[116:119]
	v_mfma_f32_16x16x32_bf16 v[112:115], v[214:217], v[182:185], v[112:115]
	v_mfma_f32_16x16x32_bf16 v[108:111], v[206:209], v[190:193], v[108:111]
	v_mfma_f32_16x16x32_bf16 v[104:107], v[214:217], v[190:193], v[104:107]
	v_mfma_f32_16x16x32_bf16 v[100:103], v[206:209], v[198:201], v[100:103]
	v_mfma_f32_16x16x32_bf16 v[96:99], v[214:217], v[198:201], v[96:99]
	v_mfma_f32_16x16x32_bf16 v[124:127], v[210:213], v[178:181], v[124:127]
	s_waitcnt lgkmcnt(0)
	v_mfma_f32_16x16x32_bf16 v[120:123], v[218:221], v[178:181], v[120:123]
	v_mfma_f32_16x16x32_bf16 v[116:119], v[210:213], v[186:189], v[116:119]
	v_mfma_f32_16x16x32_bf16 v[112:115], v[218:221], v[186:189], v[112:115]
	v_mfma_f32_16x16x32_bf16 v[108:111], v[210:213], v[194:197], v[108:111]
	v_mfma_f32_16x16x32_bf16 v[104:107], v[218:221], v[194:197], v[104:107]
	v_mfma_f32_16x16x32_bf16 v[100:103], v[210:213], v[202:205], v[100:103]
	v_mfma_f32_16x16x32_bf16 v[96:99], v[218:221], v[202:205], v[96:99]
	s_mov_b32 m0, s30
	v_lshl_add_u64 v[222:223], s[24:25], 0, v[134:135]
	s_barrier
	ds_read_b128 v[174:177], v171 offset:16384
	ds_read_b128 v[178:181], v171 offset:17408
	ds_read_b128 v[182:185], v171 offset:18432
	ds_read_b128 v[186:189], v171 offset:19456
	ds_read_b128 v[190:193], v171 offset:20480
	ds_read_b128 v[194:197], v171 offset:21504
	ds_read_b128 v[198:201], v171 offset:22528
	ds_read_b128 v[202:205], v171 offset:23552
	global_load_lds_dwordx4 v[222:223], off
	v_lshl_add_u64 v[224:225], s[24:25], 0, v[130:131]
	s_mov_b32 m0, s31
	s_nop 0
	global_load_lds_dwordx4 v[224:225], off
	s_barrier
	s_waitcnt lgkmcnt(7)
	v_mfma_f32_16x16x32_bf16 v[28:31], v[146:149], v[174:177], v[28:31]
	v_mfma_f32_16x16x32_bf16 v[24:27], v[158:161], v[174:177], v[24:27]
	s_waitcnt lgkmcnt(5)
	v_mfma_f32_16x16x32_bf16 v[20:23], v[146:149], v[182:185], v[20:23]
	v_mfma_f32_16x16x32_bf16 v[16:19], v[158:161], v[182:185], v[16:19]
	s_waitcnt lgkmcnt(3)
	v_mfma_f32_16x16x32_bf16 v[12:15], v[146:149], v[190:193], v[12:15]
	v_mfma_f32_16x16x32_bf16 v[8:11], v[158:161], v[190:193], v[8:11]
	s_waitcnt lgkmcnt(1)
	v_mfma_f32_16x16x32_bf16 v[4:7], v[146:149], v[198:201], v[4:7]
	v_mfma_f32_16x16x32_bf16 v[0:3], v[158:161], v[198:201], v[0:3]
	v_mfma_f32_16x16x32_bf16 v[28:31], v[154:157], v[178:181], v[28:31]
	v_mfma_f32_16x16x32_bf16 v[24:27], v[162:165], v[178:181], v[24:27]
	v_mfma_f32_16x16x32_bf16 v[20:23], v[154:157], v[186:189], v[20:23]
	v_mfma_f32_16x16x32_bf16 v[16:19], v[162:165], v[186:189], v[16:19]
	v_mfma_f32_16x16x32_bf16 v[12:15], v[154:157], v[194:197], v[12:15]
	v_mfma_f32_16x16x32_bf16 v[8:11], v[162:165], v[194:197], v[8:11]
	s_waitcnt lgkmcnt(0)
	v_mfma_f32_16x16x32_bf16 v[4:7], v[154:157], v[202:205], v[4:7]
	v_mfma_f32_16x16x32_bf16 v[0:3], v[162:165], v[202:205], v[0:3]
	s_barrier
	s_add_u32 s48, s22, 0x40000
	s_addc_u32 s49, s23, 0
	s_add_i32 s50, s40, s27
	v_lshl_add_u64 v[146:147], s[48:49], 0, v[132:133]
	s_mov_b32 m0, s50
	s_nop 0
	global_load_lds_dwordx4 v[146:147], off
	v_lshl_add_u64 v[146:147], s[48:49], 0, v[128:129]
	s_add_i32 m0, s50, 0x2000
	s_nop 0
	global_load_lds_dwordx4 v[146:147], off
	s_waitcnt vmcnt(6)
	s_barrier
	v_mfma_f32_16x16x32_bf16 v[92:95], v[206:209], v[174:177], v[92:95]
	v_mfma_f32_16x16x32_bf16 v[88:91], v[214:217], v[174:177], v[88:91]
	v_mfma_f32_16x16x32_bf16 v[84:87], v[206:209], v[182:185], v[84:87]
	v_mfma_f32_16x16x32_bf16 v[80:83], v[214:217], v[182:185], v[80:83]
	v_mfma_f32_16x16x32_bf16 v[72:75], v[206:209], v[190:193], v[72:75]
	v_mfma_f32_16x16x32_bf16 v[68:71], v[214:217], v[190:193], v[68:71]
	v_mfma_f32_16x16x32_bf16 v[52:55], v[206:209], v[198:201], v[52:55]
	v_mfma_f32_16x16x32_bf16 v[44:47], v[214:217], v[198:201], v[44:47]
	v_mfma_f32_16x16x32_bf16 v[92:95], v[210:213], v[178:181], v[92:95]
	v_mfma_f32_16x16x32_bf16 v[88:91], v[218:221], v[178:181], v[88:91]
	v_mfma_f32_16x16x32_bf16 v[84:87], v[210:213], v[186:189], v[84:87]
	v_mfma_f32_16x16x32_bf16 v[80:83], v[218:221], v[186:189], v[80:83]
	v_mfma_f32_16x16x32_bf16 v[72:75], v[210:213], v[194:197], v[72:75]
	v_mfma_f32_16x16x32_bf16 v[68:71], v[218:221], v[194:197], v[68:71]
	v_mfma_f32_16x16x32_bf16 v[52:55], v[210:213], v[202:205], v[52:55]
	v_mfma_f32_16x16x32_bf16 v[44:47], v[218:221], v[202:205], v[44:47]
	s_add_i32 s48, 0, 0x18000
	v_add_u32_e32 v162, s48, v168
	s_barrier
	ds_read_b128 v[146:149], v162
	ds_read_b128 v[154:157], v162 offset:1024
	ds_read_b128 v[158:161], v162 offset:2048
	ds_read_b128 v[162:165], v162 offset:3072
	s_add_u32 s24, s24, 0x40000
	s_addc_u32 s25, s25, 0
	s_mov_b32 m0, s33
	v_lshl_add_u64 v[206:207], s[24:25], 0, v[134:135]
	ds_read_b128 v[174:177], v171 offset:32768
	ds_read_b128 v[178:181], v171 offset:33792
	ds_read_b128 v[182:185], v171 offset:34816
	ds_read_b128 v[186:189], v171 offset:35840
	ds_read_b128 v[190:193], v171 offset:36864
	ds_read_b128 v[194:197], v171 offset:37888
	ds_read_b128 v[198:201], v171 offset:38912
	ds_read_b128 v[202:205], v171 offset:39936
	global_load_lds_dwordx4 v[206:207], off
	v_lshl_add_u64 v[206:207], s[24:25], 0, v[130:131]
	s_mov_b32 m0, s34
	s_nop 0
	global_load_lds_dwordx4 v[206:207], off
	s_waitcnt lgkmcnt(8)
	s_barrier
; #define PG8_STAGE(bufoff, gbase, voff) do { _Pragma("unroll") for (int _i = 0; _i < 2; ++_i) \
;         __builtin_amdgcn_global_load_lds((const unsigned*)((const char*)(gbase) + (voff)[_i]), (LAS unsigned*)(lds + (bufoff) + ldsw + _i * 8192), 16, 0, 0); } while (0)
; #define PG8_LDA(dst, b, h) do { _Pragma("unroll") for (int m = 0; m < 4; ++m) _Pragma("unroll") for (int k = 0; k < 2; ++k) dst[m][k] = *(const LAS bf16x8*)(lds + PG8_SA(b, h) + aoff + m * 2048 + k * 1024); } while (0)
; #define PG8_LDB(dst, b, h) do { _Pragma("unroll") for (int n = 0; n < 2; ++n) _Pragma("unroll") for (int k = 0; k < 2; ++k) dst[n][k] = *(const LAS bf16x8*)(lds + PG8_SB(b, h) + boff + n * 2048 + k * 1024); } while (0)
; #define PG8_MMA(ai, bj, At, Bt) do { __builtin_amdgcn_s_setprio(1); _Pragma("unroll") for (int m = 0; m < 4; ++m) _Pragma("unroll") for (int n = 0; n < 2; ++n) _Pragma("unroll") for (int k = 0; k < 2; ++k) \
;         acc[ai][bj][m][n] = __builtin_amdgcn_mfma_f32_16x16x32_bf16(Bt[n][k], At[m][k], acc[ai][bj][m][n], 0, 0, 0); __builtin_amdgcn_s_setprio(0); } while (0)
; #define PG8_WAIT_V(n) asm volatile("s_waitcnt vmcnt(" #n ")" ::: "memory")
; #define PG8_WAIT_L(n) asm volatile("s_waitcnt lgkmcnt(" #n ")" ::: "memory")
; #define PG8_BAR __builtin_amdgcn_s_barrier()
; #define PG8_SCHED __builtin_amdgcn_sched_barrier(0)
; template <class Epi>
; __device__ __forceinline__ void gemm_phase(LAS unsigned char* lds, const Gemm g, const StaticOrder& S, const Epi& E) {
;     ...
;             PG8_WAIT_L(8); PG8_BAR; PG8_WAIT_L(0); PG8_MMA(0, 0, At, B0); PG8_BAR; PG8_SCHED;
;             PG8_LDB(B1, 1, 1); PG8_STAGE(PG8_SB(1, 0), b3, voffB);
;             PG8_BAR; PG8_WAIT_L(0); PG8_MMA(0, 1, At, B1); PG8_BAR;
;             PG8_LDA(At, 1, 1); PG8_STAGE(PG8_SA(1, 0), a3, voffA);
;             PG8_BAR; PG8_WAIT_L(0); PG8_MMA(1, 0, At, B0); PG8_BAR; PG8_SCHED;
;             PG8_STAGE(PG8_SB(1, 1), b3 + hstepB, voffB);
;             PG8_WAIT_V(6); PG8_BAR; PG8_MMA(1, 1, At, B1); PG8_BAR;
	s_waitcnt lgkmcnt(7)
	v_mfma_f32_16x16x32_bf16 v[76:79], v[146:149], v[174:177], v[76:79]
	v_mfma_f32_16x16x32_bf16 v[64:67], v[158:161], v[174:177], v[64:67]
	s_waitcnt lgkmcnt(5)
	v_mfma_f32_16x16x32_bf16 v[60:63], v[146:149], v[182:185], v[60:63]
	v_mfma_f32_16x16x32_bf16 v[56:59], v[158:161], v[182:185], v[56:59]
	s_waitcnt lgkmcnt(3)
	v_mfma_f32_16x16x32_bf16 v[48:51], v[146:149], v[190:193], v[48:51]
	v_mfma_f32_16x16x32_bf16 v[40:43], v[158:161], v[190:193], v[40:43]
	s_waitcnt lgkmcnt(1)
	v_mfma_f32_16x16x32_bf16 v[36:39], v[146:149], v[198:201], v[36:39]
	v_mfma_f32_16x16x32_bf16 v[32:35], v[158:161], v[198:201], v[32:35]
	v_mfma_f32_16x16x32_bf16 v[76:79], v[154:157], v[178:181], v[76:79]
	v_mfma_f32_16x16x32_bf16 v[64:67], v[162:165], v[178:181], v[64:67]
	v_mfma_f32_16x16x32_bf16 v[60:63], v[154:157], v[186:189], v[60:63]
	v_mfma_f32_16x16x32_bf16 v[56:59], v[162:165], v[186:189], v[56:59]
	v_mfma_f32_16x16x32_bf16 v[48:51], v[154:157], v[194:197], v[48:51]
	v_mfma_f32_16x16x32_bf16 v[40:43], v[162:165], v[194:197], v[40:43]
	s_waitcnt lgkmcnt(0)
	v_mfma_f32_16x16x32_bf16 v[36:39], v[154:157], v[202:205], v[36:39]
	v_mfma_f32_16x16x32_bf16 v[32:35], v[162:165], v[202:205], v[32:35]
	s_barrier
	s_add_i32 s24, 0, 0x1c000
	s_add_i32 s25, s48, s27
	v_add_u32_e32 v218, s24, v168
	v_lshl_add_u64 v[150:151], v[150:151], 0, s[6:7]
	s_mov_b32 m0, s25
	ds_read_b128 v[206:209], v218
	ds_read_b128 v[210:213], v218 offset:1024
	ds_read_b128 v[214:217], v218 offset:2048
	ds_read_b128 v[218:221], v218 offset:3072
	global_load_lds_dwordx4 v[150:151], off
	v_lshl_add_u64 v[150:151], v[166:167], 0, s[6:7]
	s_add_i32 m0, s25, 0x2000
	s_nop 0
	global_load_lds_dwordx4 v[150:151], off
	s_barrier
	s_waitcnt lgkmcnt(3)
	v_mfma_f32_16x16x32_bf16 v[124:127], v[206:209], v[174:177], v[124:127]
	s_waitcnt lgkmcnt(1)
	v_mfma_f32_16x16x32_bf16 v[120:123], v[214:217], v[174:177], v[120:123]
	v_mfma_f32_16x16x32_bf16 v[116:119], v[206:209], v[182:185], v[116:119]
	v_mfma_f32_16x16x32_bf16 v[112:115], v[214:217], v[182:185], v[112:115]
	v_mfma_f32_16x16x32_bf16 v[108:111], v[206:209], v[190:193], v[108:111]
	v_mfma_f32_16x16x32_bf16 v[104:107], v[214:217], v[190:193], v[104:107]
	v_mfma_f32_16x16x32_bf16 v[100:103], v[206:209], v[198:201], v[100:103]
	v_mfma_f32_16x16x32_bf16 v[96:99], v[214:217], v[198:201], v[96:99]
	v_mfma_f32_16x16x32_bf16 v[124:127], v[210:213], v[178:181], v[124:127]
	s_waitcnt lgkmcnt(0)
	v_mfma_f32_16x16x32_bf16 v[120:123], v[218:221], v[178:181], v[120:123]
	v_mfma_f32_16x16x32_bf16 v[116:119], v[210:213], v[186:189], v[116:119]
	v_mfma_f32_16x16x32_bf16 v[112:115], v[218:221], v[186:189], v[112:115]
	v_mfma_f32_16x16x32_bf16 v[108:111], v[210:213], v[194:197], v[108:111]
	v_mfma_f32_16x16x32_bf16 v[104:107], v[218:221], v[194:197], v[104:107]
	v_mfma_f32_16x16x32_bf16 v[100:103], v[210:213], v[202:205], v[100:103]
	v_mfma_f32_16x16x32_bf16 v[96:99], v[218:221], v[202:205], v[96:99]
	s_mov_b32 m0, s36
	v_lshl_add_u64 v[150:151], v[222:223], 0, s[6:7]
	s_barrier
	ds_read_b128 v[174:177], v171 offset:49152
	ds_read_b128 v[178:181], v171 offset:50176
	ds_read_b128 v[182:185], v171 offset:51200
	ds_read_b128 v[186:189], v171 offset:52224
	ds_read_b128 v[190:193], v171 offset:53248
	ds_read_b128 v[194:197], v171 offset:54272
	ds_read_b128 v[198:201], v171 offset:55296
	ds_read_b128 v[202:205], v171 offset:56320
	global_load_lds_dwordx4 v[150:151], off
	v_lshl_add_u64 v[150:151], v[224:225], 0, s[6:7]
	s_mov_b32 m0, s37
	s_nop 0
	global_load_lds_dwordx4 v[150:151], off
	s_barrier
	s_waitcnt lgkmcnt(7)
	v_mfma_f32_16x16x32_bf16 v[28:31], v[146:149], v[174:177], v[28:31]
	v_mfma_f32_16x16x32_bf16 v[24:27], v[158:161], v[174:177], v[24:27]
	s_waitcnt lgkmcnt(5)
	v_mfma_f32_16x16x32_bf16 v[20:23], v[146:149], v[182:185], v[20:23]
	v_mfma_f32_16x16x32_bf16 v[16:19], v[158:161], v[182:185], v[16:19]
	s_waitcnt lgkmcnt(3)
	v_mfma_f32_16x16x32_bf16 v[12:15], v[146:149], v[190:193], v[12:15]
	v_mfma_f32_16x16x32_bf16 v[8:11], v[158:161], v[190:193], v[8:11]
	s_waitcnt lgkmcnt(1)
	v_mfma_f32_16x16x32_bf16 v[4:7], v[146:149], v[198:201], v[4:7]
	v_mfma_f32_16x16x32_bf16 v[0:3], v[158:161], v[198:201], v[0:3]
	v_mfma_f32_16x16x32_bf16 v[28:31], v[154:157], v[178:181], v[28:31]
	v_mfma_f32_16x16x32_bf16 v[24:27], v[162:165], v[178:181], v[24:27]
	v_mfma_f32_16x16x32_bf16 v[20:23], v[154:157], v[186:189], v[20:23]
	v_mfma_f32_16x16x32_bf16 v[16:19], v[162:165], v[186:189], v[16:19]
	v_mfma_f32_16x16x32_bf16 v[12:15], v[154:157], v[194:197], v[12:15]
	v_mfma_f32_16x16x32_bf16 v[8:11], v[162:165], v[194:197], v[8:11]
	s_waitcnt lgkmcnt(0)
	v_mfma_f32_16x16x32_bf16 v[4:7], v[154:157], v[202:205], v[4:7]
	v_mfma_f32_16x16x32_bf16 v[0:3], v[162:165], v[202:205], v[0:3]
	s_barrier
	s_add_u32 s22, s22, 0x40080
	s_addc_u32 s23, s23, 0
	s_add_i32 s24, s24, s27
	v_lshl_add_u64 v[146:147], s[22:23], 0, v[132:133]
	s_mov_b32 m0, s24
	s_nop 0
	global_load_lds_dwordx4 v[146:147], off
	v_lshl_add_u64 v[146:147], s[22:23], 0, v[128:129]
	s_add_i32 m0, s24, 0x2000
	s_nop 0
	global_load_lds_dwordx4 v[146:147], off
	s_waitcnt vmcnt(6)
	s_barrier
; #define PG8_WAIT_V(n) asm volatile("s_waitcnt vmcnt(" #n ")" ::: "memory")
; #define PG8_BAR __builtin_amdgcn_s_barrier()
;     __device__ __forceinline__ void operator()(const f32x4 (&acc)[2][2][4][2], const Unit& u, int wr, int wc, int fr, int fq, const float (&)[8]) const {
;         const int row0 = u.pm * BM + wr * 64 + fr;
;         float ep[8];
; #pragma unroll
;         for (int ai = 0; ai < 2; ++ai)
; #pragma unroll
;             for (int m = 0; m < 4; ++m) { const int row = row0 + ai * HALF + m * 16;
;                 if (SLOTS == 1) ep[ai * 4 + m] = ss[row];
;                 else { const f32x4 pq = *(const f32x4*)(ss + (size_t)row * 16 + 4 * fq); ep[ai * 4 + m] = (pq[0] + pq[1]) + (pq[2] + pq[3]); } }
;         if (SLOTS != 1) {
; #pragma unroll
;             for (int q = 0; q < 8; ++q) { ep[q] += __shfl_xor(ep[q], 16); ep[q] += __shfl_xor(ep[q], 32); } }
;         if (DT && u.pn == 20) {
;             if (wc == 0) {
; #pragma unroll
;                 for (int ai = 0; ai < 2; ++ai)
; #pragma unroll
;                     for (int m = 0; m < 4; ++m) { const int row = row0 + ai * HALF + m * 16; const float rs = rsqrtf(ep[ai * 4 + m] * (1.0f / 1024.0f) + EPS);
;                         *(f32x4*)(dt + (size_t)row * 32 + 8 * fq) = acc[ai][0][m][0] * rs; *(f32x4*)(dt + (size_t)row * 32 + 8 * fq + 4) = acc[ai][0][m][1] * rs; }
;             }
;             return;
;         }
;         const int col0 = u.pn * BM + wc * 32 + 8 * fq;
; #pragma unroll
;         for (int ai = 0; ai < 2; ++ai)
; #pragma unroll
; template <class Epi>
; __device__ __forceinline__ void gemm_phase(LAS unsigned char* lds, const Gemm g, const StaticOrder& S, const Epi& E) {
;     ...
;             PG8_WAIT_V(6); PG8_BAR; PG8_MMA(1, 1, At, B1); PG8_BAR;
;             PG8_LDB(B0, 1, 0); PG8_SCHED; PG8_LDA(At, 1, 0); PG8_STAGE(PG8_SA(0, 1), a2 + hstepA, voffA);
;             PG8_WAIT_L(8); PG8_BAR; PG8_WAIT_L(0); PG8_MMA(0, 0, At, B0); PG8_BAR; PG8_SCHED;
;             PG8_LDB(B1, 1, 1); PG8_STAGE(PG8_SB(1, 0), b3, voffB);
;             PG8_BAR; PG8_WAIT_L(0); PG8_MMA(0, 1, At, B1); PG8_BAR;
;             PG8_LDA(At, 1, 1); PG8_STAGE(PG8_SA(1, 0), a3, voffA);
;             PG8_BAR; PG8_WAIT_L(0); PG8_MMA(1, 0, At, B0); PG8_BAR; PG8_SCHED;
;             PG8_STAGE(PG8_SB(1, 1), b3 + hstepB, voffB);
;             PG8_WAIT_V(6); PG8_BAR; PG8_MMA(1, 1, At, B1); PG8_BAR;
;         }
	v_mfma_f32_16x16x32_bf16 v[92:95], v[206:209], v[174:177], v[92:95]
	v_mfma_f32_16x16x32_bf16 v[88:91], v[214:217], v[174:177], v[88:91]
	v_mfma_f32_16x16x32_bf16 v[84:87], v[206:209], v[182:185], v[84:87]
	v_mfma_f32_16x16x32_bf16 v[80:83], v[214:217], v[182:185], v[80:83]
	v_mfma_f32_16x16x32_bf16 v[72:75], v[206:209], v[190:193], v[72:75]
	v_mfma_f32_16x16x32_bf16 v[68:71], v[214:217], v[190:193], v[68:71]
	v_mfma_f32_16x16x32_bf16 v[52:55], v[206:209], v[198:201], v[52:55]
	v_mfma_f32_16x16x32_bf16 v[44:47], v[214:217], v[198:201], v[44:47]
	v_mfma_f32_16x16x32_bf16 v[92:95], v[210:213], v[178:181], v[92:95]
	v_mfma_f32_16x16x32_bf16 v[88:91], v[218:221], v[178:181], v[88:91]
	v_mfma_f32_16x16x32_bf16 v[84:87], v[210:213], v[186:189], v[84:87]
	v_mfma_f32_16x16x32_bf16 v[80:83], v[218:221], v[186:189], v[80:83]
	v_mfma_f32_16x16x32_bf16 v[72:75], v[210:213], v[194:197], v[72:75]
	v_mfma_f32_16x16x32_bf16 v[68:71], v[218:221], v[194:197], v[68:71]
	v_mfma_f32_16x16x32_bf16 v[52:55], v[210:213], v[202:205], v[52:55]
	v_mfma_f32_16x16x32_bf16 v[44:47], v[218:221], v[202:205], v[44:47]
	s_add_i32 s47, s47, 2
	s_add_u32 s20, s20, 0x100
	s_addc_u32 s21, s21, 0
	s_add_u32 s45, s45, 0x100
	s_addc_u32 s46, s46, 0
	s_cmp_gt_u32 s47, 13
	s_barrier
	s_cbranch_scc0 .LBB0_205
	s_bfe_u32 vcc_lo, s18, 0x20003
	s_lshl_b32 vcc_lo, vcc_lo, 10
	s_add_i32 vcc_lo, vcc_lo, 0x20010
	v_lshl_add_u32 v236, v153, 2, vcc_lo
	ds_read_b32 v228, v236
	ds_read_b32 v229, v236 offset:64
	ds_read_b32 v230, v236 offset:128
	ds_read_b32 v231, v236 offset:192
	ds_read_b32 v232, v236 offset:512
	ds_read_b32 v233, v236 offset:576
	ds_read_b32 v234, v236 offset:640
	ds_read_b32 v235, v236 offset:704
	s_waitcnt lgkmcnt(0)
	v_lshl_add_u32 v162, s18, 8, v153
	v_ashrrev_i32_e32 v163, 31, v162
	v_or_b32_e32 v160, 16, v162
	v_or_b32_e32 v158, 32, v162
	v_or_b32_e32 v156, 48, v162
	v_ashrrev_i32_e32 v161, 31, v160
	v_ashrrev_i32_e32 v159, 31, v158
	v_ashrrev_i32_e32 v157, 31, v156
	v_add_u32_e32 v154, 0x80, v162
	v_add_u32_e32 v150, 0x90, v162
	v_add_u32_e32 v148, 0xa0, v162
	v_add_u32_e32 v146, 0xb0, v162
	v_ashrrev_i32_e32 v155, 31, v154
	v_ashrrev_i32_e32 v151, 31, v150
	v_ashrrev_i32_e32 v149, 31, v148
	v_ashrrev_i32_e32 v147, 31, v146
	s_cmp_lg_u32 s43, 20
	s_mov_b64 s[18:19], -1
	s_cbranch_scc0 .LBB0_208
	s_waitcnt vmcnt(8)
	v_lshl_or_b32 v166, s43, 8, v169
	v_ashrrev_i32_e32 v167, 31, v166
	v_lshlrev_b64 v[166:167], 1, v[166:167]
	v_mov_b32_e32 v186, v228
	v_mov_b64_e32 v[164:165], s[96:97]
	v_mad_i64_i32 v[182:183], s[18:19], v162, s42, v[164:165]
	v_lshl_add_u64 v[188:189], v[182:183], 0, v[166:167]
	v_pk_mul_f32 v[184:185], v[78:79], v[186:187] op_sel_hi:[1,0]
	v_pk_mul_f32 v[182:183], v[76:77], v[186:187] op_sel_hi:[1,0]
	v_pk_mul_f32 v[190:191], v[66:67], v[186:187] op_sel_hi:[1,0]
	v_pk_mul_f32 v[192:193], v[64:65], v[186:187] op_sel_hi:[1,0]
	v_cvt_pk_bf16_f32 v182, v182, v183
	v_cvt_pk_bf16_f32 v183, v184, v185
	v_cvt_pk_bf16_f32 v184, v192, v193
	v_cvt_pk_bf16_f32 v185, v190, v191
	v_pk_mul_f32 v[124:125], v[124:125], v[186:187] op_sel_hi:[1,0]
	global_store_dwordx4 v[188:189], v[182:185], off
	v_pk_mul_f32 v[126:127], v[126:127], v[186:187] op_sel_hi:[1,0]
	s_nop 0
	v_pk_mul_f32 v[182:183], v[122:123], v[186:187] op_sel_hi:[1,0]
	v_pk_mul_f32 v[122:123], v[120:121], v[186:187] op_sel_hi:[1,0]
	v_cvt_pk_bf16_f32 v120, v124, v125
	v_cvt_pk_bf16_f32 v121, v126, v127
	v_cvt_pk_bf16_f32 v122, v122, v123
	v_cvt_pk_bf16_f32 v123, v182, v183
	global_store_dwordx4 v[188:189], v[120:123], off offset:256
	s_nop 1
	v_mov_b32_e32 v124, v229
	v_mad_i64_i32 v[120:121], s[18:19], v160, s42, v[164:165]
	v_lshl_add_u64 v[126:127], v[120:121], 0, v[166:167]
	v_pk_mul_f32 v[122:123], v[62:63], v[124:125] op_sel_hi:[1,0]
	v_pk_mul_f32 v[120:121], v[60:61], v[124:125] op_sel_hi:[1,0]
	v_pk_mul_f32 v[182:183], v[58:59], v[124:125] op_sel_hi:[1,0]
	v_pk_mul_f32 v[184:185], v[56:57], v[124:125] op_sel_hi:[1,0]
	v_cvt_pk_bf16_f32 v120, v120, v121
	v_cvt_pk_bf16_f32 v121, v122, v123
	v_cvt_pk_bf16_f32 v122, v184, v185
	v_cvt_pk_bf16_f32 v123, v182, v183
	v_pk_mul_f32 v[116:117], v[116:117], v[124:125] op_sel_hi:[1,0]
	global_store_dwordx4 v[126:127], v[120:123], off
	v_pk_mul_f32 v[118:119], v[118:119], v[124:125] op_sel_hi:[1,0]
	s_nop 0
	v_pk_mul_f32 v[120:121], v[114:115], v[124:125] op_sel_hi:[1,0]
	v_pk_mul_f32 v[114:115], v[112:113], v[124:125] op_sel_hi:[1,0]
	v_cvt_pk_bf16_f32 v112, v116, v117
	v_cvt_pk_bf16_f32 v113, v118, v119
	v_cvt_pk_bf16_f32 v114, v114, v115
	v_cvt_pk_bf16_f32 v115, v120, v121
	global_store_dwordx4 v[126:127], v[112:115], off offset:256
	s_nop 1
	v_mov_b32_e32 v116, v230
	v_mad_i64_i32 v[112:113], s[18:19], v158, s42, v[164:165]
	v_lshl_add_u64 v[118:119], v[112:113], 0, v[166:167]
	v_pk_mul_f32 v[114:115], v[50:51], v[116:117] op_sel_hi:[1,0]
	v_pk_mul_f32 v[112:113], v[48:49], v[116:117] op_sel_hi:[1,0]
	v_pk_mul_f32 v[120:121], v[42:43], v[116:117] op_sel_hi:[1,0]
	v_pk_mul_f32 v[122:123], v[40:41], v[116:117] op_sel_hi:[1,0]
	v_cvt_pk_bf16_f32 v112, v112, v113
	v_cvt_pk_bf16_f32 v113, v114, v115
	v_cvt_pk_bf16_f32 v114, v122, v123
	v_cvt_pk_bf16_f32 v115, v120, v121
	v_pk_mul_f32 v[108:109], v[108:109], v[116:117] op_sel_hi:[1,0]
	global_store_dwordx4 v[118:119], v[112:115], off
	v_pk_mul_f32 v[110:111], v[110:111], v[116:117] op_sel_hi:[1,0]
	s_nop 0
; __device__ __forceinline__ unsigned pk2(float lo, float hi) { const f32x2 v = (f32x2){lo, hi}; const bf16x2_t b = __builtin_convertvector(v, bf16x2_t); return __builtin_bit_cast(unsigned, b); }
;     __device__ __forceinline__ void operator()(const f32x4 (&acc)[2][2][4][2], const Unit& u, int wr, int wc, int fr, int fq, const float (&)[8]) const {
;     ...
;             for (int m = 0; m < 4; ++m) { const int row = row0 + ai * HALF + m * 16; const float rs = rsqrtf(ep[ai * 4 + m] * (1.0f / 1024.0f) + EPS);
;                 u16* rowp = O + (size_t)row * ldc + col0;
; #pragma unroll
;                 for (int bj = 0; bj < 2; ++bj) { f32x4 v0 = acc[ai][bj][m][0] * rs, v1 = acc[ai][bj][m][1] * rs;
;                     if (ACT == 1) {
; #pragma unroll
;                         for (int j = 0; j < 4; ++j) { const float a0 = fmaxf(v0[j], 0.f), a1 = fmaxf(v1[j], 0.f); v0[j] = a0 * a0; v1[j] = a1 * a1; } }
;                     u32x4 w; w.x = pk2(v0[0], v0[1]); w.y = pk2(v0[2], v0[3]); w.z = pk2(v1[0], v1[1]); w.w = pk2(v1[2], v1[3]);
;                     *(u32x4*)(rowp + bj * HALF) = w; } }
	v_pk_mul_f32 v[112:113], v[106:107], v[116:117] op_sel_hi:[1,0]
	v_pk_mul_f32 v[106:107], v[104:105], v[116:117] op_sel_hi:[1,0]
	v_cvt_pk_bf16_f32 v104, v108, v109
	v_cvt_pk_bf16_f32 v105, v110, v111
	v_cvt_pk_bf16_f32 v106, v106, v107
	v_cvt_pk_bf16_f32 v107, v112, v113
	global_store_dwordx4 v[118:119], v[104:107], off offset:256
	s_nop 1
	v_mov_b32_e32 v108, v231
	v_mad_i64_i32 v[104:105], s[18:19], v156, s42, v[164:165]
	v_lshl_add_u64 v[110:111], v[104:105], 0, v[166:167]
	v_pk_mul_f32 v[106:107], v[38:39], v[108:109] op_sel_hi:[1,0]
	v_pk_mul_f32 v[104:105], v[36:37], v[108:109] op_sel_hi:[1,0]
	v_pk_mul_f32 v[112:113], v[34:35], v[108:109] op_sel_hi:[1,0]
	v_pk_mul_f32 v[114:115], v[32:33], v[108:109] op_sel_hi:[1,0]
	v_cvt_pk_bf16_f32 v104, v104, v105
	v_cvt_pk_bf16_f32 v105, v106, v107
	v_cvt_pk_bf16_f32 v106, v114, v115
	v_cvt_pk_bf16_f32 v107, v112, v113
	v_pk_mul_f32 v[100:101], v[100:101], v[108:109] op_sel_hi:[1,0]
	global_store_dwordx4 v[110:111], v[104:107], off
	v_pk_mul_f32 v[102:103], v[102:103], v[108:109] op_sel_hi:[1,0]
	s_nop 0
	v_pk_mul_f32 v[104:105], v[98:99], v[108:109] op_sel_hi:[1,0]
	v_pk_mul_f32 v[98:99], v[96:97], v[108:109] op_sel_hi:[1,0]
	v_cvt_pk_bf16_f32 v96, v100, v101
	v_cvt_pk_bf16_f32 v97, v102, v103
	v_cvt_pk_bf16_f32 v98, v98, v99
	v_cvt_pk_bf16_f32 v99, v104, v105
	global_store_dwordx4 v[110:111], v[96:99], off offset:256
	s_nop 1
	v_mov_b32_e32 v100, v232
	v_mad_i64_i32 v[96:97], s[18:19], v154, s42, v[164:165]
	v_lshl_add_u64 v[102:103], v[96:97], 0, v[166:167]
	v_pk_mul_f32 v[98:99], v[30:31], v[100:101] op_sel_hi:[1,0]
	v_pk_mul_f32 v[96:97], v[28:29], v[100:101] op_sel_hi:[1,0]
	v_pk_mul_f32 v[104:105], v[26:27], v[100:101] op_sel_hi:[1,0]
	v_pk_mul_f32 v[106:107], v[24:25], v[100:101] op_sel_hi:[1,0]
	v_cvt_pk_bf16_f32 v96, v96, v97
	v_cvt_pk_bf16_f32 v97, v98, v99
	v_cvt_pk_bf16_f32 v98, v106, v107
	v_cvt_pk_bf16_f32 v99, v104, v105
	v_pk_mul_f32 v[92:93], v[92:93], v[100:101] op_sel_hi:[1,0]
	global_store_dwordx4 v[102:103], v[96:99], off
	v_pk_mul_f32 v[94:95], v[94:95], v[100:101] op_sel_hi:[1,0]
	s_nop 0
	v_pk_mul_f32 v[96:97], v[90:91], v[100:101] op_sel_hi:[1,0]
	v_pk_mul_f32 v[90:91], v[88:89], v[100:101] op_sel_hi:[1,0]
	v_cvt_pk_bf16_f32 v88, v92, v93
	v_cvt_pk_bf16_f32 v89, v94, v95
	v_cvt_pk_bf16_f32 v90, v90, v91
	v_cvt_pk_bf16_f32 v91, v96, v97
	global_store_dwordx4 v[102:103], v[88:91], off offset:256
	s_nop 1
	v_mov_b32_e32 v92, v233
	v_mad_i64_i32 v[88:89], s[18:19], v150, s42, v[164:165]
	v_lshl_add_u64 v[94:95], v[88:89], 0, v[166:167]
	v_pk_mul_f32 v[90:91], v[22:23], v[92:93] op_sel_hi:[1,0]
	v_pk_mul_f32 v[88:89], v[20:21], v[92:93] op_sel_hi:[1,0]
	v_pk_mul_f32 v[96:97], v[18:19], v[92:93] op_sel_hi:[1,0]
	v_pk_mul_f32 v[98:99], v[16:17], v[92:93] op_sel_hi:[1,0]
	v_cvt_pk_bf16_f32 v88, v88, v89
	v_cvt_pk_bf16_f32 v89, v90, v91
	v_cvt_pk_bf16_f32 v90, v98, v99
	v_cvt_pk_bf16_f32 v91, v96, v97
	v_pk_mul_f32 v[84:85], v[84:85], v[92:93] op_sel_hi:[1,0]
	global_store_dwordx4 v[94:95], v[88:91], off
	v_pk_mul_f32 v[86:87], v[86:87], v[92:93] op_sel_hi:[1,0]
	s_nop 0
	v_pk_mul_f32 v[88:89], v[82:83], v[92:93] op_sel_hi:[1,0]
	v_pk_mul_f32 v[82:83], v[80:81], v[92:93] op_sel_hi:[1,0]
	v_cvt_pk_bf16_f32 v80, v84, v85
	v_cvt_pk_bf16_f32 v81, v86, v87
	v_cvt_pk_bf16_f32 v82, v82, v83
	v_cvt_pk_bf16_f32 v83, v88, v89
	global_store_dwordx4 v[94:95], v[80:83], off offset:256
	s_nop 1
	v_mov_b32_e32 v84, v234
	v_mad_i64_i32 v[80:81], s[18:19], v148, s42, v[164:165]
	v_lshl_add_u64 v[86:87], v[80:81], 0, v[166:167]
	v_pk_mul_f32 v[82:83], v[14:15], v[84:85] op_sel_hi:[1,0]
	v_pk_mul_f32 v[80:81], v[12:13], v[84:85] op_sel_hi:[1,0]
	v_pk_mul_f32 v[88:89], v[10:11], v[84:85] op_sel_hi:[1,0]
	v_pk_mul_f32 v[90:91], v[8:9], v[84:85] op_sel_hi:[1,0]
	v_cvt_pk_bf16_f32 v80, v80, v81
	v_cvt_pk_bf16_f32 v81, v82, v83
	v_cvt_pk_bf16_f32 v82, v90, v91
	v_cvt_pk_bf16_f32 v83, v88, v89
	v_pk_mul_f32 v[72:73], v[72:73], v[84:85] op_sel_hi:[1,0]
	global_store_dwordx4 v[86:87], v[80:83], off
	v_pk_mul_f32 v[74:75], v[74:75], v[84:85] op_sel_hi:[1,0]
	s_nop 0
	v_pk_mul_f32 v[80:81], v[70:71], v[84:85] op_sel_hi:[1,0]
	v_pk_mul_f32 v[70:71], v[68:69], v[84:85] op_sel_hi:[1,0]
	v_cvt_pk_bf16_f32 v68, v72, v73
	v_cvt_pk_bf16_f32 v69, v74, v75
	v_cvt_pk_bf16_f32 v70, v70, v71
	v_cvt_pk_bf16_f32 v71, v80, v81
	global_store_dwordx4 v[86:87], v[68:71], off offset:256
	s_nop 1
	v_mov_b32_e32 v72, v235
	v_mad_i64_i32 v[68:69], s[18:19], v146, s42, v[164:165]
	v_lshl_add_u64 v[74:75], v[68:69], 0, v[166:167]
	v_pk_mul_f32 v[70:71], v[6:7], v[72:73] op_sel_hi:[1,0]
	v_pk_mul_f32 v[68:69], v[4:5], v[72:73] op_sel_hi:[1,0]
	v_pk_mul_f32 v[80:81], v[2:3], v[72:73] op_sel_hi:[1,0]
	v_pk_mul_f32 v[82:83], v[0:1], v[72:73] op_sel_hi:[1,0]
	v_cvt_pk_bf16_f32 v68, v68, v69
	v_cvt_pk_bf16_f32 v69, v70, v71
	v_cvt_pk_bf16_f32 v70, v82, v83
	v_cvt_pk_bf16_f32 v71, v80, v81
	global_store_dwordx4 v[74:75], v[68:71], off
	v_pk_mul_f32 v[54:55], v[54:55], v[72:73] op_sel_hi:[1,0]
	v_pk_mul_f32 v[52:53], v[52:53], v[72:73] op_sel_hi:[1,0]
	v_pk_mul_f32 v[68:69], v[46:47], v[72:73] op_sel_hi:[1,0]
	v_pk_mul_f32 v[46:47], v[44:45], v[72:73] op_sel_hi:[1,0]
	v_cvt_pk_bf16_f32 v44, v52, v53
	v_cvt_pk_bf16_f32 v45, v54, v55
	v_cvt_pk_bf16_f32 v46, v46, v47
	v_cvt_pk_bf16_f32 v47, v68, v69
	global_store_dwordx4 v[74:75], v[44:47], off offset:256
	s_mov_b64 s[18:19], 0

; #define PG8_STAGE(bufoff, gbase, voff) do { _Pragma("unroll") for (int _i = 0; _i < 2; ++_i) \
;         __builtin_amdgcn_global_load_lds((const unsigned*)((const char*)(gbase) + (voff)[_i]), (LAS unsigned*)(lds + (bufoff) + ldsw + _i * 8192), 16, 0, 0); } while (0)
; #define PG8_LDA(dst, b, h) do { _Pragma("unroll") for (int m = 0; m < 4; ++m) _Pragma("unroll") for (int k = 0; k < 2; ++k) dst[m][k] = *(const LAS bf16x8*)(lds + PG8_SA(b, h) + aoff + m * 2048 + k * 1024); } while (0)
; #define PG8_LDB(dst, b, h) do { _Pragma("unroll") for (int n = 0; n < 2; ++n) _Pragma("unroll") for (int k = 0; k < 2; ++k) dst[n][k] = *(const LAS bf16x8*)(lds + PG8_SB(b, h) + boff + n * 2048 + k * 1024); } while (0)
; #define PG8_MMA(ai, bj, At, Bt) do { __builtin_amdgcn_s_setprio(1); _Pragma("unroll") for (int m = 0; m < 4; ++m) _Pragma("unroll") for (int n = 0; n < 2; ++n) _Pragma("unroll") for (int k = 0; k < 2; ++k) \
;         acc[ai][bj][m][n] = __builtin_amdgcn_mfma_f32_16x16x32_bf16(Bt[n][k], At[m][k], acc[ai][bj][m][n], 0, 0, 0); __builtin_amdgcn_s_setprio(0); } while (0)
; #define PG8_BAR __builtin_amdgcn_s_barrier()
; template <class Epi>
; __device__ __forceinline__ void gemm_phase(LAS unsigned char* lds, const Gemm g, const StaticOrder& S, const Epi& E) {
;     ...
;         const bool has_next = S.next(ui + 1, nxt);
;         const char* nA = has_next ? (const char*)g.A + (size_t)nxt.pm * tstepA : cA; const char* nB = has_next ? (const char*)g.Bt + (size_t)nxt.pn * tstepB : cB;
;         for (int t = 0; t < nt; t += 2) {
;             const bool last = (t == nt - 2);
;             const char* a1 = cA + (size_t)(t + 1) * kstep;
;             const char* a2 = last ? nA : cA + (size_t)(t + 2) * kstep; const char* b2 = last ? nB : cB + (size_t)(t + 2) * kstep;
;             const char* a3 = a2 + kstep; const char* b3 = b2 + kstep;
;             if (last) E.pre(cur, wr, fr, epre);
;             PG8_LDB(B0, 0, 0); PG8_SCHED; PG8_LDA(At, 0, 0); PG8_STAGE(PG8_SA(1, 1), a1 + hstepA, voffA);
;             PG8_WAIT_L(8); PG8_BAR; PG8_WAIT_L(0); PG8_MMA(0, 0, At, B0); PG8_BAR; PG8_SCHED;
;             PG8_LDB(B1, 0, 1); PG8_STAGE(PG8_SB(0, 0), b2, voffB);
;             PG8_BAR; PG8_WAIT_L(0); PG8_MMA(0, 1, At, B1); PG8_BAR;
;             PG8_LDA(At, 0, 1); PG8_STAGE(PG8_SA(0, 0), a2, voffA);
;             PG8_BAR; PG8_WAIT_L(0); PG8_MMA(1, 0, At, B0); PG8_BAR; PG8_SCHED;
.LBB0_683:
	s_ashr_i32 s17, s16, 31
	s_lshl_b64 s[20:21], s[16:17], 20
	s_add_u32 s20, s29, s20
	s_addc_u32 s21, s30, s21
	s_and_b64 s[4:5], s[4:5], exec
	s_cselect_b32 s17, s21, s23
	s_cselect_b32 s45, s20, s22
	s_add_u32 s4, s24, 0x140080
	s_addc_u32 s5, s25, 0
	s_add_u32 s46, s22, 0x100
	s_addc_u32 s47, s23, 0
	s_mov_b32 s48, -2
	s_waitcnt lgkmcnt(0)
	ds_read_b128 v[128:131], v191
	ds_read_b128 v[132:135], v191 offset:1024
	ds_read_b128 v[136:139], v191 offset:2048
	ds_read_b128 v[140:143], v191 offset:3072
	s_add_u32 s22, s4, 0xffec0080
	s_addc_u32 s23, s5, -1
	s_cmp_eq_u32 s48, 28
	s_cselect_b32 s25, s19, s23
	s_cselect_b32 s24, s18, s22
	s_cselect_b32 s23, s17, s47
	s_cselect_b32 s22, s45, s46
	v_lshl_add_u64 v[186:187], s[4:5], 0, v[162:163]
	s_add_i32 m0, s11, 0xc000
	ds_read_b128 v[144:147], v192
	ds_read_b128 v[148:151], v192 offset:1024
	ds_read_b128 v[170:173], v192 offset:2048
	ds_read_b128 v[174:177], v192 offset:3072
	ds_read_b128 v[178:181], v192 offset:4096
	ds_read_b128 v[182:185], v192 offset:5120
	ds_read_b128 v[196:199], v192 offset:6144
	ds_read_b128 v[200:203], v192 offset:7168
	global_load_lds_dwordx4 v[186:187], off
	v_lshl_add_u64 v[186:187], s[4:5], 0, v[164:165]
	s_add_i32 m0, s11, 0xe000
	s_nop 0
	global_load_lds_dwordx4 v[186:187], off
	s_waitcnt lgkmcnt(8)
	s_barrier
	s_waitcnt lgkmcnt(7)
	v_mfma_f32_16x16x32_bf16 v[124:127], v[128:131], v[144:147], 0
	v_mfma_f32_16x16x32_bf16 v[120:123], v[136:139], v[144:147], 0
	s_waitcnt lgkmcnt(5)
	v_mfma_f32_16x16x32_bf16 v[108:111], v[128:131], v[170:173], 0
	v_mfma_f32_16x16x32_bf16 v[104:107], v[136:139], v[170:173], 0
	s_waitcnt lgkmcnt(3)
	v_mfma_f32_16x16x32_bf16 v[92:95], v[128:131], v[178:181], 0
	v_mfma_f32_16x16x32_bf16 v[88:91], v[136:139], v[178:181], 0
	s_waitcnt lgkmcnt(1)
	v_mfma_f32_16x16x32_bf16 v[76:79], v[128:131], v[196:199], 0
	v_mfma_f32_16x16x32_bf16 v[72:75], v[136:139], v[196:199], 0
	v_mfma_f32_16x16x32_bf16 v[124:127], v[132:135], v[148:151], v[124:127]
	v_mfma_f32_16x16x32_bf16 v[120:123], v[140:143], v[148:151], v[120:123]
	v_mfma_f32_16x16x32_bf16 v[108:111], v[132:135], v[174:177], v[108:111]
	v_mfma_f32_16x16x32_bf16 v[104:107], v[140:143], v[174:177], v[104:107]
	v_mfma_f32_16x16x32_bf16 v[92:95], v[132:135], v[182:185], v[92:95]
	v_mfma_f32_16x16x32_bf16 v[88:91], v[140:143], v[182:185], v[88:91]
	s_waitcnt lgkmcnt(0)
	v_mfma_f32_16x16x32_bf16 v[76:79], v[132:135], v[200:203], v[76:79]
	v_mfma_f32_16x16x32_bf16 v[72:75], v[140:143], v[200:203], v[72:75]
	s_barrier
	s_add_i32 s49, s42, s31
	v_lshl_add_u64 v[186:187], s[22:23], 0, v[156:157]
	s_mov_b32 m0, s49
	ds_read_b128 v[204:207], v193
	ds_read_b128 v[208:211], v193 offset:1024
	ds_read_b128 v[212:215], v193 offset:2048
	ds_read_b128 v[216:219], v193 offset:3072
	global_load_lds_dwordx4 v[186:187], off
	v_lshl_add_u64 v[220:221], s[22:23], 0, v[160:161]
	s_add_i32 m0, s49, 0x2000
	s_nop 0
	global_load_lds_dwordx4 v[220:221], off
	s_barrier
	s_waitcnt lgkmcnt(3)
	v_mfma_f32_16x16x32_bf16 v[116:119], v[204:207], v[144:147], 0
	s_waitcnt lgkmcnt(1)
	v_mfma_f32_16x16x32_bf16 v[112:115], v[212:215], v[144:147], 0
	v_mfma_f32_16x16x32_bf16 v[100:103], v[204:207], v[170:173], 0
	v_mfma_f32_16x16x32_bf16 v[96:99], v[212:215], v[170:173], 0
	v_mfma_f32_16x16x32_bf16 v[84:87], v[204:207], v[178:181], 0
	v_mfma_f32_16x16x32_bf16 v[80:83], v[212:215], v[178:181], 0
	v_mfma_f32_16x16x32_bf16 v[68:71], v[204:207], v[196:199], 0
	v_mfma_f32_16x16x32_bf16 v[64:67], v[212:215], v[196:199], 0
	v_mfma_f32_16x16x32_bf16 v[116:119], v[208:211], v[148:151], v[116:119]
	s_waitcnt lgkmcnt(0)
	v_mfma_f32_16x16x32_bf16 v[112:115], v[216:219], v[148:151], v[112:115]
	v_mfma_f32_16x16x32_bf16 v[100:103], v[208:211], v[174:177], v[100:103]
	v_mfma_f32_16x16x32_bf16 v[96:99], v[216:219], v[174:177], v[96:99]
	v_mfma_f32_16x16x32_bf16 v[84:87], v[208:211], v[182:185], v[84:87]
	v_mfma_f32_16x16x32_bf16 v[80:83], v[216:219], v[182:185], v[80:83]
	v_mfma_f32_16x16x32_bf16 v[68:71], v[208:211], v[200:203], v[68:71]
	v_mfma_f32_16x16x32_bf16 v[64:67], v[216:219], v[200:203], v[64:67]
	s_mov_b32 m0, s11
	v_lshl_add_u64 v[222:223], s[24:25], 0, v[154:155]
	s_barrier
	ds_read_b128 v[144:147], v192 offset:16384
	ds_read_b128 v[148:151], v192 offset:17408
	ds_read_b128 v[170:173], v192 offset:18432
	ds_read_b128 v[174:177], v192 offset:19456
	ds_read_b128 v[178:181], v192 offset:20480
	ds_read_b128 v[182:185], v192 offset:21504
	ds_read_b128 v[196:199], v192 offset:22528
	ds_read_b128 v[200:203], v192 offset:23552
	global_load_lds_dwordx4 v[222:223], off
	v_lshl_add_u64 v[224:225], s[24:25], 0, v[158:159]
	s_mov_b32 m0, s34
	s_nop 0
	global_load_lds_dwordx4 v[224:225], off
	s_barrier
	s_waitcnt lgkmcnt(7)
	v_mfma_f32_16x16x32_bf16 v[60:63], v[128:131], v[144:147], 0
	v_mfma_f32_16x16x32_bf16 v[56:59], v[136:139], v[144:147], 0
	s_waitcnt lgkmcnt(5)
	v_mfma_f32_16x16x32_bf16 v[44:47], v[128:131], v[170:173], 0
	v_mfma_f32_16x16x32_bf16 v[40:43], v[136:139], v[170:173], 0
	s_waitcnt lgkmcnt(3)
	v_mfma_f32_16x16x32_bf16 v[28:31], v[128:131], v[178:181], 0
	v_mfma_f32_16x16x32_bf16 v[24:27], v[136:139], v[178:181], 0
	s_waitcnt lgkmcnt(1)
	v_mfma_f32_16x16x32_bf16 v[12:15], v[128:131], v[196:199], 0
	v_mfma_f32_16x16x32_bf16 v[8:11], v[136:139], v[196:199], 0
	v_mfma_f32_16x16x32_bf16 v[60:63], v[132:135], v[148:151], v[60:63]
	v_mfma_f32_16x16x32_bf16 v[56:59], v[140:143], v[148:151], v[56:59]
	v_mfma_f32_16x16x32_bf16 v[44:47], v[132:135], v[174:177], v[44:47]
	v_mfma_f32_16x16x32_bf16 v[40:43], v[140:143], v[174:177], v[40:43]
	v_mfma_f32_16x16x32_bf16 v[28:31], v[132:135], v[182:185], v[28:31]
	v_mfma_f32_16x16x32_bf16 v[24:27], v[140:143], v[182:185], v[24:27]
	s_waitcnt lgkmcnt(0)
	v_mfma_f32_16x16x32_bf16 v[12:15], v[132:135], v[200:203], v[12:15]
	v_mfma_f32_16x16x32_bf16 v[8:11], v[140:143], v[200:203], v[8:11]
	s_barrier
; #define PG8_STAGE(bufoff, gbase, voff) do { _Pragma("unroll") for (int _i = 0; _i < 2; ++_i) \
;         __builtin_amdgcn_global_load_lds((const unsigned*)((const char*)(gbase) + (voff)[_i]), (LAS unsigned*)(lds + (bufoff) + ldsw + _i * 8192), 16, 0, 0); } while (0)
; #define PG8_LDA(dst, b, h) do { _Pragma("unroll") for (int m = 0; m < 4; ++m) _Pragma("unroll") for (int k = 0; k < 2; ++k) dst[m][k] = *(const LAS bf16x8*)(lds + PG8_SA(b, h) + aoff + m * 2048 + k * 1024); } while (0)
; #define PG8_LDB(dst, b, h) do { _Pragma("unroll") for (int n = 0; n < 2; ++n) _Pragma("unroll") for (int k = 0; k < 2; ++k) dst[n][k] = *(const LAS bf16x8*)(lds + PG8_SB(b, h) + boff + n * 2048 + k * 1024); } while (0)
; #define PG8_MMA(ai, bj, At, Bt) do { __builtin_amdgcn_s_setprio(1); _Pragma("unroll") for (int m = 0; m < 4; ++m) _Pragma("unroll") for (int n = 0; n < 2; ++n) _Pragma("unroll") for (int k = 0; k < 2; ++k) \
;         acc[ai][bj][m][n] = __builtin_amdgcn_mfma_f32_16x16x32_bf16(Bt[n][k], At[m][k], acc[ai][bj][m][n], 0, 0, 0); __builtin_amdgcn_s_setprio(0); } while (0)
; #define PG8_WAIT_V(n) asm volatile("s_waitcnt vmcnt(" #n ")" ::: "memory")
; #define PG8_WAIT_L(n) asm volatile("s_waitcnt lgkmcnt(" #n ")" ::: "memory")
; #define PG8_BAR __builtin_amdgcn_s_barrier()
; #define PG8_SCHED __builtin_amdgcn_sched_barrier(0)
; template <class Epi>
; __device__ __forceinline__ void gemm_phase(LAS unsigned char* lds, const Gemm g, const StaticOrder& S, const Epi& E) {
;     ...
;             PG8_BAR; PG8_WAIT_L(0); PG8_MMA(1, 0, At, B0); PG8_BAR; PG8_SCHED;
;             PG8_STAGE(PG8_SB(0, 1), b2 + hstepB, voffB);
;             PG8_WAIT_V(6); PG8_BAR; PG8_MMA(1, 1, At, B1); PG8_BAR;
;             PG8_LDB(B0, 1, 0); PG8_SCHED; PG8_LDA(At, 1, 0); PG8_STAGE(PG8_SA(0, 1), a2 + hstepA, voffA);
;             PG8_WAIT_L(8); PG8_BAR; PG8_WAIT_L(0); PG8_MMA(0, 0, At, B0); PG8_BAR; PG8_SCHED;
;             PG8_LDB(B1, 1, 1); PG8_STAGE(PG8_SB(1, 0), b3, voffB);
;             PG8_BAR; PG8_WAIT_L(0); PG8_MMA(0, 1, At, B1); PG8_BAR;
;             PG8_LDA(At, 1, 1); PG8_STAGE(PG8_SA(1, 0), a3, voffA);
;             PG8_BAR; PG8_WAIT_L(0); PG8_MMA(1, 0, At, B0); PG8_BAR; PG8_SCHED;
	s_add_u32 s50, s22, 0x80000
	s_addc_u32 s51, s23, 0
	s_add_i32 s49, s43, s31
	v_lshl_add_u64 v[128:129], s[50:51], 0, v[156:157]
	s_mov_b32 m0, s49
	s_nop 0
	global_load_lds_dwordx4 v[128:129], off
	v_lshl_add_u64 v[128:129], s[50:51], 0, v[160:161]
	s_add_i32 m0, s49, 0x2000
	s_nop 0
	global_load_lds_dwordx4 v[128:129], off
	s_waitcnt vmcnt(6)
	s_barrier
	v_mfma_f32_16x16x32_bf16 v[52:55], v[204:207], v[144:147], 0
	v_mfma_f32_16x16x32_bf16 v[48:51], v[212:215], v[144:147], 0
	v_mfma_f32_16x16x32_bf16 v[36:39], v[204:207], v[170:173], 0
	v_mfma_f32_16x16x32_bf16 v[32:35], v[212:215], v[170:173], 0
	v_mfma_f32_16x16x32_bf16 v[20:23], v[204:207], v[178:181], 0
	v_mfma_f32_16x16x32_bf16 v[16:19], v[212:215], v[178:181], 0
	v_mfma_f32_16x16x32_bf16 v[4:7], v[204:207], v[196:199], 0
	v_mfma_f32_16x16x32_bf16 v[0:3], v[212:215], v[196:199], 0
	v_mfma_f32_16x16x32_bf16 v[52:55], v[208:211], v[148:151], v[52:55]
	v_mfma_f32_16x16x32_bf16 v[48:51], v[216:219], v[148:151], v[48:51]
	v_mfma_f32_16x16x32_bf16 v[36:39], v[208:211], v[174:177], v[36:39]
	v_mfma_f32_16x16x32_bf16 v[32:35], v[216:219], v[174:177], v[32:35]
	v_mfma_f32_16x16x32_bf16 v[20:23], v[208:211], v[182:185], v[20:23]
	v_mfma_f32_16x16x32_bf16 v[16:19], v[216:219], v[182:185], v[16:19]
	v_mfma_f32_16x16x32_bf16 v[4:7], v[208:211], v[200:203], v[4:7]
	v_mfma_f32_16x16x32_bf16 v[0:3], v[216:219], v[200:203], v[0:3]
	s_add_i32 s49, 0, 0x18000
	v_add_u32_e32 v140, s49, v189
	s_barrier
	ds_read_b128 v[128:131], v140
	ds_read_b128 v[132:135], v140 offset:1024
	ds_read_b128 v[136:139], v140 offset:2048
	ds_read_b128 v[140:143], v140 offset:3072
	s_add_u32 s24, s24, 0x140000
	s_addc_u32 s25, s25, 0
	s_mov_b32 m0, s35
	v_lshl_add_u64 v[204:205], s[24:25], 0, v[154:155]
	ds_read_b128 v[144:147], v192 offset:32768
	ds_read_b128 v[148:151], v192 offset:33792
	ds_read_b128 v[170:173], v192 offset:34816
	ds_read_b128 v[174:177], v192 offset:35840
	ds_read_b128 v[178:181], v192 offset:36864
	ds_read_b128 v[182:185], v192 offset:37888
	ds_read_b128 v[196:199], v192 offset:38912
	ds_read_b128 v[200:203], v192 offset:39936
	global_load_lds_dwordx4 v[204:205], off
	v_lshl_add_u64 v[204:205], s[24:25], 0, v[158:159]
	s_mov_b32 m0, s36
	s_nop 0
	global_load_lds_dwordx4 v[204:205], off
	s_waitcnt lgkmcnt(8)
	s_barrier
	s_waitcnt lgkmcnt(7)
	v_mfma_f32_16x16x32_bf16 v[124:127], v[128:131], v[144:147], v[124:127]
	v_mfma_f32_16x16x32_bf16 v[120:123], v[136:139], v[144:147], v[120:123]
	s_waitcnt lgkmcnt(5)
	v_mfma_f32_16x16x32_bf16 v[108:111], v[128:131], v[170:173], v[108:111]
	v_mfma_f32_16x16x32_bf16 v[104:107], v[136:139], v[170:173], v[104:107]
	s_waitcnt lgkmcnt(3)
	v_mfma_f32_16x16x32_bf16 v[92:95], v[128:131], v[178:181], v[92:95]
	v_mfma_f32_16x16x32_bf16 v[88:91], v[136:139], v[178:181], v[88:91]
	s_waitcnt lgkmcnt(1)
	v_mfma_f32_16x16x32_bf16 v[76:79], v[128:131], v[196:199], v[76:79]
	v_mfma_f32_16x16x32_bf16 v[72:75], v[136:139], v[196:199], v[72:75]
	v_mfma_f32_16x16x32_bf16 v[124:127], v[132:135], v[148:151], v[124:127]
	v_mfma_f32_16x16x32_bf16 v[120:123], v[140:143], v[148:151], v[120:123]
	v_mfma_f32_16x16x32_bf16 v[108:111], v[132:135], v[174:177], v[108:111]
	v_mfma_f32_16x16x32_bf16 v[104:107], v[140:143], v[174:177], v[104:107]
	v_mfma_f32_16x16x32_bf16 v[92:95], v[132:135], v[182:185], v[92:95]
	v_mfma_f32_16x16x32_bf16 v[88:91], v[140:143], v[182:185], v[88:91]
	s_waitcnt lgkmcnt(0)
	v_mfma_f32_16x16x32_bf16 v[76:79], v[132:135], v[200:203], v[76:79]
	v_mfma_f32_16x16x32_bf16 v[72:75], v[140:143], v[200:203], v[72:75]
	s_barrier
	s_add_i32 s24, 0, 0x1c000
	s_add_i32 s25, s49, s31
	v_add_u32_e32 v195, s24, v189
	v_lshl_add_u64 v[186:187], v[186:187], 0, s[14:15]
	s_mov_b32 m0, s25
	ds_read_b128 v[204:207], v195
	ds_read_b128 v[208:211], v195 offset:1024
	ds_read_b128 v[212:215], v195 offset:2048
	ds_read_b128 v[216:219], v195 offset:3072
	global_load_lds_dwordx4 v[186:187], off
	v_lshl_add_u64 v[186:187], v[220:221], 0, s[14:15]
	s_add_i32 m0, s25, 0x2000
	s_nop 0
	global_load_lds_dwordx4 v[186:187], off
	s_barrier
	s_waitcnt lgkmcnt(3)
	v_mfma_f32_16x16x32_bf16 v[116:119], v[204:207], v[144:147], v[116:119]
	s_waitcnt lgkmcnt(1)
	v_mfma_f32_16x16x32_bf16 v[112:115], v[212:215], v[144:147], v[112:115]
	v_mfma_f32_16x16x32_bf16 v[100:103], v[204:207], v[170:173], v[100:103]
	v_mfma_f32_16x16x32_bf16 v[96:99], v[212:215], v[170:173], v[96:99]
	v_mfma_f32_16x16x32_bf16 v[84:87], v[204:207], v[178:181], v[84:87]
	v_mfma_f32_16x16x32_bf16 v[80:83], v[212:215], v[178:181], v[80:83]
	v_mfma_f32_16x16x32_bf16 v[68:71], v[204:207], v[196:199], v[68:71]
	v_mfma_f32_16x16x32_bf16 v[64:67], v[212:215], v[196:199], v[64:67]
	v_mfma_f32_16x16x32_bf16 v[116:119], v[208:211], v[148:151], v[116:119]
	s_waitcnt lgkmcnt(0)
	v_mfma_f32_16x16x32_bf16 v[112:115], v[216:219], v[148:151], v[112:115]
	v_mfma_f32_16x16x32_bf16 v[100:103], v[208:211], v[174:177], v[100:103]
	v_mfma_f32_16x16x32_bf16 v[96:99], v[216:219], v[174:177], v[96:99]
	v_mfma_f32_16x16x32_bf16 v[84:87], v[208:211], v[182:185], v[84:87]
	v_mfma_f32_16x16x32_bf16 v[80:83], v[216:219], v[182:185], v[80:83]
	v_mfma_f32_16x16x32_bf16 v[68:71], v[208:211], v[200:203], v[68:71]
	v_mfma_f32_16x16x32_bf16 v[64:67], v[216:219], v[200:203], v[64:67]
	s_mov_b32 m0, s38
	v_lshl_add_u64 v[186:187], v[222:223], 0, s[14:15]
	s_barrier
	ds_read_b128 v[144:147], v192 offset:49152
	ds_read_b128 v[148:151], v192 offset:50176
	ds_read_b128 v[170:173], v192 offset:51200
	ds_read_b128 v[174:177], v192 offset:52224
	ds_read_b128 v[178:181], v192 offset:53248
	ds_read_b128 v[182:185], v192 offset:54272
	ds_read_b128 v[196:199], v192 offset:55296
	ds_read_b128 v[200:203], v192 offset:56320
	global_load_lds_dwordx4 v[186:187], off
	v_lshl_add_u64 v[186:187], v[224:225], 0, s[14:15]
	s_mov_b32 m0, s39
	s_nop 0
	global_load_lds_dwordx4 v[186:187], off
	s_barrier
; #define PG8_STAGE(bufoff, gbase, voff) do { _Pragma("unroll") for (int _i = 0; _i < 2; ++_i) \
;         __builtin_amdgcn_global_load_lds((const unsigned*)((const char*)(gbase) + (voff)[_i]), (LAS unsigned*)(lds + (bufoff) + ldsw + _i * 8192), 16, 0, 0); } while (0)
; #define PG8_LDA(dst, b, h) do { _Pragma("unroll") for (int m = 0; m < 4; ++m) _Pragma("unroll") for (int k = 0; k < 2; ++k) dst[m][k] = *(const LAS bf16x8*)(lds + PG8_SA(b, h) + aoff + m * 2048 + k * 1024); } while (0)
; #define PG8_LDB(dst, b, h) do { _Pragma("unroll") for (int n = 0; n < 2; ++n) _Pragma("unroll") for (int k = 0; k < 2; ++k) dst[n][k] = *(const LAS bf16x8*)(lds + PG8_SB(b, h) + boff + n * 2048 + k * 1024); } while (0)
; #define PG8_MMA(ai, bj, At, Bt) do { __builtin_amdgcn_s_setprio(1); _Pragma("unroll") for (int m = 0; m < 4; ++m) _Pragma("unroll") for (int n = 0; n < 2; ++n) _Pragma("unroll") for (int k = 0; k < 2; ++k) \
;         acc[ai][bj][m][n] = __builtin_amdgcn_mfma_f32_16x16x32_bf16(Bt[n][k], At[m][k], acc[ai][bj][m][n], 0, 0, 0); __builtin_amdgcn_s_setprio(0); } while (0)
; #define PG8_WAIT_V(n) asm volatile("s_waitcnt vmcnt(" #n ")" ::: "memory")
; #define PG8_BAR __builtin_amdgcn_s_barrier()
; template <class Epi>
; __device__ __forceinline__ void gemm_phase(LAS unsigned char* lds, const Gemm g, const StaticOrder& S, const Epi& E) {
;     ...
;         const bool has_next = S.next(ui + 1, nxt);
;         const char* nA = has_next ? (const char*)g.A + (size_t)nxt.pm * tstepA : cA; const char* nB = has_next ? (const char*)g.Bt + (size_t)nxt.pn * tstepB : cB;
;         for (int t = 0; t < nt; t += 2) {
;             const bool last = (t == nt - 2);
;             const char* a1 = cA + (size_t)(t + 1) * kstep;
;             const char* a2 = last ? nA : cA + (size_t)(t + 2) * kstep; const char* b2 = last ? nB : cB + (size_t)(t + 2) * kstep;
;             const char* a3 = a2 + kstep; const char* b3 = b2 + kstep;
;             if (last) E.pre(cur, wr, fr, epre);
;             PG8_LDB(B0, 0, 0); PG8_SCHED; PG8_LDA(At, 0, 0); PG8_STAGE(PG8_SA(1, 1), a1 + hstepA, voffA);
;             PG8_WAIT_L(8); PG8_BAR; PG8_WAIT_L(0); PG8_MMA(0, 0, At, B0); PG8_BAR; PG8_SCHED;
;             PG8_LDB(B1, 0, 1); PG8_STAGE(PG8_SB(0, 0), b2, voffB);
;             PG8_BAR; PG8_WAIT_L(0); PG8_MMA(0, 1, At, B1); PG8_BAR;
;     ...
;             PG8_WAIT_V(6); PG8_BAR; PG8_MMA(1, 1, At, B1); PG8_BAR;
	s_waitcnt lgkmcnt(7)
	v_mfma_f32_16x16x32_bf16 v[60:63], v[128:131], v[144:147], v[60:63]
	v_mfma_f32_16x16x32_bf16 v[56:59], v[136:139], v[144:147], v[56:59]
	s_waitcnt lgkmcnt(5)
	v_mfma_f32_16x16x32_bf16 v[44:47], v[128:131], v[170:173], v[44:47]
	v_mfma_f32_16x16x32_bf16 v[40:43], v[136:139], v[170:173], v[40:43]
	s_waitcnt lgkmcnt(3)
	v_mfma_f32_16x16x32_bf16 v[28:31], v[128:131], v[178:181], v[28:31]
	v_mfma_f32_16x16x32_bf16 v[24:27], v[136:139], v[178:181], v[24:27]
	s_waitcnt lgkmcnt(1)
	v_mfma_f32_16x16x32_bf16 v[12:15], v[128:131], v[196:199], v[12:15]
	v_mfma_f32_16x16x32_bf16 v[8:11], v[136:139], v[196:199], v[8:11]
	v_mfma_f32_16x16x32_bf16 v[60:63], v[132:135], v[148:151], v[60:63]
	v_mfma_f32_16x16x32_bf16 v[56:59], v[140:143], v[148:151], v[56:59]
	v_mfma_f32_16x16x32_bf16 v[44:47], v[132:135], v[174:177], v[44:47]
	v_mfma_f32_16x16x32_bf16 v[40:43], v[140:143], v[174:177], v[40:43]
	v_mfma_f32_16x16x32_bf16 v[28:31], v[132:135], v[182:185], v[28:31]
	v_mfma_f32_16x16x32_bf16 v[24:27], v[140:143], v[182:185], v[24:27]
	s_waitcnt lgkmcnt(0)
	v_mfma_f32_16x16x32_bf16 v[12:15], v[132:135], v[200:203], v[12:15]
	v_mfma_f32_16x16x32_bf16 v[8:11], v[140:143], v[200:203], v[8:11]
	s_barrier
	s_add_u32 s22, s22, 0x80080
	s_addc_u32 s23, s23, 0
	s_add_i32 s24, s24, s31
	v_lshl_add_u64 v[128:129], s[22:23], 0, v[156:157]
	s_mov_b32 m0, s24
	s_nop 0
	global_load_lds_dwordx4 v[128:129], off
	v_lshl_add_u64 v[128:129], s[22:23], 0, v[160:161]
	s_add_i32 m0, s24, 0x2000
	s_nop 0
	global_load_lds_dwordx4 v[128:129], off
	s_waitcnt vmcnt(6)
	s_barrier
	v_mfma_f32_16x16x32_bf16 v[52:55], v[204:207], v[144:147], v[52:55]
	v_mfma_f32_16x16x32_bf16 v[48:51], v[212:215], v[144:147], v[48:51]
	v_mfma_f32_16x16x32_bf16 v[36:39], v[204:207], v[170:173], v[36:39]
	v_mfma_f32_16x16x32_bf16 v[32:35], v[212:215], v[170:173], v[32:35]
	v_mfma_f32_16x16x32_bf16 v[20:23], v[204:207], v[178:181], v[20:23]
	v_mfma_f32_16x16x32_bf16 v[16:19], v[212:215], v[178:181], v[16:19]
	v_mfma_f32_16x16x32_bf16 v[4:7], v[204:207], v[196:199], v[4:7]
	v_mfma_f32_16x16x32_bf16 v[0:3], v[212:215], v[196:199], v[0:3]
	v_mfma_f32_16x16x32_bf16 v[52:55], v[208:211], v[148:151], v[52:55]
	v_mfma_f32_16x16x32_bf16 v[48:51], v[216:219], v[148:151], v[48:51]
	v_mfma_f32_16x16x32_bf16 v[36:39], v[208:211], v[174:177], v[36:39]
	v_mfma_f32_16x16x32_bf16 v[32:35], v[216:219], v[174:177], v[32:35]
	v_mfma_f32_16x16x32_bf16 v[20:23], v[208:211], v[182:185], v[20:23]
	v_mfma_f32_16x16x32_bf16 v[16:19], v[216:219], v[182:185], v[16:19]
	v_mfma_f32_16x16x32_bf16 v[4:7], v[208:211], v[200:203], v[4:7]
	v_mfma_f32_16x16x32_bf16 v[0:3], v[216:219], v[200:203], v[0:3]
	s_add_i32 s48, s48, 2
	s_add_u32 s4, s4, 0x100
	s_addc_u32 s5, s5, 0
	s_add_u32 s46, s46, 0x100
	s_addc_u32 s47, s47, 0
	s_cmp_gt_u32 s48, 29
	s_barrier
.LBB0_684:
	ds_read_b128 v[128:131], v191
	ds_read_b128 v[132:135], v191 offset:1024
	ds_read_b128 v[136:139], v191 offset:2048
	ds_read_b128 v[140:143], v191 offset:3072
	s_add_u32 s22, s4, 0xffec0080
	s_addc_u32 s23, s5, -1
	s_cmp_eq_u32 s48, 28
	s_cselect_b32 s25, s19, s23
	s_cselect_b32 s24, s18, s22
	s_cselect_b32 s23, s17, s47
	s_cselect_b32 s22, s45, s46
	v_lshl_add_u64 v[186:187], s[4:5], 0, v[162:163]
	s_add_i32 m0, s11, 0xc000
	ds_read_b128 v[144:147], v192
	ds_read_b128 v[148:151], v192 offset:1024
	ds_read_b128 v[170:173], v192 offset:2048
	ds_read_b128 v[174:177], v192 offset:3072
	ds_read_b128 v[178:181], v192 offset:4096
	ds_read_b128 v[182:185], v192 offset:5120
	ds_read_b128 v[196:199], v192 offset:6144
	ds_read_b128 v[200:203], v192 offset:7168
	global_load_lds_dwordx4 v[186:187], off
	v_lshl_add_u64 v[186:187], s[4:5], 0, v[164:165]
	s_add_i32 m0, s11, 0xe000
	s_nop 0
	global_load_lds_dwordx4 v[186:187], off
	s_waitcnt lgkmcnt(8)
	s_barrier
	s_waitcnt lgkmcnt(7)
	v_mfma_f32_16x16x32_bf16 v[124:127], v[128:131], v[144:147], v[124:127]
	v_mfma_f32_16x16x32_bf16 v[120:123], v[136:139], v[144:147], v[120:123]
	s_waitcnt lgkmcnt(5)
	v_mfma_f32_16x16x32_bf16 v[108:111], v[128:131], v[170:173], v[108:111]
	v_mfma_f32_16x16x32_bf16 v[104:107], v[136:139], v[170:173], v[104:107]
	s_waitcnt lgkmcnt(3)
	v_mfma_f32_16x16x32_bf16 v[92:95], v[128:131], v[178:181], v[92:95]
	v_mfma_f32_16x16x32_bf16 v[88:91], v[136:139], v[178:181], v[88:91]
	s_waitcnt lgkmcnt(1)
	v_mfma_f32_16x16x32_bf16 v[76:79], v[128:131], v[196:199], v[76:79]
	v_mfma_f32_16x16x32_bf16 v[72:75], v[136:139], v[196:199], v[72:75]
	v_mfma_f32_16x16x32_bf16 v[124:127], v[132:135], v[148:151], v[124:127]
	v_mfma_f32_16x16x32_bf16 v[120:123], v[140:143], v[148:151], v[120:123]
	v_mfma_f32_16x16x32_bf16 v[108:111], v[132:135], v[174:177], v[108:111]
	v_mfma_f32_16x16x32_bf16 v[104:107], v[140:143], v[174:177], v[104:107]
	v_mfma_f32_16x16x32_bf16 v[92:95], v[132:135], v[182:185], v[92:95]
	v_mfma_f32_16x16x32_bf16 v[88:91], v[140:143], v[182:185], v[88:91]
	s_waitcnt lgkmcnt(0)
	v_mfma_f32_16x16x32_bf16 v[76:79], v[132:135], v[200:203], v[76:79]
	v_mfma_f32_16x16x32_bf16 v[72:75], v[140:143], v[200:203], v[72:75]
	s_barrier
	s_add_i32 s49, s42, s31
	v_lshl_add_u64 v[186:187], s[22:23], 0, v[156:157]
	s_mov_b32 m0, s49
	ds_read_b128 v[204:207], v193
	ds_read_b128 v[208:211], v193 offset:1024
	ds_read_b128 v[212:215], v193 offset:2048
	ds_read_b128 v[216:219], v193 offset:3072
	global_load_lds_dwordx4 v[186:187], off
	v_lshl_add_u64 v[220:221], s[22:23], 0, v[160:161]
	s_add_i32 m0, s49, 0x2000
	s_nop 0
	global_load_lds_dwordx4 v[220:221], off
	s_barrier
; #define PG8_STAGE(bufoff, gbase, voff) do { _Pragma("unroll") for (int _i = 0; _i < 2; ++_i) \
;         __builtin_amdgcn_global_load_lds((const unsigned*)((const char*)(gbase) + (voff)[_i]), (LAS unsigned*)(lds + (bufoff) + ldsw + _i * 8192), 16, 0, 0); } while (0)
; #define PG8_LDA(dst, b, h) do { _Pragma("unroll") for (int m = 0; m < 4; ++m) _Pragma("unroll") for (int k = 0; k < 2; ++k) dst[m][k] = *(const LAS bf16x8*)(lds + PG8_SA(b, h) + aoff + m * 2048 + k * 1024); } while (0)
; #define PG8_LDB(dst, b, h) do { _Pragma("unroll") for (int n = 0; n < 2; ++n) _Pragma("unroll") for (int k = 0; k < 2; ++k) dst[n][k] = *(const LAS bf16x8*)(lds + PG8_SB(b, h) + boff + n * 2048 + k * 1024); } while (0)
; #define PG8_MMA(ai, bj, At, Bt) do { __builtin_amdgcn_s_setprio(1); _Pragma("unroll") for (int m = 0; m < 4; ++m) _Pragma("unroll") for (int n = 0; n < 2; ++n) _Pragma("unroll") for (int k = 0; k < 2; ++k) \
;         acc[ai][bj][m][n] = __builtin_amdgcn_mfma_f32_16x16x32_bf16(Bt[n][k], At[m][k], acc[ai][bj][m][n], 0, 0, 0); __builtin_amdgcn_s_setprio(0); } while (0)
; #define PG8_WAIT_V(n) asm volatile("s_waitcnt vmcnt(" #n ")" ::: "memory")
; #define PG8_WAIT_L(n) asm volatile("s_waitcnt lgkmcnt(" #n ")" ::: "memory")
; #define PG8_BAR __builtin_amdgcn_s_barrier()
; #define PG8_SCHED __builtin_amdgcn_sched_barrier(0)
; template <class Epi>
; __device__ __forceinline__ void gemm_phase(LAS unsigned char* lds, const Gemm g, const StaticOrder& S, const Epi& E) {
;     ...
;             PG8_BAR; PG8_WAIT_L(0); PG8_MMA(0, 1, At, B1); PG8_BAR;
;             PG8_LDA(At, 0, 1); PG8_STAGE(PG8_SA(0, 0), a2, voffA);
;             PG8_BAR; PG8_WAIT_L(0); PG8_MMA(1, 0, At, B0); PG8_BAR; PG8_SCHED;
;             PG8_STAGE(PG8_SB(0, 1), b2 + hstepB, voffB);
;             PG8_WAIT_V(6); PG8_BAR; PG8_MMA(1, 1, At, B1); PG8_BAR;
;             PG8_LDB(B0, 1, 0); PG8_SCHED; PG8_LDA(At, 1, 0); PG8_STAGE(PG8_SA(0, 1), a2 + hstepA, voffA);
;             PG8_WAIT_L(8); PG8_BAR; PG8_WAIT_L(0); PG8_MMA(0, 0, At, B0); PG8_BAR; PG8_SCHED;
;             PG8_LDB(B1, 1, 1); PG8_STAGE(PG8_SB(1, 0), b3, voffB);
;             PG8_BAR; PG8_WAIT_L(0); PG8_MMA(0, 1, At, B1); PG8_BAR;
	s_waitcnt lgkmcnt(3)
	v_mfma_f32_16x16x32_bf16 v[116:119], v[204:207], v[144:147], v[116:119]
	s_waitcnt lgkmcnt(1)
	v_mfma_f32_16x16x32_bf16 v[112:115], v[212:215], v[144:147], v[112:115]
	v_mfma_f32_16x16x32_bf16 v[100:103], v[204:207], v[170:173], v[100:103]
	v_mfma_f32_16x16x32_bf16 v[96:99], v[212:215], v[170:173], v[96:99]
	v_mfma_f32_16x16x32_bf16 v[84:87], v[204:207], v[178:181], v[84:87]
	v_mfma_f32_16x16x32_bf16 v[80:83], v[212:215], v[178:181], v[80:83]
	v_mfma_f32_16x16x32_bf16 v[68:71], v[204:207], v[196:199], v[68:71]
	v_mfma_f32_16x16x32_bf16 v[64:67], v[212:215], v[196:199], v[64:67]
	v_mfma_f32_16x16x32_bf16 v[116:119], v[208:211], v[148:151], v[116:119]
	s_waitcnt lgkmcnt(0)
	v_mfma_f32_16x16x32_bf16 v[112:115], v[216:219], v[148:151], v[112:115]
	v_mfma_f32_16x16x32_bf16 v[100:103], v[208:211], v[174:177], v[100:103]
	v_mfma_f32_16x16x32_bf16 v[96:99], v[216:219], v[174:177], v[96:99]
	v_mfma_f32_16x16x32_bf16 v[84:87], v[208:211], v[182:185], v[84:87]
	v_mfma_f32_16x16x32_bf16 v[80:83], v[216:219], v[182:185], v[80:83]
	v_mfma_f32_16x16x32_bf16 v[68:71], v[208:211], v[200:203], v[68:71]
	v_mfma_f32_16x16x32_bf16 v[64:67], v[216:219], v[200:203], v[64:67]
	s_mov_b32 m0, s11
	v_lshl_add_u64 v[222:223], s[24:25], 0, v[154:155]
	s_barrier
	ds_read_b128 v[144:147], v192 offset:16384
	ds_read_b128 v[148:151], v192 offset:17408
	ds_read_b128 v[170:173], v192 offset:18432
	ds_read_b128 v[174:177], v192 offset:19456
	ds_read_b128 v[178:181], v192 offset:20480
	ds_read_b128 v[182:185], v192 offset:21504
	ds_read_b128 v[196:199], v192 offset:22528
	ds_read_b128 v[200:203], v192 offset:23552
	global_load_lds_dwordx4 v[222:223], off
	v_lshl_add_u64 v[224:225], s[24:25], 0, v[158:159]
	s_mov_b32 m0, s34
	s_nop 0
	global_load_lds_dwordx4 v[224:225], off
	s_barrier
	s_waitcnt lgkmcnt(7)
	v_mfma_f32_16x16x32_bf16 v[60:63], v[128:131], v[144:147], v[60:63]
	v_mfma_f32_16x16x32_bf16 v[56:59], v[136:139], v[144:147], v[56:59]
	s_waitcnt lgkmcnt(5)
	v_mfma_f32_16x16x32_bf16 v[44:47], v[128:131], v[170:173], v[44:47]
	v_mfma_f32_16x16x32_bf16 v[40:43], v[136:139], v[170:173], v[40:43]
	s_waitcnt lgkmcnt(3)
	v_mfma_f32_16x16x32_bf16 v[28:31], v[128:131], v[178:181], v[28:31]
	v_mfma_f32_16x16x32_bf16 v[24:27], v[136:139], v[178:181], v[24:27]
	s_waitcnt lgkmcnt(1)
	v_mfma_f32_16x16x32_bf16 v[12:15], v[128:131], v[196:199], v[12:15]
	v_mfma_f32_16x16x32_bf16 v[8:11], v[136:139], v[196:199], v[8:11]
	v_mfma_f32_16x16x32_bf16 v[60:63], v[132:135], v[148:151], v[60:63]
	v_mfma_f32_16x16x32_bf16 v[56:59], v[140:143], v[148:151], v[56:59]
	v_mfma_f32_16x16x32_bf16 v[44:47], v[132:135], v[174:177], v[44:47]
	v_mfma_f32_16x16x32_bf16 v[40:43], v[140:143], v[174:177], v[40:43]
	v_mfma_f32_16x16x32_bf16 v[28:31], v[132:135], v[182:185], v[28:31]
	v_mfma_f32_16x16x32_bf16 v[24:27], v[140:143], v[182:185], v[24:27]
	s_waitcnt lgkmcnt(0)
	v_mfma_f32_16x16x32_bf16 v[12:15], v[132:135], v[200:203], v[12:15]
	v_mfma_f32_16x16x32_bf16 v[8:11], v[140:143], v[200:203], v[8:11]
	s_barrier
	s_add_u32 s50, s22, 0x80000
	s_addc_u32 s51, s23, 0
	s_add_i32 s49, s43, s31
	v_lshl_add_u64 v[128:129], s[50:51], 0, v[156:157]
	s_mov_b32 m0, s49
	s_nop 0
	global_load_lds_dwordx4 v[128:129], off
	v_lshl_add_u64 v[128:129], s[50:51], 0, v[160:161]
	s_add_i32 m0, s49, 0x2000
	s_nop 0
	global_load_lds_dwordx4 v[128:129], off
	s_waitcnt vmcnt(6)
	s_barrier
	v_mfma_f32_16x16x32_bf16 v[52:55], v[204:207], v[144:147], v[52:55]
	v_mfma_f32_16x16x32_bf16 v[48:51], v[212:215], v[144:147], v[48:51]
	v_mfma_f32_16x16x32_bf16 v[36:39], v[204:207], v[170:173], v[36:39]
	v_mfma_f32_16x16x32_bf16 v[32:35], v[212:215], v[170:173], v[32:35]
	v_mfma_f32_16x16x32_bf16 v[20:23], v[204:207], v[178:181], v[20:23]
	v_mfma_f32_16x16x32_bf16 v[16:19], v[212:215], v[178:181], v[16:19]
	v_mfma_f32_16x16x32_bf16 v[4:7], v[204:207], v[196:199], v[4:7]
	v_mfma_f32_16x16x32_bf16 v[0:3], v[212:215], v[196:199], v[0:3]
	v_mfma_f32_16x16x32_bf16 v[52:55], v[208:211], v[148:151], v[52:55]
	v_mfma_f32_16x16x32_bf16 v[48:51], v[216:219], v[148:151], v[48:51]
	v_mfma_f32_16x16x32_bf16 v[36:39], v[208:211], v[174:177], v[36:39]
	v_mfma_f32_16x16x32_bf16 v[32:35], v[216:219], v[174:177], v[32:35]
	v_mfma_f32_16x16x32_bf16 v[20:23], v[208:211], v[182:185], v[20:23]
	v_mfma_f32_16x16x32_bf16 v[16:19], v[216:219], v[182:185], v[16:19]
	v_mfma_f32_16x16x32_bf16 v[4:7], v[208:211], v[200:203], v[4:7]
	v_mfma_f32_16x16x32_bf16 v[0:3], v[216:219], v[200:203], v[0:3]
	s_add_i32 s49, 0, 0x18000
	v_add_u32_e32 v140, s49, v189
	s_barrier
	ds_read_b128 v[128:131], v140
	ds_read_b128 v[132:135], v140 offset:1024
	ds_read_b128 v[136:139], v140 offset:2048
	ds_read_b128 v[140:143], v140 offset:3072
	s_add_u32 s24, s24, 0x140000
	s_addc_u32 s25, s25, 0
	s_mov_b32 m0, s35
	v_lshl_add_u64 v[204:205], s[24:25], 0, v[154:155]
	ds_read_b128 v[144:147], v192 offset:32768
	ds_read_b128 v[148:151], v192 offset:33792
	ds_read_b128 v[170:173], v192 offset:34816
	ds_read_b128 v[174:177], v192 offset:35840
	ds_read_b128 v[178:181], v192 offset:36864
	ds_read_b128 v[182:185], v192 offset:37888
	ds_read_b128 v[196:199], v192 offset:38912
	ds_read_b128 v[200:203], v192 offset:39936
	global_load_lds_dwordx4 v[204:205], off
	v_lshl_add_u64 v[204:205], s[24:25], 0, v[158:159]
	s_mov_b32 m0, s36
	s_nop 0
	global_load_lds_dwordx4 v[204:205], off
	s_waitcnt lgkmcnt(8)
	s_barrier
; #define PG8_STAGE(bufoff, gbase, voff) do { _Pragma("unroll") for (int _i = 0; _i < 2; ++_i) \
;         __builtin_amdgcn_global_load_lds((const unsigned*)((const char*)(gbase) + (voff)[_i]), (LAS unsigned*)(lds + (bufoff) + ldsw + _i * 8192), 16, 0, 0); } while (0)
; #define PG8_LDA(dst, b, h) do { _Pragma("unroll") for (int m = 0; m < 4; ++m) _Pragma("unroll") for (int k = 0; k < 2; ++k) dst[m][k] = *(const LAS bf16x8*)(lds + PG8_SA(b, h) + aoff + m * 2048 + k * 1024); } while (0)
; #define PG8_MMA(ai, bj, At, Bt) do { __builtin_amdgcn_s_setprio(1); _Pragma("unroll") for (int m = 0; m < 4; ++m) _Pragma("unroll") for (int n = 0; n < 2; ++n) _Pragma("unroll") for (int k = 0; k < 2; ++k) \
;         acc[ai][bj][m][n] = __builtin_amdgcn_mfma_f32_16x16x32_bf16(Bt[n][k], At[m][k], acc[ai][bj][m][n], 0, 0, 0); __builtin_amdgcn_s_setprio(0); } while (0)
; #define PG8_WAIT_V(n) asm volatile("s_waitcnt vmcnt(" #n ")" ::: "memory")
; #define PG8_WAIT_L(n) asm volatile("s_waitcnt lgkmcnt(" #n ")" ::: "memory")
; #define PG8_BAR __builtin_amdgcn_s_barrier()
; #define PG8_SCHED __builtin_amdgcn_sched_barrier(0)
; template <class Epi>
; __device__ __forceinline__ void gemm_phase(LAS unsigned char* lds, const Gemm g, const StaticOrder& S, const Epi& E) {
;     ...
;             PG8_BAR; PG8_WAIT_L(0); PG8_MMA(0, 1, At, B1); PG8_BAR;
;             PG8_LDA(At, 1, 1); PG8_STAGE(PG8_SA(1, 0), a3, voffA);
;             PG8_BAR; PG8_WAIT_L(0); PG8_MMA(1, 0, At, B0); PG8_BAR; PG8_SCHED;
;             PG8_STAGE(PG8_SB(1, 1), b3 + hstepB, voffB);
;             PG8_WAIT_V(6); PG8_BAR; PG8_MMA(1, 1, At, B1); PG8_BAR;
	s_waitcnt lgkmcnt(7)
	v_mfma_f32_16x16x32_bf16 v[124:127], v[128:131], v[144:147], v[124:127]
	v_mfma_f32_16x16x32_bf16 v[120:123], v[136:139], v[144:147], v[120:123]
	s_waitcnt lgkmcnt(5)
	v_mfma_f32_16x16x32_bf16 v[108:111], v[128:131], v[170:173], v[108:111]
	v_mfma_f32_16x16x32_bf16 v[104:107], v[136:139], v[170:173], v[104:107]
	s_waitcnt lgkmcnt(3)
	v_mfma_f32_16x16x32_bf16 v[92:95], v[128:131], v[178:181], v[92:95]
	v_mfma_f32_16x16x32_bf16 v[88:91], v[136:139], v[178:181], v[88:91]
	s_waitcnt lgkmcnt(1)
	v_mfma_f32_16x16x32_bf16 v[76:79], v[128:131], v[196:199], v[76:79]
	v_mfma_f32_16x16x32_bf16 v[72:75], v[136:139], v[196:199], v[72:75]
	v_mfma_f32_16x16x32_bf16 v[124:127], v[132:135], v[148:151], v[124:127]
	v_mfma_f32_16x16x32_bf16 v[120:123], v[140:143], v[148:151], v[120:123]
	v_mfma_f32_16x16x32_bf16 v[108:111], v[132:135], v[174:177], v[108:111]
	v_mfma_f32_16x16x32_bf16 v[104:107], v[140:143], v[174:177], v[104:107]
	v_mfma_f32_16x16x32_bf16 v[92:95], v[132:135], v[182:185], v[92:95]
	v_mfma_f32_16x16x32_bf16 v[88:91], v[140:143], v[182:185], v[88:91]
	s_waitcnt lgkmcnt(0)
	v_mfma_f32_16x16x32_bf16 v[76:79], v[132:135], v[200:203], v[76:79]
	v_mfma_f32_16x16x32_bf16 v[72:75], v[140:143], v[200:203], v[72:75]
	s_barrier
	s_add_i32 s24, 0, 0x1c000
	s_add_i32 s25, s49, s31
	v_add_u32_e32 v195, s24, v189
	v_lshl_add_u64 v[186:187], v[186:187], 0, s[14:15]
	s_mov_b32 m0, s25
	ds_read_b128 v[204:207], v195
	ds_read_b128 v[208:211], v195 offset:1024
	ds_read_b128 v[212:215], v195 offset:2048
	ds_read_b128 v[216:219], v195 offset:3072
	global_load_lds_dwordx4 v[186:187], off
	v_lshl_add_u64 v[186:187], v[220:221], 0, s[14:15]
	s_add_i32 m0, s25, 0x2000
	s_nop 0
	global_load_lds_dwordx4 v[186:187], off
	s_barrier
	s_waitcnt lgkmcnt(3)
	v_mfma_f32_16x16x32_bf16 v[116:119], v[204:207], v[144:147], v[116:119]
	s_waitcnt lgkmcnt(1)
	v_mfma_f32_16x16x32_bf16 v[112:115], v[212:215], v[144:147], v[112:115]
	v_mfma_f32_16x16x32_bf16 v[100:103], v[204:207], v[170:173], v[100:103]
	v_mfma_f32_16x16x32_bf16 v[96:99], v[212:215], v[170:173], v[96:99]
	v_mfma_f32_16x16x32_bf16 v[84:87], v[204:207], v[178:181], v[84:87]
	v_mfma_f32_16x16x32_bf16 v[80:83], v[212:215], v[178:181], v[80:83]
	v_mfma_f32_16x16x32_bf16 v[68:71], v[204:207], v[196:199], v[68:71]
	v_mfma_f32_16x16x32_bf16 v[64:67], v[212:215], v[196:199], v[64:67]
	v_mfma_f32_16x16x32_bf16 v[116:119], v[208:211], v[148:151], v[116:119]
	s_waitcnt lgkmcnt(0)
	v_mfma_f32_16x16x32_bf16 v[112:115], v[216:219], v[148:151], v[112:115]
	v_mfma_f32_16x16x32_bf16 v[100:103], v[208:211], v[174:177], v[100:103]
	v_mfma_f32_16x16x32_bf16 v[96:99], v[216:219], v[174:177], v[96:99]
	v_mfma_f32_16x16x32_bf16 v[84:87], v[208:211], v[182:185], v[84:87]
	v_mfma_f32_16x16x32_bf16 v[80:83], v[216:219], v[182:185], v[80:83]
	v_mfma_f32_16x16x32_bf16 v[68:71], v[208:211], v[200:203], v[68:71]
	v_mfma_f32_16x16x32_bf16 v[64:67], v[216:219], v[200:203], v[64:67]
	s_mov_b32 m0, s38
	v_lshl_add_u64 v[186:187], v[222:223], 0, s[14:15]
	s_barrier
	ds_read_b128 v[144:147], v192 offset:49152
	ds_read_b128 v[148:151], v192 offset:50176
	ds_read_b128 v[170:173], v192 offset:51200
	ds_read_b128 v[174:177], v192 offset:52224
	ds_read_b128 v[178:181], v192 offset:53248
	ds_read_b128 v[182:185], v192 offset:54272
	ds_read_b128 v[196:199], v192 offset:55296
	ds_read_b128 v[200:203], v192 offset:56320
	global_load_lds_dwordx4 v[186:187], off
	v_lshl_add_u64 v[186:187], v[224:225], 0, s[14:15]
	s_mov_b32 m0, s39
	s_nop 0
	global_load_lds_dwordx4 v[186:187], off
	s_barrier
	s_waitcnt lgkmcnt(7)
	v_mfma_f32_16x16x32_bf16 v[60:63], v[128:131], v[144:147], v[60:63]
	v_mfma_f32_16x16x32_bf16 v[56:59], v[136:139], v[144:147], v[56:59]
	s_waitcnt lgkmcnt(5)
	v_mfma_f32_16x16x32_bf16 v[44:47], v[128:131], v[170:173], v[44:47]
	v_mfma_f32_16x16x32_bf16 v[40:43], v[136:139], v[170:173], v[40:43]
	s_waitcnt lgkmcnt(3)
	v_mfma_f32_16x16x32_bf16 v[28:31], v[128:131], v[178:181], v[28:31]
	v_mfma_f32_16x16x32_bf16 v[24:27], v[136:139], v[178:181], v[24:27]
	s_waitcnt lgkmcnt(1)
	v_mfma_f32_16x16x32_bf16 v[12:15], v[128:131], v[196:199], v[12:15]
	v_mfma_f32_16x16x32_bf16 v[8:11], v[136:139], v[196:199], v[8:11]
	v_mfma_f32_16x16x32_bf16 v[60:63], v[132:135], v[148:151], v[60:63]
	v_mfma_f32_16x16x32_bf16 v[56:59], v[140:143], v[148:151], v[56:59]
	v_mfma_f32_16x16x32_bf16 v[44:47], v[132:135], v[174:177], v[44:47]
	v_mfma_f32_16x16x32_bf16 v[40:43], v[140:143], v[174:177], v[40:43]
	v_mfma_f32_16x16x32_bf16 v[28:31], v[132:135], v[182:185], v[28:31]
	v_mfma_f32_16x16x32_bf16 v[24:27], v[140:143], v[182:185], v[24:27]
	s_waitcnt lgkmcnt(0)
	v_mfma_f32_16x16x32_bf16 v[12:15], v[132:135], v[200:203], v[12:15]
	v_mfma_f32_16x16x32_bf16 v[8:11], v[140:143], v[200:203], v[8:11]
	s_barrier
	s_add_u32 s22, s22, 0x80080
	s_addc_u32 s23, s23, 0
	s_add_i32 s24, s24, s31
	v_lshl_add_u64 v[128:129], s[22:23], 0, v[156:157]
	s_mov_b32 m0, s24
	s_nop 0
	global_load_lds_dwordx4 v[128:129], off
	v_lshl_add_u64 v[128:129], s[22:23], 0, v[160:161]
	s_add_i32 m0, s24, 0x2000
	s_nop 0
	global_load_lds_dwordx4 v[128:129], off
	s_waitcnt vmcnt(6)
	s_barrier
; __device__ __forceinline__ unsigned pk2(float lo, float hi) { const f32x2 v = (f32x2){lo, hi}; const bf16x2_t b = __builtin_convertvector(v, bf16x2_t); return __builtin_bit_cast(unsigned, b); }
; __device__ __forceinline__ void unpack8(const u32x4 v, float* f) { f[0] = bf_lo(v.x); f[1] = bf_hi(v.x); f[2] = bf_lo(v.y); f[3] = bf_hi(v.y); f[4] = bf_lo(v.z); f[5] = bf_hi(v.z); f[6] = bf_lo(v.w); f[7] = bf_hi(v.w); }
;     __device__ __forceinline__ void operator()(const f32x4 (&acc)[2][2][4][2], const Unit& u, int wr, int wc, int fr, int fq, const float (&)[8]) const {
;         const int row0 = u.pm * BM + wr * 64 + fr, col0 = u.pn * BM + wc * 32 + 8 * fq;
; #pragma unroll
;         for (int ai = 0; ai < 2; ++ai) {
;             u32x4 bv[4][2];
; #pragma unroll
;             for (int m = 0; m < 4; ++m)
; #pragma unroll
;                 for (int bj = 0; bj < 2; ++bj) bv[m][bj] = *(const u32x4*)(xb + (size_t)(row0 + ai * HALF + m * 16) * DM + col0 + bj * HALF);
; #pragma unroll
;             for (int m = 0; m < 4; ++m) { const int row = row0 + ai * HALF + m * 16; const size_t ro = (size_t)row * DM + col0; float s = 0.f;
; #pragma unroll
;                 for (int bj = 0; bj < 2; ++bj) { float b8[8]; unpack8(bv[m][bj], b8);
;                     const f32x4 v0 = (f32x4){b8[0], b8[1], b8[2], b8[3]} + acc[ai][bj][m][0], v1 = (f32x4){b8[4], b8[5], b8[6], b8[7]} + acc[ai][bj][m][1];
;                     s += v0[0] * v0[0] + v0[1] * v0[1] + v0[2] * v0[2] + v0[3] * v0[3] + v1[0] * v1[0] + v1[1] * v1[1] + v1[2] * v1[2] + v1[3] * v1[3];
;                     if (LAST) { *(f32x4*)(out + ro + bj * HALF) = v0; *(f32x4*)(out + ro + bj * HALF + 4) = v1; }
;                     else { u32x4 w; w.x = pk2(v0[0], v0[1]); w.y = pk2(v0[2], v0[3]); w.z = pk2(v1[0], v1[1]); w.w = pk2(v1[2], v1[3]); *(u32x4*)(xb + ro + bj * HALF) = w; } }
;                 s += __shfl_xor(s, 16); s += __shfl_xor(s, 32);
;                 if (fq == 0) ss[(size_t)row * 16 + u.pn * 4 + wc] = s; }
; template <class Epi>
; __device__ __forceinline__ void gemm_phase(LAS unsigned char* lds, const Gemm g, const StaticOrder& S, const Epi& E) {
;     ...
;             PG8_BAR; PG8_WAIT_L(0); PG8_MMA(1, 0, At, B0); PG8_BAR; PG8_SCHED;
;             PG8_STAGE(PG8_SB(1, 1), b3 + hstepB, voffB);
;             PG8_WAIT_V(6); PG8_BAR; PG8_MMA(1, 1, At, B1); PG8_BAR;
;         }
	v_mfma_f32_16x16x32_bf16 v[52:55], v[204:207], v[144:147], v[52:55]
	v_mfma_f32_16x16x32_bf16 v[48:51], v[212:215], v[144:147], v[48:51]
	v_mfma_f32_16x16x32_bf16 v[36:39], v[204:207], v[170:173], v[36:39]
	v_mfma_f32_16x16x32_bf16 v[32:35], v[212:215], v[170:173], v[32:35]
	v_mfma_f32_16x16x32_bf16 v[20:23], v[204:207], v[178:181], v[20:23]
	v_mfma_f32_16x16x32_bf16 v[16:19], v[212:215], v[178:181], v[16:19]
	v_mfma_f32_16x16x32_bf16 v[4:7], v[204:207], v[196:199], v[4:7]
	v_mfma_f32_16x16x32_bf16 v[0:3], v[212:215], v[196:199], v[0:3]
	v_mfma_f32_16x16x32_bf16 v[52:55], v[208:211], v[148:151], v[52:55]
	v_mfma_f32_16x16x32_bf16 v[48:51], v[216:219], v[148:151], v[48:51]
	v_mfma_f32_16x16x32_bf16 v[36:39], v[208:211], v[174:177], v[36:39]
	v_mfma_f32_16x16x32_bf16 v[32:35], v[216:219], v[174:177], v[32:35]
	v_mfma_f32_16x16x32_bf16 v[20:23], v[208:211], v[182:185], v[20:23]
	v_mfma_f32_16x16x32_bf16 v[16:19], v[216:219], v[182:185], v[16:19]
	v_mfma_f32_16x16x32_bf16 v[4:7], v[208:211], v[200:203], v[4:7]
	v_mfma_f32_16x16x32_bf16 v[0:3], v[216:219], v[200:203], v[0:3]
	s_add_i32 s48, s48, 2
	s_add_u32 s4, s4, 0x100
	s_addc_u32 s5, s5, 0
	s_add_u32 s46, s46, 0x100
	s_addc_u32 s47, s47, 0
	s_cmp_gt_u32 s48, 29
	s_barrier
	s_cbranch_scc0 .LBB0_684
	v_lshl_or_b32 v170, s10, 8, v190
	v_lshl_add_u32 v172, s12, 8, v188
	v_ashrrev_i32_e32 v171, 31, v170
	v_lshlrev_b64 v[206:207], 1, v[170:171]
	v_ashrrev_i32_e32 v173, 31, v172
	v_lshl_add_u64 v[174:175], s[76:77], 0, v[206:207]
	v_lshlrev_b64 v[208:209], 11, v[172:173]
	v_lshl_add_u64 v[128:129], v[174:175], 0, v[208:209]
	global_load_dwordx4 v[198:201], v[128:129], off
	global_load_dwordx4 v[202:205], v[128:129], off offset:256
	v_or_b32_e32 v184, 16, v172
	v_or_b32_e32 v180, 32, v172
	v_or_b32_e32 v176, 48, v172
	v_ashrrev_i32_e32 v185, 31, v184
	v_ashrrev_i32_e32 v181, 31, v180
	v_ashrrev_i32_e32 v177, 31, v176
	v_lshlrev_b64 v[186:187], 11, v[184:185]
	v_lshlrev_b64 v[182:183], 11, v[180:181]
	v_lshlrev_b64 v[178:179], 11, v[176:177]
	v_lshl_add_u64 v[128:129], v[174:175], 0, v[186:187]
	v_lshl_add_u64 v[130:131], v[174:175], 0, v[182:183]
	v_lshl_add_u64 v[196:197], v[174:175], 0, v[178:179]
	global_load_dwordx4 v[148:151], v[128:129], off
	global_load_dwordx4 v[144:147], v[128:129], off offset:256
	global_load_dwordx4 v[140:143], v[130:131], off
	global_load_dwordx4 v[136:139], v[130:131], off offset:256
	global_load_dwordx4 v[132:135], v[196:197], off
	s_nop 0
	global_load_dwordx4 v[128:131], v[196:197], off offset:256
	v_add_u32_e32 v218, 0x80, v172
	v_ashrrev_i32_e32 v219, 31, v218
	v_lshlrev_b64 v[218:219], 11, v[218:219]
	v_lshl_add_u64 v[218:219], v[174:175], 0, v[218:219]
	global_load_dwordx4 v[220:223], v[218:219], off
	global_load_dwordx4 v[224:227], v[218:219], off offset:256
	v_add_u32_e32 v218, 0x90, v172
	v_ashrrev_i32_e32 v219, 31, v218
	v_lshlrev_b64 v[218:219], 11, v[218:219]
	v_lshl_add_u64 v[218:219], v[174:175], 0, v[218:219]
	global_load_dwordx4 v[228:231], v[218:219], off
	global_load_dwordx4 v[232:235], v[218:219], off offset:256
	v_add_u32_e32 v218, 0xa0, v172
	v_ashrrev_i32_e32 v219, 31, v218
	v_lshlrev_b64 v[218:219], 11, v[218:219]
	v_lshl_add_u64 v[218:219], v[174:175], 0, v[218:219]
	global_load_dwordx4 v[236:239], v[218:219], off
	global_load_dwordx4 v[240:243], v[218:219], off offset:256
	v_add_u32_e32 v218, 0xb0, v172
	v_ashrrev_i32_e32 v219, 31, v218
	v_lshlrev_b64 v[218:219], 11, v[218:219]
	v_lshl_add_u64 v[218:219], v[174:175], 0, v[218:219]
	global_load_dwordx4 v[244:247], v[218:219], off
	global_load_dwordx4 v[252:255], v[218:219], off offset:256
	v_and_b32_e32 v196, 64, v194
	v_xor_b32_e32 v195, 16, v194
	v_add_u32_e32 v196, 64, v196
	v_xor_b32_e32 v197, 32, v194
	v_cmp_lt_i32_e32 vcc, v195, v196
	s_waitcnt vmcnt(15)
	v_lshlrev_b32_e32 v210, 16, v198
	v_cndmask_b32_e32 v195, v194, v195, vcc
	v_cmp_lt_i32_e32 vcc, v197, v196
	v_and_b32_e32 v211, 0xffff0000, v198
	s_waitcnt vmcnt(14)
	v_lshlrev_b32_e32 v214, 16, v202
	v_and_b32_e32 v215, 0xffff0000, v202
	v_cndmask_b32_e32 v197, v194, v197, vcc
	v_lshlrev_b32_e32 v212, 16, v200
	v_and_b32_e32 v213, 0xffff0000, v200
	v_lshlrev_b32_e32 v200, 16, v201
	v_and_b32_e32 v201, 0xffff0000, v201
	v_lshlrev_b32_e32 v216, 16, v204
	v_and_b32_e32 v217, 0xffff0000, v204
	v_pk_add_f32 v[124:125], v[124:125], v[210:211]
	v_pk_add_f32 v[116:117], v[116:117], v[214:215]
	v_lshlrev_b32_e32 v196, 2, v195
	v_lshlrev_b32_e32 v195, 2, v197
	v_lshlrev_b32_e32 v198, 16, v199
	v_and_b32_e32 v199, 0xffff0000, v199
	v_lshlrev_b32_e32 v202, 16, v203
	v_and_b32_e32 v203, 0xffff0000, v203
	v_pk_add_f32 v[122:123], v[122:123], v[200:201]
	v_pk_add_f32 v[200:201], v[112:113], v[216:217]
	v_mul_f32_e32 v197, v125, v125
	v_cvt_pk_bf16_f32 v112, v124, v125
	v_mul_f32_e32 v125, v117, v117
	v_pk_add_f32 v[126:127], v[126:127], v[198:199]
	v_pk_add_f32 v[118:119], v[118:119], v[202:203]
	v_fmac_f32_e32 v197, v124, v124
	v_fmac_f32_e32 v125, v116, v116
	v_fmac_f32_e32 v197, v126, v126
	v_fmac_f32_e32 v125, v118, v118
	v_pk_add_f32 v[120:121], v[120:121], v[212:213]
	v_fmac_f32_e32 v197, v127, v127
	v_fmac_f32_e32 v125, v119, v119
	v_lshlrev_b32_e32 v204, 16, v205
	v_and_b32_e32 v205, 0xffff0000, v205
	v_fmac_f32_e32 v197, v120, v120
	v_fmac_f32_e32 v125, v200, v200
	v_pk_add_f32 v[198:199], v[114:115], v[204:205]
	v_fmac_f32_e32 v197, v121, v121
	v_fmac_f32_e32 v125, v201, v201
	v_fmac_f32_e32 v197, v122, v122
	v_fmac_f32_e32 v125, v198, v198
	v_fmac_f32_e32 v197, v123, v123
	v_fmac_f32_e32 v125, v199, v199
	v_cvt_pk_bf16_f32 v115, v122, v123
	v_add_f32_e32 v122, v197, v125
	ds_bpermute_b32 v123, v196, v122
	v_cvt_pk_bf16_f32 v114, v120, v121
	v_lshl_add_u64 v[120:121], s[76:77], 0, v[208:209]
	v_cvt_pk_bf16_f32 v113, v126, v127
	v_lshl_add_u64 v[120:121], v[120:121], 0, v[206:207]
	global_store_dwordx4 v[120:121], v[112:115], off
	s_waitcnt lgkmcnt(0)
	s_nop 0
	v_add_f32_e32 v112, v122, v123
	ds_bpermute_b32 v113, v195, v112
	v_cvt_pk_bf16_f32 v114, v116, v117
	v_cvt_pk_bf16_f32 v115, v118, v119
	v_cvt_pk_bf16_f32 v116, v200, v201
	v_cvt_pk_bf16_f32 v117, v198, v199
	global_store_dwordx4 v[120:121], v[114:117], off offset:256
	s_and_saveexec_b64 s[4:5], s[0:1]
	s_cbranch_execz .LBB0_687
	s_waitcnt lgkmcnt(0)
	v_add_f32_e32 v114, v112, v113
	s_lshl_b32 s22, s10, 2
	v_lshlrev_b64 v[112:113], 6, v[172:173]
	s_ashr_i32 s23, s22, 31
	v_lshl_add_u64 v[112:113], s[6:7], 0, v[112:113]
	v_lshl_add_u64 v[112:113], s[22:23], 2, v[112:113]
	s_lshl_b32 s12, s37, 2
	v_lshl_add_u64 v[112:113], v[112:113], 0, s[12:13]
	global_store_dword v[112:113], v114, off

; #define PG8_STAGE(bufoff, gbase, voff) do { _Pragma("unroll") for (int _i = 0; _i < 2; ++_i) \
;         __builtin_amdgcn_global_load_lds((const unsigned*)((const char*)(gbase) + (voff)[_i]), (LAS unsigned*)(lds + (bufoff) + ldsw + _i * 8192), 16, 0, 0); } while (0)
; #define PG8_LDA(dst, b, h) do { _Pragma("unroll") for (int m = 0; m < 4; ++m) _Pragma("unroll") for (int k = 0; k < 2; ++k) dst[m][k] = *(const LAS bf16x8*)(lds + PG8_SA(b, h) + aoff + m * 2048 + k * 1024); } while (0)
; #define PG8_LDB(dst, b, h) do { _Pragma("unroll") for (int n = 0; n < 2; ++n) _Pragma("unroll") for (int k = 0; k < 2; ++k) dst[n][k] = *(const LAS bf16x8*)(lds + PG8_SB(b, h) + boff + n * 2048 + k * 1024); } while (0)
; #define PG8_MMA(ai, bj, At, Bt) do { __builtin_amdgcn_s_setprio(1); _Pragma("unroll") for (int m = 0; m < 4; ++m) _Pragma("unroll") for (int n = 0; n < 2; ++n) _Pragma("unroll") for (int k = 0; k < 2; ++k) \
;         acc[ai][bj][m][n] = __builtin_amdgcn_mfma_f32_16x16x32_bf16(Bt[n][k], At[m][k], acc[ai][bj][m][n], 0, 0, 0); __builtin_amdgcn_s_setprio(0); } while (0)
; #define PG8_BAR __builtin_amdgcn_s_barrier()
; template <class Epi>
; __device__ __forceinline__ void gemm_phase(LAS unsigned char* lds, const Gemm g, const StaticOrder& S, const Epi& E) {
;     ...
;         const bool has_next = S.next(ui + 1, nxt);
;         const char* nA = has_next ? (const char*)g.A + (size_t)nxt.pm * tstepA : cA; const char* nB = has_next ? (const char*)g.Bt + (size_t)nxt.pn * tstepB : cB;
;         for (int t = 0; t < nt; t += 2) {
;             const bool last = (t == nt - 2);
;             const char* a1 = cA + (size_t)(t + 1) * kstep;
;             const char* a2 = last ? nA : cA + (size_t)(t + 2) * kstep; const char* b2 = last ? nB : cB + (size_t)(t + 2) * kstep;
;             const char* a3 = a2 + kstep; const char* b3 = b2 + kstep;
;             if (last) E.pre(cur, wr, fr, epre);
;             PG8_LDB(B0, 0, 0); PG8_SCHED; PG8_LDA(At, 0, 0); PG8_STAGE(PG8_SA(1, 1), a1 + hstepA, voffA);
;             PG8_WAIT_L(8); PG8_BAR; PG8_WAIT_L(0); PG8_MMA(0, 0, At, B0); PG8_BAR; PG8_SCHED;
;             PG8_LDB(B1, 0, 1); PG8_STAGE(PG8_SB(0, 0), b2, voffB);
;             PG8_BAR; PG8_WAIT_L(0); PG8_MMA(0, 1, At, B1); PG8_BAR;
;             PG8_LDA(At, 0, 1); PG8_STAGE(PG8_SA(0, 0), a2, voffA);
;             PG8_BAR; PG8_WAIT_L(0); PG8_MMA(1, 0, At, B0); PG8_BAR; PG8_SCHED;
.LBB0_769:
	s_ashr_i32 s13, s12, 31
	v_cmp_lt_i64_e32 vcc, s[14:15], v[142:143]
	s_lshl_b64 s[14:15], s[12:13], 19
	s_add_u32 s14, s76, s14
	s_addc_u32 s15, s77, s15
	s_and_b64 s[16:17], vcc, exec
	s_cselect_b32 s13, s15, s21
	s_cselect_b32 s41, s14, s20
	s_ashr_i32 s11, s10, 31
	s_lshl_b64 s[16:17], s[10:11], 19
	s_add_u32 s16, s27, s16
	s_addc_u32 s17, s28, s17
	s_and_b64 s[24:25], vcc, exec
	s_cselect_b32 s11, s17, s23
	s_cselect_b32 s42, s16, s22
	s_add_u32 s20, s20, 0x40080
	s_addc_u32 s21, s21, 0
	s_add_u32 s43, s22, 0x100
	s_addc_u32 s44, s23, 0
	s_mov_b32 s45, -2
	ds_read_b128 v[146:149], v177
	ds_read_b128 v[154:157], v177 offset:1024
	ds_read_b128 v[158:161], v177 offset:2048
	ds_read_b128 v[162:165], v177 offset:3072
	s_add_u32 s22, s20, 0xfffc0080
	s_addc_u32 s23, s21, -1
	s_cmp_eq_u32 s45, 12
	s_cselect_b32 s25, s13, s23
	s_cselect_b32 s24, s41, s22
	s_cselect_b32 s23, s11, s44
	s_cselect_b32 s22, s42, s43
	v_lshl_add_u64 v[150:151], s[20:21], 0, v[138:139]
	s_add_i32 m0, s19, 0xc000
	ds_read_b128 v[166:169], v178
	ds_read_b128 v[170:173], v178 offset:1024
	ds_read_b128 v[182:185], v178 offset:2048
	ds_read_b128 v[186:189], v178 offset:3072
	ds_read_b128 v[190:193], v178 offset:4096
	ds_read_b128 v[194:197], v178 offset:5120
	ds_read_b128 v[198:201], v178 offset:6144
	ds_read_b128 v[202:205], v178 offset:7168
	global_load_lds_dwordx4 v[150:151], off
	v_lshl_add_u64 v[150:151], s[20:21], 0, v[140:141]
	s_add_i32 m0, s19, 0xe000
	s_nop 0
	global_load_lds_dwordx4 v[150:151], off
	s_waitcnt lgkmcnt(8)
	s_barrier
	s_waitcnt lgkmcnt(7)
	v_mfma_f32_16x16x32_bf16 v[124:127], v[146:149], v[166:169], 0
	v_mfma_f32_16x16x32_bf16 v[120:123], v[158:161], v[166:169], 0
	s_waitcnt lgkmcnt(5)
	v_mfma_f32_16x16x32_bf16 v[108:111], v[146:149], v[182:185], 0
	v_mfma_f32_16x16x32_bf16 v[104:107], v[158:161], v[182:185], 0
	s_waitcnt lgkmcnt(3)
	v_mfma_f32_16x16x32_bf16 v[92:95], v[146:149], v[190:193], 0
	v_mfma_f32_16x16x32_bf16 v[88:91], v[158:161], v[190:193], 0
	s_waitcnt lgkmcnt(1)
	v_mfma_f32_16x16x32_bf16 v[76:79], v[146:149], v[198:201], 0
	v_mfma_f32_16x16x32_bf16 v[72:75], v[158:161], v[198:201], 0
	v_mfma_f32_16x16x32_bf16 v[124:127], v[154:157], v[170:173], v[124:127]
	v_mfma_f32_16x16x32_bf16 v[120:123], v[162:165], v[170:173], v[120:123]
	v_mfma_f32_16x16x32_bf16 v[108:111], v[154:157], v[186:189], v[108:111]
	v_mfma_f32_16x16x32_bf16 v[104:107], v[162:165], v[186:189], v[104:107]
	v_mfma_f32_16x16x32_bf16 v[92:95], v[154:157], v[194:197], v[92:95]
	v_mfma_f32_16x16x32_bf16 v[88:91], v[162:165], v[194:197], v[88:91]
	s_waitcnt lgkmcnt(0)
	v_mfma_f32_16x16x32_bf16 v[76:79], v[154:157], v[202:205], v[76:79]
	v_mfma_f32_16x16x32_bf16 v[72:75], v[162:165], v[202:205], v[72:75]
	s_barrier
	s_add_i32 s46, s7, s29
	v_lshl_add_u64 v[150:151], s[22:23], 0, v[130:131]
	s_mov_b32 m0, s46
	ds_read_b128 v[206:209], v179
	ds_read_b128 v[210:213], v179 offset:1024
	ds_read_b128 v[214:217], v179 offset:2048
	ds_read_b128 v[218:221], v179 offset:3072
	global_load_lds_dwordx4 v[150:151], off
	v_lshl_add_u64 v[222:223], s[22:23], 0, v[134:135]
	s_add_i32 m0, s46, 0x2000
	s_nop 0
	global_load_lds_dwordx4 v[222:223], off
	s_barrier
	s_waitcnt lgkmcnt(3)
	v_mfma_f32_16x16x32_bf16 v[116:119], v[206:209], v[166:169], 0
	s_waitcnt lgkmcnt(1)
	v_mfma_f32_16x16x32_bf16 v[112:115], v[214:217], v[166:169], 0
	v_mfma_f32_16x16x32_bf16 v[100:103], v[206:209], v[182:185], 0
	v_mfma_f32_16x16x32_bf16 v[96:99], v[214:217], v[182:185], 0
	v_mfma_f32_16x16x32_bf16 v[84:87], v[206:209], v[190:193], 0
	v_mfma_f32_16x16x32_bf16 v[80:83], v[214:217], v[190:193], 0
	v_mfma_f32_16x16x32_bf16 v[68:71], v[206:209], v[198:201], 0
	v_mfma_f32_16x16x32_bf16 v[64:67], v[214:217], v[198:201], 0
	v_mfma_f32_16x16x32_bf16 v[116:119], v[210:213], v[170:173], v[116:119]
	s_waitcnt lgkmcnt(0)
	v_mfma_f32_16x16x32_bf16 v[112:115], v[218:221], v[170:173], v[112:115]
	v_mfma_f32_16x16x32_bf16 v[100:103], v[210:213], v[186:189], v[100:103]
	v_mfma_f32_16x16x32_bf16 v[96:99], v[218:221], v[186:189], v[96:99]
	v_mfma_f32_16x16x32_bf16 v[84:87], v[210:213], v[194:197], v[84:87]
	v_mfma_f32_16x16x32_bf16 v[80:83], v[218:221], v[194:197], v[80:83]
	v_mfma_f32_16x16x32_bf16 v[68:71], v[210:213], v[202:205], v[68:71]
	v_mfma_f32_16x16x32_bf16 v[64:67], v[218:221], v[202:205], v[64:67]
	s_mov_b32 m0, s19
	v_lshl_add_u64 v[224:225], s[24:25], 0, v[128:129]
	s_barrier
	ds_read_b128 v[166:169], v178 offset:16384
	ds_read_b128 v[170:173], v178 offset:17408
	ds_read_b128 v[182:185], v178 offset:18432
	ds_read_b128 v[186:189], v178 offset:19456
	ds_read_b128 v[190:193], v178 offset:20480
	ds_read_b128 v[194:197], v178 offset:21504
	ds_read_b128 v[198:201], v178 offset:22528
	ds_read_b128 v[202:205], v178 offset:23552
	global_load_lds_dwordx4 v[224:225], off
	v_lshl_add_u64 v[226:227], s[24:25], 0, v[132:133]
	s_mov_b32 m0, s30
	s_nop 0
	global_load_lds_dwordx4 v[226:227], off
	s_barrier
	s_waitcnt lgkmcnt(7)
	v_mfma_f32_16x16x32_bf16 v[60:63], v[146:149], v[166:169], 0
	v_mfma_f32_16x16x32_bf16 v[56:59], v[158:161], v[166:169], 0
	s_waitcnt lgkmcnt(5)
	v_mfma_f32_16x16x32_bf16 v[44:47], v[146:149], v[182:185], 0
	v_mfma_f32_16x16x32_bf16 v[40:43], v[158:161], v[182:185], 0
	s_waitcnt lgkmcnt(3)
	v_mfma_f32_16x16x32_bf16 v[28:31], v[146:149], v[190:193], 0
	v_mfma_f32_16x16x32_bf16 v[24:27], v[158:161], v[190:193], 0
	s_waitcnt lgkmcnt(1)
	v_mfma_f32_16x16x32_bf16 v[12:15], v[146:149], v[198:201], 0
	v_mfma_f32_16x16x32_bf16 v[8:11], v[158:161], v[198:201], 0
	v_mfma_f32_16x16x32_bf16 v[60:63], v[154:157], v[170:173], v[60:63]
	v_mfma_f32_16x16x32_bf16 v[56:59], v[162:165], v[170:173], v[56:59]
	v_mfma_f32_16x16x32_bf16 v[44:47], v[154:157], v[186:189], v[44:47]
	v_mfma_f32_16x16x32_bf16 v[40:43], v[162:165], v[186:189], v[40:43]
	v_mfma_f32_16x16x32_bf16 v[28:31], v[154:157], v[194:197], v[28:31]
	v_mfma_f32_16x16x32_bf16 v[24:27], v[162:165], v[194:197], v[24:27]
	s_waitcnt lgkmcnt(0)
	v_mfma_f32_16x16x32_bf16 v[12:15], v[154:157], v[202:205], v[12:15]
	v_mfma_f32_16x16x32_bf16 v[8:11], v[162:165], v[202:205], v[8:11]
	s_barrier
; #define PG8_STAGE(bufoff, gbase, voff) do { _Pragma("unroll") for (int _i = 0; _i < 2; ++_i) \
;         __builtin_amdgcn_global_load_lds((const unsigned*)((const char*)(gbase) + (voff)[_i]), (LAS unsigned*)(lds + (bufoff) + ldsw + _i * 8192), 16, 0, 0); } while (0)
; #define PG8_LDA(dst, b, h) do { _Pragma("unroll") for (int m = 0; m < 4; ++m) _Pragma("unroll") for (int k = 0; k < 2; ++k) dst[m][k] = *(const LAS bf16x8*)(lds + PG8_SA(b, h) + aoff + m * 2048 + k * 1024); } while (0)
; #define PG8_LDB(dst, b, h) do { _Pragma("unroll") for (int n = 0; n < 2; ++n) _Pragma("unroll") for (int k = 0; k < 2; ++k) dst[n][k] = *(const LAS bf16x8*)(lds + PG8_SB(b, h) + boff + n * 2048 + k * 1024); } while (0)
; #define PG8_MMA(ai, bj, At, Bt) do { __builtin_amdgcn_s_setprio(1); _Pragma("unroll") for (int m = 0; m < 4; ++m) _Pragma("unroll") for (int n = 0; n < 2; ++n) _Pragma("unroll") for (int k = 0; k < 2; ++k) \
;         acc[ai][bj][m][n] = __builtin_amdgcn_mfma_f32_16x16x32_bf16(Bt[n][k], At[m][k], acc[ai][bj][m][n], 0, 0, 0); __builtin_amdgcn_s_setprio(0); } while (0)
; #define PG8_WAIT_V(n) asm volatile("s_waitcnt vmcnt(" #n ")" ::: "memory")
; #define PG8_WAIT_L(n) asm volatile("s_waitcnt lgkmcnt(" #n ")" ::: "memory")
; #define PG8_BAR __builtin_amdgcn_s_barrier()
; #define PG8_SCHED __builtin_amdgcn_sched_barrier(0)
; template <class Epi>
; __device__ __forceinline__ void gemm_phase(LAS unsigned char* lds, const Gemm g, const StaticOrder& S, const Epi& E) {
;     ...
;             PG8_BAR; PG8_WAIT_L(0); PG8_MMA(1, 0, At, B0); PG8_BAR; PG8_SCHED;
;             PG8_STAGE(PG8_SB(0, 1), b2 + hstepB, voffB);
;             PG8_WAIT_V(6); PG8_BAR; PG8_MMA(1, 1, At, B1); PG8_BAR;
;             PG8_LDB(B0, 1, 0); PG8_SCHED; PG8_LDA(At, 1, 0); PG8_STAGE(PG8_SA(0, 1), a2 + hstepA, voffA);
;             PG8_WAIT_L(8); PG8_BAR; PG8_WAIT_L(0); PG8_MMA(0, 0, At, B0); PG8_BAR; PG8_SCHED;
;             PG8_LDB(B1, 1, 1); PG8_STAGE(PG8_SB(1, 0), b3, voffB);
;             PG8_BAR; PG8_WAIT_L(0); PG8_MMA(0, 1, At, B1); PG8_BAR;
;             PG8_LDA(At, 1, 1); PG8_STAGE(PG8_SA(1, 0), a3, voffA);
;             PG8_BAR; PG8_WAIT_L(0); PG8_MMA(1, 0, At, B0); PG8_BAR; PG8_SCHED;
	s_add_u32 s46, s22, 0x40000
	s_addc_u32 s47, s23, 0
	s_add_i32 s48, s38, s29
	v_lshl_add_u64 v[146:147], s[46:47], 0, v[130:131]
	s_mov_b32 m0, s48
	s_nop 0
	global_load_lds_dwordx4 v[146:147], off
	v_lshl_add_u64 v[146:147], s[46:47], 0, v[134:135]
	s_add_i32 m0, s48, 0x2000
	s_nop 0
	global_load_lds_dwordx4 v[146:147], off
	s_waitcnt vmcnt(6)
	s_barrier
	v_mfma_f32_16x16x32_bf16 v[52:55], v[206:209], v[166:169], 0
	v_mfma_f32_16x16x32_bf16 v[48:51], v[214:217], v[166:169], 0
	v_mfma_f32_16x16x32_bf16 v[36:39], v[206:209], v[182:185], 0
	v_mfma_f32_16x16x32_bf16 v[32:35], v[214:217], v[182:185], 0
	v_mfma_f32_16x16x32_bf16 v[20:23], v[206:209], v[190:193], 0
	v_mfma_f32_16x16x32_bf16 v[16:19], v[214:217], v[190:193], 0
	v_mfma_f32_16x16x32_bf16 v[4:7], v[206:209], v[198:201], 0
	v_mfma_f32_16x16x32_bf16 v[0:3], v[214:217], v[198:201], 0
	v_mfma_f32_16x16x32_bf16 v[52:55], v[210:213], v[170:173], v[52:55]
	v_mfma_f32_16x16x32_bf16 v[48:51], v[218:221], v[170:173], v[48:51]
	v_mfma_f32_16x16x32_bf16 v[36:39], v[210:213], v[186:189], v[36:39]
	v_mfma_f32_16x16x32_bf16 v[32:35], v[218:221], v[186:189], v[32:35]
	v_mfma_f32_16x16x32_bf16 v[20:23], v[210:213], v[194:197], v[20:23]
	v_mfma_f32_16x16x32_bf16 v[16:19], v[218:221], v[194:197], v[16:19]
	v_mfma_f32_16x16x32_bf16 v[4:7], v[210:213], v[202:205], v[4:7]
	v_mfma_f32_16x16x32_bf16 v[0:3], v[218:221], v[202:205], v[0:3]
	s_add_i32 s46, 0, 0x18000
	v_add_u32_e32 v162, s46, v175
	s_barrier
	ds_read_b128 v[146:149], v162
	ds_read_b128 v[154:157], v162 offset:1024
	ds_read_b128 v[158:161], v162 offset:2048
	ds_read_b128 v[162:165], v162 offset:3072
	s_add_u32 s24, s24, 0x40000
	s_addc_u32 s25, s25, 0
	s_mov_b32 m0, s31
	v_lshl_add_u64 v[206:207], s[24:25], 0, v[128:129]
	ds_read_b128 v[166:169], v178 offset:32768
	ds_read_b128 v[170:173], v178 offset:33792
	ds_read_b128 v[182:185], v178 offset:34816
	ds_read_b128 v[186:189], v178 offset:35840
	ds_read_b128 v[190:193], v178 offset:36864
	ds_read_b128 v[194:197], v178 offset:37888
	ds_read_b128 v[198:201], v178 offset:38912
	ds_read_b128 v[202:205], v178 offset:39936
	global_load_lds_dwordx4 v[206:207], off
	v_lshl_add_u64 v[206:207], s[24:25], 0, v[132:133]
	s_mov_b32 m0, s33
	s_nop 0
	global_load_lds_dwordx4 v[206:207], off
	s_waitcnt lgkmcnt(8)
	s_barrier
	s_waitcnt lgkmcnt(7)
	v_mfma_f32_16x16x32_bf16 v[124:127], v[146:149], v[166:169], v[124:127]
	v_mfma_f32_16x16x32_bf16 v[120:123], v[158:161], v[166:169], v[120:123]
	s_waitcnt lgkmcnt(5)
	v_mfma_f32_16x16x32_bf16 v[108:111], v[146:149], v[182:185], v[108:111]
	v_mfma_f32_16x16x32_bf16 v[104:107], v[158:161], v[182:185], v[104:107]
	s_waitcnt lgkmcnt(3)
	v_mfma_f32_16x16x32_bf16 v[92:95], v[146:149], v[190:193], v[92:95]
	v_mfma_f32_16x16x32_bf16 v[88:91], v[158:161], v[190:193], v[88:91]
	s_waitcnt lgkmcnt(1)
	v_mfma_f32_16x16x32_bf16 v[76:79], v[146:149], v[198:201], v[76:79]
	v_mfma_f32_16x16x32_bf16 v[72:75], v[158:161], v[198:201], v[72:75]
	v_mfma_f32_16x16x32_bf16 v[124:127], v[154:157], v[170:173], v[124:127]
	v_mfma_f32_16x16x32_bf16 v[120:123], v[162:165], v[170:173], v[120:123]
	v_mfma_f32_16x16x32_bf16 v[108:111], v[154:157], v[186:189], v[108:111]
	v_mfma_f32_16x16x32_bf16 v[104:107], v[162:165], v[186:189], v[104:107]
	v_mfma_f32_16x16x32_bf16 v[92:95], v[154:157], v[194:197], v[92:95]
	v_mfma_f32_16x16x32_bf16 v[88:91], v[162:165], v[194:197], v[88:91]
	s_waitcnt lgkmcnt(0)
	v_mfma_f32_16x16x32_bf16 v[76:79], v[154:157], v[202:205], v[76:79]
	v_mfma_f32_16x16x32_bf16 v[72:75], v[162:165], v[202:205], v[72:75]
	s_barrier
	s_add_i32 s24, 0, 0x1c000
	s_add_i32 s25, s46, s29
	v_add_u32_e32 v181, s24, v175
	v_lshl_add_u64 v[150:151], v[150:151], 0, s[4:5]
	s_mov_b32 m0, s25
	ds_read_b128 v[206:209], v181
	ds_read_b128 v[210:213], v181 offset:1024
	ds_read_b128 v[214:217], v181 offset:2048
	ds_read_b128 v[218:221], v181 offset:3072
	global_load_lds_dwordx4 v[150:151], off
	v_lshl_add_u64 v[150:151], v[222:223], 0, s[4:5]
	s_add_i32 m0, s25, 0x2000
	s_nop 0
	global_load_lds_dwordx4 v[150:151], off
	s_barrier
	s_waitcnt lgkmcnt(3)
	v_mfma_f32_16x16x32_bf16 v[116:119], v[206:209], v[166:169], v[116:119]
	s_waitcnt lgkmcnt(1)
	v_mfma_f32_16x16x32_bf16 v[112:115], v[214:217], v[166:169], v[112:115]
	v_mfma_f32_16x16x32_bf16 v[100:103], v[206:209], v[182:185], v[100:103]
	v_mfma_f32_16x16x32_bf16 v[96:99], v[214:217], v[182:185], v[96:99]
	v_mfma_f32_16x16x32_bf16 v[84:87], v[206:209], v[190:193], v[84:87]
	v_mfma_f32_16x16x32_bf16 v[80:83], v[214:217], v[190:193], v[80:83]
	v_mfma_f32_16x16x32_bf16 v[68:71], v[206:209], v[198:201], v[68:71]
	v_mfma_f32_16x16x32_bf16 v[64:67], v[214:217], v[198:201], v[64:67]
	v_mfma_f32_16x16x32_bf16 v[116:119], v[210:213], v[170:173], v[116:119]
	s_waitcnt lgkmcnt(0)
	v_mfma_f32_16x16x32_bf16 v[112:115], v[218:221], v[170:173], v[112:115]
	v_mfma_f32_16x16x32_bf16 v[100:103], v[210:213], v[186:189], v[100:103]
	v_mfma_f32_16x16x32_bf16 v[96:99], v[218:221], v[186:189], v[96:99]
	v_mfma_f32_16x16x32_bf16 v[84:87], v[210:213], v[194:197], v[84:87]
	v_mfma_f32_16x16x32_bf16 v[80:83], v[218:221], v[194:197], v[80:83]
	v_mfma_f32_16x16x32_bf16 v[68:71], v[210:213], v[202:205], v[68:71]
	v_mfma_f32_16x16x32_bf16 v[64:67], v[218:221], v[202:205], v[64:67]
	s_mov_b32 m0, s35
	v_lshl_add_u64 v[150:151], v[224:225], 0, s[4:5]
	s_barrier
	ds_read_b128 v[166:169], v178 offset:49152
	ds_read_b128 v[170:173], v178 offset:50176
	ds_read_b128 v[182:185], v178 offset:51200
	ds_read_b128 v[186:189], v178 offset:52224
	ds_read_b128 v[190:193], v178 offset:53248
	ds_read_b128 v[194:197], v178 offset:54272
	ds_read_b128 v[198:201], v178 offset:55296
	ds_read_b128 v[202:205], v178 offset:56320
	global_load_lds_dwordx4 v[150:151], off
	v_lshl_add_u64 v[150:151], v[226:227], 0, s[4:5]
	s_mov_b32 m0, s36
	s_nop 0
	global_load_lds_dwordx4 v[150:151], off
	s_barrier
; #define PG8_STAGE(bufoff, gbase, voff) do { _Pragma("unroll") for (int _i = 0; _i < 2; ++_i) \
;         __builtin_amdgcn_global_load_lds((const unsigned*)((const char*)(gbase) + (voff)[_i]), (LAS unsigned*)(lds + (bufoff) + ldsw + _i * 8192), 16, 0, 0); } while (0)
; #define PG8_LDA(dst, b, h) do { _Pragma("unroll") for (int m = 0; m < 4; ++m) _Pragma("unroll") for (int k = 0; k < 2; ++k) dst[m][k] = *(const LAS bf16x8*)(lds + PG8_SA(b, h) + aoff + m * 2048 + k * 1024); } while (0)
; #define PG8_LDB(dst, b, h) do { _Pragma("unroll") for (int n = 0; n < 2; ++n) _Pragma("unroll") for (int k = 0; k < 2; ++k) dst[n][k] = *(const LAS bf16x8*)(lds + PG8_SB(b, h) + boff + n * 2048 + k * 1024); } while (0)
; #define PG8_MMA(ai, bj, At, Bt) do { __builtin_amdgcn_s_setprio(1); _Pragma("unroll") for (int m = 0; m < 4; ++m) _Pragma("unroll") for (int n = 0; n < 2; ++n) _Pragma("unroll") for (int k = 0; k < 2; ++k) \
;         acc[ai][bj][m][n] = __builtin_amdgcn_mfma_f32_16x16x32_bf16(Bt[n][k], At[m][k], acc[ai][bj][m][n], 0, 0, 0); __builtin_amdgcn_s_setprio(0); } while (0)
; #define PG8_WAIT_V(n) asm volatile("s_waitcnt vmcnt(" #n ")" ::: "memory")
; #define PG8_BAR __builtin_amdgcn_s_barrier()
; template <class Epi>
; __device__ __forceinline__ void gemm_phase(LAS unsigned char* lds, const Gemm g, const StaticOrder& S, const Epi& E) {
;     ...
;         const bool has_next = S.next(ui + 1, nxt);
;         const char* nA = has_next ? (const char*)g.A + (size_t)nxt.pm * tstepA : cA; const char* nB = has_next ? (const char*)g.Bt + (size_t)nxt.pn * tstepB : cB;
;         for (int t = 0; t < nt; t += 2) {
;             const bool last = (t == nt - 2);
;             const char* a1 = cA + (size_t)(t + 1) * kstep;
;             const char* a2 = last ? nA : cA + (size_t)(t + 2) * kstep; const char* b2 = last ? nB : cB + (size_t)(t + 2) * kstep;
;             const char* a3 = a2 + kstep; const char* b3 = b2 + kstep;
;             if (last) E.pre(cur, wr, fr, epre);
;             PG8_LDB(B0, 0, 0); PG8_SCHED; PG8_LDA(At, 0, 0); PG8_STAGE(PG8_SA(1, 1), a1 + hstepA, voffA);
;             PG8_WAIT_L(8); PG8_BAR; PG8_WAIT_L(0); PG8_MMA(0, 0, At, B0); PG8_BAR; PG8_SCHED;
;             PG8_LDB(B1, 0, 1); PG8_STAGE(PG8_SB(0, 0), b2, voffB);
;             PG8_BAR; PG8_WAIT_L(0); PG8_MMA(0, 1, At, B1); PG8_BAR;
;     ...
;             PG8_WAIT_V(6); PG8_BAR; PG8_MMA(1, 1, At, B1); PG8_BAR;
	s_waitcnt lgkmcnt(7)
	v_mfma_f32_16x16x32_bf16 v[60:63], v[146:149], v[166:169], v[60:63]
	v_mfma_f32_16x16x32_bf16 v[56:59], v[158:161], v[166:169], v[56:59]
	s_waitcnt lgkmcnt(5)
	v_mfma_f32_16x16x32_bf16 v[44:47], v[146:149], v[182:185], v[44:47]
	v_mfma_f32_16x16x32_bf16 v[40:43], v[158:161], v[182:185], v[40:43]
	s_waitcnt lgkmcnt(3)
	v_mfma_f32_16x16x32_bf16 v[28:31], v[146:149], v[190:193], v[28:31]
	v_mfma_f32_16x16x32_bf16 v[24:27], v[158:161], v[190:193], v[24:27]
	s_waitcnt lgkmcnt(1)
	v_mfma_f32_16x16x32_bf16 v[12:15], v[146:149], v[198:201], v[12:15]
	v_mfma_f32_16x16x32_bf16 v[8:11], v[158:161], v[198:201], v[8:11]
	v_mfma_f32_16x16x32_bf16 v[60:63], v[154:157], v[170:173], v[60:63]
	v_mfma_f32_16x16x32_bf16 v[56:59], v[162:165], v[170:173], v[56:59]
	v_mfma_f32_16x16x32_bf16 v[44:47], v[154:157], v[186:189], v[44:47]
	v_mfma_f32_16x16x32_bf16 v[40:43], v[162:165], v[186:189], v[40:43]
	v_mfma_f32_16x16x32_bf16 v[28:31], v[154:157], v[194:197], v[28:31]
	v_mfma_f32_16x16x32_bf16 v[24:27], v[162:165], v[194:197], v[24:27]
	s_waitcnt lgkmcnt(0)
	v_mfma_f32_16x16x32_bf16 v[12:15], v[154:157], v[202:205], v[12:15]
	v_mfma_f32_16x16x32_bf16 v[8:11], v[162:165], v[202:205], v[8:11]
	s_barrier
	s_add_u32 s22, s22, 0x40080
	s_addc_u32 s23, s23, 0
	s_add_i32 s24, s24, s29
	v_lshl_add_u64 v[146:147], s[22:23], 0, v[130:131]
	s_mov_b32 m0, s24
	s_nop 0
	global_load_lds_dwordx4 v[146:147], off
	v_lshl_add_u64 v[146:147], s[22:23], 0, v[134:135]
	s_add_i32 m0, s24, 0x2000
	s_nop 0
	global_load_lds_dwordx4 v[146:147], off
	s_waitcnt vmcnt(6)
	s_barrier
	v_mfma_f32_16x16x32_bf16 v[52:55], v[206:209], v[166:169], v[52:55]
	v_mfma_f32_16x16x32_bf16 v[48:51], v[214:217], v[166:169], v[48:51]
	v_mfma_f32_16x16x32_bf16 v[36:39], v[206:209], v[182:185], v[36:39]
	v_mfma_f32_16x16x32_bf16 v[32:35], v[214:217], v[182:185], v[32:35]
	v_mfma_f32_16x16x32_bf16 v[20:23], v[206:209], v[190:193], v[20:23]
	v_mfma_f32_16x16x32_bf16 v[16:19], v[214:217], v[190:193], v[16:19]
	v_mfma_f32_16x16x32_bf16 v[4:7], v[206:209], v[198:201], v[4:7]
	v_mfma_f32_16x16x32_bf16 v[0:3], v[214:217], v[198:201], v[0:3]
	v_mfma_f32_16x16x32_bf16 v[52:55], v[210:213], v[170:173], v[52:55]
	v_mfma_f32_16x16x32_bf16 v[48:51], v[218:221], v[170:173], v[48:51]
	v_mfma_f32_16x16x32_bf16 v[36:39], v[210:213], v[186:189], v[36:39]
	v_mfma_f32_16x16x32_bf16 v[32:35], v[218:221], v[186:189], v[32:35]
	v_mfma_f32_16x16x32_bf16 v[20:23], v[210:213], v[194:197], v[20:23]
	v_mfma_f32_16x16x32_bf16 v[16:19], v[218:221], v[194:197], v[16:19]
	v_mfma_f32_16x16x32_bf16 v[4:7], v[210:213], v[202:205], v[4:7]
	v_mfma_f32_16x16x32_bf16 v[0:3], v[218:221], v[202:205], v[0:3]
	s_add_i32 s45, s45, 2
	s_add_u32 s20, s20, 0x100
	s_addc_u32 s21, s21, 0
	s_add_u32 s43, s43, 0x100
	s_addc_u32 s44, s44, 0
	s_cmp_gt_u32 s45, 13
	s_barrier
.LBB0_770:
	ds_read_b128 v[146:149], v177
	ds_read_b128 v[154:157], v177 offset:1024
	ds_read_b128 v[158:161], v177 offset:2048
	ds_read_b128 v[162:165], v177 offset:3072
	s_add_u32 s22, s20, 0xfffc0080
	s_addc_u32 s23, s21, -1
	s_cmp_eq_u32 s45, 12
	s_cselect_b32 s25, s13, s23
	s_cselect_b32 s24, s41, s22
	s_cselect_b32 s23, s11, s44
	s_cselect_b32 s22, s42, s43
	v_lshl_add_u64 v[150:151], s[20:21], 0, v[138:139]
	s_add_i32 m0, s19, 0xc000
	ds_read_b128 v[166:169], v178
	ds_read_b128 v[170:173], v178 offset:1024
	ds_read_b128 v[182:185], v178 offset:2048
	ds_read_b128 v[186:189], v178 offset:3072
	ds_read_b128 v[190:193], v178 offset:4096
	ds_read_b128 v[194:197], v178 offset:5120
	ds_read_b128 v[198:201], v178 offset:6144
	ds_read_b128 v[202:205], v178 offset:7168
	global_load_lds_dwordx4 v[150:151], off
	v_lshl_add_u64 v[150:151], s[20:21], 0, v[140:141]
	s_add_i32 m0, s19, 0xe000
	s_nop 0
	global_load_lds_dwordx4 v[150:151], off
	s_waitcnt lgkmcnt(8)
	s_barrier
	s_waitcnt lgkmcnt(7)
	v_mfma_f32_16x16x32_bf16 v[124:127], v[146:149], v[166:169], v[124:127]
	v_mfma_f32_16x16x32_bf16 v[120:123], v[158:161], v[166:169], v[120:123]
	s_waitcnt lgkmcnt(5)
	v_mfma_f32_16x16x32_bf16 v[108:111], v[146:149], v[182:185], v[108:111]
	v_mfma_f32_16x16x32_bf16 v[104:107], v[158:161], v[182:185], v[104:107]
	s_waitcnt lgkmcnt(3)
	v_mfma_f32_16x16x32_bf16 v[92:95], v[146:149], v[190:193], v[92:95]
	v_mfma_f32_16x16x32_bf16 v[88:91], v[158:161], v[190:193], v[88:91]
	s_waitcnt lgkmcnt(1)
	v_mfma_f32_16x16x32_bf16 v[76:79], v[146:149], v[198:201], v[76:79]
	v_mfma_f32_16x16x32_bf16 v[72:75], v[158:161], v[198:201], v[72:75]
	v_mfma_f32_16x16x32_bf16 v[124:127], v[154:157], v[170:173], v[124:127]
	v_mfma_f32_16x16x32_bf16 v[120:123], v[162:165], v[170:173], v[120:123]
	v_mfma_f32_16x16x32_bf16 v[108:111], v[154:157], v[186:189], v[108:111]
	v_mfma_f32_16x16x32_bf16 v[104:107], v[162:165], v[186:189], v[104:107]
	v_mfma_f32_16x16x32_bf16 v[92:95], v[154:157], v[194:197], v[92:95]
	v_mfma_f32_16x16x32_bf16 v[88:91], v[162:165], v[194:197], v[88:91]
	s_waitcnt lgkmcnt(0)
	v_mfma_f32_16x16x32_bf16 v[76:79], v[154:157], v[202:205], v[76:79]
	v_mfma_f32_16x16x32_bf16 v[72:75], v[162:165], v[202:205], v[72:75]
	s_barrier
	s_add_i32 s46, s7, s29
	v_lshl_add_u64 v[150:151], s[22:23], 0, v[130:131]
	s_mov_b32 m0, s46
	ds_read_b128 v[206:209], v179
	ds_read_b128 v[210:213], v179 offset:1024
	ds_read_b128 v[214:217], v179 offset:2048
	ds_read_b128 v[218:221], v179 offset:3072
	global_load_lds_dwordx4 v[150:151], off
	v_lshl_add_u64 v[222:223], s[22:23], 0, v[134:135]
	s_add_i32 m0, s46, 0x2000
	s_nop 0
	global_load_lds_dwordx4 v[222:223], off
	s_barrier
; #define PG8_STAGE(bufoff, gbase, voff) do { _Pragma("unroll") for (int _i = 0; _i < 2; ++_i) \
;         __builtin_amdgcn_global_load_lds((const unsigned*)((const char*)(gbase) + (voff)[_i]), (LAS unsigned*)(lds + (bufoff) + ldsw + _i * 8192), 16, 0, 0); } while (0)
; #define PG8_LDA(dst, b, h) do { _Pragma("unroll") for (int m = 0; m < 4; ++m) _Pragma("unroll") for (int k = 0; k < 2; ++k) dst[m][k] = *(const LAS bf16x8*)(lds + PG8_SA(b, h) + aoff + m * 2048 + k * 1024); } while (0)
; #define PG8_LDB(dst, b, h) do { _Pragma("unroll") for (int n = 0; n < 2; ++n) _Pragma("unroll") for (int k = 0; k < 2; ++k) dst[n][k] = *(const LAS bf16x8*)(lds + PG8_SB(b, h) + boff + n * 2048 + k * 1024); } while (0)
; #define PG8_MMA(ai, bj, At, Bt) do { __builtin_amdgcn_s_setprio(1); _Pragma("unroll") for (int m = 0; m < 4; ++m) _Pragma("unroll") for (int n = 0; n < 2; ++n) _Pragma("unroll") for (int k = 0; k < 2; ++k) \
;         acc[ai][bj][m][n] = __builtin_amdgcn_mfma_f32_16x16x32_bf16(Bt[n][k], At[m][k], acc[ai][bj][m][n], 0, 0, 0); __builtin_amdgcn_s_setprio(0); } while (0)
; #define PG8_WAIT_V(n) asm volatile("s_waitcnt vmcnt(" #n ")" ::: "memory")
; #define PG8_WAIT_L(n) asm volatile("s_waitcnt lgkmcnt(" #n ")" ::: "memory")
; #define PG8_BAR __builtin_amdgcn_s_barrier()
; #define PG8_SCHED __builtin_amdgcn_sched_barrier(0)
; template <class Epi>
; __device__ __forceinline__ void gemm_phase(LAS unsigned char* lds, const Gemm g, const StaticOrder& S, const Epi& E) {
;     ...
;             PG8_BAR; PG8_WAIT_L(0); PG8_MMA(0, 1, At, B1); PG8_BAR;
;             PG8_LDA(At, 0, 1); PG8_STAGE(PG8_SA(0, 0), a2, voffA);
;             PG8_BAR; PG8_WAIT_L(0); PG8_MMA(1, 0, At, B0); PG8_BAR; PG8_SCHED;
;             PG8_STAGE(PG8_SB(0, 1), b2 + hstepB, voffB);
;             PG8_WAIT_V(6); PG8_BAR; PG8_MMA(1, 1, At, B1); PG8_BAR;
;             PG8_LDB(B0, 1, 0); PG8_SCHED; PG8_LDA(At, 1, 0); PG8_STAGE(PG8_SA(0, 1), a2 + hstepA, voffA);
;             PG8_WAIT_L(8); PG8_BAR; PG8_WAIT_L(0); PG8_MMA(0, 0, At, B0); PG8_BAR; PG8_SCHED;
;             PG8_LDB(B1, 1, 1); PG8_STAGE(PG8_SB(1, 0), b3, voffB);
;             PG8_BAR; PG8_WAIT_L(0); PG8_MMA(0, 1, At, B1); PG8_BAR;
	s_waitcnt lgkmcnt(3)
	v_mfma_f32_16x16x32_bf16 v[116:119], v[206:209], v[166:169], v[116:119]
	s_waitcnt lgkmcnt(1)
	v_mfma_f32_16x16x32_bf16 v[112:115], v[214:217], v[166:169], v[112:115]
	v_mfma_f32_16x16x32_bf16 v[100:103], v[206:209], v[182:185], v[100:103]
	v_mfma_f32_16x16x32_bf16 v[96:99], v[214:217], v[182:185], v[96:99]
	v_mfma_f32_16x16x32_bf16 v[84:87], v[206:209], v[190:193], v[84:87]
	v_mfma_f32_16x16x32_bf16 v[80:83], v[214:217], v[190:193], v[80:83]
	v_mfma_f32_16x16x32_bf16 v[68:71], v[206:209], v[198:201], v[68:71]
	v_mfma_f32_16x16x32_bf16 v[64:67], v[214:217], v[198:201], v[64:67]
	v_mfma_f32_16x16x32_bf16 v[116:119], v[210:213], v[170:173], v[116:119]
	s_waitcnt lgkmcnt(0)
	v_mfma_f32_16x16x32_bf16 v[112:115], v[218:221], v[170:173], v[112:115]
	v_mfma_f32_16x16x32_bf16 v[100:103], v[210:213], v[186:189], v[100:103]
	v_mfma_f32_16x16x32_bf16 v[96:99], v[218:221], v[186:189], v[96:99]
	v_mfma_f32_16x16x32_bf16 v[84:87], v[210:213], v[194:197], v[84:87]
	v_mfma_f32_16x16x32_bf16 v[80:83], v[218:221], v[194:197], v[80:83]
	v_mfma_f32_16x16x32_bf16 v[68:71], v[210:213], v[202:205], v[68:71]
	v_mfma_f32_16x16x32_bf16 v[64:67], v[218:221], v[202:205], v[64:67]
	s_mov_b32 m0, s19
	v_lshl_add_u64 v[224:225], s[24:25], 0, v[128:129]
	s_barrier
	ds_read_b128 v[166:169], v178 offset:16384
	ds_read_b128 v[170:173], v178 offset:17408
	ds_read_b128 v[182:185], v178 offset:18432
	ds_read_b128 v[186:189], v178 offset:19456
	ds_read_b128 v[190:193], v178 offset:20480
	ds_read_b128 v[194:197], v178 offset:21504
	ds_read_b128 v[198:201], v178 offset:22528
	ds_read_b128 v[202:205], v178 offset:23552
	global_load_lds_dwordx4 v[224:225], off
	v_lshl_add_u64 v[226:227], s[24:25], 0, v[132:133]
	s_mov_b32 m0, s30
	s_nop 0
	global_load_lds_dwordx4 v[226:227], off
	s_barrier
	s_waitcnt lgkmcnt(7)
	v_mfma_f32_16x16x32_bf16 v[60:63], v[146:149], v[166:169], v[60:63]
	v_mfma_f32_16x16x32_bf16 v[56:59], v[158:161], v[166:169], v[56:59]
	s_waitcnt lgkmcnt(5)
	v_mfma_f32_16x16x32_bf16 v[44:47], v[146:149], v[182:185], v[44:47]
	v_mfma_f32_16x16x32_bf16 v[40:43], v[158:161], v[182:185], v[40:43]
	s_waitcnt lgkmcnt(3)
	v_mfma_f32_16x16x32_bf16 v[28:31], v[146:149], v[190:193], v[28:31]
	v_mfma_f32_16x16x32_bf16 v[24:27], v[158:161], v[190:193], v[24:27]
	s_waitcnt lgkmcnt(1)
	v_mfma_f32_16x16x32_bf16 v[12:15], v[146:149], v[198:201], v[12:15]
	v_mfma_f32_16x16x32_bf16 v[8:11], v[158:161], v[198:201], v[8:11]
	v_mfma_f32_16x16x32_bf16 v[60:63], v[154:157], v[170:173], v[60:63]
	v_mfma_f32_16x16x32_bf16 v[56:59], v[162:165], v[170:173], v[56:59]
	v_mfma_f32_16x16x32_bf16 v[44:47], v[154:157], v[186:189], v[44:47]
	v_mfma_f32_16x16x32_bf16 v[40:43], v[162:165], v[186:189], v[40:43]
	v_mfma_f32_16x16x32_bf16 v[28:31], v[154:157], v[194:197], v[28:31]
	v_mfma_f32_16x16x32_bf16 v[24:27], v[162:165], v[194:197], v[24:27]
	s_waitcnt lgkmcnt(0)
	v_mfma_f32_16x16x32_bf16 v[12:15], v[154:157], v[202:205], v[12:15]
	v_mfma_f32_16x16x32_bf16 v[8:11], v[162:165], v[202:205], v[8:11]
	s_barrier
	s_add_u32 s46, s22, 0x40000
	s_addc_u32 s47, s23, 0
	s_add_i32 s48, s38, s29
	v_lshl_add_u64 v[146:147], s[46:47], 0, v[130:131]
	s_mov_b32 m0, s48
	s_nop 0
	global_load_lds_dwordx4 v[146:147], off
	v_lshl_add_u64 v[146:147], s[46:47], 0, v[134:135]
	s_add_i32 m0, s48, 0x2000
	s_nop 0
	global_load_lds_dwordx4 v[146:147], off
	s_waitcnt vmcnt(6)
	s_barrier
	v_mfma_f32_16x16x32_bf16 v[52:55], v[206:209], v[166:169], v[52:55]
	v_mfma_f32_16x16x32_bf16 v[48:51], v[214:217], v[166:169], v[48:51]
	v_mfma_f32_16x16x32_bf16 v[36:39], v[206:209], v[182:185], v[36:39]
	v_mfma_f32_16x16x32_bf16 v[32:35], v[214:217], v[182:185], v[32:35]
	v_mfma_f32_16x16x32_bf16 v[20:23], v[206:209], v[190:193], v[20:23]
	v_mfma_f32_16x16x32_bf16 v[16:19], v[214:217], v[190:193], v[16:19]
	v_mfma_f32_16x16x32_bf16 v[4:7], v[206:209], v[198:201], v[4:7]
	v_mfma_f32_16x16x32_bf16 v[0:3], v[214:217], v[198:201], v[0:3]
	v_mfma_f32_16x16x32_bf16 v[52:55], v[210:213], v[170:173], v[52:55]
	v_mfma_f32_16x16x32_bf16 v[48:51], v[218:221], v[170:173], v[48:51]
	v_mfma_f32_16x16x32_bf16 v[36:39], v[210:213], v[186:189], v[36:39]
	v_mfma_f32_16x16x32_bf16 v[32:35], v[218:221], v[186:189], v[32:35]
	v_mfma_f32_16x16x32_bf16 v[20:23], v[210:213], v[194:197], v[20:23]
	v_mfma_f32_16x16x32_bf16 v[16:19], v[218:221], v[194:197], v[16:19]
	v_mfma_f32_16x16x32_bf16 v[4:7], v[210:213], v[202:205], v[4:7]
	v_mfma_f32_16x16x32_bf16 v[0:3], v[218:221], v[202:205], v[0:3]
	s_add_i32 s46, 0, 0x18000
	v_add_u32_e32 v162, s46, v175
	s_barrier
	ds_read_b128 v[146:149], v162
	ds_read_b128 v[154:157], v162 offset:1024
	ds_read_b128 v[158:161], v162 offset:2048
	ds_read_b128 v[162:165], v162 offset:3072
	s_add_u32 s24, s24, 0x40000
	s_addc_u32 s25, s25, 0
	s_mov_b32 m0, s31
	v_lshl_add_u64 v[206:207], s[24:25], 0, v[128:129]
	ds_read_b128 v[166:169], v178 offset:32768
	ds_read_b128 v[170:173], v178 offset:33792
	ds_read_b128 v[182:185], v178 offset:34816
	ds_read_b128 v[186:189], v178 offset:35840
	ds_read_b128 v[190:193], v178 offset:36864
	ds_read_b128 v[194:197], v178 offset:37888
	ds_read_b128 v[198:201], v178 offset:38912
	ds_read_b128 v[202:205], v178 offset:39936
	global_load_lds_dwordx4 v[206:207], off
	v_lshl_add_u64 v[206:207], s[24:25], 0, v[132:133]
	s_mov_b32 m0, s33
	s_nop 0
	global_load_lds_dwordx4 v[206:207], off
	s_waitcnt lgkmcnt(8)
	s_barrier
; #define PG8_STAGE(bufoff, gbase, voff) do { _Pragma("unroll") for (int _i = 0; _i < 2; ++_i) \
;         __builtin_amdgcn_global_load_lds((const unsigned*)((const char*)(gbase) + (voff)[_i]), (LAS unsigned*)(lds + (bufoff) + ldsw + _i * 8192), 16, 0, 0); } while (0)
; #define PG8_LDA(dst, b, h) do { _Pragma("unroll") for (int m = 0; m < 4; ++m) _Pragma("unroll") for (int k = 0; k < 2; ++k) dst[m][k] = *(const LAS bf16x8*)(lds + PG8_SA(b, h) + aoff + m * 2048 + k * 1024); } while (0)
; #define PG8_MMA(ai, bj, At, Bt) do { __builtin_amdgcn_s_setprio(1); _Pragma("unroll") for (int m = 0; m < 4; ++m) _Pragma("unroll") for (int n = 0; n < 2; ++n) _Pragma("unroll") for (int k = 0; k < 2; ++k) \
;         acc[ai][bj][m][n] = __builtin_amdgcn_mfma_f32_16x16x32_bf16(Bt[n][k], At[m][k], acc[ai][bj][m][n], 0, 0, 0); __builtin_amdgcn_s_setprio(0); } while (0)
; #define PG8_WAIT_V(n) asm volatile("s_waitcnt vmcnt(" #n ")" ::: "memory")
; #define PG8_WAIT_L(n) asm volatile("s_waitcnt lgkmcnt(" #n ")" ::: "memory")
; #define PG8_BAR __builtin_amdgcn_s_barrier()
; #define PG8_SCHED __builtin_amdgcn_sched_barrier(0)
; template <class Epi>
; __device__ __forceinline__ void gemm_phase(LAS unsigned char* lds, const Gemm g, const StaticOrder& S, const Epi& E) {
;     ...
;             PG8_BAR; PG8_WAIT_L(0); PG8_MMA(0, 1, At, B1); PG8_BAR;
;             PG8_LDA(At, 1, 1); PG8_STAGE(PG8_SA(1, 0), a3, voffA);
;             PG8_BAR; PG8_WAIT_L(0); PG8_MMA(1, 0, At, B0); PG8_BAR; PG8_SCHED;
;             PG8_STAGE(PG8_SB(1, 1), b3 + hstepB, voffB);
;             PG8_WAIT_V(6); PG8_BAR; PG8_MMA(1, 1, At, B1); PG8_BAR;
	s_waitcnt lgkmcnt(7)
	v_mfma_f32_16x16x32_bf16 v[124:127], v[146:149], v[166:169], v[124:127]
	v_mfma_f32_16x16x32_bf16 v[120:123], v[158:161], v[166:169], v[120:123]
	s_waitcnt lgkmcnt(5)
	v_mfma_f32_16x16x32_bf16 v[108:111], v[146:149], v[182:185], v[108:111]
	v_mfma_f32_16x16x32_bf16 v[104:107], v[158:161], v[182:185], v[104:107]
	s_waitcnt lgkmcnt(3)
	v_mfma_f32_16x16x32_bf16 v[92:95], v[146:149], v[190:193], v[92:95]
	v_mfma_f32_16x16x32_bf16 v[88:91], v[158:161], v[190:193], v[88:91]
	s_waitcnt lgkmcnt(1)
	v_mfma_f32_16x16x32_bf16 v[76:79], v[146:149], v[198:201], v[76:79]
	v_mfma_f32_16x16x32_bf16 v[72:75], v[158:161], v[198:201], v[72:75]
	v_mfma_f32_16x16x32_bf16 v[124:127], v[154:157], v[170:173], v[124:127]
	v_mfma_f32_16x16x32_bf16 v[120:123], v[162:165], v[170:173], v[120:123]
	v_mfma_f32_16x16x32_bf16 v[108:111], v[154:157], v[186:189], v[108:111]
	v_mfma_f32_16x16x32_bf16 v[104:107], v[162:165], v[186:189], v[104:107]
	v_mfma_f32_16x16x32_bf16 v[92:95], v[154:157], v[194:197], v[92:95]
	v_mfma_f32_16x16x32_bf16 v[88:91], v[162:165], v[194:197], v[88:91]
	s_waitcnt lgkmcnt(0)
	v_mfma_f32_16x16x32_bf16 v[76:79], v[154:157], v[202:205], v[76:79]
	v_mfma_f32_16x16x32_bf16 v[72:75], v[162:165], v[202:205], v[72:75]
	s_barrier
	s_add_i32 s24, 0, 0x1c000
	s_add_i32 s25, s46, s29
	v_add_u32_e32 v181, s24, v175
	v_lshl_add_u64 v[150:151], v[150:151], 0, s[4:5]
	s_mov_b32 m0, s25
	ds_read_b128 v[206:209], v181
	ds_read_b128 v[210:213], v181 offset:1024
	ds_read_b128 v[214:217], v181 offset:2048
	ds_read_b128 v[218:221], v181 offset:3072
	global_load_lds_dwordx4 v[150:151], off
	v_lshl_add_u64 v[150:151], v[222:223], 0, s[4:5]
	s_add_i32 m0, s25, 0x2000
	s_nop 0
	global_load_lds_dwordx4 v[150:151], off
	s_barrier
	s_waitcnt lgkmcnt(3)
	v_mfma_f32_16x16x32_bf16 v[116:119], v[206:209], v[166:169], v[116:119]
	s_waitcnt lgkmcnt(1)
	v_mfma_f32_16x16x32_bf16 v[112:115], v[214:217], v[166:169], v[112:115]
	v_mfma_f32_16x16x32_bf16 v[100:103], v[206:209], v[182:185], v[100:103]
	v_mfma_f32_16x16x32_bf16 v[96:99], v[214:217], v[182:185], v[96:99]
	v_mfma_f32_16x16x32_bf16 v[84:87], v[206:209], v[190:193], v[84:87]
	v_mfma_f32_16x16x32_bf16 v[80:83], v[214:217], v[190:193], v[80:83]
	v_mfma_f32_16x16x32_bf16 v[68:71], v[206:209], v[198:201], v[68:71]
	v_mfma_f32_16x16x32_bf16 v[64:67], v[214:217], v[198:201], v[64:67]
	v_mfma_f32_16x16x32_bf16 v[116:119], v[210:213], v[170:173], v[116:119]
	s_waitcnt lgkmcnt(0)
	v_mfma_f32_16x16x32_bf16 v[112:115], v[218:221], v[170:173], v[112:115]
	v_mfma_f32_16x16x32_bf16 v[100:103], v[210:213], v[186:189], v[100:103]
	v_mfma_f32_16x16x32_bf16 v[96:99], v[218:221], v[186:189], v[96:99]
	v_mfma_f32_16x16x32_bf16 v[84:87], v[210:213], v[194:197], v[84:87]
	v_mfma_f32_16x16x32_bf16 v[80:83], v[218:221], v[194:197], v[80:83]
	v_mfma_f32_16x16x32_bf16 v[68:71], v[210:213], v[202:205], v[68:71]
	v_mfma_f32_16x16x32_bf16 v[64:67], v[218:221], v[202:205], v[64:67]
	s_mov_b32 m0, s35
	v_lshl_add_u64 v[150:151], v[224:225], 0, s[4:5]
	s_barrier
	ds_read_b128 v[166:169], v178 offset:49152
	ds_read_b128 v[170:173], v178 offset:50176
	ds_read_b128 v[182:185], v178 offset:51200
	ds_read_b128 v[186:189], v178 offset:52224
	ds_read_b128 v[190:193], v178 offset:53248
	ds_read_b128 v[194:197], v178 offset:54272
	ds_read_b128 v[198:201], v178 offset:55296
	ds_read_b128 v[202:205], v178 offset:56320
	global_load_lds_dwordx4 v[150:151], off
	v_lshl_add_u64 v[150:151], v[226:227], 0, s[4:5]
	s_mov_b32 m0, s36
	s_nop 0
	global_load_lds_dwordx4 v[150:151], off
	s_barrier
	s_waitcnt lgkmcnt(7)
	v_mfma_f32_16x16x32_bf16 v[60:63], v[146:149], v[166:169], v[60:63]
	v_mfma_f32_16x16x32_bf16 v[56:59], v[158:161], v[166:169], v[56:59]
	s_waitcnt lgkmcnt(5)
	v_mfma_f32_16x16x32_bf16 v[44:47], v[146:149], v[182:185], v[44:47]
	v_mfma_f32_16x16x32_bf16 v[40:43], v[158:161], v[182:185], v[40:43]
	s_waitcnt lgkmcnt(3)
	v_mfma_f32_16x16x32_bf16 v[28:31], v[146:149], v[190:193], v[28:31]
	v_mfma_f32_16x16x32_bf16 v[24:27], v[158:161], v[190:193], v[24:27]
	s_waitcnt lgkmcnt(1)
	v_mfma_f32_16x16x32_bf16 v[12:15], v[146:149], v[198:201], v[12:15]
	v_mfma_f32_16x16x32_bf16 v[8:11], v[158:161], v[198:201], v[8:11]
	v_mfma_f32_16x16x32_bf16 v[60:63], v[154:157], v[170:173], v[60:63]
	v_mfma_f32_16x16x32_bf16 v[56:59], v[162:165], v[170:173], v[56:59]
	v_mfma_f32_16x16x32_bf16 v[44:47], v[154:157], v[186:189], v[44:47]
	v_mfma_f32_16x16x32_bf16 v[40:43], v[162:165], v[186:189], v[40:43]
	v_mfma_f32_16x16x32_bf16 v[28:31], v[154:157], v[194:197], v[28:31]
	v_mfma_f32_16x16x32_bf16 v[24:27], v[162:165], v[194:197], v[24:27]
	s_waitcnt lgkmcnt(0)
	v_mfma_f32_16x16x32_bf16 v[12:15], v[154:157], v[202:205], v[12:15]
	v_mfma_f32_16x16x32_bf16 v[8:11], v[162:165], v[202:205], v[8:11]
	s_barrier
	s_add_u32 s22, s22, 0x40080
	s_addc_u32 s23, s23, 0
	s_add_i32 s24, s24, s29
	v_lshl_add_u64 v[146:147], s[22:23], 0, v[130:131]
	s_mov_b32 m0, s24
	s_nop 0
	global_load_lds_dwordx4 v[146:147], off
	v_lshl_add_u64 v[146:147], s[22:23], 0, v[134:135]
	s_add_i32 m0, s24, 0x2000
	s_nop 0
	global_load_lds_dwordx4 v[146:147], off
	s_waitcnt vmcnt(6)
	s_barrier
; #define PG8_WAIT_V(n) asm volatile("s_waitcnt vmcnt(" #n ")" ::: "memory")
; #define PG8_BAR __builtin_amdgcn_s_barrier()
;     __device__ __forceinline__ void operator()(const f32x4 (&acc)[2][2][4][2], const Unit& u, int wr, int wc, int fr, int fq, const float (&)[8]) const {
;         const int row0 = u.pm * BM + wr * 64 + fr;
;         float ep[8];
; #pragma unroll
;         for (int ai = 0; ai < 2; ++ai)
; #pragma unroll
;             for (int m = 0; m < 4; ++m) { const int row = row0 + ai * HALF + m * 16;
;                 if (SLOTS == 1) ep[ai * 4 + m] = ss[row];
;                 else { const f32x4 pq = *(const f32x4*)(ss + (size_t)row * 16 + 4 * fq); ep[ai * 4 + m] = (pq[0] + pq[1]) + (pq[2] + pq[3]); } }
;         if (SLOTS != 1) {
; #pragma unroll
;             for (int q = 0; q < 8; ++q) { ep[q] += __shfl_xor(ep[q], 16); ep[q] += __shfl_xor(ep[q], 32); } }
;         if (DT && u.pn == 20) {
;             if (wc == 0) {
; #pragma unroll
;                 for (int ai = 0; ai < 2; ++ai)
; #pragma unroll
;                     for (int m = 0; m < 4; ++m) { const int row = row0 + ai * HALF + m * 16; const float rs = rsqrtf(ep[ai * 4 + m] * (1.0f / 1024.0f) + EPS);
;                         *(f32x4*)(dt + (size_t)row * 32 + 8 * fq) = acc[ai][0][m][0] * rs; *(f32x4*)(dt + (size_t)row * 32 + 8 * fq + 4) = acc[ai][0][m][1] * rs; }
;             }
;             return;
;         }
;         const int col0 = u.pn * BM + wc * 32 + 8 * fq;
; #pragma unroll
;         for (int ai = 0; ai < 2; ++ai)
; #pragma unroll
; template <class Epi>
; __device__ __forceinline__ void gemm_phase(LAS unsigned char* lds, const Gemm g, const StaticOrder& S, const Epi& E) {
;     ...
;             PG8_WAIT_V(6); PG8_BAR; PG8_MMA(1, 1, At, B1); PG8_BAR;
;             PG8_LDB(B0, 1, 0); PG8_SCHED; PG8_LDA(At, 1, 0); PG8_STAGE(PG8_SA(0, 1), a2 + hstepA, voffA);
;             PG8_WAIT_L(8); PG8_BAR; PG8_WAIT_L(0); PG8_MMA(0, 0, At, B0); PG8_BAR; PG8_SCHED;
;             PG8_LDB(B1, 1, 1); PG8_STAGE(PG8_SB(1, 0), b3, voffB);
;             PG8_BAR; PG8_WAIT_L(0); PG8_MMA(0, 1, At, B1); PG8_BAR;
;             PG8_LDA(At, 1, 1); PG8_STAGE(PG8_SA(1, 0), a3, voffA);
;             PG8_BAR; PG8_WAIT_L(0); PG8_MMA(1, 0, At, B0); PG8_BAR; PG8_SCHED;
;             PG8_STAGE(PG8_SB(1, 1), b3 + hstepB, voffB);
;             PG8_WAIT_V(6); PG8_BAR; PG8_MMA(1, 1, At, B1); PG8_BAR;
;         }
	v_mfma_f32_16x16x32_bf16 v[52:55], v[206:209], v[166:169], v[52:55]
	v_mfma_f32_16x16x32_bf16 v[48:51], v[214:217], v[166:169], v[48:51]
	v_mfma_f32_16x16x32_bf16 v[36:39], v[206:209], v[182:185], v[36:39]
	v_mfma_f32_16x16x32_bf16 v[32:35], v[214:217], v[182:185], v[32:35]
	v_mfma_f32_16x16x32_bf16 v[20:23], v[206:209], v[190:193], v[20:23]
	v_mfma_f32_16x16x32_bf16 v[16:19], v[214:217], v[190:193], v[16:19]
	v_mfma_f32_16x16x32_bf16 v[4:7], v[206:209], v[198:201], v[4:7]
	v_mfma_f32_16x16x32_bf16 v[0:3], v[214:217], v[198:201], v[0:3]
	v_mfma_f32_16x16x32_bf16 v[52:55], v[210:213], v[170:173], v[52:55]
	v_mfma_f32_16x16x32_bf16 v[48:51], v[218:221], v[170:173], v[48:51]
	v_mfma_f32_16x16x32_bf16 v[36:39], v[210:213], v[186:189], v[36:39]
	v_mfma_f32_16x16x32_bf16 v[32:35], v[218:221], v[186:189], v[32:35]
	v_mfma_f32_16x16x32_bf16 v[20:23], v[210:213], v[194:197], v[20:23]
	v_mfma_f32_16x16x32_bf16 v[16:19], v[218:221], v[194:197], v[16:19]
	v_mfma_f32_16x16x32_bf16 v[4:7], v[210:213], v[202:205], v[4:7]
	v_mfma_f32_16x16x32_bf16 v[0:3], v[218:221], v[202:205], v[0:3]
	s_add_i32 s45, s45, 2
	s_add_u32 s20, s20, 0x100
	s_addc_u32 s21, s21, 0
	s_add_u32 s43, s43, 0x100
	s_addc_u32 s44, s44, 0
	s_cmp_gt_u32 s45, 13
	s_barrier
	s_cbranch_scc0 .LBB0_770
	s_bfe_u32 vcc_lo, s18, 0x20003
	s_lshl_b32 vcc_lo, vcc_lo, 10
	s_add_i32 vcc_lo, vcc_lo, 0x20010
	v_lshl_add_u32 v236, v174, 2, vcc_lo
	ds_read_b32 v228, v236
	ds_read_b32 v229, v236 offset:64
	ds_read_b32 v230, v236 offset:128
	ds_read_b32 v231, v236 offset:192
	ds_read_b32 v232, v236 offset:512
	ds_read_b32 v233, v236 offset:576
	ds_read_b32 v234, v236 offset:640
	ds_read_b32 v235, v236 offset:704
	s_waitcnt lgkmcnt(0)
	v_lshl_add_u32 v148, s18, 8, v174
	v_ashrrev_i32_e32 v149, 31, v148
	v_or_b32_e32 v172, 16, v148
	v_ashrrev_i32_e32 v173, 31, v172
	v_or_b32_e32 v168, 32, v148
	v_or_b32_e32 v164, 48, v148
	v_ashrrev_i32_e32 v169, 31, v168
	v_ashrrev_i32_e32 v165, 31, v164
	v_add_u32_e32 v162, 0x80, v148
	v_add_u32_e32 v156, 0x90, v148
	v_ashrrev_i32_e32 v163, 31, v162
	v_ashrrev_i32_e32 v157, 31, v156
	v_add_u32_e32 v150, 0xa0, v148
	v_ashrrev_i32_e32 v151, 31, v150
	v_add_u32_e32 v146, 0xb0, v148
	v_ashrrev_i32_e32 v147, 31, v146
	v_lshl_or_b32 v166, s40, 8, v176
	v_ashrrev_i32_e32 v167, 31, v166
	v_lshlrev_b64 v[170:171], 13, v[148:149]
	v_lshlrev_b64 v[148:149], 1, v[166:167]
	v_lshl_add_u64 v[166:167], s[96:97], 0, v[170:171]
	v_lshl_add_u64 v[212:213], v[166:167], 0, v[148:149]
	s_mov_b32 s40, s10
	s_mov_b32 s18, s12
	s_mov_b64 s[22:23], s[16:17]
	s_mov_b64 s[20:21], s[14:15]
	s_waitcnt vmcnt(8)
	s_waitcnt lgkmcnt(0)
	s_waitcnt lgkmcnt(0)
	v_mov_b32_e32 v184, v228
	v_pk_mul_f32 v[120:121], v[120:121], v[184:185] op_sel_hi:[1,0]
	v_pk_mul_f32 v[126:127], v[126:127], v[184:185] op_sel_hi:[1,0]
	v_pk_mul_f32 v[124:125], v[124:125], v[184:185] op_sel_hi:[1,0]
	v_pk_mul_f32 v[122:123], v[122:123], v[184:185] op_sel_hi:[1,0]
	v_max_f32_e32 v120, 0, v120
	v_max_f32_e32 v121, 0, v121
	v_max_f32_e32 v124, 0, v124
	v_max_f32_e32 v125, 0, v125
	v_pk_mul_f32 v[190:191], v[120:121], v[120:121]
	v_max_f32_e32 v120, 0, v126
	v_max_f32_e32 v122, 0, v122
	v_max_f32_e32 v121, 0, v127
	v_max_f32_e32 v123, 0, v123
	v_pk_mul_f32 v[124:125], v[124:125], v[124:125]
	v_pk_mul_f32 v[126:127], v[120:121], v[120:121]
	v_pk_mul_f32 v[194:195], v[122:123], v[122:123]
	v_pk_mul_f32 v[114:115], v[114:115], v[184:185] op_sel_hi:[1,0]
	v_cvt_pk_bf16_f32 v120, v124, v125
	v_cvt_pk_bf16_f32 v121, v126, v127
	v_cvt_pk_bf16_f32 v122, v190, v191
	v_cvt_pk_bf16_f32 v123, v194, v195
	v_pk_mul_f32 v[116:117], v[116:117], v[184:185] op_sel_hi:[1,0]
	v_pk_mul_f32 v[112:113], v[112:113], v[184:185] op_sel_hi:[1,0]
	v_max_f32_e32 v114, 0, v114
	v_max_f32_e32 v115, 0, v115
	global_store_dwordx4 v[212:213], v[120:123], off
	v_pk_mul_f32 v[118:119], v[118:119], v[184:185] op_sel_hi:[1,0]
	v_max_f32_e32 v116, 0, v116
	v_max_f32_e32 v112, 0, v112
	v_max_f32_e32 v117, 0, v117
	v_max_f32_e32 v113, 0, v113
	v_pk_mul_f32 v[122:123], v[114:115], v[114:115]
	v_pk_mul_f32 v[116:117], v[116:117], v[116:117]
	v_pk_mul_f32 v[120:121], v[112:113], v[112:113]
	v_max_f32_e32 v112, 0, v118
	v_max_f32_e32 v113, 0, v119
	v_pk_mul_f32 v[118:119], v[112:113], v[112:113]
	v_cvt_pk_bf16_f32 v112, v116, v117
	v_cvt_pk_bf16_f32 v113, v118, v119
	v_cvt_pk_bf16_f32 v114, v120, v121
	v_cvt_pk_bf16_f32 v115, v122, v123
	global_store_dwordx4 v[212:213], v[112:115], off offset:256
	s_nop 1
	v_mov_b32_e32 v112, v229
	v_pk_mul_f32 v[104:105], v[104:105], v[112:113] op_sel_hi:[1,0]
	v_pk_mul_f32 v[110:111], v[110:111], v[112:113] op_sel_hi:[1,0]
	v_pk_mul_f32 v[108:109], v[108:109], v[112:113] op_sel_hi:[1,0]
	v_pk_mul_f32 v[106:107], v[106:107], v[112:113] op_sel_hi:[1,0]
	v_max_f32_e32 v104, 0, v104
	v_max_f32_e32 v105, 0, v105
	v_lshlrev_b64 v[114:115], 13, v[172:173]
	v_max_f32_e32 v108, 0, v108
	v_max_f32_e32 v109, 0, v109
	v_pk_mul_f32 v[116:117], v[104:105], v[104:105]
	v_max_f32_e32 v104, 0, v110
	v_max_f32_e32 v106, 0, v106
	v_max_f32_e32 v105, 0, v111
	v_max_f32_e32 v107, 0, v107
	v_lshl_add_u64 v[114:115], s[96:97], 0, v[114:115]
	v_pk_mul_f32 v[108:109], v[108:109], v[108:109]
	v_pk_mul_f32 v[110:111], v[104:105], v[104:105]
	v_pk_mul_f32 v[118:119], v[106:107], v[106:107]
	v_pk_mul_f32 v[96:97], v[96:97], v[112:113] op_sel_hi:[1,0]
	v_lshl_add_u64 v[114:115], v[114:115], 0, v[148:149]
	v_cvt_pk_bf16_f32 v104, v108, v109
	v_cvt_pk_bf16_f32 v105, v110, v111
	v_cvt_pk_bf16_f32 v106, v116, v117
	v_cvt_pk_bf16_f32 v107, v118, v119
	v_pk_mul_f32 v[102:103], v[102:103], v[112:113] op_sel_hi:[1,0]
	v_max_f32_e32 v96, 0, v96
	v_max_f32_e32 v97, 0, v97
	global_store_dwordx4 v[114:115], v[104:107], off
	v_pk_mul_f32 v[100:101], v[100:101], v[112:113] op_sel_hi:[1,0]
	v_pk_mul_f32 v[98:99], v[98:99], v[112:113] op_sel_hi:[1,0]
	v_pk_mul_f32 v[104:105], v[96:97], v[96:97]
	v_max_f32_e32 v96, 0, v102
	v_max_f32_e32 v97, 0, v103
	v_max_f32_e32 v100, 0, v100
	v_max_f32_e32 v101, 0, v101
	v_pk_mul_f32 v[100:101], v[100:101], v[100:101]
	v_pk_mul_f32 v[108:109], v[96:97], v[96:97]
	v_cvt_pk_bf16_f32 v96, v100, v101
	s_waitcnt lgkmcnt(0)
; __device__ __forceinline__ unsigned pk2(float lo, float hi) { const f32x2 v = (f32x2){lo, hi}; const bf16x2_t b = __builtin_convertvector(v, bf16x2_t); return __builtin_bit_cast(unsigned, b); }
;     __device__ __forceinline__ void operator()(const f32x4 (&acc)[2][2][4][2], const Unit& u, int wr, int wc, int fr, int fq, const float (&)[8]) const {
;     ...
;             for (int m = 0; m < 4; ++m) { const int row = row0 + ai * HALF + m * 16; const float rs = rsqrtf(ep[ai * 4 + m] * (1.0f / 1024.0f) + EPS);
;                 u16* rowp = O + (size_t)row * ldc + col0;
; #pragma unroll
;                 for (int bj = 0; bj < 2; ++bj) { f32x4 v0 = acc[ai][bj][m][0] * rs, v1 = acc[ai][bj][m][1] * rs;
;                     if (ACT == 1) {
; #pragma unroll
;                         for (int j = 0; j < 4; ++j) { const float a0 = fmaxf(v0[j], 0.f), a1 = fmaxf(v1[j], 0.f); v0[j] = a0 * a0; v1[j] = a1 * a1; } }
;                     u32x4 w; w.x = pk2(v0[0], v0[1]); w.y = pk2(v0[2], v0[3]); w.z = pk2(v1[0], v1[1]); w.w = pk2(v1[2], v1[3]);
;                     *(u32x4*)(rowp + bj * HALF) = w; } }
	v_max_f32_e32 v98, 0, v98
	v_max_f32_e32 v99, 0, v99
	v_pk_mul_f32 v[110:111], v[98:99], v[98:99]
	v_cvt_pk_bf16_f32 v97, v108, v109
	v_cvt_pk_bf16_f32 v98, v104, v105
	v_cvt_pk_bf16_f32 v99, v110, v111
	global_store_dwordx4 v[114:115], v[96:99], off offset:256
	s_waitcnt lgkmcnt(0)
	s_nop 0
	s_nop 0
	s_nop 0
	s_nop 1
	v_lshlrev_b64 v[98:99], 13, v[168:169]
	v_lshl_add_u64 v[98:99], s[96:97], 0, v[98:99]
	v_lshl_add_u64 v[98:99], v[98:99], 0, v[148:149]
	v_mov_b32_e32 v100, v230
	v_pk_mul_f32 v[88:89], v[88:89], v[100:101] op_sel_hi:[1,0]
	v_pk_mul_f32 v[94:95], v[94:95], v[100:101] op_sel_hi:[1,0]
	v_pk_mul_f32 v[92:93], v[92:93], v[100:101] op_sel_hi:[1,0]
	v_pk_mul_f32 v[90:91], v[90:91], v[100:101] op_sel_hi:[1,0]
	v_max_f32_e32 v88, 0, v88
	v_max_f32_e32 v89, 0, v89
	v_max_f32_e32 v92, 0, v92
	v_max_f32_e32 v93, 0, v93
	v_pk_mul_f32 v[102:103], v[88:89], v[88:89]
	v_max_f32_e32 v88, 0, v94
	v_max_f32_e32 v90, 0, v90
	v_max_f32_e32 v89, 0, v95
	v_max_f32_e32 v91, 0, v91
	v_pk_mul_f32 v[92:93], v[92:93], v[92:93]
	v_pk_mul_f32 v[94:95], v[88:89], v[88:89]
	v_pk_mul_f32 v[104:105], v[90:91], v[90:91]
	v_pk_mul_f32 v[82:83], v[82:83], v[100:101] op_sel_hi:[1,0]
	v_cvt_pk_bf16_f32 v88, v92, v93
	v_cvt_pk_bf16_f32 v89, v94, v95
	v_cvt_pk_bf16_f32 v90, v102, v103
	v_cvt_pk_bf16_f32 v91, v104, v105
	v_pk_mul_f32 v[84:85], v[84:85], v[100:101] op_sel_hi:[1,0]
	v_pk_mul_f32 v[80:81], v[80:81], v[100:101] op_sel_hi:[1,0]
	v_max_f32_e32 v82, 0, v82
	v_max_f32_e32 v83, 0, v83
	global_store_dwordx4 v[98:99], v[88:91], off
	v_pk_mul_f32 v[86:87], v[86:87], v[100:101] op_sel_hi:[1,0]
	v_max_f32_e32 v84, 0, v84
	v_max_f32_e32 v80, 0, v80
	v_max_f32_e32 v85, 0, v85
	v_max_f32_e32 v81, 0, v81
	v_pk_mul_f32 v[90:91], v[82:83], v[82:83]
	v_pk_mul_f32 v[84:85], v[84:85], v[84:85]
	v_pk_mul_f32 v[88:89], v[80:81], v[80:81]
	v_max_f32_e32 v80, 0, v86
	v_max_f32_e32 v81, 0, v87
	v_pk_mul_f32 v[86:87], v[80:81], v[80:81]
	v_cvt_pk_bf16_f32 v80, v84, v85
	v_cvt_pk_bf16_f32 v81, v86, v87
	v_cvt_pk_bf16_f32 v82, v88, v89
	v_cvt_pk_bf16_f32 v83, v90, v91
	global_store_dwordx4 v[98:99], v[80:83], off offset:256
	s_nop 1
	v_mov_b32_e32 v80, v231
	v_pk_mul_f32 v[72:73], v[72:73], v[80:81] op_sel_hi:[1,0]
	v_pk_mul_f32 v[78:79], v[78:79], v[80:81] op_sel_hi:[1,0]
	v_pk_mul_f32 v[76:77], v[76:77], v[80:81] op_sel_hi:[1,0]
	v_pk_mul_f32 v[74:75], v[74:75], v[80:81] op_sel_hi:[1,0]
	v_max_f32_e32 v72, 0, v72
	v_max_f32_e32 v73, 0, v73
	v_lshlrev_b64 v[82:83], 13, v[164:165]
	v_max_f32_e32 v76, 0, v76
	v_max_f32_e32 v77, 0, v77
	v_pk_mul_f32 v[84:85], v[72:73], v[72:73]
	v_max_f32_e32 v72, 0, v78
	v_max_f32_e32 v74, 0, v74
	v_max_f32_e32 v73, 0, v79
	v_max_f32_e32 v75, 0, v75
	v_lshl_add_u64 v[82:83], s[96:97], 0, v[82:83]
	v_pk_mul_f32 v[76:77], v[76:77], v[76:77]
	v_pk_mul_f32 v[78:79], v[72:73], v[72:73]
	v_pk_mul_f32 v[86:87], v[74:75], v[74:75]
	v_pk_mul_f32 v[64:65], v[64:65], v[80:81] op_sel_hi:[1,0]
	v_lshl_add_u64 v[82:83], v[82:83], 0, v[148:149]
	v_cvt_pk_bf16_f32 v72, v76, v77
	v_cvt_pk_bf16_f32 v73, v78, v79
	v_cvt_pk_bf16_f32 v74, v84, v85
	v_cvt_pk_bf16_f32 v75, v86, v87
	v_pk_mul_f32 v[70:71], v[70:71], v[80:81] op_sel_hi:[1,0]
	v_max_f32_e32 v64, 0, v64
	v_max_f32_e32 v65, 0, v65
	global_store_dwordx4 v[82:83], v[72:75], off
	v_pk_mul_f32 v[68:69], v[68:69], v[80:81] op_sel_hi:[1,0]
	v_pk_mul_f32 v[66:67], v[66:67], v[80:81] op_sel_hi:[1,0]
	v_pk_mul_f32 v[72:73], v[64:65], v[64:65]
	v_max_f32_e32 v64, 0, v70
	v_max_f32_e32 v65, 0, v71
	v_max_f32_e32 v68, 0, v68
	v_max_f32_e32 v69, 0, v69
	v_pk_mul_f32 v[68:69], v[68:69], v[68:69]
	v_pk_mul_f32 v[76:77], v[64:65], v[64:65]
	v_cvt_pk_bf16_f32 v64, v68, v69
	s_waitcnt lgkmcnt(0)
	v_max_f32_e32 v66, 0, v66
	v_max_f32_e32 v67, 0, v67
	v_pk_mul_f32 v[78:79], v[66:67], v[66:67]
	v_cvt_pk_bf16_f32 v65, v76, v77
	v_cvt_pk_bf16_f32 v66, v72, v73
	v_cvt_pk_bf16_f32 v67, v78, v79
	global_store_dwordx4 v[82:83], v[64:67], off offset:256
	s_waitcnt lgkmcnt(0)
	s_nop 0
	s_nop 0
	s_nop 0
	s_nop 1
	v_lshlrev_b64 v[66:67], 13, v[162:163]
	v_lshl_add_u64 v[66:67], s[96:97], 0, v[66:67]
	v_lshl_add_u64 v[66:67], v[66:67], 0, v[148:149]
	v_mov_b32_e32 v68, v232
	v_pk_mul_f32 v[56:57], v[56:57], v[68:69] op_sel_hi:[1,0]
	v_pk_mul_f32 v[62:63], v[62:63], v[68:69] op_sel_hi:[1,0]
	v_pk_mul_f32 v[60:61], v[60:61], v[68:69] op_sel_hi:[1,0]
	v_pk_mul_f32 v[58:59], v[58:59], v[68:69] op_sel_hi:[1,0]
	v_max_f32_e32 v56, 0, v56
	v_max_f32_e32 v57, 0, v57
	v_max_f32_e32 v60, 0, v60
	v_max_f32_e32 v61, 0, v61
	v_pk_mul_f32 v[70:71], v[56:57], v[56:57]
	v_max_f32_e32 v56, 0, v62
	v_max_f32_e32 v58, 0, v58
	v_max_f32_e32 v57, 0, v63
	v_max_f32_e32 v59, 0, v59
	v_pk_mul_f32 v[60:61], v[60:61], v[60:61]
	v_pk_mul_f32 v[62:63], v[56:57], v[56:57]
	v_pk_mul_f32 v[72:73], v[58:59], v[58:59]
	v_pk_mul_f32 v[50:51], v[50:51], v[68:69] op_sel_hi:[1,0]
	v_cvt_pk_bf16_f32 v56, v60, v61
	v_cvt_pk_bf16_f32 v57, v62, v63
	v_cvt_pk_bf16_f32 v58, v70, v71
	v_cvt_pk_bf16_f32 v59, v72, v73
	v_pk_mul_f32 v[52:53], v[52:53], v[68:69] op_sel_hi:[1,0]
	v_pk_mul_f32 v[48:49], v[48:49], v[68:69] op_sel_hi:[1,0]
	v_max_f32_e32 v50, 0, v50
	v_max_f32_e32 v51, 0, v51
	global_store_dwordx4 v[66:67], v[56:59], off
	v_pk_mul_f32 v[54:55], v[54:55], v[68:69] op_sel_hi:[1,0]
	v_max_f32_e32 v52, 0, v52
	v_max_f32_e32 v48, 0, v48
	v_max_f32_e32 v53, 0, v53
	v_max_f32_e32 v49, 0, v49
	v_pk_mul_f32 v[58:59], v[50:51], v[50:51]
	v_pk_mul_f32 v[52:53], v[52:53], v[52:53]
	v_pk_mul_f32 v[56:57], v[48:49], v[48:49]
	v_max_f32_e32 v48, 0, v54
	v_max_f32_e32 v49, 0, v55
	v_pk_mul_f32 v[54:55], v[48:49], v[48:49]
	v_cvt_pk_bf16_f32 v48, v52, v53
; __device__ __forceinline__ unsigned pk2(float lo, float hi) { const f32x2 v = (f32x2){lo, hi}; const bf16x2_t b = __builtin_convertvector(v, bf16x2_t); return __builtin_bit_cast(unsigned, b); }
; #define PG8_WAIT_V(n) asm volatile("s_waitcnt vmcnt(" #n ")" ::: "memory")
; #define PG8_BAR __builtin_amdgcn_s_barrier()
;     __device__ __forceinline__ void operator()(const f32x4 (&acc)[2][2][4][2], const Unit& u, int wr, int wc, int fr, int fq, const float (&)[8]) const {
;     ...
;             for (int m = 0; m < 4; ++m) { const int row = row0 + ai * HALF + m * 16; const float rs = rsqrtf(ep[ai * 4 + m] * (1.0f / 1024.0f) + EPS);
;                 u16* rowp = O + (size_t)row * ldc + col0;
; #pragma unroll
;                 for (int bj = 0; bj < 2; ++bj) { f32x4 v0 = acc[ai][bj][m][0] * rs, v1 = acc[ai][bj][m][1] * rs;
;                     if (ACT == 1) {
; #pragma unroll
;                         for (int j = 0; j < 4; ++j) { const float a0 = fmaxf(v0[j], 0.f), a1 = fmaxf(v1[j], 0.f); v0[j] = a0 * a0; v1[j] = a1 * a1; } }
;                     u32x4 w; w.x = pk2(v0[0], v0[1]); w.y = pk2(v0[2], v0[3]); w.z = pk2(v1[0], v1[1]); w.w = pk2(v1[2], v1[3]);
;                     *(u32x4*)(rowp + bj * HALF) = w; } }
; template <class Epi>
; __device__ __forceinline__ void gemm_phase(LAS unsigned char* lds, const Gemm g, const StaticOrder& S, const Epi& E) {
;     ...
;         if (!has_next) break;
; #pragma unroll
;         for (int a = 0; a < 2; ++a)
; #pragma unroll
;             for (int b = 0; b < 2; ++b)
; #pragma unroll
;                 for (int m = 0; m < 4; ++m)
; #pragma unroll
;                     for (int n = 0; n < 2; ++n) acc[a][b][m][n] = (f32x4){0.f, 0.f, 0.f, 0.f};
;         cur = nxt; cA = nA; cB = nB; ++ui;
;     }
;     PG8_WAIT_V(0);
;     if (wr == 0) PG8_BAR;
;     PG8_BAR;
	v_cvt_pk_bf16_f32 v49, v54, v55
	v_cvt_pk_bf16_f32 v50, v56, v57
	v_cvt_pk_bf16_f32 v51, v58, v59
	global_store_dwordx4 v[66:67], v[48:51], off offset:256
	s_nop 1
	v_mov_b32_e32 v48, v233
	v_pk_mul_f32 v[40:41], v[40:41], v[48:49] op_sel_hi:[1,0]
	v_pk_mul_f32 v[46:47], v[46:47], v[48:49] op_sel_hi:[1,0]
	v_pk_mul_f32 v[44:45], v[44:45], v[48:49] op_sel_hi:[1,0]
	v_pk_mul_f32 v[42:43], v[42:43], v[48:49] op_sel_hi:[1,0]
	v_max_f32_e32 v40, 0, v40
	v_max_f32_e32 v41, 0, v41
	v_lshlrev_b64 v[50:51], 13, v[156:157]
	v_max_f32_e32 v44, 0, v44
	v_max_f32_e32 v45, 0, v45
	v_pk_mul_f32 v[52:53], v[40:41], v[40:41]
	v_max_f32_e32 v40, 0, v46
	v_max_f32_e32 v42, 0, v42
	v_max_f32_e32 v41, 0, v47
	v_max_f32_e32 v43, 0, v43
	v_lshl_add_u64 v[50:51], s[96:97], 0, v[50:51]
	v_pk_mul_f32 v[44:45], v[44:45], v[44:45]
	v_pk_mul_f32 v[46:47], v[40:41], v[40:41]
	v_pk_mul_f32 v[54:55], v[42:43], v[42:43]
	v_pk_mul_f32 v[32:33], v[32:33], v[48:49] op_sel_hi:[1,0]
	v_lshl_add_u64 v[50:51], v[50:51], 0, v[148:149]
	v_cvt_pk_bf16_f32 v40, v44, v45
	v_cvt_pk_bf16_f32 v41, v46, v47
	v_cvt_pk_bf16_f32 v42, v52, v53
	v_cvt_pk_bf16_f32 v43, v54, v55
	v_pk_mul_f32 v[38:39], v[38:39], v[48:49] op_sel_hi:[1,0]
	v_max_f32_e32 v32, 0, v32
	v_max_f32_e32 v33, 0, v33
	global_store_dwordx4 v[50:51], v[40:43], off
	v_pk_mul_f32 v[36:37], v[36:37], v[48:49] op_sel_hi:[1,0]
	v_pk_mul_f32 v[34:35], v[34:35], v[48:49] op_sel_hi:[1,0]
	v_pk_mul_f32 v[40:41], v[32:33], v[32:33]
	v_max_f32_e32 v32, 0, v38
	v_max_f32_e32 v33, 0, v39
	v_max_f32_e32 v36, 0, v36
	v_max_f32_e32 v37, 0, v37
	v_pk_mul_f32 v[36:37], v[36:37], v[36:37]
	v_pk_mul_f32 v[44:45], v[32:33], v[32:33]
	v_cvt_pk_bf16_f32 v32, v36, v37
	s_waitcnt lgkmcnt(0)
	v_max_f32_e32 v34, 0, v34
	v_max_f32_e32 v35, 0, v35
	v_pk_mul_f32 v[46:47], v[34:35], v[34:35]
	v_cvt_pk_bf16_f32 v33, v44, v45
	v_cvt_pk_bf16_f32 v34, v40, v41
	v_cvt_pk_bf16_f32 v35, v46, v47
	global_store_dwordx4 v[50:51], v[32:35], off offset:256
	s_waitcnt lgkmcnt(0)
	s_nop 0
	s_nop 0
	s_nop 0
	s_nop 1
	v_lshlrev_b64 v[34:35], 13, v[150:151]
	v_lshl_add_u64 v[34:35], s[96:97], 0, v[34:35]
	v_lshl_add_u64 v[34:35], v[34:35], 0, v[148:149]
	v_mov_b32_e32 v36, v234
	v_pk_mul_f32 v[24:25], v[24:25], v[36:37] op_sel_hi:[1,0]
	v_pk_mul_f32 v[30:31], v[30:31], v[36:37] op_sel_hi:[1,0]
	v_pk_mul_f32 v[28:29], v[28:29], v[36:37] op_sel_hi:[1,0]
	v_pk_mul_f32 v[26:27], v[26:27], v[36:37] op_sel_hi:[1,0]
	v_max_f32_e32 v24, 0, v24
	v_max_f32_e32 v25, 0, v25
	v_max_f32_e32 v28, 0, v28
	v_max_f32_e32 v29, 0, v29
	v_pk_mul_f32 v[38:39], v[24:25], v[24:25]
	v_max_f32_e32 v24, 0, v30
	v_max_f32_e32 v26, 0, v26
	v_max_f32_e32 v25, 0, v31
	v_max_f32_e32 v27, 0, v27
	v_pk_mul_f32 v[28:29], v[28:29], v[28:29]
	v_pk_mul_f32 v[30:31], v[24:25], v[24:25]
	v_pk_mul_f32 v[40:41], v[26:27], v[26:27]
	v_pk_mul_f32 v[18:19], v[18:19], v[36:37] op_sel_hi:[1,0]
	v_cvt_pk_bf16_f32 v24, v28, v29
	v_cvt_pk_bf16_f32 v25, v30, v31
	v_cvt_pk_bf16_f32 v26, v38, v39
	v_cvt_pk_bf16_f32 v27, v40, v41
	v_pk_mul_f32 v[20:21], v[20:21], v[36:37] op_sel_hi:[1,0]
	v_pk_mul_f32 v[16:17], v[16:17], v[36:37] op_sel_hi:[1,0]
	v_max_f32_e32 v18, 0, v18
	v_max_f32_e32 v19, 0, v19
	global_store_dwordx4 v[34:35], v[24:27], off
	v_pk_mul_f32 v[22:23], v[22:23], v[36:37] op_sel_hi:[1,0]
	v_max_f32_e32 v20, 0, v20
	v_max_f32_e32 v16, 0, v16
	v_max_f32_e32 v21, 0, v21
	v_max_f32_e32 v17, 0, v17
	v_pk_mul_f32 v[26:27], v[18:19], v[18:19]
	v_pk_mul_f32 v[20:21], v[20:21], v[20:21]
	v_pk_mul_f32 v[24:25], v[16:17], v[16:17]
	v_max_f32_e32 v16, 0, v22
	v_max_f32_e32 v17, 0, v23
	v_pk_mul_f32 v[22:23], v[16:17], v[16:17]
	v_cvt_pk_bf16_f32 v16, v20, v21
	v_cvt_pk_bf16_f32 v17, v22, v23
	v_cvt_pk_bf16_f32 v18, v24, v25
	v_cvt_pk_bf16_f32 v19, v26, v27
	global_store_dwordx4 v[34:35], v[16:19], off offset:256
	s_nop 1
	v_mov_b32_e32 v16, v235
	v_pk_mul_f32 v[8:9], v[8:9], v[16:17] op_sel_hi:[1,0]
	v_pk_mul_f32 v[14:15], v[14:15], v[16:17] op_sel_hi:[1,0]
	v_pk_mul_f32 v[12:13], v[12:13], v[16:17] op_sel_hi:[1,0]
	v_pk_mul_f32 v[10:11], v[10:11], v[16:17] op_sel_hi:[1,0]
	v_max_f32_e32 v8, 0, v8
	v_max_f32_e32 v9, 0, v9
	v_lshlrev_b64 v[18:19], 13, v[146:147]
	v_max_f32_e32 v12, 0, v12
	v_max_f32_e32 v13, 0, v13
	v_pk_mul_f32 v[20:21], v[8:9], v[8:9]
	v_max_f32_e32 v8, 0, v14
	v_max_f32_e32 v10, 0, v10
	v_max_f32_e32 v9, 0, v15
	v_max_f32_e32 v11, 0, v11
	v_lshl_add_u64 v[18:19], s[96:97], 0, v[18:19]
	v_pk_mul_f32 v[12:13], v[12:13], v[12:13]
	v_pk_mul_f32 v[14:15], v[8:9], v[8:9]
	v_pk_mul_f32 v[22:23], v[10:11], v[10:11]
	v_pk_mul_f32 v[0:1], v[0:1], v[16:17] op_sel_hi:[1,0]
	v_lshl_add_u64 v[18:19], v[18:19], 0, v[148:149]
	v_cvt_pk_bf16_f32 v8, v12, v13
	v_cvt_pk_bf16_f32 v9, v14, v15
	v_cvt_pk_bf16_f32 v10, v20, v21
	v_cvt_pk_bf16_f32 v11, v22, v23
	v_pk_mul_f32 v[6:7], v[6:7], v[16:17] op_sel_hi:[1,0]
	v_pk_mul_f32 v[4:5], v[4:5], v[16:17] op_sel_hi:[1,0]
	v_pk_mul_f32 v[2:3], v[2:3], v[16:17] op_sel_hi:[1,0]
	v_max_f32_e32 v0, 0, v0
	v_max_f32_e32 v1, 0, v1
	global_store_dwordx4 v[18:19], v[8:11], off
	v_max_f32_e32 v4, 0, v4
	v_max_f32_e32 v5, 0, v5
	v_pk_mul_f32 v[8:9], v[0:1], v[0:1]
	v_max_f32_e32 v0, 0, v6
	v_max_f32_e32 v2, 0, v2
	v_max_f32_e32 v1, 0, v7
	v_max_f32_e32 v3, 0, v3
	v_pk_mul_f32 v[4:5], v[4:5], v[4:5]
	v_pk_mul_f32 v[6:7], v[0:1], v[0:1]
	v_pk_mul_f32 v[10:11], v[2:3], v[2:3]
	v_cvt_pk_bf16_f32 v0, v4, v5
	v_cvt_pk_bf16_f32 v1, v6, v7
	v_cvt_pk_bf16_f32 v2, v8, v9
	v_cvt_pk_bf16_f32 v3, v10, v11
	s_and_b64 vcc, exec, s[0:1]
	global_store_dwordx4 v[18:19], v[0:3], off offset:256
	s_cbranch_vccz .LBB0_763
	s_waitcnt vmcnt(0)
	s_cmpk_gt_u32 s9, 0xff
	s_cbranch_scc1 .LBB0_774
	s_barrier

; #define PG8_STAGE(bufoff, gbase, voff) do { _Pragma("unroll") for (int _i = 0; _i < 2; ++_i) \
;         __builtin_amdgcn_global_load_lds((const unsigned*)((const char*)(gbase) + (voff)[_i]), (LAS unsigned*)(lds + (bufoff) + ldsw + _i * 8192), 16, 0, 0); } while (0)
; #define PG8_LDA(dst, b, h) do { _Pragma("unroll") for (int m = 0; m < 4; ++m) _Pragma("unroll") for (int k = 0; k < 2; ++k) dst[m][k] = *(const LAS bf16x8*)(lds + PG8_SA(b, h) + aoff + m * 2048 + k * 1024); } while (0)
; #define PG8_LDB(dst, b, h) do { _Pragma("unroll") for (int n = 0; n < 2; ++n) _Pragma("unroll") for (int k = 0; k < 2; ++k) dst[n][k] = *(const LAS bf16x8*)(lds + PG8_SB(b, h) + boff + n * 2048 + k * 1024); } while (0)
; #define PG8_MMA(ai, bj, At, Bt) do { __builtin_amdgcn_s_setprio(1); _Pragma("unroll") for (int m = 0; m < 4; ++m) _Pragma("unroll") for (int n = 0; n < 2; ++n) _Pragma("unroll") for (int k = 0; k < 2; ++k) \
;         acc[ai][bj][m][n] = __builtin_amdgcn_mfma_f32_16x16x32_bf16(Bt[n][k], At[m][k], acc[ai][bj][m][n], 0, 0, 0); __builtin_amdgcn_s_setprio(0); } while (0)
; #define PG8_BAR __builtin_amdgcn_s_barrier()
; template <class Epi>
; __device__ __forceinline__ void gemm_phase(LAS unsigned char* lds, const Gemm g, const StaticOrder& S, const Epi& E) {
;     ...
;         const bool has_next = S.next(ui + 1, nxt);
;         const char* nA = has_next ? (const char*)g.A + (size_t)nxt.pm * tstepA : cA; const char* nB = has_next ? (const char*)g.Bt + (size_t)nxt.pn * tstepB : cB;
;         for (int t = 0; t < nt; t += 2) {
;             const bool last = (t == nt - 2);
;             const char* a1 = cA + (size_t)(t + 1) * kstep;
;             const char* a2 = last ? nA : cA + (size_t)(t + 2) * kstep; const char* b2 = last ? nB : cB + (size_t)(t + 2) * kstep;
;             const char* a3 = a2 + kstep; const char* b3 = b2 + kstep;
;             if (last) E.pre(cur, wr, fr, epre);
;             PG8_LDB(B0, 0, 0); PG8_SCHED; PG8_LDA(At, 0, 0); PG8_STAGE(PG8_SA(1, 1), a1 + hstepA, voffA);
;             PG8_WAIT_L(8); PG8_BAR; PG8_WAIT_L(0); PG8_MMA(0, 0, At, B0); PG8_BAR; PG8_SCHED;
;             PG8_LDB(B1, 0, 1); PG8_STAGE(PG8_SB(0, 0), b2, voffB);
;             PG8_BAR; PG8_WAIT_L(0); PG8_MMA(0, 1, At, B1); PG8_BAR;
;             PG8_LDA(At, 0, 1); PG8_STAGE(PG8_SA(0, 0), a2, voffA);
;             PG8_BAR; PG8_WAIT_L(0); PG8_MMA(1, 0, At, B0); PG8_BAR; PG8_SCHED;
.LBB0_843:
	s_ashr_i32 s17, s16, 31
	v_cmp_lt_i64_e32 vcc, s[18:19], v[166:167]
	s_lshl_b64 s[18:19], s[16:17], 21
	s_add_u32 s18, s96, s18
	s_addc_u32 s19, s97, s19
	s_and_b64 s[20:21], vcc, exec
	s_cselect_b32 s17, s19, s23
	s_cselect_b32 s44, s18, s22
	s_ashr_i32 s15, s14, 31
	s_lshl_b64 s[20:21], s[14:15], 21
	s_add_u32 s20, s29, s20
	s_addc_u32 s21, s30, s21
	s_and_b64 s[26:27], vcc, exec
	s_cselect_b32 s15, s21, s25
	s_cselect_b32 s45, s20, s24
	s_add_u32 s22, s22, 0x100080
	s_addc_u32 s23, s23, 0
	s_add_u32 s46, s24, 0x100
	s_addc_u32 s47, s25, 0
	s_mov_b32 s48, -2
	s_waitcnt lgkmcnt(0)
	ds_read_b128 v[128:131], v191
	ds_read_b128 v[132:135], v191 offset:1024
	ds_read_b128 v[136:139], v191 offset:2048
	ds_read_b128 v[140:143], v191 offset:3072
	s_add_u32 s24, s22, 0xfff00080
	s_addc_u32 s25, s23, -1
	s_cmp_eq_u32 s48, 60
	s_cselect_b32 s27, s17, s25
	s_cselect_b32 s26, s44, s24
	s_cselect_b32 s25, s15, s47
	s_cselect_b32 s24, s45, s46
	v_lshl_add_u64 v[186:187], s[22:23], 0, v[162:163]
	s_add_i32 m0, s7, 0xc000
	ds_read_b128 v[144:147], v192
	ds_read_b128 v[148:151], v192 offset:1024
	ds_read_b128 v[170:173], v192 offset:2048
	ds_read_b128 v[174:177], v192 offset:3072
	ds_read_b128 v[178:181], v192 offset:4096
	ds_read_b128 v[182:185], v192 offset:5120
	ds_read_b128 v[196:199], v192 offset:6144
	ds_read_b128 v[200:203], v192 offset:7168
	global_load_lds_dwordx4 v[186:187], off
	v_lshl_add_u64 v[186:187], s[22:23], 0, v[164:165]
	s_add_i32 m0, s7, 0xe000
	s_nop 0
	global_load_lds_dwordx4 v[186:187], off
	s_waitcnt lgkmcnt(8)
	s_barrier
	s_waitcnt lgkmcnt(7)
	v_mfma_f32_16x16x32_bf16 v[124:127], v[128:131], v[144:147], 0
	v_mfma_f32_16x16x32_bf16 v[120:123], v[136:139], v[144:147], 0
	s_waitcnt lgkmcnt(5)
	v_mfma_f32_16x16x32_bf16 v[108:111], v[128:131], v[170:173], 0
	v_mfma_f32_16x16x32_bf16 v[104:107], v[136:139], v[170:173], 0
	s_waitcnt lgkmcnt(3)
	v_mfma_f32_16x16x32_bf16 v[92:95], v[128:131], v[178:181], 0
	v_mfma_f32_16x16x32_bf16 v[88:91], v[136:139], v[178:181], 0
	s_waitcnt lgkmcnt(1)
	v_mfma_f32_16x16x32_bf16 v[76:79], v[128:131], v[196:199], 0
	v_mfma_f32_16x16x32_bf16 v[72:75], v[136:139], v[196:199], 0
	v_mfma_f32_16x16x32_bf16 v[124:127], v[132:135], v[148:151], v[124:127]
	v_mfma_f32_16x16x32_bf16 v[120:123], v[140:143], v[148:151], v[120:123]
	v_mfma_f32_16x16x32_bf16 v[108:111], v[132:135], v[174:177], v[108:111]
	v_mfma_f32_16x16x32_bf16 v[104:107], v[140:143], v[174:177], v[104:107]
	v_mfma_f32_16x16x32_bf16 v[92:95], v[132:135], v[182:185], v[92:95]
	v_mfma_f32_16x16x32_bf16 v[88:91], v[140:143], v[182:185], v[88:91]
	s_waitcnt lgkmcnt(0)
	v_mfma_f32_16x16x32_bf16 v[76:79], v[132:135], v[200:203], v[76:79]
	v_mfma_f32_16x16x32_bf16 v[72:75], v[140:143], v[200:203], v[72:75]
	s_barrier
	s_add_i32 s49, s42, s31
	v_lshl_add_u64 v[186:187], s[24:25], 0, v[156:157]
	s_mov_b32 m0, s49
	ds_read_b128 v[204:207], v193
	ds_read_b128 v[208:211], v193 offset:1024
	ds_read_b128 v[212:215], v193 offset:2048
	ds_read_b128 v[216:219], v193 offset:3072
	global_load_lds_dwordx4 v[186:187], off
	v_lshl_add_u64 v[220:221], s[24:25], 0, v[160:161]
	s_add_i32 m0, s49, 0x2000
	s_nop 0
	global_load_lds_dwordx4 v[220:221], off
	s_barrier
	s_waitcnt lgkmcnt(3)
	v_mfma_f32_16x16x32_bf16 v[116:119], v[204:207], v[144:147], 0
	s_waitcnt lgkmcnt(1)
	v_mfma_f32_16x16x32_bf16 v[112:115], v[212:215], v[144:147], 0
	v_mfma_f32_16x16x32_bf16 v[100:103], v[204:207], v[170:173], 0
	v_mfma_f32_16x16x32_bf16 v[96:99], v[212:215], v[170:173], 0
	v_mfma_f32_16x16x32_bf16 v[84:87], v[204:207], v[178:181], 0
	v_mfma_f32_16x16x32_bf16 v[80:83], v[212:215], v[178:181], 0
	v_mfma_f32_16x16x32_bf16 v[68:71], v[204:207], v[196:199], 0
	v_mfma_f32_16x16x32_bf16 v[64:67], v[212:215], v[196:199], 0
	v_mfma_f32_16x16x32_bf16 v[116:119], v[208:211], v[148:151], v[116:119]
	s_waitcnt lgkmcnt(0)
	v_mfma_f32_16x16x32_bf16 v[112:115], v[216:219], v[148:151], v[112:115]
	v_mfma_f32_16x16x32_bf16 v[100:103], v[208:211], v[174:177], v[100:103]
	v_mfma_f32_16x16x32_bf16 v[96:99], v[216:219], v[174:177], v[96:99]
	v_mfma_f32_16x16x32_bf16 v[84:87], v[208:211], v[182:185], v[84:87]
	v_mfma_f32_16x16x32_bf16 v[80:83], v[216:219], v[182:185], v[80:83]
	v_mfma_f32_16x16x32_bf16 v[68:71], v[208:211], v[200:203], v[68:71]
	v_mfma_f32_16x16x32_bf16 v[64:67], v[216:219], v[200:203], v[64:67]
	s_mov_b32 m0, s7
	v_lshl_add_u64 v[222:223], s[26:27], 0, v[154:155]
	s_barrier
	ds_read_b128 v[144:147], v192 offset:16384
	ds_read_b128 v[148:151], v192 offset:17408
	ds_read_b128 v[170:173], v192 offset:18432
	ds_read_b128 v[174:177], v192 offset:19456
	ds_read_b128 v[178:181], v192 offset:20480
	ds_read_b128 v[182:185], v192 offset:21504
	ds_read_b128 v[196:199], v192 offset:22528
	ds_read_b128 v[200:203], v192 offset:23552
	global_load_lds_dwordx4 v[222:223], off
	v_lshl_add_u64 v[224:225], s[26:27], 0, v[158:159]
	s_mov_b32 m0, s34
	s_nop 0
	global_load_lds_dwordx4 v[224:225], off
	s_barrier
	s_waitcnt lgkmcnt(7)
	v_mfma_f32_16x16x32_bf16 v[60:63], v[128:131], v[144:147], 0
	v_mfma_f32_16x16x32_bf16 v[56:59], v[136:139], v[144:147], 0
	s_waitcnt lgkmcnt(5)
	v_mfma_f32_16x16x32_bf16 v[44:47], v[128:131], v[170:173], 0
	v_mfma_f32_16x16x32_bf16 v[40:43], v[136:139], v[170:173], 0
	s_waitcnt lgkmcnt(3)
	v_mfma_f32_16x16x32_bf16 v[28:31], v[128:131], v[178:181], 0
	v_mfma_f32_16x16x32_bf16 v[24:27], v[136:139], v[178:181], 0
	s_waitcnt lgkmcnt(1)
	v_mfma_f32_16x16x32_bf16 v[12:15], v[128:131], v[196:199], 0
	v_mfma_f32_16x16x32_bf16 v[8:11], v[136:139], v[196:199], 0
	v_mfma_f32_16x16x32_bf16 v[60:63], v[132:135], v[148:151], v[60:63]
	v_mfma_f32_16x16x32_bf16 v[56:59], v[140:143], v[148:151], v[56:59]
	v_mfma_f32_16x16x32_bf16 v[44:47], v[132:135], v[174:177], v[44:47]
	v_mfma_f32_16x16x32_bf16 v[40:43], v[140:143], v[174:177], v[40:43]
	v_mfma_f32_16x16x32_bf16 v[28:31], v[132:135], v[182:185], v[28:31]
	v_mfma_f32_16x16x32_bf16 v[24:27], v[140:143], v[182:185], v[24:27]
	s_waitcnt lgkmcnt(0)
	v_mfma_f32_16x16x32_bf16 v[12:15], v[132:135], v[200:203], v[12:15]
	v_mfma_f32_16x16x32_bf16 v[8:11], v[140:143], v[200:203], v[8:11]
	s_barrier
; #define PG8_STAGE(bufoff, gbase, voff) do { _Pragma("unroll") for (int _i = 0; _i < 2; ++_i) \
;         __builtin_amdgcn_global_load_lds((const unsigned*)((const char*)(gbase) + (voff)[_i]), (LAS unsigned*)(lds + (bufoff) + ldsw + _i * 8192), 16, 0, 0); } while (0)
; #define PG8_LDA(dst, b, h) do { _Pragma("unroll") for (int m = 0; m < 4; ++m) _Pragma("unroll") for (int k = 0; k < 2; ++k) dst[m][k] = *(const LAS bf16x8*)(lds + PG8_SA(b, h) + aoff + m * 2048 + k * 1024); } while (0)
; #define PG8_LDB(dst, b, h) do { _Pragma("unroll") for (int n = 0; n < 2; ++n) _Pragma("unroll") for (int k = 0; k < 2; ++k) dst[n][k] = *(const LAS bf16x8*)(lds + PG8_SB(b, h) + boff + n * 2048 + k * 1024); } while (0)
; #define PG8_MMA(ai, bj, At, Bt) do { __builtin_amdgcn_s_setprio(1); _Pragma("unroll") for (int m = 0; m < 4; ++m) _Pragma("unroll") for (int n = 0; n < 2; ++n) _Pragma("unroll") for (int k = 0; k < 2; ++k) \
;         acc[ai][bj][m][n] = __builtin_amdgcn_mfma_f32_16x16x32_bf16(Bt[n][k], At[m][k], acc[ai][bj][m][n], 0, 0, 0); __builtin_amdgcn_s_setprio(0); } while (0)
; #define PG8_WAIT_V(n) asm volatile("s_waitcnt vmcnt(" #n ")" ::: "memory")
; #define PG8_WAIT_L(n) asm volatile("s_waitcnt lgkmcnt(" #n ")" ::: "memory")
; #define PG8_BAR __builtin_amdgcn_s_barrier()
; #define PG8_SCHED __builtin_amdgcn_sched_barrier(0)
; template <class Epi>
; __device__ __forceinline__ void gemm_phase(LAS unsigned char* lds, const Gemm g, const StaticOrder& S, const Epi& E) {
;     ...
;             PG8_STAGE(PG8_SB(0, 1), b2 + hstepB, voffB);
;             PG8_WAIT_V(6); PG8_BAR; PG8_MMA(1, 1, At, B1); PG8_BAR;
;             PG8_LDB(B0, 1, 0); PG8_SCHED; PG8_LDA(At, 1, 0); PG8_STAGE(PG8_SA(0, 1), a2 + hstepA, voffA);
;             PG8_WAIT_L(8); PG8_BAR; PG8_WAIT_L(0); PG8_MMA(0, 0, At, B0); PG8_BAR; PG8_SCHED;
;             PG8_LDB(B1, 1, 1); PG8_STAGE(PG8_SB(1, 0), b3, voffB);
;             PG8_BAR; PG8_WAIT_L(0); PG8_MMA(0, 1, At, B1); PG8_BAR;
;             PG8_LDA(At, 1, 1); PG8_STAGE(PG8_SA(1, 0), a3, voffA);
	s_add_u32 s50, s24, 0x100000
	s_addc_u32 s51, s25, 0
	s_add_i32 s49, s43, s31
	v_lshl_add_u64 v[128:129], s[50:51], 0, v[156:157]
	s_mov_b32 m0, s49
	s_nop 0
	global_load_lds_dwordx4 v[128:129], off
	v_lshl_add_u64 v[128:129], s[50:51], 0, v[160:161]
	s_add_i32 m0, s49, 0x2000
	s_nop 0
	global_load_lds_dwordx4 v[128:129], off
	s_waitcnt vmcnt(6)
	s_barrier
	v_mfma_f32_16x16x32_bf16 v[52:55], v[204:207], v[144:147], 0
	v_mfma_f32_16x16x32_bf16 v[48:51], v[212:215], v[144:147], 0
	v_mfma_f32_16x16x32_bf16 v[36:39], v[204:207], v[170:173], 0
	v_mfma_f32_16x16x32_bf16 v[32:35], v[212:215], v[170:173], 0
	v_mfma_f32_16x16x32_bf16 v[20:23], v[204:207], v[178:181], 0
	v_mfma_f32_16x16x32_bf16 v[16:19], v[212:215], v[178:181], 0
	v_mfma_f32_16x16x32_bf16 v[4:7], v[204:207], v[196:199], 0
	v_mfma_f32_16x16x32_bf16 v[0:3], v[212:215], v[196:199], 0
	v_mfma_f32_16x16x32_bf16 v[52:55], v[208:211], v[148:151], v[52:55]
	v_mfma_f32_16x16x32_bf16 v[48:51], v[216:219], v[148:151], v[48:51]
	v_mfma_f32_16x16x32_bf16 v[36:39], v[208:211], v[174:177], v[36:39]
	v_mfma_f32_16x16x32_bf16 v[32:35], v[216:219], v[174:177], v[32:35]
	v_mfma_f32_16x16x32_bf16 v[20:23], v[208:211], v[182:185], v[20:23]
	v_mfma_f32_16x16x32_bf16 v[16:19], v[216:219], v[182:185], v[16:19]
	v_mfma_f32_16x16x32_bf16 v[4:7], v[208:211], v[200:203], v[4:7]
	v_mfma_f32_16x16x32_bf16 v[0:3], v[216:219], v[200:203], v[0:3]
	s_add_i32 s49, 0, 0x18000
	v_add_u32_e32 v140, s49, v189
	s_barrier
	ds_read_b128 v[128:131], v140
	ds_read_b128 v[132:135], v140 offset:1024
	ds_read_b128 v[136:139], v140 offset:2048
	ds_read_b128 v[140:143], v140 offset:3072
	s_add_u32 s26, s26, 0x100000
	s_addc_u32 s27, s27, 0
	s_mov_b32 m0, s35
	v_lshl_add_u64 v[204:205], s[26:27], 0, v[154:155]
	ds_read_b128 v[144:147], v192 offset:32768
	ds_read_b128 v[148:151], v192 offset:33792
	ds_read_b128 v[170:173], v192 offset:34816
	ds_read_b128 v[174:177], v192 offset:35840
	ds_read_b128 v[178:181], v192 offset:36864
	ds_read_b128 v[182:185], v192 offset:37888
	ds_read_b128 v[196:199], v192 offset:38912
	ds_read_b128 v[200:203], v192 offset:39936
	global_load_lds_dwordx4 v[204:205], off
	v_lshl_add_u64 v[204:205], s[26:27], 0, v[158:159]
	s_mov_b32 m0, s36
	s_nop 0
	global_load_lds_dwordx4 v[204:205], off
	s_waitcnt lgkmcnt(8)
	s_barrier
	s_waitcnt lgkmcnt(7)
	v_mfma_f32_16x16x32_bf16 v[124:127], v[128:131], v[144:147], v[124:127]
	v_mfma_f32_16x16x32_bf16 v[120:123], v[136:139], v[144:147], v[120:123]
	s_waitcnt lgkmcnt(5)
	v_mfma_f32_16x16x32_bf16 v[108:111], v[128:131], v[170:173], v[108:111]
	v_mfma_f32_16x16x32_bf16 v[104:107], v[136:139], v[170:173], v[104:107]
	s_waitcnt lgkmcnt(3)
	v_mfma_f32_16x16x32_bf16 v[92:95], v[128:131], v[178:181], v[92:95]
	v_mfma_f32_16x16x32_bf16 v[88:91], v[136:139], v[178:181], v[88:91]
	s_waitcnt lgkmcnt(1)
	v_mfma_f32_16x16x32_bf16 v[76:79], v[128:131], v[196:199], v[76:79]
	v_mfma_f32_16x16x32_bf16 v[72:75], v[136:139], v[196:199], v[72:75]
	v_mfma_f32_16x16x32_bf16 v[124:127], v[132:135], v[148:151], v[124:127]
	v_mfma_f32_16x16x32_bf16 v[120:123], v[140:143], v[148:151], v[120:123]
	v_mfma_f32_16x16x32_bf16 v[108:111], v[132:135], v[174:177], v[108:111]
	v_mfma_f32_16x16x32_bf16 v[104:107], v[140:143], v[174:177], v[104:107]
	v_mfma_f32_16x16x32_bf16 v[92:95], v[132:135], v[182:185], v[92:95]
	v_mfma_f32_16x16x32_bf16 v[88:91], v[140:143], v[182:185], v[88:91]
	s_waitcnt lgkmcnt(0)
	v_mfma_f32_16x16x32_bf16 v[76:79], v[132:135], v[200:203], v[76:79]
	v_mfma_f32_16x16x32_bf16 v[72:75], v[140:143], v[200:203], v[72:75]
	s_barrier
	s_add_i32 s26, 0, 0x1c000
	s_add_i32 s27, s49, s31
	v_add_u32_e32 v195, s26, v189
	v_lshl_add_u64 v[186:187], v[186:187], 0, s[12:13]
	s_mov_b32 m0, s27
	ds_read_b128 v[204:207], v195
	ds_read_b128 v[208:211], v195 offset:1024
	ds_read_b128 v[212:215], v195 offset:2048
	ds_read_b128 v[216:219], v195 offset:3072
	global_load_lds_dwordx4 v[186:187], off
	v_lshl_add_u64 v[186:187], v[220:221], 0, s[12:13]
	s_add_i32 m0, s27, 0x2000
	s_nop 0
	global_load_lds_dwordx4 v[186:187], off
	s_barrier
	s_waitcnt lgkmcnt(3)
	v_mfma_f32_16x16x32_bf16 v[116:119], v[204:207], v[144:147], v[116:119]
	s_waitcnt lgkmcnt(1)
	v_mfma_f32_16x16x32_bf16 v[112:115], v[212:215], v[144:147], v[112:115]
	v_mfma_f32_16x16x32_bf16 v[100:103], v[204:207], v[170:173], v[100:103]
	v_mfma_f32_16x16x32_bf16 v[96:99], v[212:215], v[170:173], v[96:99]
	v_mfma_f32_16x16x32_bf16 v[84:87], v[204:207], v[178:181], v[84:87]
	v_mfma_f32_16x16x32_bf16 v[80:83], v[212:215], v[178:181], v[80:83]
	v_mfma_f32_16x16x32_bf16 v[68:71], v[204:207], v[196:199], v[68:71]
	v_mfma_f32_16x16x32_bf16 v[64:67], v[212:215], v[196:199], v[64:67]
	v_mfma_f32_16x16x32_bf16 v[116:119], v[208:211], v[148:151], v[116:119]
	s_waitcnt lgkmcnt(0)
	v_mfma_f32_16x16x32_bf16 v[112:115], v[216:219], v[148:151], v[112:115]
	v_mfma_f32_16x16x32_bf16 v[100:103], v[208:211], v[174:177], v[100:103]
	v_mfma_f32_16x16x32_bf16 v[96:99], v[216:219], v[174:177], v[96:99]
	v_mfma_f32_16x16x32_bf16 v[84:87], v[208:211], v[182:185], v[84:87]
	v_mfma_f32_16x16x32_bf16 v[80:83], v[216:219], v[182:185], v[80:83]
	v_mfma_f32_16x16x32_bf16 v[68:71], v[208:211], v[200:203], v[68:71]
	v_mfma_f32_16x16x32_bf16 v[64:67], v[216:219], v[200:203], v[64:67]
	s_mov_b32 m0, s38
	v_lshl_add_u64 v[186:187], v[222:223], 0, s[12:13]
	s_barrier
	ds_read_b128 v[144:147], v192 offset:49152
	ds_read_b128 v[148:151], v192 offset:50176
	ds_read_b128 v[170:173], v192 offset:51200
	ds_read_b128 v[174:177], v192 offset:52224
	ds_read_b128 v[178:181], v192 offset:53248
	ds_read_b128 v[182:185], v192 offset:54272
	ds_read_b128 v[196:199], v192 offset:55296
	ds_read_b128 v[200:203], v192 offset:56320
	global_load_lds_dwordx4 v[186:187], off
	v_lshl_add_u64 v[186:187], v[224:225], 0, s[12:13]
	s_mov_b32 m0, s39
	s_nop 0
	global_load_lds_dwordx4 v[186:187], off
	s_barrier
; #define PG8_STAGE(bufoff, gbase, voff) do { _Pragma("unroll") for (int _i = 0; _i < 2; ++_i) \
;         __builtin_amdgcn_global_load_lds((const unsigned*)((const char*)(gbase) + (voff)[_i]), (LAS unsigned*)(lds + (bufoff) + ldsw + _i * 8192), 16, 0, 0); } while (0)
; #define PG8_LDA(dst, b, h) do { _Pragma("unroll") for (int m = 0; m < 4; ++m) _Pragma("unroll") for (int k = 0; k < 2; ++k) dst[m][k] = *(const LAS bf16x8*)(lds + PG8_SA(b, h) + aoff + m * 2048 + k * 1024); } while (0)
; #define PG8_WAIT_V(n) asm volatile("s_waitcnt vmcnt(" #n ")" ::: "memory")
; template <class Epi>
; __device__ __forceinline__ void gemm_phase(LAS unsigned char* lds, const Gemm g, const StaticOrder& S, const Epi& E) {
;     ...
;         for (int t = 0; t < nt; t += 2) {
;             const bool last = (t == nt - 2);
;             const char* a1 = cA + (size_t)(t + 1) * kstep;
;             const char* a2 = last ? nA : cA + (size_t)(t + 2) * kstep; const char* b2 = last ? nB : cB + (size_t)(t + 2) * kstep;
;             const char* a3 = a2 + kstep; const char* b3 = b2 + kstep;
;             if (last) E.pre(cur, wr, fr, epre);
;             PG8_LDB(B0, 0, 0); PG8_SCHED; PG8_LDA(At, 0, 0); PG8_STAGE(PG8_SA(1, 1), a1 + hstepA, voffA);
;             PG8_WAIT_L(8); PG8_BAR; PG8_WAIT_L(0); PG8_MMA(0, 0, At, B0); PG8_BAR; PG8_SCHED;
;             PG8_LDB(B1, 0, 1); PG8_STAGE(PG8_SB(0, 0), b2, voffB);
;             PG8_BAR; PG8_WAIT_L(0); PG8_MMA(0, 1, At, B1); PG8_BAR;
;             PG8_LDA(At, 0, 1); PG8_STAGE(PG8_SA(0, 0), a2, voffA);
;             PG8_BAR; PG8_WAIT_L(0); PG8_MMA(1, 0, At, B0); PG8_BAR; PG8_SCHED;
;             PG8_STAGE(PG8_SB(0, 1), b2 + hstepB, voffB);
;             PG8_WAIT_V(6); PG8_BAR; PG8_MMA(1, 1, At, B1); PG8_BAR;
;             PG8_LDB(B0, 1, 0); PG8_SCHED; PG8_LDA(At, 1, 0); PG8_STAGE(PG8_SA(0, 1), a2 + hstepA, voffA);
;             PG8_WAIT_L(8); PG8_BAR; PG8_WAIT_L(0); PG8_MMA(0, 0, At, B0); PG8_BAR; PG8_SCHED;
;             PG8_LDB(B1, 1, 1); PG8_STAGE(PG8_SB(1, 0), b3, voffB);
;             PG8_BAR; PG8_WAIT_L(0); PG8_MMA(0, 1, At, B1); PG8_BAR;
;             PG8_LDA(At, 1, 1); PG8_STAGE(PG8_SA(1, 0), a3, voffA);
;             PG8_BAR; PG8_WAIT_L(0); PG8_MMA(1, 0, At, B0); PG8_BAR; PG8_SCHED;
;             PG8_STAGE(PG8_SB(1, 1), b3 + hstepB, voffB);
;             PG8_WAIT_V(6); PG8_BAR; PG8_MMA(1, 1, At, B1); PG8_BAR;
	s_waitcnt lgkmcnt(7)
	v_mfma_f32_16x16x32_bf16 v[60:63], v[128:131], v[144:147], v[60:63]
	v_mfma_f32_16x16x32_bf16 v[56:59], v[136:139], v[144:147], v[56:59]
	s_waitcnt lgkmcnt(5)
	v_mfma_f32_16x16x32_bf16 v[44:47], v[128:131], v[170:173], v[44:47]
	v_mfma_f32_16x16x32_bf16 v[40:43], v[136:139], v[170:173], v[40:43]
	s_waitcnt lgkmcnt(3)
	v_mfma_f32_16x16x32_bf16 v[28:31], v[128:131], v[178:181], v[28:31]
	v_mfma_f32_16x16x32_bf16 v[24:27], v[136:139], v[178:181], v[24:27]
	s_waitcnt lgkmcnt(1)
	v_mfma_f32_16x16x32_bf16 v[12:15], v[128:131], v[196:199], v[12:15]
	v_mfma_f32_16x16x32_bf16 v[8:11], v[136:139], v[196:199], v[8:11]
	v_mfma_f32_16x16x32_bf16 v[60:63], v[132:135], v[148:151], v[60:63]
	v_mfma_f32_16x16x32_bf16 v[56:59], v[140:143], v[148:151], v[56:59]
	v_mfma_f32_16x16x32_bf16 v[44:47], v[132:135], v[174:177], v[44:47]
	v_mfma_f32_16x16x32_bf16 v[40:43], v[140:143], v[174:177], v[40:43]
	v_mfma_f32_16x16x32_bf16 v[28:31], v[132:135], v[182:185], v[28:31]
	v_mfma_f32_16x16x32_bf16 v[24:27], v[140:143], v[182:185], v[24:27]
	s_waitcnt lgkmcnt(0)
	v_mfma_f32_16x16x32_bf16 v[12:15], v[132:135], v[200:203], v[12:15]
	v_mfma_f32_16x16x32_bf16 v[8:11], v[140:143], v[200:203], v[8:11]
	s_barrier
	s_add_u32 s24, s24, 0x100080
	s_addc_u32 s25, s25, 0
	s_add_i32 s26, s26, s31
	v_lshl_add_u64 v[128:129], s[24:25], 0, v[156:157]
	s_mov_b32 m0, s26
	s_nop 0
	global_load_lds_dwordx4 v[128:129], off
	v_lshl_add_u64 v[128:129], s[24:25], 0, v[160:161]
	s_add_i32 m0, s26, 0x2000
	s_nop 0
	global_load_lds_dwordx4 v[128:129], off
	s_waitcnt vmcnt(6)
	s_barrier
	v_mfma_f32_16x16x32_bf16 v[52:55], v[204:207], v[144:147], v[52:55]
	v_mfma_f32_16x16x32_bf16 v[48:51], v[212:215], v[144:147], v[48:51]
	v_mfma_f32_16x16x32_bf16 v[36:39], v[204:207], v[170:173], v[36:39]
	v_mfma_f32_16x16x32_bf16 v[32:35], v[212:215], v[170:173], v[32:35]
	v_mfma_f32_16x16x32_bf16 v[20:23], v[204:207], v[178:181], v[20:23]
	v_mfma_f32_16x16x32_bf16 v[16:19], v[212:215], v[178:181], v[16:19]
	v_mfma_f32_16x16x32_bf16 v[4:7], v[204:207], v[196:199], v[4:7]
	v_mfma_f32_16x16x32_bf16 v[0:3], v[212:215], v[196:199], v[0:3]
	v_mfma_f32_16x16x32_bf16 v[52:55], v[208:211], v[148:151], v[52:55]
	v_mfma_f32_16x16x32_bf16 v[48:51], v[216:219], v[148:151], v[48:51]
	v_mfma_f32_16x16x32_bf16 v[36:39], v[208:211], v[174:177], v[36:39]
	v_mfma_f32_16x16x32_bf16 v[32:35], v[216:219], v[174:177], v[32:35]
	v_mfma_f32_16x16x32_bf16 v[20:23], v[208:211], v[182:185], v[20:23]
	v_mfma_f32_16x16x32_bf16 v[16:19], v[216:219], v[182:185], v[16:19]
	v_mfma_f32_16x16x32_bf16 v[4:7], v[208:211], v[200:203], v[4:7]
	v_mfma_f32_16x16x32_bf16 v[0:3], v[216:219], v[200:203], v[0:3]
	s_add_i32 s48, s48, 2
	s_add_u32 s22, s22, 0x100
	s_addc_u32 s23, s23, 0
	s_add_u32 s46, s46, 0x100
	s_addc_u32 s47, s47, 0
	s_cmp_gt_u32 s48, 61
	s_barrier
.LBB0_844:
	ds_read_b128 v[128:131], v191
	ds_read_b128 v[132:135], v191 offset:1024
	ds_read_b128 v[136:139], v191 offset:2048
	ds_read_b128 v[140:143], v191 offset:3072
	s_add_u32 s24, s22, 0xfff00080
	s_addc_u32 s25, s23, -1
	s_cmp_eq_u32 s48, 60
	s_cselect_b32 s27, s17, s25
	s_cselect_b32 s26, s44, s24
	s_cselect_b32 s25, s15, s47
	s_cselect_b32 s24, s45, s46
	v_lshl_add_u64 v[186:187], s[22:23], 0, v[162:163]
	s_add_i32 m0, s7, 0xc000
	ds_read_b128 v[144:147], v192
	ds_read_b128 v[148:151], v192 offset:1024
	ds_read_b128 v[170:173], v192 offset:2048
	ds_read_b128 v[174:177], v192 offset:3072
	ds_read_b128 v[178:181], v192 offset:4096
	ds_read_b128 v[182:185], v192 offset:5120
	ds_read_b128 v[196:199], v192 offset:6144
	ds_read_b128 v[200:203], v192 offset:7168
	global_load_lds_dwordx4 v[186:187], off
	v_lshl_add_u64 v[186:187], s[22:23], 0, v[164:165]
	s_add_i32 m0, s7, 0xe000
	s_nop 0
	global_load_lds_dwordx4 v[186:187], off
	s_waitcnt lgkmcnt(8)
	s_barrier
	s_waitcnt lgkmcnt(7)
	v_mfma_f32_16x16x32_bf16 v[124:127], v[128:131], v[144:147], v[124:127]
	v_mfma_f32_16x16x32_bf16 v[120:123], v[136:139], v[144:147], v[120:123]
	s_waitcnt lgkmcnt(5)
	v_mfma_f32_16x16x32_bf16 v[108:111], v[128:131], v[170:173], v[108:111]
	v_mfma_f32_16x16x32_bf16 v[104:107], v[136:139], v[170:173], v[104:107]
	s_waitcnt lgkmcnt(3)
	v_mfma_f32_16x16x32_bf16 v[92:95], v[128:131], v[178:181], v[92:95]
	v_mfma_f32_16x16x32_bf16 v[88:91], v[136:139], v[178:181], v[88:91]
	s_waitcnt lgkmcnt(1)
	v_mfma_f32_16x16x32_bf16 v[76:79], v[128:131], v[196:199], v[76:79]
	v_mfma_f32_16x16x32_bf16 v[72:75], v[136:139], v[196:199], v[72:75]
	v_mfma_f32_16x16x32_bf16 v[124:127], v[132:135], v[148:151], v[124:127]
	v_mfma_f32_16x16x32_bf16 v[120:123], v[140:143], v[148:151], v[120:123]
	v_mfma_f32_16x16x32_bf16 v[108:111], v[132:135], v[174:177], v[108:111]
	v_mfma_f32_16x16x32_bf16 v[104:107], v[140:143], v[174:177], v[104:107]
	v_mfma_f32_16x16x32_bf16 v[92:95], v[132:135], v[182:185], v[92:95]
	v_mfma_f32_16x16x32_bf16 v[88:91], v[140:143], v[182:185], v[88:91]
	s_waitcnt lgkmcnt(0)
	v_mfma_f32_16x16x32_bf16 v[76:79], v[132:135], v[200:203], v[76:79]
	v_mfma_f32_16x16x32_bf16 v[72:75], v[140:143], v[200:203], v[72:75]
	s_barrier
	s_add_i32 s49, s42, s31
	v_lshl_add_u64 v[186:187], s[24:25], 0, v[156:157]
	s_mov_b32 m0, s49
	ds_read_b128 v[204:207], v193
	ds_read_b128 v[208:211], v193 offset:1024
	ds_read_b128 v[212:215], v193 offset:2048
	ds_read_b128 v[216:219], v193 offset:3072
	global_load_lds_dwordx4 v[186:187], off
	v_lshl_add_u64 v[220:221], s[24:25], 0, v[160:161]
	s_add_i32 m0, s49, 0x2000
	s_nop 0
	global_load_lds_dwordx4 v[220:221], off
	s_barrier
; #define PG8_STAGE(bufoff, gbase, voff) do { _Pragma("unroll") for (int _i = 0; _i < 2; ++_i) \
;         __builtin_amdgcn_global_load_lds((const unsigned*)((const char*)(gbase) + (voff)[_i]), (LAS unsigned*)(lds + (bufoff) + ldsw + _i * 8192), 16, 0, 0); } while (0)
; #define PG8_LDA(dst, b, h) do { _Pragma("unroll") for (int m = 0; m < 4; ++m) _Pragma("unroll") for (int k = 0; k < 2; ++k) dst[m][k] = *(const LAS bf16x8*)(lds + PG8_SA(b, h) + aoff + m * 2048 + k * 1024); } while (0)
; #define PG8_LDB(dst, b, h) do { _Pragma("unroll") for (int n = 0; n < 2; ++n) _Pragma("unroll") for (int k = 0; k < 2; ++k) dst[n][k] = *(const LAS bf16x8*)(lds + PG8_SB(b, h) + boff + n * 2048 + k * 1024); } while (0)
; #define PG8_MMA(ai, bj, At, Bt) do { __builtin_amdgcn_s_setprio(1); _Pragma("unroll") for (int m = 0; m < 4; ++m) _Pragma("unroll") for (int n = 0; n < 2; ++n) _Pragma("unroll") for (int k = 0; k < 2; ++k) \
;         acc[ai][bj][m][n] = __builtin_amdgcn_mfma_f32_16x16x32_bf16(Bt[n][k], At[m][k], acc[ai][bj][m][n], 0, 0, 0); __builtin_amdgcn_s_setprio(0); } while (0)
; #define PG8_WAIT_V(n) asm volatile("s_waitcnt vmcnt(" #n ")" ::: "memory")
; #define PG8_WAIT_L(n) asm volatile("s_waitcnt lgkmcnt(" #n ")" ::: "memory")
; #define PG8_BAR __builtin_amdgcn_s_barrier()
; #define PG8_SCHED __builtin_amdgcn_sched_barrier(0)
; template <class Epi>
; __device__ __forceinline__ void gemm_phase(LAS unsigned char* lds, const Gemm g, const StaticOrder& S, const Epi& E) {
;     ...
;             PG8_BAR; PG8_WAIT_L(0); PG8_MMA(0, 1, At, B1); PG8_BAR;
;             PG8_LDA(At, 0, 1); PG8_STAGE(PG8_SA(0, 0), a2, voffA);
;             PG8_BAR; PG8_WAIT_L(0); PG8_MMA(1, 0, At, B0); PG8_BAR; PG8_SCHED;
;             PG8_STAGE(PG8_SB(0, 1), b2 + hstepB, voffB);
;             PG8_WAIT_V(6); PG8_BAR; PG8_MMA(1, 1, At, B1); PG8_BAR;
;             PG8_LDB(B0, 1, 0); PG8_SCHED; PG8_LDA(At, 1, 0); PG8_STAGE(PG8_SA(0, 1), a2 + hstepA, voffA);
;             PG8_WAIT_L(8); PG8_BAR; PG8_WAIT_L(0); PG8_MMA(0, 0, At, B0); PG8_BAR; PG8_SCHED;
	s_waitcnt lgkmcnt(3)
	v_mfma_f32_16x16x32_bf16 v[116:119], v[204:207], v[144:147], v[116:119]
	s_waitcnt lgkmcnt(1)
	v_mfma_f32_16x16x32_bf16 v[112:115], v[212:215], v[144:147], v[112:115]
	v_mfma_f32_16x16x32_bf16 v[100:103], v[204:207], v[170:173], v[100:103]
	v_mfma_f32_16x16x32_bf16 v[96:99], v[212:215], v[170:173], v[96:99]
	v_mfma_f32_16x16x32_bf16 v[84:87], v[204:207], v[178:181], v[84:87]
	v_mfma_f32_16x16x32_bf16 v[80:83], v[212:215], v[178:181], v[80:83]
	v_mfma_f32_16x16x32_bf16 v[68:71], v[204:207], v[196:199], v[68:71]
	v_mfma_f32_16x16x32_bf16 v[64:67], v[212:215], v[196:199], v[64:67]
	v_mfma_f32_16x16x32_bf16 v[116:119], v[208:211], v[148:151], v[116:119]
	s_waitcnt lgkmcnt(0)
	v_mfma_f32_16x16x32_bf16 v[112:115], v[216:219], v[148:151], v[112:115]
	v_mfma_f32_16x16x32_bf16 v[100:103], v[208:211], v[174:177], v[100:103]
	v_mfma_f32_16x16x32_bf16 v[96:99], v[216:219], v[174:177], v[96:99]
	v_mfma_f32_16x16x32_bf16 v[84:87], v[208:211], v[182:185], v[84:87]
	v_mfma_f32_16x16x32_bf16 v[80:83], v[216:219], v[182:185], v[80:83]
	v_mfma_f32_16x16x32_bf16 v[68:71], v[208:211], v[200:203], v[68:71]
	v_mfma_f32_16x16x32_bf16 v[64:67], v[216:219], v[200:203], v[64:67]
	s_mov_b32 m0, s7
	v_lshl_add_u64 v[222:223], s[26:27], 0, v[154:155]
	s_barrier
	ds_read_b128 v[144:147], v192 offset:16384
	ds_read_b128 v[148:151], v192 offset:17408
	ds_read_b128 v[170:173], v192 offset:18432
	ds_read_b128 v[174:177], v192 offset:19456
	ds_read_b128 v[178:181], v192 offset:20480
	ds_read_b128 v[182:185], v192 offset:21504
	ds_read_b128 v[196:199], v192 offset:22528
	ds_read_b128 v[200:203], v192 offset:23552
	global_load_lds_dwordx4 v[222:223], off
	v_lshl_add_u64 v[224:225], s[26:27], 0, v[158:159]
	s_mov_b32 m0, s34
	s_nop 0
	global_load_lds_dwordx4 v[224:225], off
	s_barrier
	s_waitcnt lgkmcnt(7)
	v_mfma_f32_16x16x32_bf16 v[60:63], v[128:131], v[144:147], v[60:63]
	v_mfma_f32_16x16x32_bf16 v[56:59], v[136:139], v[144:147], v[56:59]
	s_waitcnt lgkmcnt(5)
	v_mfma_f32_16x16x32_bf16 v[44:47], v[128:131], v[170:173], v[44:47]
	v_mfma_f32_16x16x32_bf16 v[40:43], v[136:139], v[170:173], v[40:43]
	s_waitcnt lgkmcnt(3)
	v_mfma_f32_16x16x32_bf16 v[28:31], v[128:131], v[178:181], v[28:31]
	v_mfma_f32_16x16x32_bf16 v[24:27], v[136:139], v[178:181], v[24:27]
	s_waitcnt lgkmcnt(1)
	v_mfma_f32_16x16x32_bf16 v[12:15], v[128:131], v[196:199], v[12:15]
	v_mfma_f32_16x16x32_bf16 v[8:11], v[136:139], v[196:199], v[8:11]
	v_mfma_f32_16x16x32_bf16 v[60:63], v[132:135], v[148:151], v[60:63]
	v_mfma_f32_16x16x32_bf16 v[56:59], v[140:143], v[148:151], v[56:59]
	v_mfma_f32_16x16x32_bf16 v[44:47], v[132:135], v[174:177], v[44:47]
	v_mfma_f32_16x16x32_bf16 v[40:43], v[140:143], v[174:177], v[40:43]
	v_mfma_f32_16x16x32_bf16 v[28:31], v[132:135], v[182:185], v[28:31]
	v_mfma_f32_16x16x32_bf16 v[24:27], v[140:143], v[182:185], v[24:27]
	s_waitcnt lgkmcnt(0)
	v_mfma_f32_16x16x32_bf16 v[12:15], v[132:135], v[200:203], v[12:15]
	v_mfma_f32_16x16x32_bf16 v[8:11], v[140:143], v[200:203], v[8:11]
	s_barrier
	s_add_u32 s50, s24, 0x100000
	s_addc_u32 s51, s25, 0
	s_add_i32 s49, s43, s31
	v_lshl_add_u64 v[128:129], s[50:51], 0, v[156:157]
	s_mov_b32 m0, s49
	s_nop 0
	global_load_lds_dwordx4 v[128:129], off
	v_lshl_add_u64 v[128:129], s[50:51], 0, v[160:161]
	s_add_i32 m0, s49, 0x2000
	s_nop 0
	global_load_lds_dwordx4 v[128:129], off
	s_waitcnt vmcnt(6)
	s_barrier
	v_mfma_f32_16x16x32_bf16 v[52:55], v[204:207], v[144:147], v[52:55]
	v_mfma_f32_16x16x32_bf16 v[48:51], v[212:215], v[144:147], v[48:51]
	v_mfma_f32_16x16x32_bf16 v[36:39], v[204:207], v[170:173], v[36:39]
	v_mfma_f32_16x16x32_bf16 v[32:35], v[212:215], v[170:173], v[32:35]
	v_mfma_f32_16x16x32_bf16 v[20:23], v[204:207], v[178:181], v[20:23]
	v_mfma_f32_16x16x32_bf16 v[16:19], v[212:215], v[178:181], v[16:19]
	v_mfma_f32_16x16x32_bf16 v[4:7], v[204:207], v[196:199], v[4:7]
	v_mfma_f32_16x16x32_bf16 v[0:3], v[212:215], v[196:199], v[0:3]
	v_mfma_f32_16x16x32_bf16 v[52:55], v[208:211], v[148:151], v[52:55]
	v_mfma_f32_16x16x32_bf16 v[48:51], v[216:219], v[148:151], v[48:51]
	v_mfma_f32_16x16x32_bf16 v[36:39], v[208:211], v[174:177], v[36:39]
	v_mfma_f32_16x16x32_bf16 v[32:35], v[216:219], v[174:177], v[32:35]
	v_mfma_f32_16x16x32_bf16 v[20:23], v[208:211], v[182:185], v[20:23]
	v_mfma_f32_16x16x32_bf16 v[16:19], v[216:219], v[182:185], v[16:19]
	v_mfma_f32_16x16x32_bf16 v[4:7], v[208:211], v[200:203], v[4:7]
	v_mfma_f32_16x16x32_bf16 v[0:3], v[216:219], v[200:203], v[0:3]
	s_add_i32 s49, 0, 0x18000
	v_add_u32_e32 v140, s49, v189
	s_barrier
	ds_read_b128 v[128:131], v140
	ds_read_b128 v[132:135], v140 offset:1024
	ds_read_b128 v[136:139], v140 offset:2048
	ds_read_b128 v[140:143], v140 offset:3072
	s_add_u32 s26, s26, 0x100000
	s_addc_u32 s27, s27, 0
	s_mov_b32 m0, s35
	v_lshl_add_u64 v[204:205], s[26:27], 0, v[154:155]
	ds_read_b128 v[144:147], v192 offset:32768
	ds_read_b128 v[148:151], v192 offset:33792
	ds_read_b128 v[170:173], v192 offset:34816
	ds_read_b128 v[174:177], v192 offset:35840
	ds_read_b128 v[178:181], v192 offset:36864
	ds_read_b128 v[182:185], v192 offset:37888
	ds_read_b128 v[196:199], v192 offset:38912
	ds_read_b128 v[200:203], v192 offset:39936
	global_load_lds_dwordx4 v[204:205], off
	v_lshl_add_u64 v[204:205], s[26:27], 0, v[158:159]
	s_mov_b32 m0, s36
	s_nop 0
	global_load_lds_dwordx4 v[204:205], off
	s_waitcnt lgkmcnt(8)
	s_barrier
; #define PG8_STAGE(bufoff, gbase, voff) do { _Pragma("unroll") for (int _i = 0; _i < 2; ++_i) \
;         __builtin_amdgcn_global_load_lds((const unsigned*)((const char*)(gbase) + (voff)[_i]), (LAS unsigned*)(lds + (bufoff) + ldsw + _i * 8192), 16, 0, 0); } while (0)
; #define PG8_LDA(dst, b, h) do { _Pragma("unroll") for (int m = 0; m < 4; ++m) _Pragma("unroll") for (int k = 0; k < 2; ++k) dst[m][k] = *(const LAS bf16x8*)(lds + PG8_SA(b, h) + aoff + m * 2048 + k * 1024); } while (0)
; #define PG8_LDB(dst, b, h) do { _Pragma("unroll") for (int n = 0; n < 2; ++n) _Pragma("unroll") for (int k = 0; k < 2; ++k) dst[n][k] = *(const LAS bf16x8*)(lds + PG8_SB(b, h) + boff + n * 2048 + k * 1024); } while (0)
; #define PG8_MMA(ai, bj, At, Bt) do { __builtin_amdgcn_s_setprio(1); _Pragma("unroll") for (int m = 0; m < 4; ++m) _Pragma("unroll") for (int n = 0; n < 2; ++n) _Pragma("unroll") for (int k = 0; k < 2; ++k) \
;         acc[ai][bj][m][n] = __builtin_amdgcn_mfma_f32_16x16x32_bf16(Bt[n][k], At[m][k], acc[ai][bj][m][n], 0, 0, 0); __builtin_amdgcn_s_setprio(0); } while (0)
; #define PG8_WAIT_L(n) asm volatile("s_waitcnt lgkmcnt(" #n ")" ::: "memory")
; #define PG8_BAR __builtin_amdgcn_s_barrier()
; #define PG8_SCHED __builtin_amdgcn_sched_barrier(0)
; template <class Epi>
; __device__ __forceinline__ void gemm_phase(LAS unsigned char* lds, const Gemm g, const StaticOrder& S, const Epi& E) {
;     ...
;             PG8_WAIT_L(8); PG8_BAR; PG8_WAIT_L(0); PG8_MMA(0, 0, At, B0); PG8_BAR; PG8_SCHED;
;             PG8_LDB(B1, 1, 1); PG8_STAGE(PG8_SB(1, 0), b3, voffB);
;             PG8_BAR; PG8_WAIT_L(0); PG8_MMA(0, 1, At, B1); PG8_BAR;
;             PG8_LDA(At, 1, 1); PG8_STAGE(PG8_SA(1, 0), a3, voffA);
;             PG8_BAR; PG8_WAIT_L(0); PG8_MMA(1, 0, At, B0); PG8_BAR; PG8_SCHED;
;             PG8_STAGE(PG8_SB(1, 1), b3 + hstepB, voffB);
	s_waitcnt lgkmcnt(7)
	v_mfma_f32_16x16x32_bf16 v[124:127], v[128:131], v[144:147], v[124:127]
	v_mfma_f32_16x16x32_bf16 v[120:123], v[136:139], v[144:147], v[120:123]
	s_waitcnt lgkmcnt(5)
	v_mfma_f32_16x16x32_bf16 v[108:111], v[128:131], v[170:173], v[108:111]
	v_mfma_f32_16x16x32_bf16 v[104:107], v[136:139], v[170:173], v[104:107]
	s_waitcnt lgkmcnt(3)
	v_mfma_f32_16x16x32_bf16 v[92:95], v[128:131], v[178:181], v[92:95]
	v_mfma_f32_16x16x32_bf16 v[88:91], v[136:139], v[178:181], v[88:91]
	s_waitcnt lgkmcnt(1)
	v_mfma_f32_16x16x32_bf16 v[76:79], v[128:131], v[196:199], v[76:79]
	v_mfma_f32_16x16x32_bf16 v[72:75], v[136:139], v[196:199], v[72:75]
	v_mfma_f32_16x16x32_bf16 v[124:127], v[132:135], v[148:151], v[124:127]
	v_mfma_f32_16x16x32_bf16 v[120:123], v[140:143], v[148:151], v[120:123]
	v_mfma_f32_16x16x32_bf16 v[108:111], v[132:135], v[174:177], v[108:111]
	v_mfma_f32_16x16x32_bf16 v[104:107], v[140:143], v[174:177], v[104:107]
	v_mfma_f32_16x16x32_bf16 v[92:95], v[132:135], v[182:185], v[92:95]
	v_mfma_f32_16x16x32_bf16 v[88:91], v[140:143], v[182:185], v[88:91]
	s_waitcnt lgkmcnt(0)
	v_mfma_f32_16x16x32_bf16 v[76:79], v[132:135], v[200:203], v[76:79]
	v_mfma_f32_16x16x32_bf16 v[72:75], v[140:143], v[200:203], v[72:75]
	s_barrier
	s_add_i32 s26, 0, 0x1c000
	s_add_i32 s27, s49, s31
	v_add_u32_e32 v195, s26, v189
	v_lshl_add_u64 v[186:187], v[186:187], 0, s[12:13]
	s_mov_b32 m0, s27
	ds_read_b128 v[204:207], v195
	ds_read_b128 v[208:211], v195 offset:1024
	ds_read_b128 v[212:215], v195 offset:2048
	ds_read_b128 v[216:219], v195 offset:3072
	global_load_lds_dwordx4 v[186:187], off
	v_lshl_add_u64 v[186:187], v[220:221], 0, s[12:13]
	s_add_i32 m0, s27, 0x2000
	s_nop 0
	global_load_lds_dwordx4 v[186:187], off
	s_barrier
	s_waitcnt lgkmcnt(3)
	v_mfma_f32_16x16x32_bf16 v[116:119], v[204:207], v[144:147], v[116:119]
	s_waitcnt lgkmcnt(1)
	v_mfma_f32_16x16x32_bf16 v[112:115], v[212:215], v[144:147], v[112:115]
	v_mfma_f32_16x16x32_bf16 v[100:103], v[204:207], v[170:173], v[100:103]
	v_mfma_f32_16x16x32_bf16 v[96:99], v[212:215], v[170:173], v[96:99]
	v_mfma_f32_16x16x32_bf16 v[84:87], v[204:207], v[178:181], v[84:87]
	v_mfma_f32_16x16x32_bf16 v[80:83], v[212:215], v[178:181], v[80:83]
	v_mfma_f32_16x16x32_bf16 v[68:71], v[204:207], v[196:199], v[68:71]
	v_mfma_f32_16x16x32_bf16 v[64:67], v[212:215], v[196:199], v[64:67]
	v_mfma_f32_16x16x32_bf16 v[116:119], v[208:211], v[148:151], v[116:119]
	s_waitcnt lgkmcnt(0)
	v_mfma_f32_16x16x32_bf16 v[112:115], v[216:219], v[148:151], v[112:115]
	v_mfma_f32_16x16x32_bf16 v[100:103], v[208:211], v[174:177], v[100:103]
	v_mfma_f32_16x16x32_bf16 v[96:99], v[216:219], v[174:177], v[96:99]
	v_mfma_f32_16x16x32_bf16 v[84:87], v[208:211], v[182:185], v[84:87]
	v_mfma_f32_16x16x32_bf16 v[80:83], v[216:219], v[182:185], v[80:83]
	v_mfma_f32_16x16x32_bf16 v[68:71], v[208:211], v[200:203], v[68:71]
	v_mfma_f32_16x16x32_bf16 v[64:67], v[216:219], v[200:203], v[64:67]
	s_mov_b32 m0, s38
	v_lshl_add_u64 v[186:187], v[222:223], 0, s[12:13]
	s_barrier
	ds_read_b128 v[144:147], v192 offset:49152
	ds_read_b128 v[148:151], v192 offset:50176
	ds_read_b128 v[170:173], v192 offset:51200
	ds_read_b128 v[174:177], v192 offset:52224
	ds_read_b128 v[178:181], v192 offset:53248
	ds_read_b128 v[182:185], v192 offset:54272
	ds_read_b128 v[196:199], v192 offset:55296
	ds_read_b128 v[200:203], v192 offset:56320
	global_load_lds_dwordx4 v[186:187], off
	v_lshl_add_u64 v[186:187], v[224:225], 0, s[12:13]
	s_mov_b32 m0, s39
	s_nop 0
	global_load_lds_dwordx4 v[186:187], off
	s_barrier
	s_waitcnt lgkmcnt(7)
	v_mfma_f32_16x16x32_bf16 v[60:63], v[128:131], v[144:147], v[60:63]
	v_mfma_f32_16x16x32_bf16 v[56:59], v[136:139], v[144:147], v[56:59]
	s_waitcnt lgkmcnt(5)
	v_mfma_f32_16x16x32_bf16 v[44:47], v[128:131], v[170:173], v[44:47]
	v_mfma_f32_16x16x32_bf16 v[40:43], v[136:139], v[170:173], v[40:43]
	s_waitcnt lgkmcnt(3)
	v_mfma_f32_16x16x32_bf16 v[28:31], v[128:131], v[178:181], v[28:31]
	v_mfma_f32_16x16x32_bf16 v[24:27], v[136:139], v[178:181], v[24:27]
	s_waitcnt lgkmcnt(1)
	v_mfma_f32_16x16x32_bf16 v[12:15], v[128:131], v[196:199], v[12:15]
	v_mfma_f32_16x16x32_bf16 v[8:11], v[136:139], v[196:199], v[8:11]
	v_mfma_f32_16x16x32_bf16 v[60:63], v[132:135], v[148:151], v[60:63]
	v_mfma_f32_16x16x32_bf16 v[56:59], v[140:143], v[148:151], v[56:59]
	v_mfma_f32_16x16x32_bf16 v[44:47], v[132:135], v[174:177], v[44:47]
	v_mfma_f32_16x16x32_bf16 v[40:43], v[140:143], v[174:177], v[40:43]
	v_mfma_f32_16x16x32_bf16 v[28:31], v[132:135], v[182:185], v[28:31]
	v_mfma_f32_16x16x32_bf16 v[24:27], v[140:143], v[182:185], v[24:27]
	s_waitcnt lgkmcnt(0)
	v_mfma_f32_16x16x32_bf16 v[12:15], v[132:135], v[200:203], v[12:15]
	v_mfma_f32_16x16x32_bf16 v[8:11], v[140:143], v[200:203], v[8:11]
	s_barrier
	s_add_u32 s24, s24, 0x100080
	s_addc_u32 s25, s25, 0
	s_add_i32 s26, s26, s31
	v_lshl_add_u64 v[128:129], s[24:25], 0, v[156:157]
	s_mov_b32 m0, s26
	s_nop 0
	global_load_lds_dwordx4 v[128:129], off
	v_lshl_add_u64 v[128:129], s[24:25], 0, v[160:161]
	s_add_i32 m0, s26, 0x2000
	s_nop 0
	global_load_lds_dwordx4 v[128:129], off
	s_waitcnt vmcnt(6)
	s_barrier
; __device__ __forceinline__ unsigned pk2(float lo, float hi) { const f32x2 v = (f32x2){lo, hi}; const bf16x2_t b = __builtin_convertvector(v, bf16x2_t); return __builtin_bit_cast(unsigned, b); }
; __device__ __forceinline__ void unpack8(const u32x4 v, float* f) { f[0] = bf_lo(v.x); f[1] = bf_hi(v.x); f[2] = bf_lo(v.y); f[3] = bf_hi(v.y); f[4] = bf_lo(v.z); f[5] = bf_hi(v.z); f[6] = bf_lo(v.w); f[7] = bf_hi(v.w); }
; #define PG8_WAIT_V(n) asm volatile("s_waitcnt vmcnt(" #n ")" ::: "memory")
; #define PG8_BAR __builtin_amdgcn_s_barrier()
;     __device__ __forceinline__ void operator()(const f32x4 (&acc)[2][2][4][2], const Unit& u, int wr, int wc, int fr, int fq, const float (&)[8]) const {
;         const int row0 = u.pm * BM + wr * 64 + fr, col0 = u.pn * BM + wc * 32 + 8 * fq;
; #pragma unroll
;         for (int ai = 0; ai < 2; ++ai) {
;             u32x4 bv[4][2];
; #pragma unroll
;             for (int m = 0; m < 4; ++m)
; #pragma unroll
;                 for (int bj = 0; bj < 2; ++bj) bv[m][bj] = *(const u32x4*)(xb + (size_t)(row0 + ai * HALF + m * 16) * DM + col0 + bj * HALF);
; #pragma unroll
;             for (int m = 0; m < 4; ++m) { const int row = row0 + ai * HALF + m * 16; const size_t ro = (size_t)row * DM + col0; float s = 0.f;
; #pragma unroll
;                 for (int bj = 0; bj < 2; ++bj) { float b8[8]; unpack8(bv[m][bj], b8);
;                     const f32x4 v0 = (f32x4){b8[0], b8[1], b8[2], b8[3]} + acc[ai][bj][m][0], v1 = (f32x4){b8[4], b8[5], b8[6], b8[7]} + acc[ai][bj][m][1];
;                     s += v0[0] * v0[0] + v0[1] * v0[1] + v0[2] * v0[2] + v0[3] * v0[3] + v1[0] * v1[0] + v1[1] * v1[1] + v1[2] * v1[2] + v1[3] * v1[3];
;                     if (LAST) { *(f32x4*)(out + ro + bj * HALF) = v0; *(f32x4*)(out + ro + bj * HALF + 4) = v1; }
;                     else { u32x4 w; w.x = pk2(v0[0], v0[1]); w.y = pk2(v0[2], v0[3]); w.z = pk2(v1[0], v1[1]); w.w = pk2(v1[2], v1[3]); *(u32x4*)(xb + ro + bj * HALF) = w; } }
;                 s += __shfl_xor(s, 16); s += __shfl_xor(s, 32);
;                 if (fq == 0) ss[(size_t)row * 16 + u.pn * 4 + wc] = s; }
; template <class Epi>
; __device__ __forceinline__ void gemm_phase(LAS unsigned char* lds, const Gemm g, const StaticOrder& S, const Epi& E) {
;     ...
;             PG8_WAIT_V(6); PG8_BAR; PG8_MMA(1, 1, At, B1); PG8_BAR;
;         }
	v_mfma_f32_16x16x32_bf16 v[52:55], v[204:207], v[144:147], v[52:55]
	v_mfma_f32_16x16x32_bf16 v[48:51], v[212:215], v[144:147], v[48:51]
	v_mfma_f32_16x16x32_bf16 v[36:39], v[204:207], v[170:173], v[36:39]
	v_mfma_f32_16x16x32_bf16 v[32:35], v[212:215], v[170:173], v[32:35]
	v_mfma_f32_16x16x32_bf16 v[20:23], v[204:207], v[178:181], v[20:23]
	v_mfma_f32_16x16x32_bf16 v[16:19], v[212:215], v[178:181], v[16:19]
	v_mfma_f32_16x16x32_bf16 v[4:7], v[204:207], v[196:199], v[4:7]
	v_mfma_f32_16x16x32_bf16 v[0:3], v[212:215], v[196:199], v[0:3]
	v_mfma_f32_16x16x32_bf16 v[52:55], v[208:211], v[148:151], v[52:55]
	v_mfma_f32_16x16x32_bf16 v[48:51], v[216:219], v[148:151], v[48:51]
	v_mfma_f32_16x16x32_bf16 v[36:39], v[208:211], v[174:177], v[36:39]
	v_mfma_f32_16x16x32_bf16 v[32:35], v[216:219], v[174:177], v[32:35]
	v_mfma_f32_16x16x32_bf16 v[20:23], v[208:211], v[182:185], v[20:23]
	v_mfma_f32_16x16x32_bf16 v[16:19], v[216:219], v[182:185], v[16:19]
	v_mfma_f32_16x16x32_bf16 v[4:7], v[208:211], v[200:203], v[4:7]
	v_mfma_f32_16x16x32_bf16 v[0:3], v[216:219], v[200:203], v[0:3]
	s_add_i32 s48, s48, 2
	s_add_u32 s22, s22, 0x100
	s_addc_u32 s23, s23, 0
	s_add_u32 s46, s46, 0x100
	s_addc_u32 s47, s47, 0
	s_cmp_gt_u32 s48, 61
	s_barrier
	s_cbranch_scc0 .LBB0_844
	v_lshl_or_b32 v170, s6, 8, v190
	v_lshl_add_u32 v172, s8, 8, v188
	v_ashrrev_i32_e32 v171, 31, v170
	v_lshlrev_b64 v[206:207], 1, v[170:171]
	v_ashrrev_i32_e32 v173, 31, v172
	v_lshl_add_u64 v[174:175], s[76:77], 0, v[206:207]
	v_lshlrev_b64 v[208:209], 11, v[172:173]
	v_lshl_add_u64 v[128:129], v[174:175], 0, v[208:209]
	global_load_dwordx4 v[198:201], v[128:129], off
	global_load_dwordx4 v[202:205], v[128:129], off offset:256
	v_or_b32_e32 v184, 16, v172
	v_or_b32_e32 v180, 32, v172
	v_or_b32_e32 v176, 48, v172
	v_ashrrev_i32_e32 v185, 31, v184
	v_ashrrev_i32_e32 v181, 31, v180
	v_ashrrev_i32_e32 v177, 31, v176
	v_lshlrev_b64 v[186:187], 11, v[184:185]
	v_lshlrev_b64 v[182:183], 11, v[180:181]
	v_lshlrev_b64 v[178:179], 11, v[176:177]
	v_lshl_add_u64 v[128:129], v[174:175], 0, v[186:187]
	v_lshl_add_u64 v[130:131], v[174:175], 0, v[182:183]
	v_lshl_add_u64 v[196:197], v[174:175], 0, v[178:179]
	global_load_dwordx4 v[148:151], v[128:129], off
	global_load_dwordx4 v[144:147], v[128:129], off offset:256
	global_load_dwordx4 v[140:143], v[130:131], off
	global_load_dwordx4 v[136:139], v[130:131], off offset:256
	global_load_dwordx4 v[132:135], v[196:197], off
	s_nop 0
	global_load_dwordx4 v[128:131], v[196:197], off offset:256
	v_add_u32_e32 v218, 0x80, v172
	v_ashrrev_i32_e32 v219, 31, v218
	v_lshlrev_b64 v[218:219], 11, v[218:219]
	v_lshl_add_u64 v[218:219], v[174:175], 0, v[218:219]
	global_load_dwordx4 v[220:223], v[218:219], off
	global_load_dwordx4 v[224:227], v[218:219], off offset:256
	v_add_u32_e32 v218, 0x90, v172
	v_ashrrev_i32_e32 v219, 31, v218
	v_lshlrev_b64 v[218:219], 11, v[218:219]
	v_lshl_add_u64 v[218:219], v[174:175], 0, v[218:219]
	global_load_dwordx4 v[228:231], v[218:219], off
	global_load_dwordx4 v[232:235], v[218:219], off offset:256
	v_add_u32_e32 v218, 0xa0, v172
	v_ashrrev_i32_e32 v219, 31, v218
	v_lshlrev_b64 v[218:219], 11, v[218:219]
	v_lshl_add_u64 v[218:219], v[174:175], 0, v[218:219]
	global_load_dwordx4 v[236:239], v[218:219], off
	global_load_dwordx4 v[240:243], v[218:219], off offset:256
	v_add_u32_e32 v218, 0xb0, v172
	v_ashrrev_i32_e32 v219, 31, v218
	v_lshlrev_b64 v[218:219], 11, v[218:219]
	v_lshl_add_u64 v[218:219], v[174:175], 0, v[218:219]
	global_load_dwordx4 v[244:247], v[218:219], off
	global_load_dwordx4 v[252:255], v[218:219], off offset:256
	v_and_b32_e32 v196, 64, v194
	v_xor_b32_e32 v195, 16, v194
	v_add_u32_e32 v196, 64, v196
	v_xor_b32_e32 v197, 32, v194
	v_cmp_lt_i32_e32 vcc, v195, v196
	s_waitcnt vmcnt(15)
	v_lshlrev_b32_e32 v210, 16, v198
	v_cndmask_b32_e32 v195, v194, v195, vcc
	v_cmp_lt_i32_e32 vcc, v197, v196
	v_and_b32_e32 v211, 0xffff0000, v198
	s_waitcnt vmcnt(14)
	v_lshlrev_b32_e32 v214, 16, v202
	v_and_b32_e32 v215, 0xffff0000, v202
	v_cndmask_b32_e32 v197, v194, v197, vcc
	v_lshlrev_b32_e32 v212, 16, v200
	v_and_b32_e32 v213, 0xffff0000, v200
	v_lshlrev_b32_e32 v200, 16, v201
	v_and_b32_e32 v201, 0xffff0000, v201
	v_lshlrev_b32_e32 v216, 16, v204
	v_and_b32_e32 v217, 0xffff0000, v204
	v_pk_add_f32 v[124:125], v[124:125], v[210:211]
	v_pk_add_f32 v[116:117], v[116:117], v[214:215]
	v_lshlrev_b32_e32 v196, 2, v195
	v_lshlrev_b32_e32 v195, 2, v197
	v_lshlrev_b32_e32 v198, 16, v199
	v_and_b32_e32 v199, 0xffff0000, v199
	v_lshlrev_b32_e32 v202, 16, v203
	v_and_b32_e32 v203, 0xffff0000, v203
	v_pk_add_f32 v[122:123], v[122:123], v[200:201]
	v_pk_add_f32 v[200:201], v[112:113], v[216:217]
	v_mul_f32_e32 v197, v125, v125
	v_cvt_pk_bf16_f32 v112, v124, v125
	v_mul_f32_e32 v125, v117, v117
	v_pk_add_f32 v[126:127], v[126:127], v[198:199]
	v_pk_add_f32 v[118:119], v[118:119], v[202:203]
	v_fmac_f32_e32 v197, v124, v124
	v_fmac_f32_e32 v125, v116, v116
	v_fmac_f32_e32 v197, v126, v126
	v_fmac_f32_e32 v125, v118, v118
	v_pk_add_f32 v[120:121], v[120:121], v[212:213]
	v_fmac_f32_e32 v197, v127, v127
	v_fmac_f32_e32 v125, v119, v119
	v_lshlrev_b32_e32 v204, 16, v205
	v_and_b32_e32 v205, 0xffff0000, v205
	v_fmac_f32_e32 v197, v120, v120
	v_fmac_f32_e32 v125, v200, v200
	v_pk_add_f32 v[198:199], v[114:115], v[204:205]
	v_fmac_f32_e32 v197, v121, v121
	v_fmac_f32_e32 v125, v201, v201
	v_fmac_f32_e32 v197, v122, v122
	v_fmac_f32_e32 v125, v198, v198
	v_fmac_f32_e32 v197, v123, v123
	v_fmac_f32_e32 v125, v199, v199
	v_cvt_pk_bf16_f32 v115, v122, v123
	v_add_f32_e32 v122, v197, v125
	ds_bpermute_b32 v123, v196, v122
	v_cvt_pk_bf16_f32 v114, v120, v121
	v_lshl_add_u64 v[120:121], s[76:77], 0, v[208:209]
	v_cvt_pk_bf16_f32 v113, v126, v127
	v_lshl_add_u64 v[120:121], v[120:121], 0, v[206:207]
	global_store_dwordx4 v[120:121], v[112:115], off
	s_waitcnt lgkmcnt(0)
	s_nop 0
	v_add_f32_e32 v112, v122, v123
	ds_bpermute_b32 v113, v195, v112
	v_cvt_pk_bf16_f32 v114, v116, v117
	v_cvt_pk_bf16_f32 v115, v118, v119
	v_cvt_pk_bf16_f32 v116, v200, v201
	v_cvt_pk_bf16_f32 v117, v198, v199
	global_store_dwordx4 v[120:121], v[114:117], off offset:256
	s_and_saveexec_b64 s[22:23], s[0:1]
	s_cbranch_execz .LBB0_847
	s_waitcnt lgkmcnt(0)
	v_add_f32_e32 v114, v112, v113
	s_lshl_b32 s24, s6, 2
	v_lshlrev_b64 v[112:113], 6, v[172:173]
	s_ashr_i32 s25, s24, 31
	v_lshl_add_u64 v[112:113], s[10:11], 0, v[112:113]
	v_lshl_add_u64 v[112:113], s[24:25], 2, v[112:113]
	s_lshl_b32 s8, s37, 2
	v_lshl_add_u64 v[112:113], v[112:113], 0, s[8:9]
	global_store_dword v[112:113], v114, off

; #define PG8_STAGE(bufoff, gbase, voff) do { _Pragma("unroll") for (int _i = 0; _i < 2; ++_i) \
;         __builtin_amdgcn_global_load_lds((const unsigned*)((const char*)(gbase) + (voff)[_i]), (LAS unsigned*)(lds + (bufoff) + ldsw + _i * 8192), 16, 0, 0); } while (0)
; #define PG8_LDA(dst, b, h) do { _Pragma("unroll") for (int m = 0; m < 4; ++m) _Pragma("unroll") for (int k = 0; k < 2; ++k) dst[m][k] = *(const LAS bf16x8*)(lds + PG8_SA(b, h) + aoff + m * 2048 + k * 1024); } while (0)
; #define PG8_LDB(dst, b, h) do { _Pragma("unroll") for (int n = 0; n < 2; ++n) _Pragma("unroll") for (int k = 0; k < 2; ++k) dst[n][k] = *(const LAS bf16x8*)(lds + PG8_SB(b, h) + boff + n * 2048 + k * 1024); } while (0)
; #define PG8_MMA(ai, bj, At, Bt) do { __builtin_amdgcn_s_setprio(1); _Pragma("unroll") for (int m = 0; m < 4; ++m) _Pragma("unroll") for (int n = 0; n < 2; ++n) _Pragma("unroll") for (int k = 0; k < 2; ++k) \
;         acc[ai][bj][m][n] = __builtin_amdgcn_mfma_f32_16x16x32_bf16(Bt[n][k], At[m][k], acc[ai][bj][m][n], 0, 0, 0); __builtin_amdgcn_s_setprio(0); } while (0)
; #define PG8_BAR __builtin_amdgcn_s_barrier()
; template <class Epi>
; __device__ __forceinline__ void gemm_phase(LAS unsigned char* lds, const Gemm g, const StaticOrder& S, const Epi& E) {
;     ...
;         const bool has_next = S.next(ui + 1, nxt);
;         const char* nA = has_next ? (const char*)g.A + (size_t)nxt.pm * tstepA : cA; const char* nB = has_next ? (const char*)g.Bt + (size_t)nxt.pn * tstepB : cB;
;         for (int t = 0; t < nt; t += 2) {
;             const bool last = (t == nt - 2);
;             const char* a1 = cA + (size_t)(t + 1) * kstep;
;             const char* a2 = last ? nA : cA + (size_t)(t + 2) * kstep; const char* b2 = last ? nB : cB + (size_t)(t + 2) * kstep;
;             const char* a3 = a2 + kstep; const char* b3 = b2 + kstep;
;             if (last) E.pre(cur, wr, fr, epre);
;             PG8_LDB(B0, 0, 0); PG8_SCHED; PG8_LDA(At, 0, 0); PG8_STAGE(PG8_SA(1, 1), a1 + hstepA, voffA);
;             PG8_WAIT_L(8); PG8_BAR; PG8_WAIT_L(0); PG8_MMA(0, 0, At, B0); PG8_BAR; PG8_SCHED;
;             PG8_LDB(B1, 0, 1); PG8_STAGE(PG8_SB(0, 0), b2, voffB);
;             PG8_BAR; PG8_WAIT_L(0); PG8_MMA(0, 1, At, B1); PG8_BAR;
;             PG8_LDA(At, 0, 1); PG8_STAGE(PG8_SA(0, 0), a2, voffA);
;             PG8_BAR; PG8_WAIT_L(0); PG8_MMA(1, 0, At, B0); PG8_BAR; PG8_SCHED;
.LBB0_921:
	s_ashr_i32 s13, s12, 31
	v_cmp_lt_i64_e32 vcc, s[14:15], v[142:143]
	s_lshl_b64 s[14:15], s[12:13], 19
	s_add_u32 s14, s76, s14
	s_addc_u32 s15, s77, s15
	s_and_b64 s[16:17], vcc, exec
	s_cselect_b32 s13, s15, s21
	s_cselect_b32 s43, s14, s20
	s_ashr_i32 s11, s10, 31
	s_lshl_b64 s[16:17], s[10:11], 19
	s_add_u32 s16, s9, s16
	s_addc_u32 s17, s26, s17
	s_and_b64 s[24:25], vcc, exec
	s_cselect_b32 s11, s17, s23
	s_cselect_b32 s44, s16, s22
	s_add_u32 s20, s20, 0x40080
	s_addc_u32 s21, s21, 0
	s_add_u32 s45, s22, 0x100
	s_addc_u32 s46, s23, 0
	s_mov_b32 s47, -2
	ds_read_b128 v[146:149], v173
	ds_read_b128 v[154:157], v173 offset:1024
	ds_read_b128 v[158:161], v173 offset:2048
	ds_read_b128 v[162:165], v173 offset:3072
	s_add_u32 s22, s20, 0xfffc0080
	s_addc_u32 s23, s21, -1
	s_cmp_eq_u32 s47, 12
	s_cselect_b32 s25, s13, s23
	s_cselect_b32 s24, s43, s22
	s_cselect_b32 s23, s11, s46
	s_cselect_b32 s22, s44, s45
	v_lshl_add_u64 v[150:151], s[20:21], 0, v[138:139]
	s_add_i32 m0, s19, 0xc000
	ds_read_b128 v[166:169], v174
	ds_read_b128 v[178:181], v174 offset:1024
	ds_read_b128 v[182:185], v174 offset:2048
	ds_read_b128 v[186:189], v174 offset:3072
	ds_read_b128 v[190:193], v174 offset:4096
	ds_read_b128 v[194:197], v174 offset:5120
	ds_read_b128 v[198:201], v174 offset:6144
	ds_read_b128 v[202:205], v174 offset:7168
	global_load_lds_dwordx4 v[150:151], off
	v_lshl_add_u64 v[150:151], s[20:21], 0, v[140:141]
	s_add_i32 m0, s19, 0xe000
	s_nop 0
	global_load_lds_dwordx4 v[150:151], off
	s_waitcnt lgkmcnt(8)
	s_barrier
	s_waitcnt lgkmcnt(7)
	v_mfma_f32_16x16x32_bf16 v[124:127], v[146:149], v[166:169], 0
	v_mfma_f32_16x16x32_bf16 v[120:123], v[158:161], v[166:169], 0
	s_waitcnt lgkmcnt(5)
	v_mfma_f32_16x16x32_bf16 v[112:115], v[146:149], v[182:185], 0
	v_mfma_f32_16x16x32_bf16 v[104:107], v[158:161], v[182:185], 0
	s_waitcnt lgkmcnt(3)
	v_mfma_f32_16x16x32_bf16 v[92:95], v[146:149], v[190:193], 0
	v_mfma_f32_16x16x32_bf16 v[88:91], v[158:161], v[190:193], 0
	s_waitcnt lgkmcnt(1)
	v_mfma_f32_16x16x32_bf16 v[80:83], v[146:149], v[198:201], 0
	v_mfma_f32_16x16x32_bf16 v[72:75], v[158:161], v[198:201], 0
	v_mfma_f32_16x16x32_bf16 v[124:127], v[154:157], v[178:181], v[124:127]
	v_mfma_f32_16x16x32_bf16 v[120:123], v[162:165], v[178:181], v[120:123]
	v_mfma_f32_16x16x32_bf16 v[112:115], v[154:157], v[186:189], v[112:115]
	v_mfma_f32_16x16x32_bf16 v[104:107], v[162:165], v[186:189], v[104:107]
	v_mfma_f32_16x16x32_bf16 v[92:95], v[154:157], v[194:197], v[92:95]
	v_mfma_f32_16x16x32_bf16 v[88:91], v[162:165], v[194:197], v[88:91]
	s_waitcnt lgkmcnt(0)
	v_mfma_f32_16x16x32_bf16 v[80:83], v[154:157], v[202:205], v[80:83]
	v_mfma_f32_16x16x32_bf16 v[72:75], v[162:165], v[202:205], v[72:75]
	s_barrier
	s_add_i32 s48, s38, s27
	v_lshl_add_u64 v[150:151], s[22:23], 0, v[132:133]
	s_mov_b32 m0, s48
	ds_read_b128 v[206:209], v175
	ds_read_b128 v[210:213], v175 offset:1024
	ds_read_b128 v[214:217], v175 offset:2048
	ds_read_b128 v[218:221], v175 offset:3072
	global_load_lds_dwordx4 v[150:151], off
	v_lshl_add_u64 v[222:223], s[22:23], 0, v[128:129]
	s_add_i32 m0, s48, 0x2000
	s_nop 0
	global_load_lds_dwordx4 v[222:223], off
	s_barrier
	s_waitcnt lgkmcnt(3)
	v_mfma_f32_16x16x32_bf16 v[116:119], v[206:209], v[166:169], 0
	s_waitcnt lgkmcnt(1)
	v_mfma_f32_16x16x32_bf16 v[108:111], v[214:217], v[166:169], 0
	v_mfma_f32_16x16x32_bf16 v[100:103], v[206:209], v[182:185], 0
	v_mfma_f32_16x16x32_bf16 v[96:99], v[214:217], v[182:185], 0
	v_mfma_f32_16x16x32_bf16 v[84:87], v[206:209], v[190:193], 0
	v_mfma_f32_16x16x32_bf16 v[76:79], v[214:217], v[190:193], 0
	v_mfma_f32_16x16x32_bf16 v[68:71], v[206:209], v[198:201], 0
	v_mfma_f32_16x16x32_bf16 v[64:67], v[214:217], v[198:201], 0
	v_mfma_f32_16x16x32_bf16 v[116:119], v[210:213], v[178:181], v[116:119]
	s_waitcnt lgkmcnt(0)
	v_mfma_f32_16x16x32_bf16 v[108:111], v[218:221], v[178:181], v[108:111]
	v_mfma_f32_16x16x32_bf16 v[100:103], v[210:213], v[186:189], v[100:103]
	v_mfma_f32_16x16x32_bf16 v[96:99], v[218:221], v[186:189], v[96:99]
	v_mfma_f32_16x16x32_bf16 v[84:87], v[210:213], v[194:197], v[84:87]
	v_mfma_f32_16x16x32_bf16 v[76:79], v[218:221], v[194:197], v[76:79]
	v_mfma_f32_16x16x32_bf16 v[68:71], v[210:213], v[202:205], v[68:71]
	v_mfma_f32_16x16x32_bf16 v[64:67], v[218:221], v[202:205], v[64:67]
	s_mov_b32 m0, s19
	v_lshl_add_u64 v[224:225], s[24:25], 0, v[134:135]
	s_barrier
	ds_read_b128 v[166:169], v174 offset:16384
	ds_read_b128 v[178:181], v174 offset:17408
	ds_read_b128 v[182:185], v174 offset:18432
	ds_read_b128 v[186:189], v174 offset:19456
	ds_read_b128 v[190:193], v174 offset:20480
	ds_read_b128 v[194:197], v174 offset:21504
	ds_read_b128 v[198:201], v174 offset:22528
	ds_read_b128 v[202:205], v174 offset:23552
	global_load_lds_dwordx4 v[224:225], off
	v_lshl_add_u64 v[226:227], s[24:25], 0, v[130:131]
	s_mov_b32 m0, s30
	s_nop 0
	global_load_lds_dwordx4 v[226:227], off
	s_barrier
	s_waitcnt lgkmcnt(7)
	v_mfma_f32_16x16x32_bf16 v[60:63], v[146:149], v[166:169], 0
	v_mfma_f32_16x16x32_bf16 v[56:59], v[158:161], v[166:169], 0
	s_waitcnt lgkmcnt(5)
	v_mfma_f32_16x16x32_bf16 v[48:51], v[146:149], v[182:185], 0
	v_mfma_f32_16x16x32_bf16 v[40:43], v[158:161], v[182:185], 0
	s_waitcnt lgkmcnt(3)
	v_mfma_f32_16x16x32_bf16 v[32:35], v[146:149], v[190:193], 0
	v_mfma_f32_16x16x32_bf16 v[24:27], v[158:161], v[190:193], 0
	s_waitcnt lgkmcnt(1)
	v_mfma_f32_16x16x32_bf16 v[16:19], v[146:149], v[198:201], 0
	v_mfma_f32_16x16x32_bf16 v[8:11], v[158:161], v[198:201], 0
	v_mfma_f32_16x16x32_bf16 v[60:63], v[154:157], v[178:181], v[60:63]
	v_mfma_f32_16x16x32_bf16 v[56:59], v[162:165], v[178:181], v[56:59]
	v_mfma_f32_16x16x32_bf16 v[48:51], v[154:157], v[186:189], v[48:51]
	v_mfma_f32_16x16x32_bf16 v[40:43], v[162:165], v[186:189], v[40:43]
	v_mfma_f32_16x16x32_bf16 v[32:35], v[154:157], v[194:197], v[32:35]
	v_mfma_f32_16x16x32_bf16 v[24:27], v[162:165], v[194:197], v[24:27]
	s_waitcnt lgkmcnt(0)
	v_mfma_f32_16x16x32_bf16 v[16:19], v[154:157], v[202:205], v[16:19]
	v_mfma_f32_16x16x32_bf16 v[8:11], v[162:165], v[202:205], v[8:11]
	s_barrier
; #define PG8_STAGE(bufoff, gbase, voff) do { _Pragma("unroll") for (int _i = 0; _i < 2; ++_i) \
;         __builtin_amdgcn_global_load_lds((const unsigned*)((const char*)(gbase) + (voff)[_i]), (LAS unsigned*)(lds + (bufoff) + ldsw + _i * 8192), 16, 0, 0); } while (0)
; #define PG8_LDA(dst, b, h) do { _Pragma("unroll") for (int m = 0; m < 4; ++m) _Pragma("unroll") for (int k = 0; k < 2; ++k) dst[m][k] = *(const LAS bf16x8*)(lds + PG8_SA(b, h) + aoff + m * 2048 + k * 1024); } while (0)
; #define PG8_LDB(dst, b, h) do { _Pragma("unroll") for (int n = 0; n < 2; ++n) _Pragma("unroll") for (int k = 0; k < 2; ++k) dst[n][k] = *(const LAS bf16x8*)(lds + PG8_SB(b, h) + boff + n * 2048 + k * 1024); } while (0)
; #define PG8_MMA(ai, bj, At, Bt) do { __builtin_amdgcn_s_setprio(1); _Pragma("unroll") for (int m = 0; m < 4; ++m) _Pragma("unroll") for (int n = 0; n < 2; ++n) _Pragma("unroll") for (int k = 0; k < 2; ++k) \
;         acc[ai][bj][m][n] = __builtin_amdgcn_mfma_f32_16x16x32_bf16(Bt[n][k], At[m][k], acc[ai][bj][m][n], 0, 0, 0); __builtin_amdgcn_s_setprio(0); } while (0)
; #define PG8_WAIT_V(n) asm volatile("s_waitcnt vmcnt(" #n ")" ::: "memory")
; #define PG8_WAIT_L(n) asm volatile("s_waitcnt lgkmcnt(" #n ")" ::: "memory")
; #define PG8_BAR __builtin_amdgcn_s_barrier()
; #define PG8_SCHED __builtin_amdgcn_sched_barrier(0)
; template <class Epi>
; __device__ __forceinline__ void gemm_phase(LAS unsigned char* lds, const Gemm g, const StaticOrder& S, const Epi& E) {
;     ...
;             PG8_STAGE(PG8_SB(0, 1), b2 + hstepB, voffB);
;             PG8_WAIT_V(6); PG8_BAR; PG8_MMA(1, 1, At, B1); PG8_BAR;
;             PG8_LDB(B0, 1, 0); PG8_SCHED; PG8_LDA(At, 1, 0); PG8_STAGE(PG8_SA(0, 1), a2 + hstepA, voffA);
;             PG8_WAIT_L(8); PG8_BAR; PG8_WAIT_L(0); PG8_MMA(0, 0, At, B0); PG8_BAR; PG8_SCHED;
;             PG8_LDB(B1, 1, 1); PG8_STAGE(PG8_SB(1, 0), b3, voffB);
;             PG8_BAR; PG8_WAIT_L(0); PG8_MMA(0, 1, At, B1); PG8_BAR;
;             PG8_LDA(At, 1, 1); PG8_STAGE(PG8_SA(1, 0), a3, voffA);
;             PG8_BAR; PG8_WAIT_L(0); PG8_MMA(1, 0, At, B0); PG8_BAR; PG8_SCHED;
	s_add_u32 s48, s22, 0x40000
	s_addc_u32 s49, s23, 0
	s_add_i32 s50, s39, s27
	v_lshl_add_u64 v[146:147], s[48:49], 0, v[132:133]
	s_mov_b32 m0, s50
	s_nop 0
	global_load_lds_dwordx4 v[146:147], off
	v_lshl_add_u64 v[146:147], s[48:49], 0, v[128:129]
	s_add_i32 m0, s50, 0x2000
	s_nop 0
	global_load_lds_dwordx4 v[146:147], off
	s_waitcnt vmcnt(6)
	s_barrier
	v_mfma_f32_16x16x32_bf16 v[52:55], v[206:209], v[166:169], 0
	v_mfma_f32_16x16x32_bf16 v[44:47], v[214:217], v[166:169], 0
	v_mfma_f32_16x16x32_bf16 v[36:39], v[206:209], v[182:185], 0
	v_mfma_f32_16x16x32_bf16 v[28:31], v[214:217], v[182:185], 0
	v_mfma_f32_16x16x32_bf16 v[20:23], v[206:209], v[190:193], 0
	v_mfma_f32_16x16x32_bf16 v[12:15], v[214:217], v[190:193], 0
	v_mfma_f32_16x16x32_bf16 v[4:7], v[206:209], v[198:201], 0
	v_mfma_f32_16x16x32_bf16 v[0:3], v[214:217], v[198:201], 0
	v_mfma_f32_16x16x32_bf16 v[52:55], v[210:213], v[178:181], v[52:55]
	v_mfma_f32_16x16x32_bf16 v[44:47], v[218:221], v[178:181], v[44:47]
	v_mfma_f32_16x16x32_bf16 v[36:39], v[210:213], v[186:189], v[36:39]
	v_mfma_f32_16x16x32_bf16 v[28:31], v[218:221], v[186:189], v[28:31]
	v_mfma_f32_16x16x32_bf16 v[20:23], v[210:213], v[194:197], v[20:23]
	v_mfma_f32_16x16x32_bf16 v[12:15], v[218:221], v[194:197], v[12:15]
	v_mfma_f32_16x16x32_bf16 v[4:7], v[210:213], v[202:205], v[4:7]
	v_mfma_f32_16x16x32_bf16 v[0:3], v[218:221], v[202:205], v[0:3]
	s_add_i32 s48, 0, 0x18000
	v_add_u32_e32 v162, s48, v171
	s_barrier
	ds_read_b128 v[146:149], v162
	ds_read_b128 v[154:157], v162 offset:1024
	ds_read_b128 v[158:161], v162 offset:2048
	ds_read_b128 v[162:165], v162 offset:3072
	s_add_u32 s24, s24, 0x40000
	s_addc_u32 s25, s25, 0
	s_mov_b32 m0, s31
	v_lshl_add_u64 v[206:207], s[24:25], 0, v[134:135]
	ds_read_b128 v[166:169], v174 offset:32768
	ds_read_b128 v[178:181], v174 offset:33792
	ds_read_b128 v[182:185], v174 offset:34816
	ds_read_b128 v[186:189], v174 offset:35840
	ds_read_b128 v[190:193], v174 offset:36864
	ds_read_b128 v[194:197], v174 offset:37888
	ds_read_b128 v[198:201], v174 offset:38912
	ds_read_b128 v[202:205], v174 offset:39936
	global_load_lds_dwordx4 v[206:207], off
	v_lshl_add_u64 v[206:207], s[24:25], 0, v[130:131]
	s_mov_b32 m0, s33
	s_nop 0
	global_load_lds_dwordx4 v[206:207], off
	s_waitcnt lgkmcnt(8)
	s_barrier
	s_waitcnt lgkmcnt(7)
	v_mfma_f32_16x16x32_bf16 v[124:127], v[146:149], v[166:169], v[124:127]
	v_mfma_f32_16x16x32_bf16 v[120:123], v[158:161], v[166:169], v[120:123]
	s_waitcnt lgkmcnt(5)
	v_mfma_f32_16x16x32_bf16 v[112:115], v[146:149], v[182:185], v[112:115]
	v_mfma_f32_16x16x32_bf16 v[104:107], v[158:161], v[182:185], v[104:107]
	s_waitcnt lgkmcnt(3)
	v_mfma_f32_16x16x32_bf16 v[92:95], v[146:149], v[190:193], v[92:95]
	v_mfma_f32_16x16x32_bf16 v[88:91], v[158:161], v[190:193], v[88:91]
	s_waitcnt lgkmcnt(1)
	v_mfma_f32_16x16x32_bf16 v[80:83], v[146:149], v[198:201], v[80:83]
	v_mfma_f32_16x16x32_bf16 v[72:75], v[158:161], v[198:201], v[72:75]
	v_mfma_f32_16x16x32_bf16 v[124:127], v[154:157], v[178:181], v[124:127]
	v_mfma_f32_16x16x32_bf16 v[120:123], v[162:165], v[178:181], v[120:123]
	v_mfma_f32_16x16x32_bf16 v[112:115], v[154:157], v[186:189], v[112:115]
	v_mfma_f32_16x16x32_bf16 v[104:107], v[162:165], v[186:189], v[104:107]
	v_mfma_f32_16x16x32_bf16 v[92:95], v[154:157], v[194:197], v[92:95]
	v_mfma_f32_16x16x32_bf16 v[88:91], v[162:165], v[194:197], v[88:91]
	s_waitcnt lgkmcnt(0)
	v_mfma_f32_16x16x32_bf16 v[80:83], v[154:157], v[202:205], v[80:83]
	v_mfma_f32_16x16x32_bf16 v[72:75], v[162:165], v[202:205], v[72:75]
	s_barrier
	s_add_i32 s24, 0, 0x1c000
	s_add_i32 s25, s48, s27
	v_add_u32_e32 v177, s24, v171
	v_lshl_add_u64 v[150:151], v[150:151], 0, s[4:5]
	s_mov_b32 m0, s25
	ds_read_b128 v[206:209], v177
	ds_read_b128 v[210:213], v177 offset:1024
	ds_read_b128 v[214:217], v177 offset:2048
	ds_read_b128 v[218:221], v177 offset:3072
	global_load_lds_dwordx4 v[150:151], off
	v_lshl_add_u64 v[150:151], v[222:223], 0, s[4:5]
	s_add_i32 m0, s25, 0x2000
	s_nop 0
	global_load_lds_dwordx4 v[150:151], off
	s_barrier
	s_waitcnt lgkmcnt(3)
	v_mfma_f32_16x16x32_bf16 v[116:119], v[206:209], v[166:169], v[116:119]
	s_waitcnt lgkmcnt(1)
	v_mfma_f32_16x16x32_bf16 v[108:111], v[214:217], v[166:169], v[108:111]
	v_mfma_f32_16x16x32_bf16 v[100:103], v[206:209], v[182:185], v[100:103]
	v_mfma_f32_16x16x32_bf16 v[96:99], v[214:217], v[182:185], v[96:99]
	v_mfma_f32_16x16x32_bf16 v[84:87], v[206:209], v[190:193], v[84:87]
	v_mfma_f32_16x16x32_bf16 v[76:79], v[214:217], v[190:193], v[76:79]
	v_mfma_f32_16x16x32_bf16 v[68:71], v[206:209], v[198:201], v[68:71]
	v_mfma_f32_16x16x32_bf16 v[64:67], v[214:217], v[198:201], v[64:67]
	v_mfma_f32_16x16x32_bf16 v[116:119], v[210:213], v[178:181], v[116:119]
	s_waitcnt lgkmcnt(0)
	v_mfma_f32_16x16x32_bf16 v[108:111], v[218:221], v[178:181], v[108:111]
	v_mfma_f32_16x16x32_bf16 v[100:103], v[210:213], v[186:189], v[100:103]
	v_mfma_f32_16x16x32_bf16 v[96:99], v[218:221], v[186:189], v[96:99]
	v_mfma_f32_16x16x32_bf16 v[84:87], v[210:213], v[194:197], v[84:87]
	v_mfma_f32_16x16x32_bf16 v[76:79], v[218:221], v[194:197], v[76:79]
	v_mfma_f32_16x16x32_bf16 v[68:71], v[210:213], v[202:205], v[68:71]
	v_mfma_f32_16x16x32_bf16 v[64:67], v[218:221], v[202:205], v[64:67]
	s_mov_b32 m0, s35
	v_lshl_add_u64 v[150:151], v[224:225], 0, s[4:5]
	s_barrier
	ds_read_b128 v[166:169], v174 offset:49152
	ds_read_b128 v[178:181], v174 offset:50176
	ds_read_b128 v[182:185], v174 offset:51200
	ds_read_b128 v[186:189], v174 offset:52224
	ds_read_b128 v[190:193], v174 offset:53248
	ds_read_b128 v[194:197], v174 offset:54272
	ds_read_b128 v[198:201], v174 offset:55296
	ds_read_b128 v[202:205], v174 offset:56320
	global_load_lds_dwordx4 v[150:151], off
	v_lshl_add_u64 v[150:151], v[226:227], 0, s[4:5]
	s_mov_b32 m0, s36
	s_nop 0
	global_load_lds_dwordx4 v[150:151], off
	s_barrier
; #define PG8_STAGE(bufoff, gbase, voff) do { _Pragma("unroll") for (int _i = 0; _i < 2; ++_i) \
;         __builtin_amdgcn_global_load_lds((const unsigned*)((const char*)(gbase) + (voff)[_i]), (LAS unsigned*)(lds + (bufoff) + ldsw + _i * 8192), 16, 0, 0); } while (0)
; #define PG8_LDA(dst, b, h) do { _Pragma("unroll") for (int m = 0; m < 4; ++m) _Pragma("unroll") for (int k = 0; k < 2; ++k) dst[m][k] = *(const LAS bf16x8*)(lds + PG8_SA(b, h) + aoff + m * 2048 + k * 1024); } while (0)
; #define PG8_WAIT_V(n) asm volatile("s_waitcnt vmcnt(" #n ")" ::: "memory")
; template <class Epi>
; __device__ __forceinline__ void gemm_phase(LAS unsigned char* lds, const Gemm g, const StaticOrder& S, const Epi& E) {
;     ...
;         for (int t = 0; t < nt; t += 2) {
;             const bool last = (t == nt - 2);
;             const char* a1 = cA + (size_t)(t + 1) * kstep;
;             const char* a2 = last ? nA : cA + (size_t)(t + 2) * kstep; const char* b2 = last ? nB : cB + (size_t)(t + 2) * kstep;
;             const char* a3 = a2 + kstep; const char* b3 = b2 + kstep;
;             if (last) E.pre(cur, wr, fr, epre);
;             PG8_LDB(B0, 0, 0); PG8_SCHED; PG8_LDA(At, 0, 0); PG8_STAGE(PG8_SA(1, 1), a1 + hstepA, voffA);
;             PG8_WAIT_L(8); PG8_BAR; PG8_WAIT_L(0); PG8_MMA(0, 0, At, B0); PG8_BAR; PG8_SCHED;
;             PG8_LDB(B1, 0, 1); PG8_STAGE(PG8_SB(0, 0), b2, voffB);
;             PG8_BAR; PG8_WAIT_L(0); PG8_MMA(0, 1, At, B1); PG8_BAR;
;             PG8_LDA(At, 0, 1); PG8_STAGE(PG8_SA(0, 0), a2, voffA);
;             PG8_BAR; PG8_WAIT_L(0); PG8_MMA(1, 0, At, B0); PG8_BAR; PG8_SCHED;
;             PG8_STAGE(PG8_SB(0, 1), b2 + hstepB, voffB);
;             PG8_WAIT_V(6); PG8_BAR; PG8_MMA(1, 1, At, B1); PG8_BAR;
;             PG8_LDB(B0, 1, 0); PG8_SCHED; PG8_LDA(At, 1, 0); PG8_STAGE(PG8_SA(0, 1), a2 + hstepA, voffA);
;             PG8_WAIT_L(8); PG8_BAR; PG8_WAIT_L(0); PG8_MMA(0, 0, At, B0); PG8_BAR; PG8_SCHED;
;             PG8_LDB(B1, 1, 1); PG8_STAGE(PG8_SB(1, 0), b3, voffB);
;             PG8_BAR; PG8_WAIT_L(0); PG8_MMA(0, 1, At, B1); PG8_BAR;
;             PG8_LDA(At, 1, 1); PG8_STAGE(PG8_SA(1, 0), a3, voffA);
;             PG8_BAR; PG8_WAIT_L(0); PG8_MMA(1, 0, At, B0); PG8_BAR; PG8_SCHED;
;             PG8_STAGE(PG8_SB(1, 1), b3 + hstepB, voffB);
;             PG8_WAIT_V(6); PG8_BAR; PG8_MMA(1, 1, At, B1); PG8_BAR;
	s_waitcnt lgkmcnt(7)
	v_mfma_f32_16x16x32_bf16 v[60:63], v[146:149], v[166:169], v[60:63]
	v_mfma_f32_16x16x32_bf16 v[56:59], v[158:161], v[166:169], v[56:59]
	s_waitcnt lgkmcnt(5)
	v_mfma_f32_16x16x32_bf16 v[48:51], v[146:149], v[182:185], v[48:51]
	v_mfma_f32_16x16x32_bf16 v[40:43], v[158:161], v[182:185], v[40:43]
	s_waitcnt lgkmcnt(3)
	v_mfma_f32_16x16x32_bf16 v[32:35], v[146:149], v[190:193], v[32:35]
	v_mfma_f32_16x16x32_bf16 v[24:27], v[158:161], v[190:193], v[24:27]
	s_waitcnt lgkmcnt(1)
	v_mfma_f32_16x16x32_bf16 v[16:19], v[146:149], v[198:201], v[16:19]
	v_mfma_f32_16x16x32_bf16 v[8:11], v[158:161], v[198:201], v[8:11]
	v_mfma_f32_16x16x32_bf16 v[60:63], v[154:157], v[178:181], v[60:63]
	v_mfma_f32_16x16x32_bf16 v[56:59], v[162:165], v[178:181], v[56:59]
	v_mfma_f32_16x16x32_bf16 v[48:51], v[154:157], v[186:189], v[48:51]
	v_mfma_f32_16x16x32_bf16 v[40:43], v[162:165], v[186:189], v[40:43]
	v_mfma_f32_16x16x32_bf16 v[32:35], v[154:157], v[194:197], v[32:35]
	v_mfma_f32_16x16x32_bf16 v[24:27], v[162:165], v[194:197], v[24:27]
	s_waitcnt lgkmcnt(0)
	v_mfma_f32_16x16x32_bf16 v[16:19], v[154:157], v[202:205], v[16:19]
	v_mfma_f32_16x16x32_bf16 v[8:11], v[162:165], v[202:205], v[8:11]
	s_barrier
	s_add_u32 s22, s22, 0x40080
	s_addc_u32 s23, s23, 0
	s_add_i32 s24, s24, s27
	v_lshl_add_u64 v[146:147], s[22:23], 0, v[132:133]
	s_mov_b32 m0, s24
	s_nop 0
	global_load_lds_dwordx4 v[146:147], off
	v_lshl_add_u64 v[146:147], s[22:23], 0, v[128:129]
	s_add_i32 m0, s24, 0x2000
	s_nop 0
	global_load_lds_dwordx4 v[146:147], off
	s_waitcnt vmcnt(6)
	s_barrier
	v_mfma_f32_16x16x32_bf16 v[52:55], v[206:209], v[166:169], v[52:55]
	v_mfma_f32_16x16x32_bf16 v[44:47], v[214:217], v[166:169], v[44:47]
	v_mfma_f32_16x16x32_bf16 v[36:39], v[206:209], v[182:185], v[36:39]
	v_mfma_f32_16x16x32_bf16 v[28:31], v[214:217], v[182:185], v[28:31]
	v_mfma_f32_16x16x32_bf16 v[20:23], v[206:209], v[190:193], v[20:23]
	v_mfma_f32_16x16x32_bf16 v[12:15], v[214:217], v[190:193], v[12:15]
	v_mfma_f32_16x16x32_bf16 v[4:7], v[206:209], v[198:201], v[4:7]
	v_mfma_f32_16x16x32_bf16 v[0:3], v[214:217], v[198:201], v[0:3]
	v_mfma_f32_16x16x32_bf16 v[52:55], v[210:213], v[178:181], v[52:55]
	v_mfma_f32_16x16x32_bf16 v[44:47], v[218:221], v[178:181], v[44:47]
	v_mfma_f32_16x16x32_bf16 v[36:39], v[210:213], v[186:189], v[36:39]
	v_mfma_f32_16x16x32_bf16 v[28:31], v[218:221], v[186:189], v[28:31]
	v_mfma_f32_16x16x32_bf16 v[20:23], v[210:213], v[194:197], v[20:23]
	v_mfma_f32_16x16x32_bf16 v[12:15], v[218:221], v[194:197], v[12:15]
	v_mfma_f32_16x16x32_bf16 v[4:7], v[210:213], v[202:205], v[4:7]
	v_mfma_f32_16x16x32_bf16 v[0:3], v[218:221], v[202:205], v[0:3]
	s_add_i32 s47, s47, 2
	s_add_u32 s20, s20, 0x100
	s_addc_u32 s21, s21, 0
	s_add_u32 s45, s45, 0x100
	s_addc_u32 s46, s46, 0
	s_cmp_gt_u32 s47, 13
	s_barrier
.LBB0_922:
	ds_read_b128 v[146:149], v173
	ds_read_b128 v[154:157], v173 offset:1024
	ds_read_b128 v[158:161], v173 offset:2048
	ds_read_b128 v[162:165], v173 offset:3072
	s_add_u32 s22, s20, 0xfffc0080
	s_addc_u32 s23, s21, -1
	s_cmp_eq_u32 s47, 12
	s_cselect_b32 s25, s13, s23
	s_cselect_b32 s24, s43, s22
	s_cselect_b32 s23, s11, s46
	s_cselect_b32 s22, s44, s45
	v_lshl_add_u64 v[150:151], s[20:21], 0, v[138:139]
	s_add_i32 m0, s19, 0xc000
	ds_read_b128 v[166:169], v174
	ds_read_b128 v[178:181], v174 offset:1024
	ds_read_b128 v[182:185], v174 offset:2048
	ds_read_b128 v[186:189], v174 offset:3072
	ds_read_b128 v[190:193], v174 offset:4096
	ds_read_b128 v[194:197], v174 offset:5120
	ds_read_b128 v[198:201], v174 offset:6144
	ds_read_b128 v[202:205], v174 offset:7168
	global_load_lds_dwordx4 v[150:151], off
	v_lshl_add_u64 v[150:151], s[20:21], 0, v[140:141]
	s_add_i32 m0, s19, 0xe000
	s_nop 0
	global_load_lds_dwordx4 v[150:151], off
	s_waitcnt lgkmcnt(8)
	s_barrier
	s_waitcnt lgkmcnt(7)
	v_mfma_f32_16x16x32_bf16 v[124:127], v[146:149], v[166:169], v[124:127]
	v_mfma_f32_16x16x32_bf16 v[120:123], v[158:161], v[166:169], v[120:123]
	s_waitcnt lgkmcnt(5)
	v_mfma_f32_16x16x32_bf16 v[112:115], v[146:149], v[182:185], v[112:115]
	v_mfma_f32_16x16x32_bf16 v[104:107], v[158:161], v[182:185], v[104:107]
	s_waitcnt lgkmcnt(3)
	v_mfma_f32_16x16x32_bf16 v[92:95], v[146:149], v[190:193], v[92:95]
	v_mfma_f32_16x16x32_bf16 v[88:91], v[158:161], v[190:193], v[88:91]
	s_waitcnt lgkmcnt(1)
	v_mfma_f32_16x16x32_bf16 v[80:83], v[146:149], v[198:201], v[80:83]
	v_mfma_f32_16x16x32_bf16 v[72:75], v[158:161], v[198:201], v[72:75]
	v_mfma_f32_16x16x32_bf16 v[124:127], v[154:157], v[178:181], v[124:127]
	v_mfma_f32_16x16x32_bf16 v[120:123], v[162:165], v[178:181], v[120:123]
	v_mfma_f32_16x16x32_bf16 v[112:115], v[154:157], v[186:189], v[112:115]
	v_mfma_f32_16x16x32_bf16 v[104:107], v[162:165], v[186:189], v[104:107]
	v_mfma_f32_16x16x32_bf16 v[92:95], v[154:157], v[194:197], v[92:95]
	v_mfma_f32_16x16x32_bf16 v[88:91], v[162:165], v[194:197], v[88:91]
	s_waitcnt lgkmcnt(0)
	v_mfma_f32_16x16x32_bf16 v[80:83], v[154:157], v[202:205], v[80:83]
	v_mfma_f32_16x16x32_bf16 v[72:75], v[162:165], v[202:205], v[72:75]
	s_barrier
	s_add_i32 s48, s38, s27
	v_lshl_add_u64 v[150:151], s[22:23], 0, v[132:133]
	s_mov_b32 m0, s48
	ds_read_b128 v[206:209], v175
	ds_read_b128 v[210:213], v175 offset:1024
	ds_read_b128 v[214:217], v175 offset:2048
	ds_read_b128 v[218:221], v175 offset:3072
	global_load_lds_dwordx4 v[150:151], off
	v_lshl_add_u64 v[222:223], s[22:23], 0, v[128:129]
	s_add_i32 m0, s48, 0x2000
	s_nop 0
	global_load_lds_dwordx4 v[222:223], off
	s_barrier
; #define PG8_STAGE(bufoff, gbase, voff) do { _Pragma("unroll") for (int _i = 0; _i < 2; ++_i) \
;         __builtin_amdgcn_global_load_lds((const unsigned*)((const char*)(gbase) + (voff)[_i]), (LAS unsigned*)(lds + (bufoff) + ldsw + _i * 8192), 16, 0, 0); } while (0)
; #define PG8_LDA(dst, b, h) do { _Pragma("unroll") for (int m = 0; m < 4; ++m) _Pragma("unroll") for (int k = 0; k < 2; ++k) dst[m][k] = *(const LAS bf16x8*)(lds + PG8_SA(b, h) + aoff + m * 2048 + k * 1024); } while (0)
; #define PG8_LDB(dst, b, h) do { _Pragma("unroll") for (int n = 0; n < 2; ++n) _Pragma("unroll") for (int k = 0; k < 2; ++k) dst[n][k] = *(const LAS bf16x8*)(lds + PG8_SB(b, h) + boff + n * 2048 + k * 1024); } while (0)
; #define PG8_MMA(ai, bj, At, Bt) do { __builtin_amdgcn_s_setprio(1); _Pragma("unroll") for (int m = 0; m < 4; ++m) _Pragma("unroll") for (int n = 0; n < 2; ++n) _Pragma("unroll") for (int k = 0; k < 2; ++k) \
;         acc[ai][bj][m][n] = __builtin_amdgcn_mfma_f32_16x16x32_bf16(Bt[n][k], At[m][k], acc[ai][bj][m][n], 0, 0, 0); __builtin_amdgcn_s_setprio(0); } while (0)
; #define PG8_WAIT_V(n) asm volatile("s_waitcnt vmcnt(" #n ")" ::: "memory")
; #define PG8_WAIT_L(n) asm volatile("s_waitcnt lgkmcnt(" #n ")" ::: "memory")
; #define PG8_BAR __builtin_amdgcn_s_barrier()
; #define PG8_SCHED __builtin_amdgcn_sched_barrier(0)
; template <class Epi>
; __device__ __forceinline__ void gemm_phase(LAS unsigned char* lds, const Gemm g, const StaticOrder& S, const Epi& E) {
;     ...
;             PG8_BAR; PG8_WAIT_L(0); PG8_MMA(0, 1, At, B1); PG8_BAR;
;             PG8_LDA(At, 0, 1); PG8_STAGE(PG8_SA(0, 0), a2, voffA);
;             PG8_BAR; PG8_WAIT_L(0); PG8_MMA(1, 0, At, B0); PG8_BAR; PG8_SCHED;
;             PG8_STAGE(PG8_SB(0, 1), b2 + hstepB, voffB);
;             PG8_WAIT_V(6); PG8_BAR; PG8_MMA(1, 1, At, B1); PG8_BAR;
;             PG8_LDB(B0, 1, 0); PG8_SCHED; PG8_LDA(At, 1, 0); PG8_STAGE(PG8_SA(0, 1), a2 + hstepA, voffA);
;             PG8_WAIT_L(8); PG8_BAR; PG8_WAIT_L(0); PG8_MMA(0, 0, At, B0); PG8_BAR; PG8_SCHED;
	s_waitcnt lgkmcnt(3)
	v_mfma_f32_16x16x32_bf16 v[116:119], v[206:209], v[166:169], v[116:119]
	s_waitcnt lgkmcnt(1)
	v_mfma_f32_16x16x32_bf16 v[108:111], v[214:217], v[166:169], v[108:111]
	v_mfma_f32_16x16x32_bf16 v[100:103], v[206:209], v[182:185], v[100:103]
	v_mfma_f32_16x16x32_bf16 v[96:99], v[214:217], v[182:185], v[96:99]
	v_mfma_f32_16x16x32_bf16 v[84:87], v[206:209], v[190:193], v[84:87]
	v_mfma_f32_16x16x32_bf16 v[76:79], v[214:217], v[190:193], v[76:79]
	v_mfma_f32_16x16x32_bf16 v[68:71], v[206:209], v[198:201], v[68:71]
	v_mfma_f32_16x16x32_bf16 v[64:67], v[214:217], v[198:201], v[64:67]
	v_mfma_f32_16x16x32_bf16 v[116:119], v[210:213], v[178:181], v[116:119]
	s_waitcnt lgkmcnt(0)
	v_mfma_f32_16x16x32_bf16 v[108:111], v[218:221], v[178:181], v[108:111]
	v_mfma_f32_16x16x32_bf16 v[100:103], v[210:213], v[186:189], v[100:103]
	v_mfma_f32_16x16x32_bf16 v[96:99], v[218:221], v[186:189], v[96:99]
	v_mfma_f32_16x16x32_bf16 v[84:87], v[210:213], v[194:197], v[84:87]
	v_mfma_f32_16x16x32_bf16 v[76:79], v[218:221], v[194:197], v[76:79]
	v_mfma_f32_16x16x32_bf16 v[68:71], v[210:213], v[202:205], v[68:71]
	v_mfma_f32_16x16x32_bf16 v[64:67], v[218:221], v[202:205], v[64:67]
	s_mov_b32 m0, s19
	v_lshl_add_u64 v[224:225], s[24:25], 0, v[134:135]
	s_barrier
	ds_read_b128 v[166:169], v174 offset:16384
	ds_read_b128 v[178:181], v174 offset:17408
	ds_read_b128 v[182:185], v174 offset:18432
	ds_read_b128 v[186:189], v174 offset:19456
	ds_read_b128 v[190:193], v174 offset:20480
	ds_read_b128 v[194:197], v174 offset:21504
	ds_read_b128 v[198:201], v174 offset:22528
	ds_read_b128 v[202:205], v174 offset:23552
	global_load_lds_dwordx4 v[224:225], off
	v_lshl_add_u64 v[226:227], s[24:25], 0, v[130:131]
	s_mov_b32 m0, s30
	s_nop 0
	global_load_lds_dwordx4 v[226:227], off
	s_barrier
	s_waitcnt lgkmcnt(7)
	v_mfma_f32_16x16x32_bf16 v[60:63], v[146:149], v[166:169], v[60:63]
	v_mfma_f32_16x16x32_bf16 v[56:59], v[158:161], v[166:169], v[56:59]
	s_waitcnt lgkmcnt(5)
	v_mfma_f32_16x16x32_bf16 v[48:51], v[146:149], v[182:185], v[48:51]
	v_mfma_f32_16x16x32_bf16 v[40:43], v[158:161], v[182:185], v[40:43]
	s_waitcnt lgkmcnt(3)
	v_mfma_f32_16x16x32_bf16 v[32:35], v[146:149], v[190:193], v[32:35]
	v_mfma_f32_16x16x32_bf16 v[24:27], v[158:161], v[190:193], v[24:27]
	s_waitcnt lgkmcnt(1)
	v_mfma_f32_16x16x32_bf16 v[16:19], v[146:149], v[198:201], v[16:19]
	v_mfma_f32_16x16x32_bf16 v[8:11], v[158:161], v[198:201], v[8:11]
	v_mfma_f32_16x16x32_bf16 v[60:63], v[154:157], v[178:181], v[60:63]
	v_mfma_f32_16x16x32_bf16 v[56:59], v[162:165], v[178:181], v[56:59]
	v_mfma_f32_16x16x32_bf16 v[48:51], v[154:157], v[186:189], v[48:51]
	v_mfma_f32_16x16x32_bf16 v[40:43], v[162:165], v[186:189], v[40:43]
	v_mfma_f32_16x16x32_bf16 v[32:35], v[154:157], v[194:197], v[32:35]
	v_mfma_f32_16x16x32_bf16 v[24:27], v[162:165], v[194:197], v[24:27]
	s_waitcnt lgkmcnt(0)
	v_mfma_f32_16x16x32_bf16 v[16:19], v[154:157], v[202:205], v[16:19]
	v_mfma_f32_16x16x32_bf16 v[8:11], v[162:165], v[202:205], v[8:11]
	s_barrier
	s_add_u32 s48, s22, 0x40000
	s_addc_u32 s49, s23, 0
	s_add_i32 s50, s39, s27
	v_lshl_add_u64 v[146:147], s[48:49], 0, v[132:133]
	s_mov_b32 m0, s50
	s_nop 0
	global_load_lds_dwordx4 v[146:147], off
	v_lshl_add_u64 v[146:147], s[48:49], 0, v[128:129]
	s_add_i32 m0, s50, 0x2000
	s_nop 0
	global_load_lds_dwordx4 v[146:147], off
	s_waitcnt vmcnt(6)
	s_barrier
	v_mfma_f32_16x16x32_bf16 v[52:55], v[206:209], v[166:169], v[52:55]
	v_mfma_f32_16x16x32_bf16 v[44:47], v[214:217], v[166:169], v[44:47]
	v_mfma_f32_16x16x32_bf16 v[36:39], v[206:209], v[182:185], v[36:39]
	v_mfma_f32_16x16x32_bf16 v[28:31], v[214:217], v[182:185], v[28:31]
	v_mfma_f32_16x16x32_bf16 v[20:23], v[206:209], v[190:193], v[20:23]
	v_mfma_f32_16x16x32_bf16 v[12:15], v[214:217], v[190:193], v[12:15]
	v_mfma_f32_16x16x32_bf16 v[4:7], v[206:209], v[198:201], v[4:7]
	v_mfma_f32_16x16x32_bf16 v[0:3], v[214:217], v[198:201], v[0:3]
	v_mfma_f32_16x16x32_bf16 v[52:55], v[210:213], v[178:181], v[52:55]
	v_mfma_f32_16x16x32_bf16 v[44:47], v[218:221], v[178:181], v[44:47]
	v_mfma_f32_16x16x32_bf16 v[36:39], v[210:213], v[186:189], v[36:39]
	v_mfma_f32_16x16x32_bf16 v[28:31], v[218:221], v[186:189], v[28:31]
	v_mfma_f32_16x16x32_bf16 v[20:23], v[210:213], v[194:197], v[20:23]
	v_mfma_f32_16x16x32_bf16 v[12:15], v[218:221], v[194:197], v[12:15]
	v_mfma_f32_16x16x32_bf16 v[4:7], v[210:213], v[202:205], v[4:7]
	v_mfma_f32_16x16x32_bf16 v[0:3], v[218:221], v[202:205], v[0:3]
	s_add_i32 s48, 0, 0x18000
	v_add_u32_e32 v162, s48, v171
	s_barrier
	ds_read_b128 v[146:149], v162
	ds_read_b128 v[154:157], v162 offset:1024
	ds_read_b128 v[158:161], v162 offset:2048
	ds_read_b128 v[162:165], v162 offset:3072
	s_add_u32 s24, s24, 0x40000
	s_addc_u32 s25, s25, 0
	s_mov_b32 m0, s31
	v_lshl_add_u64 v[206:207], s[24:25], 0, v[134:135]
	ds_read_b128 v[166:169], v174 offset:32768
	ds_read_b128 v[178:181], v174 offset:33792
	ds_read_b128 v[182:185], v174 offset:34816
	ds_read_b128 v[186:189], v174 offset:35840
	ds_read_b128 v[190:193], v174 offset:36864
	ds_read_b128 v[194:197], v174 offset:37888
	ds_read_b128 v[198:201], v174 offset:38912
	ds_read_b128 v[202:205], v174 offset:39936
	global_load_lds_dwordx4 v[206:207], off
	v_lshl_add_u64 v[206:207], s[24:25], 0, v[130:131]
	s_mov_b32 m0, s33
	s_nop 0
	global_load_lds_dwordx4 v[206:207], off
	s_waitcnt lgkmcnt(8)
	s_barrier
; #define PG8_STAGE(bufoff, gbase, voff) do { _Pragma("unroll") for (int _i = 0; _i < 2; ++_i) \
;         __builtin_amdgcn_global_load_lds((const unsigned*)((const char*)(gbase) + (voff)[_i]), (LAS unsigned*)(lds + (bufoff) + ldsw + _i * 8192), 16, 0, 0); } while (0)
; #define PG8_LDA(dst, b, h) do { _Pragma("unroll") for (int m = 0; m < 4; ++m) _Pragma("unroll") for (int k = 0; k < 2; ++k) dst[m][k] = *(const LAS bf16x8*)(lds + PG8_SA(b, h) + aoff + m * 2048 + k * 1024); } while (0)
; #define PG8_LDB(dst, b, h) do { _Pragma("unroll") for (int n = 0; n < 2; ++n) _Pragma("unroll") for (int k = 0; k < 2; ++k) dst[n][k] = *(const LAS bf16x8*)(lds + PG8_SB(b, h) + boff + n * 2048 + k * 1024); } while (0)
; #define PG8_MMA(ai, bj, At, Bt) do { __builtin_amdgcn_s_setprio(1); _Pragma("unroll") for (int m = 0; m < 4; ++m) _Pragma("unroll") for (int n = 0; n < 2; ++n) _Pragma("unroll") for (int k = 0; k < 2; ++k) \
;         acc[ai][bj][m][n] = __builtin_amdgcn_mfma_f32_16x16x32_bf16(Bt[n][k], At[m][k], acc[ai][bj][m][n], 0, 0, 0); __builtin_amdgcn_s_setprio(0); } while (0)
; #define PG8_WAIT_V(n) asm volatile("s_waitcnt vmcnt(" #n ")" ::: "memory")
; #define PG8_WAIT_L(n) asm volatile("s_waitcnt lgkmcnt(" #n ")" ::: "memory")
; #define PG8_BAR __builtin_amdgcn_s_barrier()
; #define PG8_SCHED __builtin_amdgcn_sched_barrier(0)
; template <class Epi>
; __device__ __forceinline__ void gemm_phase(LAS unsigned char* lds, const Gemm g, const StaticOrder& S, const Epi& E) {
;     ...
;             PG8_WAIT_L(8); PG8_BAR; PG8_WAIT_L(0); PG8_MMA(0, 0, At, B0); PG8_BAR; PG8_SCHED;
;             PG8_LDB(B1, 1, 1); PG8_STAGE(PG8_SB(1, 0), b3, voffB);
;             PG8_BAR; PG8_WAIT_L(0); PG8_MMA(0, 1, At, B1); PG8_BAR;
;             PG8_LDA(At, 1, 1); PG8_STAGE(PG8_SA(1, 0), a3, voffA);
;             PG8_BAR; PG8_WAIT_L(0); PG8_MMA(1, 0, At, B0); PG8_BAR; PG8_SCHED;
;             PG8_STAGE(PG8_SB(1, 1), b3 + hstepB, voffB);
;             PG8_WAIT_V(6); PG8_BAR; PG8_MMA(1, 1, At, B1); PG8_BAR;
	s_waitcnt lgkmcnt(7)
	v_mfma_f32_16x16x32_bf16 v[124:127], v[146:149], v[166:169], v[124:127]
	v_mfma_f32_16x16x32_bf16 v[120:123], v[158:161], v[166:169], v[120:123]
	s_waitcnt lgkmcnt(5)
	v_mfma_f32_16x16x32_bf16 v[112:115], v[146:149], v[182:185], v[112:115]
	v_mfma_f32_16x16x32_bf16 v[104:107], v[158:161], v[182:185], v[104:107]
	s_waitcnt lgkmcnt(3)
	v_mfma_f32_16x16x32_bf16 v[92:95], v[146:149], v[190:193], v[92:95]
	v_mfma_f32_16x16x32_bf16 v[88:91], v[158:161], v[190:193], v[88:91]
	s_waitcnt lgkmcnt(1)
	v_mfma_f32_16x16x32_bf16 v[80:83], v[146:149], v[198:201], v[80:83]
	v_mfma_f32_16x16x32_bf16 v[72:75], v[158:161], v[198:201], v[72:75]
	v_mfma_f32_16x16x32_bf16 v[124:127], v[154:157], v[178:181], v[124:127]
	v_mfma_f32_16x16x32_bf16 v[120:123], v[162:165], v[178:181], v[120:123]
	v_mfma_f32_16x16x32_bf16 v[112:115], v[154:157], v[186:189], v[112:115]
	v_mfma_f32_16x16x32_bf16 v[104:107], v[162:165], v[186:189], v[104:107]
	v_mfma_f32_16x16x32_bf16 v[92:95], v[154:157], v[194:197], v[92:95]
	v_mfma_f32_16x16x32_bf16 v[88:91], v[162:165], v[194:197], v[88:91]
	s_waitcnt lgkmcnt(0)
	v_mfma_f32_16x16x32_bf16 v[80:83], v[154:157], v[202:205], v[80:83]
	v_mfma_f32_16x16x32_bf16 v[72:75], v[162:165], v[202:205], v[72:75]
	s_barrier
	s_add_i32 s24, 0, 0x1c000
	s_add_i32 s25, s48, s27
	v_add_u32_e32 v177, s24, v171
	v_lshl_add_u64 v[150:151], v[150:151], 0, s[4:5]
	s_mov_b32 m0, s25
	ds_read_b128 v[206:209], v177
	ds_read_b128 v[210:213], v177 offset:1024
	ds_read_b128 v[214:217], v177 offset:2048
	ds_read_b128 v[218:221], v177 offset:3072
	global_load_lds_dwordx4 v[150:151], off
	v_lshl_add_u64 v[150:151], v[222:223], 0, s[4:5]
	s_add_i32 m0, s25, 0x2000
	s_nop 0
	global_load_lds_dwordx4 v[150:151], off
	s_barrier
	s_waitcnt lgkmcnt(3)
	v_mfma_f32_16x16x32_bf16 v[116:119], v[206:209], v[166:169], v[116:119]
	s_waitcnt lgkmcnt(1)
	v_mfma_f32_16x16x32_bf16 v[108:111], v[214:217], v[166:169], v[108:111]
	v_mfma_f32_16x16x32_bf16 v[100:103], v[206:209], v[182:185], v[100:103]
	v_mfma_f32_16x16x32_bf16 v[96:99], v[214:217], v[182:185], v[96:99]
	v_mfma_f32_16x16x32_bf16 v[84:87], v[206:209], v[190:193], v[84:87]
	v_mfma_f32_16x16x32_bf16 v[76:79], v[214:217], v[190:193], v[76:79]
	v_mfma_f32_16x16x32_bf16 v[68:71], v[206:209], v[198:201], v[68:71]
	v_mfma_f32_16x16x32_bf16 v[64:67], v[214:217], v[198:201], v[64:67]
	v_mfma_f32_16x16x32_bf16 v[116:119], v[210:213], v[178:181], v[116:119]
	s_waitcnt lgkmcnt(0)
	v_mfma_f32_16x16x32_bf16 v[108:111], v[218:221], v[178:181], v[108:111]
	v_mfma_f32_16x16x32_bf16 v[100:103], v[210:213], v[186:189], v[100:103]
	v_mfma_f32_16x16x32_bf16 v[96:99], v[218:221], v[186:189], v[96:99]
	v_mfma_f32_16x16x32_bf16 v[84:87], v[210:213], v[194:197], v[84:87]
	v_mfma_f32_16x16x32_bf16 v[76:79], v[218:221], v[194:197], v[76:79]
	v_mfma_f32_16x16x32_bf16 v[68:71], v[210:213], v[202:205], v[68:71]
	v_mfma_f32_16x16x32_bf16 v[64:67], v[218:221], v[202:205], v[64:67]
	s_mov_b32 m0, s35
	v_lshl_add_u64 v[150:151], v[224:225], 0, s[4:5]
	s_barrier
	ds_read_b128 v[166:169], v174 offset:49152
	ds_read_b128 v[178:181], v174 offset:50176
	ds_read_b128 v[182:185], v174 offset:51200
	ds_read_b128 v[186:189], v174 offset:52224
	ds_read_b128 v[190:193], v174 offset:53248
	ds_read_b128 v[194:197], v174 offset:54272
	ds_read_b128 v[198:201], v174 offset:55296
	ds_read_b128 v[202:205], v174 offset:56320
	global_load_lds_dwordx4 v[150:151], off
	v_lshl_add_u64 v[150:151], v[226:227], 0, s[4:5]
	s_mov_b32 m0, s36
	s_nop 0
	global_load_lds_dwordx4 v[150:151], off
	s_barrier
	s_waitcnt lgkmcnt(7)
	v_mfma_f32_16x16x32_bf16 v[60:63], v[146:149], v[166:169], v[60:63]
	v_mfma_f32_16x16x32_bf16 v[56:59], v[158:161], v[166:169], v[56:59]
	s_waitcnt lgkmcnt(5)
	v_mfma_f32_16x16x32_bf16 v[48:51], v[146:149], v[182:185], v[48:51]
	v_mfma_f32_16x16x32_bf16 v[40:43], v[158:161], v[182:185], v[40:43]
	s_waitcnt lgkmcnt(3)
	v_mfma_f32_16x16x32_bf16 v[32:35], v[146:149], v[190:193], v[32:35]
	v_mfma_f32_16x16x32_bf16 v[24:27], v[158:161], v[190:193], v[24:27]
	s_waitcnt lgkmcnt(1)
	v_mfma_f32_16x16x32_bf16 v[16:19], v[146:149], v[198:201], v[16:19]
	v_mfma_f32_16x16x32_bf16 v[8:11], v[158:161], v[198:201], v[8:11]
	v_mfma_f32_16x16x32_bf16 v[60:63], v[154:157], v[178:181], v[60:63]
	v_mfma_f32_16x16x32_bf16 v[56:59], v[162:165], v[178:181], v[56:59]
	v_mfma_f32_16x16x32_bf16 v[48:51], v[154:157], v[186:189], v[48:51]
	v_mfma_f32_16x16x32_bf16 v[40:43], v[162:165], v[186:189], v[40:43]
	v_mfma_f32_16x16x32_bf16 v[32:35], v[154:157], v[194:197], v[32:35]
	v_mfma_f32_16x16x32_bf16 v[24:27], v[162:165], v[194:197], v[24:27]
	s_waitcnt lgkmcnt(0)
	v_mfma_f32_16x16x32_bf16 v[16:19], v[154:157], v[202:205], v[16:19]
	v_mfma_f32_16x16x32_bf16 v[8:11], v[162:165], v[202:205], v[8:11]
	s_barrier
	s_add_u32 s22, s22, 0x40080
	s_addc_u32 s23, s23, 0
	s_add_i32 s24, s24, s27
	v_lshl_add_u64 v[146:147], s[22:23], 0, v[132:133]
	s_mov_b32 m0, s24
	s_nop 0
	global_load_lds_dwordx4 v[146:147], off
	v_lshl_add_u64 v[146:147], s[22:23], 0, v[128:129]
	s_add_i32 m0, s24, 0x2000
	s_nop 0
	global_load_lds_dwordx4 v[146:147], off
	s_waitcnt vmcnt(6)
	s_barrier
; __device__ __forceinline__ unsigned pk2(float lo, float hi) { const f32x2 v = (f32x2){lo, hi}; const bf16x2_t b = __builtin_convertvector(v, bf16x2_t); return __builtin_bit_cast(unsigned, b); }
; #define PG8_MMA(ai, bj, At, Bt) do { __builtin_amdgcn_s_setprio(1); _Pragma("unroll") for (int m = 0; m < 4; ++m) _Pragma("unroll") for (int n = 0; n < 2; ++n) _Pragma("unroll") for (int k = 0; k < 2; ++k) \
;         acc[ai][bj][m][n] = __builtin_amdgcn_mfma_f32_16x16x32_bf16(Bt[n][k], At[m][k], acc[ai][bj][m][n], 0, 0, 0); __builtin_amdgcn_s_setprio(0); } while (0)
; #define PG8_WAIT_V(n) asm volatile("s_waitcnt vmcnt(" #n ")" ::: "memory")
; #define PG8_BAR __builtin_amdgcn_s_barrier()
;     __device__ __forceinline__ void operator()(const f32x4 (&acc)[2][2][4][2], const Unit& u, int wr, int wc, int fr, int fq, const float (&)[8]) const {
;     ...
;         const int col0 = u.pn * BM + wc * 32 + 8 * fq;
; #pragma unroll
;         for (int ai = 0; ai < 2; ++ai)
; #pragma unroll
;             for (int m = 0; m < 4; ++m) { const int row = row0 + ai * HALF + m * 16; const float rs = rsqrtf(ep[ai * 4 + m] * (1.0f / 1024.0f) + EPS);
;                 u16* rowp = O + (size_t)row * ldc + col0;
; #pragma unroll
;                 for (int bj = 0; bj < 2; ++bj) { f32x4 v0 = acc[ai][bj][m][0] * rs, v1 = acc[ai][bj][m][1] * rs;
;                     if (ACT == 1) {
; #pragma unroll
;                         for (int j = 0; j < 4; ++j) { const float a0 = fmaxf(v0[j], 0.f), a1 = fmaxf(v1[j], 0.f); v0[j] = a0 * a0; v1[j] = a1 * a1; } }
;                     u32x4 w; w.x = pk2(v0[0], v0[1]); w.y = pk2(v0[2], v0[3]); w.z = pk2(v1[0], v1[1]); w.w = pk2(v1[2], v1[3]);
;                     *(u32x4*)(rowp + bj * HALF) = w; } }
; template <class Epi>
; __device__ __forceinline__ void gemm_phase(LAS unsigned char* lds, const Gemm g, const StaticOrder& S, const Epi& E) {
;     ...
;             PG8_WAIT_V(6); PG8_BAR; PG8_MMA(1, 1, At, B1); PG8_BAR;
;         }
;         E(acc, cur, wr, wc, fr, fq, epre);
	v_mfma_f32_16x16x32_bf16 v[52:55], v[206:209], v[166:169], v[52:55]
	v_mfma_f32_16x16x32_bf16 v[44:47], v[214:217], v[166:169], v[44:47]
	v_mfma_f32_16x16x32_bf16 v[36:39], v[206:209], v[182:185], v[36:39]
	v_mfma_f32_16x16x32_bf16 v[28:31], v[214:217], v[182:185], v[28:31]
	v_mfma_f32_16x16x32_bf16 v[20:23], v[206:209], v[190:193], v[20:23]
	v_mfma_f32_16x16x32_bf16 v[12:15], v[214:217], v[190:193], v[12:15]
	v_mfma_f32_16x16x32_bf16 v[4:7], v[206:209], v[198:201], v[4:7]
	v_mfma_f32_16x16x32_bf16 v[0:3], v[214:217], v[198:201], v[0:3]
	v_mfma_f32_16x16x32_bf16 v[52:55], v[210:213], v[178:181], v[52:55]
	v_mfma_f32_16x16x32_bf16 v[44:47], v[218:221], v[178:181], v[44:47]
	v_mfma_f32_16x16x32_bf16 v[36:39], v[210:213], v[186:189], v[36:39]
	v_mfma_f32_16x16x32_bf16 v[28:31], v[218:221], v[186:189], v[28:31]
	v_mfma_f32_16x16x32_bf16 v[20:23], v[210:213], v[194:197], v[20:23]
	v_mfma_f32_16x16x32_bf16 v[12:15], v[218:221], v[194:197], v[12:15]
	v_mfma_f32_16x16x32_bf16 v[4:7], v[210:213], v[202:205], v[4:7]
	v_mfma_f32_16x16x32_bf16 v[0:3], v[218:221], v[202:205], v[0:3]
	s_add_i32 s47, s47, 2
	s_add_u32 s20, s20, 0x100
	s_addc_u32 s21, s21, 0
	s_add_u32 s45, s45, 0x100
	s_addc_u32 s46, s46, 0
	s_cmp_gt_u32 s47, 13
	s_barrier
	s_cbranch_scc0 .LBB0_922
	s_bfe_u32 vcc_lo, s18, 0x20003
	s_lshl_b32 vcc_lo, vcc_lo, 10
	s_add_i32 vcc_lo, vcc_lo, 0x20010
	v_lshl_add_u32 v236, v170, 2, vcc_lo
	ds_read_b32 v228, v236
	ds_read_b32 v229, v236 offset:64
	ds_read_b32 v230, v236 offset:128
	ds_read_b32 v231, v236 offset:192
	ds_read_b32 v232, v236 offset:512
	ds_read_b32 v233, v236 offset:576
	ds_read_b32 v234, v236 offset:640
	ds_read_b32 v235, v236 offset:704
	s_waitcnt lgkmcnt(0)
	v_lshl_add_u32 v154, s18, 8, v170
	v_or_b32_e32 v206, 16, v154
	v_or_b32_e32 v168, 32, v154
	v_or_b32_e32 v162, 48, v154
	v_add_u32_e32 v160, 0x80, v154
	v_add_u32_e32 v156, 0x90, v154
	v_add_u32_e32 v150, 0xa0, v154
	v_add_u32_e32 v146, 0xb0, v154
	v_lshl_or_b32 v208, s42, 8, v172
	v_mov_b64_e32 v[148:149], s[96:97]
	v_ashrrev_i32_e32 v209, 31, v208
	v_mad_i64_i32 v[210:211], s[20:21], v154, s40, v[148:149]
	s_nop 0
	v_lshlrev_b64 v[154:155], 1, v[208:209]
	v_lshl_add_u64 v[208:209], v[210:211], 0, v[154:155]
	s_mov_b32 s42, s10
	s_mov_b32 s18, s12
	s_mov_b64 s[22:23], s[16:17]
	s_waitcnt vmcnt(8)
	s_waitcnt lgkmcnt(0)
	s_waitcnt lgkmcnt(0)
	v_mov_b32_e32 v178, v228
	v_pk_mul_f32 v[126:127], v[126:127], v[178:179] op_sel_hi:[1,0]
	v_pk_mul_f32 v[124:125], v[124:125], v[178:179] op_sel_hi:[1,0]
	v_pk_mul_f32 v[190:191], v[122:123], v[178:179] op_sel_hi:[1,0]
	v_pk_mul_f32 v[122:123], v[120:121], v[178:179] op_sel_hi:[1,0]
	v_cvt_pk_bf16_f32 v120, v124, v125
	v_cvt_pk_bf16_f32 v121, v126, v127
	v_cvt_pk_bf16_f32 v122, v122, v123
	v_cvt_pk_bf16_f32 v123, v190, v191
	v_pk_mul_f32 v[116:117], v[116:117], v[178:179] op_sel_hi:[1,0]
	global_store_dwordx4 v[208:209], v[120:123], off
	s_nop 0
	v_pk_mul_f32 v[118:119], v[118:119], v[178:179] op_sel_hi:[1,0]
	v_pk_mul_f32 v[120:121], v[110:111], v[178:179] op_sel_hi:[1,0]
	v_pk_mul_f32 v[110:111], v[108:109], v[178:179] op_sel_hi:[1,0]
	v_cvt_pk_bf16_f32 v108, v116, v117
	v_cvt_pk_bf16_f32 v109, v118, v119
	v_cvt_pk_bf16_f32 v110, v110, v111
	v_cvt_pk_bf16_f32 v111, v120, v121
	global_store_dwordx4 v[208:209], v[108:111], off offset:256
	s_nop 1
	v_mov_b32_e32 v108, v229
	v_mad_i64_i32 v[110:111], s[20:21], v206, s40, v[148:149]
	v_pk_mul_f32 v[114:115], v[114:115], v[108:109] op_sel_hi:[1,0]
	v_pk_mul_f32 v[112:113], v[112:113], v[108:109] op_sel_hi:[1,0]
	v_pk_mul_f32 v[116:117], v[106:107], v[108:109] op_sel_hi:[1,0]
	v_pk_mul_f32 v[106:107], v[104:105], v[108:109] op_sel_hi:[1,0]
	v_lshl_add_u64 v[110:111], v[110:111], 0, v[154:155]
	v_cvt_pk_bf16_f32 v104, v112, v113
	v_cvt_pk_bf16_f32 v105, v114, v115
	v_cvt_pk_bf16_f32 v106, v106, v107
	v_cvt_pk_bf16_f32 v107, v116, v117
	global_store_dwordx4 v[110:111], v[104:107], off
	v_pk_mul_f32 v[100:101], v[100:101], v[108:109] op_sel_hi:[1,0]
	v_pk_mul_f32 v[112:113], v[98:99], v[108:109] op_sel_hi:[1,0]
	v_pk_mul_f32 v[98:99], v[96:97], v[108:109] op_sel_hi:[1,0]
	v_cvt_pk_bf16_f32 v96, v100, v101
	v_pk_mul_f32 v[102:103], v[102:103], v[108:109] op_sel_hi:[1,0]
	v_cvt_pk_bf16_f32 v98, v98, v99
	s_waitcnt lgkmcnt(0)
	v_cvt_pk_bf16_f32 v97, v102, v103
	v_cvt_pk_bf16_f32 v99, v112, v113
	global_store_dwordx4 v[110:111], v[96:99], off offset:256
	s_nop 0
	s_waitcnt lgkmcnt(0)
; __device__ __forceinline__ unsigned pk2(float lo, float hi) { const f32x2 v = (f32x2){lo, hi}; const bf16x2_t b = __builtin_convertvector(v, bf16x2_t); return __builtin_bit_cast(unsigned, b); }
; #define PG8_WAIT_V(n) asm volatile("s_waitcnt vmcnt(" #n ")" ::: "memory")
; #define PG8_BAR __builtin_amdgcn_s_barrier()
;     __device__ __forceinline__ void operator()(const f32x4 (&acc)[2][2][4][2], const Unit& u, int wr, int wc, int fr, int fq, const float (&)[8]) const {
;     ...
;         const int col0 = u.pn * BM + wc * 32 + 8 * fq;
; #pragma unroll
;         for (int ai = 0; ai < 2; ++ai)
; #pragma unroll
;             for (int m = 0; m < 4; ++m) { const int row = row0 + ai * HALF + m * 16; const float rs = rsqrtf(ep[ai * 4 + m] * (1.0f / 1024.0f) + EPS);
;                 u16* rowp = O + (size_t)row * ldc + col0;
; #pragma unroll
;                 for (int bj = 0; bj < 2; ++bj) { f32x4 v0 = acc[ai][bj][m][0] * rs, v1 = acc[ai][bj][m][1] * rs;
;                     if (ACT == 1) {
; #pragma unroll
;                         for (int j = 0; j < 4; ++j) { const float a0 = fmaxf(v0[j], 0.f), a1 = fmaxf(v1[j], 0.f); v0[j] = a0 * a0; v1[j] = a1 * a1; } }
;                     u32x4 w; w.x = pk2(v0[0], v0[1]); w.y = pk2(v0[2], v0[3]); w.z = pk2(v1[0], v1[1]); w.w = pk2(v1[2], v1[3]);
;                     *(u32x4*)(rowp + bj * HALF) = w; } }
; template <class Epi>
; __device__ __forceinline__ void gemm_phase(LAS unsigned char* lds, const Gemm g, const StaticOrder& S, const Epi& E) {
;     ...
;         if (!has_next) break;
; #pragma unroll
;         for (int a = 0; a < 2; ++a)
; #pragma unroll
;             for (int b = 0; b < 2; ++b)
; #pragma unroll
;                 for (int m = 0; m < 4; ++m)
; #pragma unroll
;                     for (int n = 0; n < 2; ++n) acc[a][b][m][n] = (f32x4){0.f, 0.f, 0.f, 0.f};
;         cur = nxt; cA = nA; cB = nB; ++ui;
;     }
;     PG8_WAIT_V(0);
;     if (wr == 0) PG8_BAR;
;     PG8_BAR;
	v_mad_i64_i32 v[98:99], s[20:21], v168, s40, v[148:149]
	v_lshl_add_u64 v[98:99], v[98:99], 0, v[154:155]
	v_mov_b32_e32 v100, v230
	v_pk_mul_f32 v[94:95], v[94:95], v[100:101] op_sel_hi:[1,0]
	v_pk_mul_f32 v[92:93], v[92:93], v[100:101] op_sel_hi:[1,0]
	v_pk_mul_f32 v[102:103], v[90:91], v[100:101] op_sel_hi:[1,0]
	v_pk_mul_f32 v[90:91], v[88:89], v[100:101] op_sel_hi:[1,0]
	v_cvt_pk_bf16_f32 v88, v92, v93
	v_cvt_pk_bf16_f32 v89, v94, v95
	v_cvt_pk_bf16_f32 v90, v90, v91
	v_cvt_pk_bf16_f32 v91, v102, v103
	v_pk_mul_f32 v[84:85], v[84:85], v[100:101] op_sel_hi:[1,0]
	global_store_dwordx4 v[98:99], v[88:91], off
	s_nop 0
	v_pk_mul_f32 v[86:87], v[86:87], v[100:101] op_sel_hi:[1,0]
	v_pk_mul_f32 v[88:89], v[78:79], v[100:101] op_sel_hi:[1,0]
	v_pk_mul_f32 v[78:79], v[76:77], v[100:101] op_sel_hi:[1,0]
	v_cvt_pk_bf16_f32 v76, v84, v85
	v_cvt_pk_bf16_f32 v77, v86, v87
	v_cvt_pk_bf16_f32 v78, v78, v79
	v_cvt_pk_bf16_f32 v79, v88, v89
	global_store_dwordx4 v[98:99], v[76:79], off offset:256
	s_nop 1
	v_mov_b32_e32 v76, v231
	v_mad_i64_i32 v[78:79], s[20:21], v162, s40, v[148:149]
	v_pk_mul_f32 v[82:83], v[82:83], v[76:77] op_sel_hi:[1,0]
	v_pk_mul_f32 v[80:81], v[80:81], v[76:77] op_sel_hi:[1,0]
	v_pk_mul_f32 v[84:85], v[74:75], v[76:77] op_sel_hi:[1,0]
	v_pk_mul_f32 v[74:75], v[72:73], v[76:77] op_sel_hi:[1,0]
	v_lshl_add_u64 v[78:79], v[78:79], 0, v[154:155]
	v_cvt_pk_bf16_f32 v72, v80, v81
	v_cvt_pk_bf16_f32 v73, v82, v83
	v_cvt_pk_bf16_f32 v74, v74, v75
	v_cvt_pk_bf16_f32 v75, v84, v85
	global_store_dwordx4 v[78:79], v[72:75], off
	v_pk_mul_f32 v[68:69], v[68:69], v[76:77] op_sel_hi:[1,0]
	v_pk_mul_f32 v[80:81], v[66:67], v[76:77] op_sel_hi:[1,0]
	v_pk_mul_f32 v[66:67], v[64:65], v[76:77] op_sel_hi:[1,0]
	v_cvt_pk_bf16_f32 v64, v68, v69
	v_pk_mul_f32 v[70:71], v[70:71], v[76:77] op_sel_hi:[1,0]
	v_cvt_pk_bf16_f32 v66, v66, v67
	s_waitcnt lgkmcnt(0)
	v_cvt_pk_bf16_f32 v65, v70, v71
	v_cvt_pk_bf16_f32 v67, v80, v81
	global_store_dwordx4 v[78:79], v[64:67], off offset:256
	s_waitcnt lgkmcnt(0)
	s_nop 0
	s_nop 0
	s_nop 0
	s_nop 1
	v_mad_i64_i32 v[66:67], s[20:21], v160, s40, v[148:149]
	v_lshl_add_u64 v[66:67], v[66:67], 0, v[154:155]
	v_mov_b32_e32 v68, v232
	v_pk_mul_f32 v[62:63], v[62:63], v[68:69] op_sel_hi:[1,0]
	v_pk_mul_f32 v[60:61], v[60:61], v[68:69] op_sel_hi:[1,0]
	v_pk_mul_f32 v[70:71], v[58:59], v[68:69] op_sel_hi:[1,0]
	v_pk_mul_f32 v[58:59], v[56:57], v[68:69] op_sel_hi:[1,0]
	v_cvt_pk_bf16_f32 v56, v60, v61
	v_cvt_pk_bf16_f32 v57, v62, v63
	v_cvt_pk_bf16_f32 v58, v58, v59
	v_cvt_pk_bf16_f32 v59, v70, v71
	v_pk_mul_f32 v[52:53], v[52:53], v[68:69] op_sel_hi:[1,0]
	global_store_dwordx4 v[66:67], v[56:59], off
	s_nop 0
	v_pk_mul_f32 v[54:55], v[54:55], v[68:69] op_sel_hi:[1,0]
	v_pk_mul_f32 v[56:57], v[46:47], v[68:69] op_sel_hi:[1,0]
	v_pk_mul_f32 v[46:47], v[44:45], v[68:69] op_sel_hi:[1,0]
	v_cvt_pk_bf16_f32 v44, v52, v53
	v_cvt_pk_bf16_f32 v45, v54, v55
	v_cvt_pk_bf16_f32 v46, v46, v47
	v_cvt_pk_bf16_f32 v47, v56, v57
	global_store_dwordx4 v[66:67], v[44:47], off offset:256
	s_nop 1
	v_mov_b32_e32 v44, v233
	v_mad_i64_i32 v[46:47], s[20:21], v156, s40, v[148:149]
	v_pk_mul_f32 v[50:51], v[50:51], v[44:45] op_sel_hi:[1,0]
	v_pk_mul_f32 v[48:49], v[48:49], v[44:45] op_sel_hi:[1,0]
	v_pk_mul_f32 v[52:53], v[42:43], v[44:45] op_sel_hi:[1,0]
	v_pk_mul_f32 v[42:43], v[40:41], v[44:45] op_sel_hi:[1,0]
	v_lshl_add_u64 v[46:47], v[46:47], 0, v[154:155]
	v_cvt_pk_bf16_f32 v40, v48, v49
	v_cvt_pk_bf16_f32 v41, v50, v51
	v_cvt_pk_bf16_f32 v42, v42, v43
	v_cvt_pk_bf16_f32 v43, v52, v53
	global_store_dwordx4 v[46:47], v[40:43], off
	v_pk_mul_f32 v[36:37], v[36:37], v[44:45] op_sel_hi:[1,0]
	v_pk_mul_f32 v[48:49], v[30:31], v[44:45] op_sel_hi:[1,0]
	v_pk_mul_f32 v[30:31], v[28:29], v[44:45] op_sel_hi:[1,0]
	v_cvt_pk_bf16_f32 v28, v36, v37
	v_pk_mul_f32 v[38:39], v[38:39], v[44:45] op_sel_hi:[1,0]
	v_cvt_pk_bf16_f32 v30, v30, v31
	s_waitcnt lgkmcnt(0)
	v_cvt_pk_bf16_f32 v29, v38, v39
	v_cvt_pk_bf16_f32 v31, v48, v49
	global_store_dwordx4 v[46:47], v[28:31], off offset:256
	s_waitcnt lgkmcnt(0)
	s_nop 0
	s_nop 0
	s_nop 0
	s_nop 1
	v_mad_i64_i32 v[30:31], s[20:21], v150, s40, v[148:149]
	v_lshl_add_u64 v[30:31], v[30:31], 0, v[154:155]
	v_mov_b32_e32 v36, v234
	v_pk_mul_f32 v[34:35], v[34:35], v[36:37] op_sel_hi:[1,0]
	v_pk_mul_f32 v[32:33], v[32:33], v[36:37] op_sel_hi:[1,0]
	v_pk_mul_f32 v[38:39], v[26:27], v[36:37] op_sel_hi:[1,0]
	v_pk_mul_f32 v[26:27], v[24:25], v[36:37] op_sel_hi:[1,0]
	v_cvt_pk_bf16_f32 v24, v32, v33
	v_cvt_pk_bf16_f32 v25, v34, v35
	v_cvt_pk_bf16_f32 v26, v26, v27
	v_cvt_pk_bf16_f32 v27, v38, v39
	v_pk_mul_f32 v[20:21], v[20:21], v[36:37] op_sel_hi:[1,0]
	global_store_dwordx4 v[30:31], v[24:27], off
	s_nop 0
	v_pk_mul_f32 v[22:23], v[22:23], v[36:37] op_sel_hi:[1,0]
	v_pk_mul_f32 v[24:25], v[14:15], v[36:37] op_sel_hi:[1,0]
	v_pk_mul_f32 v[14:15], v[12:13], v[36:37] op_sel_hi:[1,0]
	v_cvt_pk_bf16_f32 v12, v20, v21
	v_cvt_pk_bf16_f32 v13, v22, v23
	v_cvt_pk_bf16_f32 v14, v14, v15
	v_cvt_pk_bf16_f32 v15, v24, v25
	global_store_dwordx4 v[30:31], v[12:15], off offset:256
	s_nop 1
	v_mov_b32_e32 v12, v235
	v_mad_i64_i32 v[14:15], s[20:21], v146, s40, v[148:149]
	v_pk_mul_f32 v[18:19], v[18:19], v[12:13] op_sel_hi:[1,0]
	v_pk_mul_f32 v[16:17], v[16:17], v[12:13] op_sel_hi:[1,0]
	v_pk_mul_f32 v[20:21], v[10:11], v[12:13] op_sel_hi:[1,0]
	v_pk_mul_f32 v[10:11], v[8:9], v[12:13] op_sel_hi:[1,0]
	v_lshl_add_u64 v[14:15], v[14:15], 0, v[154:155]
	v_cvt_pk_bf16_f32 v8, v16, v17
	v_cvt_pk_bf16_f32 v9, v18, v19
	v_cvt_pk_bf16_f32 v10, v10, v11
	v_cvt_pk_bf16_f32 v11, v20, v21
	global_store_dwordx4 v[14:15], v[8:11], off
	v_pk_mul_f32 v[6:7], v[6:7], v[12:13] op_sel_hi:[1,0]
	v_pk_mul_f32 v[4:5], v[4:5], v[12:13] op_sel_hi:[1,0]
	v_pk_mul_f32 v[8:9], v[2:3], v[12:13] op_sel_hi:[1,0]
	v_pk_mul_f32 v[2:3], v[0:1], v[12:13] op_sel_hi:[1,0]
	v_cvt_pk_bf16_f32 v0, v4, v5
	v_cvt_pk_bf16_f32 v1, v6, v7
	v_cvt_pk_bf16_f32 v2, v2, v3
	v_cvt_pk_bf16_f32 v3, v8, v9
	s_and_b64 vcc, exec, s[0:1]
	s_mov_b64 s[20:21], s[14:15]
	global_store_dwordx4 v[14:15], v[0:3], off offset:256
	s_cbranch_vccz .LBB0_919
	s_waitcnt vmcnt(0)
	v_readlane_b32 s40, v251, 54
	s_cmpk_gt_u32 s7, 0xff
	v_readlane_b32 s41, v251, 55
	s_cbranch_scc1 .LBB0_926
	s_barrier

; #define PG8_STAGE(bufoff, gbase, voff) do { _Pragma("unroll") for (int _i = 0; _i < 2; ++_i) \
;         __builtin_amdgcn_global_load_lds((const unsigned*)((const char*)(gbase) + (voff)[_i]), (LAS unsigned*)(lds + (bufoff) + ldsw + _i * 8192), 16, 0, 0); } while (0)
; #define PG8_LDA(dst, b, h) do { _Pragma("unroll") for (int m = 0; m < 4; ++m) _Pragma("unroll") for (int k = 0; k < 2; ++k) dst[m][k] = *(const LAS bf16x8*)(lds + PG8_SA(b, h) + aoff + m * 2048 + k * 1024); } while (0)
; #define PG8_LDB(dst, b, h) do { _Pragma("unroll") for (int n = 0; n < 2; ++n) _Pragma("unroll") for (int k = 0; k < 2; ++k) dst[n][k] = *(const LAS bf16x8*)(lds + PG8_SB(b, h) + boff + n * 2048 + k * 1024); } while (0)
; #define PG8_MMA(ai, bj, At, Bt) do { __builtin_amdgcn_s_setprio(1); _Pragma("unroll") for (int m = 0; m < 4; ++m) _Pragma("unroll") for (int n = 0; n < 2; ++n) _Pragma("unroll") for (int k = 0; k < 2; ++k) \
;         acc[ai][bj][m][n] = __builtin_amdgcn_mfma_f32_16x16x32_bf16(Bt[n][k], At[m][k], acc[ai][bj][m][n], 0, 0, 0); __builtin_amdgcn_s_setprio(0); } while (0)
; #define PG8_BAR __builtin_amdgcn_s_barrier()
; template <class Epi>
; __device__ __forceinline__ void gemm_phase(LAS unsigned char* lds, const Gemm g, const StaticOrder& S, const Epi& E) {
;     ...
;         const bool has_next = S.next(ui + 1, nxt);
;         const char* nA = has_next ? (const char*)g.A + (size_t)nxt.pm * tstepA : cA; const char* nB = has_next ? (const char*)g.Bt + (size_t)nxt.pn * tstepB : cB;
;         for (int t = 0; t < nt; t += 2) {
;             const bool last = (t == nt - 2);
;             const char* a1 = cA + (size_t)(t + 1) * kstep;
;             const char* a2 = last ? nA : cA + (size_t)(t + 2) * kstep; const char* b2 = last ? nB : cB + (size_t)(t + 2) * kstep;
;             const char* a3 = a2 + kstep; const char* b3 = b2 + kstep;
;             if (last) E.pre(cur, wr, fr, epre);
;             PG8_LDB(B0, 0, 0); PG8_SCHED; PG8_LDA(At, 0, 0); PG8_STAGE(PG8_SA(1, 1), a1 + hstepA, voffA);
;             PG8_WAIT_L(8); PG8_BAR; PG8_WAIT_L(0); PG8_MMA(0, 0, At, B0); PG8_BAR; PG8_SCHED;
;             PG8_LDB(B1, 0, 1); PG8_STAGE(PG8_SB(0, 0), b2, voffB);
;             PG8_BAR; PG8_WAIT_L(0); PG8_MMA(0, 1, At, B1); PG8_BAR;
;             PG8_LDA(At, 0, 1); PG8_STAGE(PG8_SA(0, 0), a2, voffA);
;             PG8_BAR; PG8_WAIT_L(0); PG8_MMA(1, 0, At, B0); PG8_BAR; PG8_SCHED;
.LBB0_1117:
	s_ashr_i32 s17, s16, 31
	s_lshl_b64 s[20:21], s[16:17], 19
	s_add_u32 s20, s27, s20
	s_addc_u32 s21, s28, s21
	s_and_b64 s[4:5], s[4:5], exec
	s_cselect_b32 s17, s21, s23
	s_cselect_b32 s43, s20, s22
	s_add_u32 s4, s24, 0x140080
	s_addc_u32 s5, s25, 0
	s_add_u32 s44, s22, 0x100
	s_addc_u32 s45, s23, 0
	s_mov_b32 s46, -2
	s_waitcnt lgkmcnt(0)
	ds_read_b128 v[128:131], v190
	ds_read_b128 v[132:135], v190 offset:1024
	ds_read_b128 v[136:139], v190 offset:2048
	ds_read_b128 v[140:143], v190 offset:3072
	s_add_u32 s22, s4, 0xffec0080
	s_addc_u32 s23, s5, -1
	s_cmp_eq_u32 s46, 12
	s_cselect_b32 s25, s19, s23
	s_cselect_b32 s24, s18, s22
	s_cselect_b32 s23, s17, s45
	s_cselect_b32 s22, s43, s44
	v_lshl_add_u64 v[186:187], s[4:5], 0, v[162:163]
	s_add_i32 m0, s9, 0xc000
	ds_read_b128 v[144:147], v191
	ds_read_b128 v[148:151], v191 offset:1024
	ds_read_b128 v[170:173], v191 offset:2048
	ds_read_b128 v[174:177], v191 offset:3072
	ds_read_b128 v[178:181], v191 offset:4096
	ds_read_b128 v[182:185], v191 offset:5120
	ds_read_b128 v[194:197], v191 offset:6144
	ds_read_b128 v[198:201], v191 offset:7168
	global_load_lds_dwordx4 v[186:187], off
	v_lshl_add_u64 v[186:187], s[4:5], 0, v[164:165]
	s_add_i32 m0, s9, 0xe000
	s_nop 0
	global_load_lds_dwordx4 v[186:187], off
	s_waitcnt lgkmcnt(8)
	s_barrier
	s_waitcnt lgkmcnt(7)
	v_mfma_f32_16x16x32_bf16 v[124:127], v[128:131], v[144:147], 0
	v_mfma_f32_16x16x32_bf16 v[120:123], v[136:139], v[144:147], 0
	s_waitcnt lgkmcnt(5)
	v_mfma_f32_16x16x32_bf16 v[108:111], v[128:131], v[170:173], 0
	v_mfma_f32_16x16x32_bf16 v[104:107], v[136:139], v[170:173], 0
	s_waitcnt lgkmcnt(3)
	v_mfma_f32_16x16x32_bf16 v[92:95], v[128:131], v[178:181], 0
	v_mfma_f32_16x16x32_bf16 v[88:91], v[136:139], v[178:181], 0
	s_waitcnt lgkmcnt(1)
	v_mfma_f32_16x16x32_bf16 v[76:79], v[128:131], v[194:197], 0
	v_mfma_f32_16x16x32_bf16 v[72:75], v[136:139], v[194:197], 0
	v_mfma_f32_16x16x32_bf16 v[124:127], v[132:135], v[148:151], v[124:127]
	v_mfma_f32_16x16x32_bf16 v[120:123], v[140:143], v[148:151], v[120:123]
	v_mfma_f32_16x16x32_bf16 v[108:111], v[132:135], v[174:177], v[108:111]
	v_mfma_f32_16x16x32_bf16 v[104:107], v[140:143], v[174:177], v[104:107]
	v_mfma_f32_16x16x32_bf16 v[92:95], v[132:135], v[182:185], v[92:95]
	v_mfma_f32_16x16x32_bf16 v[88:91], v[140:143], v[182:185], v[88:91]
	s_waitcnt lgkmcnt(0)
	v_mfma_f32_16x16x32_bf16 v[76:79], v[132:135], v[198:201], v[76:79]
	v_mfma_f32_16x16x32_bf16 v[72:75], v[140:143], v[198:201], v[72:75]
	s_barrier
	s_add_i32 s47, s40, s29
	v_lshl_add_u64 v[186:187], s[22:23], 0, v[156:157]
	s_mov_b32 m0, s47
	ds_read_b128 v[202:205], v192
	ds_read_b128 v[206:209], v192 offset:1024
	ds_read_b128 v[210:213], v192 offset:2048
	ds_read_b128 v[214:217], v192 offset:3072
	global_load_lds_dwordx4 v[186:187], off
	v_lshl_add_u64 v[218:219], s[22:23], 0, v[160:161]
	s_add_i32 m0, s47, 0x2000
	s_nop 0
	global_load_lds_dwordx4 v[218:219], off
	s_barrier
	s_waitcnt lgkmcnt(3)
	v_mfma_f32_16x16x32_bf16 v[116:119], v[202:205], v[144:147], 0
	s_waitcnt lgkmcnt(1)
	v_mfma_f32_16x16x32_bf16 v[112:115], v[210:213], v[144:147], 0
	v_mfma_f32_16x16x32_bf16 v[100:103], v[202:205], v[170:173], 0
	v_mfma_f32_16x16x32_bf16 v[96:99], v[210:213], v[170:173], 0
	v_mfma_f32_16x16x32_bf16 v[84:87], v[202:205], v[178:181], 0
	v_mfma_f32_16x16x32_bf16 v[80:83], v[210:213], v[178:181], 0
	v_mfma_f32_16x16x32_bf16 v[68:71], v[202:205], v[194:197], 0
	v_mfma_f32_16x16x32_bf16 v[64:67], v[210:213], v[194:197], 0
	v_mfma_f32_16x16x32_bf16 v[116:119], v[206:209], v[148:151], v[116:119]
	s_waitcnt lgkmcnt(0)
	v_mfma_f32_16x16x32_bf16 v[112:115], v[214:217], v[148:151], v[112:115]
	v_mfma_f32_16x16x32_bf16 v[100:103], v[206:209], v[174:177], v[100:103]
	v_mfma_f32_16x16x32_bf16 v[96:99], v[214:217], v[174:177], v[96:99]
	v_mfma_f32_16x16x32_bf16 v[84:87], v[206:209], v[182:185], v[84:87]
	v_mfma_f32_16x16x32_bf16 v[80:83], v[214:217], v[182:185], v[80:83]
	v_mfma_f32_16x16x32_bf16 v[68:71], v[206:209], v[198:201], v[68:71]
	v_mfma_f32_16x16x32_bf16 v[64:67], v[214:217], v[198:201], v[64:67]
	s_mov_b32 m0, s9
	v_lshl_add_u64 v[220:221], s[24:25], 0, v[154:155]
	s_barrier
	ds_read_b128 v[144:147], v191 offset:16384
	ds_read_b128 v[148:151], v191 offset:17408
	ds_read_b128 v[170:173], v191 offset:18432
	ds_read_b128 v[174:177], v191 offset:19456
	ds_read_b128 v[178:181], v191 offset:20480
	ds_read_b128 v[182:185], v191 offset:21504
	ds_read_b128 v[194:197], v191 offset:22528
	ds_read_b128 v[198:201], v191 offset:23552
	global_load_lds_dwordx4 v[220:221], off
	v_lshl_add_u64 v[222:223], s[24:25], 0, v[158:159]
	s_mov_b32 m0, s30
	s_nop 0
	global_load_lds_dwordx4 v[222:223], off
	s_barrier
	s_waitcnt lgkmcnt(7)
	v_mfma_f32_16x16x32_bf16 v[60:63], v[128:131], v[144:147], 0
	v_mfma_f32_16x16x32_bf16 v[56:59], v[136:139], v[144:147], 0
	s_waitcnt lgkmcnt(5)
	v_mfma_f32_16x16x32_bf16 v[44:47], v[128:131], v[170:173], 0
	v_mfma_f32_16x16x32_bf16 v[40:43], v[136:139], v[170:173], 0
	s_waitcnt lgkmcnt(3)
	v_mfma_f32_16x16x32_bf16 v[28:31], v[128:131], v[178:181], 0
	v_mfma_f32_16x16x32_bf16 v[24:27], v[136:139], v[178:181], 0
	s_waitcnt lgkmcnt(1)
	v_mfma_f32_16x16x32_bf16 v[12:15], v[128:131], v[194:197], 0
	v_mfma_f32_16x16x32_bf16 v[8:11], v[136:139], v[194:197], 0
	v_mfma_f32_16x16x32_bf16 v[60:63], v[132:135], v[148:151], v[60:63]
	v_mfma_f32_16x16x32_bf16 v[56:59], v[140:143], v[148:151], v[56:59]
	v_mfma_f32_16x16x32_bf16 v[44:47], v[132:135], v[174:177], v[44:47]
	v_mfma_f32_16x16x32_bf16 v[40:43], v[140:143], v[174:177], v[40:43]
	v_mfma_f32_16x16x32_bf16 v[28:31], v[132:135], v[182:185], v[28:31]
	v_mfma_f32_16x16x32_bf16 v[24:27], v[140:143], v[182:185], v[24:27]
	s_waitcnt lgkmcnt(0)
	v_mfma_f32_16x16x32_bf16 v[12:15], v[132:135], v[198:201], v[12:15]
	v_mfma_f32_16x16x32_bf16 v[8:11], v[140:143], v[198:201], v[8:11]
	s_barrier
; #define PG8_STAGE(bufoff, gbase, voff) do { _Pragma("unroll") for (int _i = 0; _i < 2; ++_i) \
;         __builtin_amdgcn_global_load_lds((const unsigned*)((const char*)(gbase) + (voff)[_i]), (LAS unsigned*)(lds + (bufoff) + ldsw + _i * 8192), 16, 0, 0); } while (0)
; #define PG8_LDA(dst, b, h) do { _Pragma("unroll") for (int m = 0; m < 4; ++m) _Pragma("unroll") for (int k = 0; k < 2; ++k) dst[m][k] = *(const LAS bf16x8*)(lds + PG8_SA(b, h) + aoff + m * 2048 + k * 1024); } while (0)
; #define PG8_LDB(dst, b, h) do { _Pragma("unroll") for (int n = 0; n < 2; ++n) _Pragma("unroll") for (int k = 0; k < 2; ++k) dst[n][k] = *(const LAS bf16x8*)(lds + PG8_SB(b, h) + boff + n * 2048 + k * 1024); } while (0)
; #define PG8_MMA(ai, bj, At, Bt) do { __builtin_amdgcn_s_setprio(1); _Pragma("unroll") for (int m = 0; m < 4; ++m) _Pragma("unroll") for (int n = 0; n < 2; ++n) _Pragma("unroll") for (int k = 0; k < 2; ++k) \
;         acc[ai][bj][m][n] = __builtin_amdgcn_mfma_f32_16x16x32_bf16(Bt[n][k], At[m][k], acc[ai][bj][m][n], 0, 0, 0); __builtin_amdgcn_s_setprio(0); } while (0)
; #define PG8_WAIT_V(n) asm volatile("s_waitcnt vmcnt(" #n ")" ::: "memory")
; #define PG8_WAIT_L(n) asm volatile("s_waitcnt lgkmcnt(" #n ")" ::: "memory")
; #define PG8_BAR __builtin_amdgcn_s_barrier()
; #define PG8_SCHED __builtin_amdgcn_sched_barrier(0)
; template <class Epi>
; __device__ __forceinline__ void gemm_phase(LAS unsigned char* lds, const Gemm g, const StaticOrder& S, const Epi& E) {
;     ...
;             PG8_STAGE(PG8_SB(0, 1), b2 + hstepB, voffB);
;             PG8_WAIT_V(6); PG8_BAR; PG8_MMA(1, 1, At, B1); PG8_BAR;
;             PG8_LDB(B0, 1, 0); PG8_SCHED; PG8_LDA(At, 1, 0); PG8_STAGE(PG8_SA(0, 1), a2 + hstepA, voffA);
;             PG8_WAIT_L(8); PG8_BAR; PG8_WAIT_L(0); PG8_MMA(0, 0, At, B0); PG8_BAR; PG8_SCHED;
;             PG8_LDB(B1, 1, 1); PG8_STAGE(PG8_SB(1, 0), b3, voffB);
;             PG8_BAR; PG8_WAIT_L(0); PG8_MMA(0, 1, At, B1); PG8_BAR;
;             PG8_LDA(At, 1, 1); PG8_STAGE(PG8_SA(1, 0), a3, voffA);
;             PG8_BAR; PG8_WAIT_L(0); PG8_MMA(1, 0, At, B0); PG8_BAR; PG8_SCHED;
	s_add_u32 s48, s22, 0x40000
	s_addc_u32 s49, s23, 0
	s_add_i32 s47, s41, s29
	v_lshl_add_u64 v[128:129], s[48:49], 0, v[156:157]
	s_mov_b32 m0, s47
	s_nop 0
	global_load_lds_dwordx4 v[128:129], off
	v_lshl_add_u64 v[128:129], s[48:49], 0, v[160:161]
	s_add_i32 m0, s47, 0x2000
	s_nop 0
	global_load_lds_dwordx4 v[128:129], off
	s_waitcnt vmcnt(6)
	s_barrier
	v_mfma_f32_16x16x32_bf16 v[52:55], v[202:205], v[144:147], 0
	v_mfma_f32_16x16x32_bf16 v[48:51], v[210:213], v[144:147], 0
	v_mfma_f32_16x16x32_bf16 v[36:39], v[202:205], v[170:173], 0
	v_mfma_f32_16x16x32_bf16 v[32:35], v[210:213], v[170:173], 0
	v_mfma_f32_16x16x32_bf16 v[20:23], v[202:205], v[178:181], 0
	v_mfma_f32_16x16x32_bf16 v[16:19], v[210:213], v[178:181], 0
	v_mfma_f32_16x16x32_bf16 v[4:7], v[202:205], v[194:197], 0
	v_mfma_f32_16x16x32_bf16 v[0:3], v[210:213], v[194:197], 0
	v_mfma_f32_16x16x32_bf16 v[52:55], v[206:209], v[148:151], v[52:55]
	v_mfma_f32_16x16x32_bf16 v[48:51], v[214:217], v[148:151], v[48:51]
	v_mfma_f32_16x16x32_bf16 v[36:39], v[206:209], v[174:177], v[36:39]
	v_mfma_f32_16x16x32_bf16 v[32:35], v[214:217], v[174:177], v[32:35]
	v_mfma_f32_16x16x32_bf16 v[20:23], v[206:209], v[182:185], v[20:23]
	v_mfma_f32_16x16x32_bf16 v[16:19], v[214:217], v[182:185], v[16:19]
	v_mfma_f32_16x16x32_bf16 v[4:7], v[206:209], v[198:201], v[4:7]
	v_mfma_f32_16x16x32_bf16 v[0:3], v[214:217], v[198:201], v[0:3]
	s_add_i32 s47, 0, 0x18000
	v_add_u32_e32 v140, s47, v188
	s_barrier
	ds_read_b128 v[128:131], v140
	ds_read_b128 v[132:135], v140 offset:1024
	ds_read_b128 v[136:139], v140 offset:2048
	ds_read_b128 v[140:143], v140 offset:3072
	s_add_u32 s24, s24, 0x140000
	s_addc_u32 s25, s25, 0
	s_mov_b32 m0, s31
	v_lshl_add_u64 v[202:203], s[24:25], 0, v[154:155]
	ds_read_b128 v[144:147], v191 offset:32768
	ds_read_b128 v[148:151], v191 offset:33792
	ds_read_b128 v[170:173], v191 offset:34816
	ds_read_b128 v[174:177], v191 offset:35840
	ds_read_b128 v[178:181], v191 offset:36864
	ds_read_b128 v[182:185], v191 offset:37888
	ds_read_b128 v[194:197], v191 offset:38912
	ds_read_b128 v[198:201], v191 offset:39936
	global_load_lds_dwordx4 v[202:203], off
	v_lshl_add_u64 v[202:203], s[24:25], 0, v[158:159]
	s_mov_b32 m0, s34
	s_nop 0
	global_load_lds_dwordx4 v[202:203], off
	s_waitcnt lgkmcnt(8)
	s_barrier
	s_waitcnt lgkmcnt(7)
	v_mfma_f32_16x16x32_bf16 v[124:127], v[128:131], v[144:147], v[124:127]
	v_mfma_f32_16x16x32_bf16 v[120:123], v[136:139], v[144:147], v[120:123]
	s_waitcnt lgkmcnt(5)
	v_mfma_f32_16x16x32_bf16 v[108:111], v[128:131], v[170:173], v[108:111]
	v_mfma_f32_16x16x32_bf16 v[104:107], v[136:139], v[170:173], v[104:107]
	s_waitcnt lgkmcnt(3)
	v_mfma_f32_16x16x32_bf16 v[92:95], v[128:131], v[178:181], v[92:95]
	v_mfma_f32_16x16x32_bf16 v[88:91], v[136:139], v[178:181], v[88:91]
	s_waitcnt lgkmcnt(1)
	v_mfma_f32_16x16x32_bf16 v[76:79], v[128:131], v[194:197], v[76:79]
	v_mfma_f32_16x16x32_bf16 v[72:75], v[136:139], v[194:197], v[72:75]
	v_mfma_f32_16x16x32_bf16 v[124:127], v[132:135], v[148:151], v[124:127]
	v_mfma_f32_16x16x32_bf16 v[120:123], v[140:143], v[148:151], v[120:123]
	v_mfma_f32_16x16x32_bf16 v[108:111], v[132:135], v[174:177], v[108:111]
	v_mfma_f32_16x16x32_bf16 v[104:107], v[140:143], v[174:177], v[104:107]
	v_mfma_f32_16x16x32_bf16 v[92:95], v[132:135], v[182:185], v[92:95]
	v_mfma_f32_16x16x32_bf16 v[88:91], v[140:143], v[182:185], v[88:91]
	s_waitcnt lgkmcnt(0)
	v_mfma_f32_16x16x32_bf16 v[76:79], v[132:135], v[198:201], v[76:79]
	v_mfma_f32_16x16x32_bf16 v[72:75], v[140:143], v[198:201], v[72:75]
	s_barrier
	s_add_i32 s24, 0, 0x1c000
	s_add_i32 s25, s47, s29
	v_add_u32_e32 v214, s24, v188
	v_lshl_add_u64 v[186:187], v[186:187], 0, s[14:15]
	s_mov_b32 m0, s25
	ds_read_b128 v[202:205], v214
	ds_read_b128 v[206:209], v214 offset:1024
	ds_read_b128 v[210:213], v214 offset:2048
	ds_read_b128 v[214:217], v214 offset:3072
	global_load_lds_dwordx4 v[186:187], off
	v_lshl_add_u64 v[186:187], v[218:219], 0, s[14:15]
	s_add_i32 m0, s25, 0x2000
	s_nop 0
	global_load_lds_dwordx4 v[186:187], off
	s_barrier
	s_waitcnt lgkmcnt(3)
	v_mfma_f32_16x16x32_bf16 v[116:119], v[202:205], v[144:147], v[116:119]
	s_waitcnt lgkmcnt(1)
	v_mfma_f32_16x16x32_bf16 v[112:115], v[210:213], v[144:147], v[112:115]
	v_mfma_f32_16x16x32_bf16 v[100:103], v[202:205], v[170:173], v[100:103]
	v_mfma_f32_16x16x32_bf16 v[96:99], v[210:213], v[170:173], v[96:99]
	v_mfma_f32_16x16x32_bf16 v[84:87], v[202:205], v[178:181], v[84:87]
	v_mfma_f32_16x16x32_bf16 v[80:83], v[210:213], v[178:181], v[80:83]
	v_mfma_f32_16x16x32_bf16 v[68:71], v[202:205], v[194:197], v[68:71]
	v_mfma_f32_16x16x32_bf16 v[64:67], v[210:213], v[194:197], v[64:67]
	v_mfma_f32_16x16x32_bf16 v[116:119], v[206:209], v[148:151], v[116:119]
	s_waitcnt lgkmcnt(0)
	v_mfma_f32_16x16x32_bf16 v[112:115], v[214:217], v[148:151], v[112:115]
	v_mfma_f32_16x16x32_bf16 v[100:103], v[206:209], v[174:177], v[100:103]
	v_mfma_f32_16x16x32_bf16 v[96:99], v[214:217], v[174:177], v[96:99]
	v_mfma_f32_16x16x32_bf16 v[84:87], v[206:209], v[182:185], v[84:87]
	v_mfma_f32_16x16x32_bf16 v[80:83], v[214:217], v[182:185], v[80:83]
	v_mfma_f32_16x16x32_bf16 v[68:71], v[206:209], v[198:201], v[68:71]
	v_mfma_f32_16x16x32_bf16 v[64:67], v[214:217], v[198:201], v[64:67]
	s_mov_b32 m0, s36
	v_lshl_add_u64 v[186:187], v[220:221], 0, s[14:15]
	s_barrier
	ds_read_b128 v[144:147], v191 offset:49152
	ds_read_b128 v[148:151], v191 offset:50176
	ds_read_b128 v[170:173], v191 offset:51200
	ds_read_b128 v[174:177], v191 offset:52224
	ds_read_b128 v[178:181], v191 offset:53248
	ds_read_b128 v[182:185], v191 offset:54272
	ds_read_b128 v[194:197], v191 offset:55296
	ds_read_b128 v[198:201], v191 offset:56320
	global_load_lds_dwordx4 v[186:187], off
	v_lshl_add_u64 v[186:187], v[222:223], 0, s[14:15]
	s_mov_b32 m0, s37
	s_nop 0
	global_load_lds_dwordx4 v[186:187], off
	s_barrier
; #define PG8_STAGE(bufoff, gbase, voff) do { _Pragma("unroll") for (int _i = 0; _i < 2; ++_i) \
;         __builtin_amdgcn_global_load_lds((const unsigned*)((const char*)(gbase) + (voff)[_i]), (LAS unsigned*)(lds + (bufoff) + ldsw + _i * 8192), 16, 0, 0); } while (0)
; #define PG8_LDA(dst, b, h) do { _Pragma("unroll") for (int m = 0; m < 4; ++m) _Pragma("unroll") for (int k = 0; k < 2; ++k) dst[m][k] = *(const LAS bf16x8*)(lds + PG8_SA(b, h) + aoff + m * 2048 + k * 1024); } while (0)
; #define PG8_WAIT_V(n) asm volatile("s_waitcnt vmcnt(" #n ")" ::: "memory")
; template <class Epi>
; __device__ __forceinline__ void gemm_phase(LAS unsigned char* lds, const Gemm g, const StaticOrder& S, const Epi& E) {
;     ...
;         for (int t = 0; t < nt; t += 2) {
;             const bool last = (t == nt - 2);
;             const char* a1 = cA + (size_t)(t + 1) * kstep;
;             const char* a2 = last ? nA : cA + (size_t)(t + 2) * kstep; const char* b2 = last ? nB : cB + (size_t)(t + 2) * kstep;
;             const char* a3 = a2 + kstep; const char* b3 = b2 + kstep;
;             if (last) E.pre(cur, wr, fr, epre);
;             PG8_LDB(B0, 0, 0); PG8_SCHED; PG8_LDA(At, 0, 0); PG8_STAGE(PG8_SA(1, 1), a1 + hstepA, voffA);
;             PG8_WAIT_L(8); PG8_BAR; PG8_WAIT_L(0); PG8_MMA(0, 0, At, B0); PG8_BAR; PG8_SCHED;
;             PG8_LDB(B1, 0, 1); PG8_STAGE(PG8_SB(0, 0), b2, voffB);
;             PG8_BAR; PG8_WAIT_L(0); PG8_MMA(0, 1, At, B1); PG8_BAR;
;             PG8_LDA(At, 0, 1); PG8_STAGE(PG8_SA(0, 0), a2, voffA);
;             PG8_BAR; PG8_WAIT_L(0); PG8_MMA(1, 0, At, B0); PG8_BAR; PG8_SCHED;
;             PG8_STAGE(PG8_SB(0, 1), b2 + hstepB, voffB);
;             PG8_WAIT_V(6); PG8_BAR; PG8_MMA(1, 1, At, B1); PG8_BAR;
;             PG8_LDB(B0, 1, 0); PG8_SCHED; PG8_LDA(At, 1, 0); PG8_STAGE(PG8_SA(0, 1), a2 + hstepA, voffA);
;             PG8_WAIT_L(8); PG8_BAR; PG8_WAIT_L(0); PG8_MMA(0, 0, At, B0); PG8_BAR; PG8_SCHED;
;             PG8_LDB(B1, 1, 1); PG8_STAGE(PG8_SB(1, 0), b3, voffB);
;             PG8_BAR; PG8_WAIT_L(0); PG8_MMA(0, 1, At, B1); PG8_BAR;
;             PG8_LDA(At, 1, 1); PG8_STAGE(PG8_SA(1, 0), a3, voffA);
;             PG8_BAR; PG8_WAIT_L(0); PG8_MMA(1, 0, At, B0); PG8_BAR; PG8_SCHED;
;             PG8_STAGE(PG8_SB(1, 1), b3 + hstepB, voffB);
;             PG8_WAIT_V(6); PG8_BAR; PG8_MMA(1, 1, At, B1); PG8_BAR;
	s_waitcnt lgkmcnt(7)
	v_mfma_f32_16x16x32_bf16 v[60:63], v[128:131], v[144:147], v[60:63]
	v_mfma_f32_16x16x32_bf16 v[56:59], v[136:139], v[144:147], v[56:59]
	s_waitcnt lgkmcnt(5)
	v_mfma_f32_16x16x32_bf16 v[44:47], v[128:131], v[170:173], v[44:47]
	v_mfma_f32_16x16x32_bf16 v[40:43], v[136:139], v[170:173], v[40:43]
	s_waitcnt lgkmcnt(3)
	v_mfma_f32_16x16x32_bf16 v[28:31], v[128:131], v[178:181], v[28:31]
	v_mfma_f32_16x16x32_bf16 v[24:27], v[136:139], v[178:181], v[24:27]
	s_waitcnt lgkmcnt(1)
	v_mfma_f32_16x16x32_bf16 v[12:15], v[128:131], v[194:197], v[12:15]
	v_mfma_f32_16x16x32_bf16 v[8:11], v[136:139], v[194:197], v[8:11]
	v_mfma_f32_16x16x32_bf16 v[60:63], v[132:135], v[148:151], v[60:63]
	v_mfma_f32_16x16x32_bf16 v[56:59], v[140:143], v[148:151], v[56:59]
	v_mfma_f32_16x16x32_bf16 v[44:47], v[132:135], v[174:177], v[44:47]
	v_mfma_f32_16x16x32_bf16 v[40:43], v[140:143], v[174:177], v[40:43]
	v_mfma_f32_16x16x32_bf16 v[28:31], v[132:135], v[182:185], v[28:31]
	v_mfma_f32_16x16x32_bf16 v[24:27], v[140:143], v[182:185], v[24:27]
	s_waitcnt lgkmcnt(0)
	v_mfma_f32_16x16x32_bf16 v[12:15], v[132:135], v[198:201], v[12:15]
	v_mfma_f32_16x16x32_bf16 v[8:11], v[140:143], v[198:201], v[8:11]
	s_barrier
	s_add_u32 s22, s22, 0x40080
	s_addc_u32 s23, s23, 0
	s_add_i32 s24, s24, s29
	v_lshl_add_u64 v[128:129], s[22:23], 0, v[156:157]
	s_mov_b32 m0, s24
	s_nop 0
	global_load_lds_dwordx4 v[128:129], off
	v_lshl_add_u64 v[128:129], s[22:23], 0, v[160:161]
	s_add_i32 m0, s24, 0x2000
	s_nop 0
	global_load_lds_dwordx4 v[128:129], off
	s_waitcnt vmcnt(6)
	s_barrier
	v_mfma_f32_16x16x32_bf16 v[52:55], v[202:205], v[144:147], v[52:55]
	v_mfma_f32_16x16x32_bf16 v[48:51], v[210:213], v[144:147], v[48:51]
	v_mfma_f32_16x16x32_bf16 v[36:39], v[202:205], v[170:173], v[36:39]
	v_mfma_f32_16x16x32_bf16 v[32:35], v[210:213], v[170:173], v[32:35]
	v_mfma_f32_16x16x32_bf16 v[20:23], v[202:205], v[178:181], v[20:23]
	v_mfma_f32_16x16x32_bf16 v[16:19], v[210:213], v[178:181], v[16:19]
	v_mfma_f32_16x16x32_bf16 v[4:7], v[202:205], v[194:197], v[4:7]
	v_mfma_f32_16x16x32_bf16 v[0:3], v[210:213], v[194:197], v[0:3]
	v_mfma_f32_16x16x32_bf16 v[52:55], v[206:209], v[148:151], v[52:55]
	v_mfma_f32_16x16x32_bf16 v[48:51], v[214:217], v[148:151], v[48:51]
	v_mfma_f32_16x16x32_bf16 v[36:39], v[206:209], v[174:177], v[36:39]
	v_mfma_f32_16x16x32_bf16 v[32:35], v[214:217], v[174:177], v[32:35]
	v_mfma_f32_16x16x32_bf16 v[20:23], v[206:209], v[182:185], v[20:23]
	v_mfma_f32_16x16x32_bf16 v[16:19], v[214:217], v[182:185], v[16:19]
	v_mfma_f32_16x16x32_bf16 v[4:7], v[206:209], v[198:201], v[4:7]
	v_mfma_f32_16x16x32_bf16 v[0:3], v[214:217], v[198:201], v[0:3]
	s_add_i32 s46, s46, 2
	s_add_u32 s4, s4, 0x100
	s_addc_u32 s5, s5, 0
	s_add_u32 s44, s44, 0x100
	s_addc_u32 s45, s45, 0
	s_cmp_gt_u32 s46, 13
	s_barrier
.LBB0_1118:
	ds_read_b128 v[128:131], v190
	ds_read_b128 v[132:135], v190 offset:1024
	ds_read_b128 v[136:139], v190 offset:2048
	ds_read_b128 v[140:143], v190 offset:3072
	s_add_u32 s22, s4, 0xffec0080
	s_addc_u32 s23, s5, -1
	s_cmp_eq_u32 s46, 12
	s_cselect_b32 s25, s19, s23
	s_cselect_b32 s24, s18, s22
	s_cselect_b32 s23, s17, s45
	s_cselect_b32 s22, s43, s44
	v_lshl_add_u64 v[186:187], s[4:5], 0, v[162:163]
	s_add_i32 m0, s9, 0xc000
	ds_read_b128 v[144:147], v191
	ds_read_b128 v[148:151], v191 offset:1024
	ds_read_b128 v[170:173], v191 offset:2048
	ds_read_b128 v[174:177], v191 offset:3072
	ds_read_b128 v[178:181], v191 offset:4096
	ds_read_b128 v[182:185], v191 offset:5120
	ds_read_b128 v[194:197], v191 offset:6144
	ds_read_b128 v[198:201], v191 offset:7168
	global_load_lds_dwordx4 v[186:187], off
	v_lshl_add_u64 v[186:187], s[4:5], 0, v[164:165]
	s_add_i32 m0, s9, 0xe000
	s_nop 0
	global_load_lds_dwordx4 v[186:187], off
	s_waitcnt lgkmcnt(8)
	s_barrier
	s_waitcnt lgkmcnt(7)
	v_mfma_f32_16x16x32_bf16 v[124:127], v[128:131], v[144:147], v[124:127]
	v_mfma_f32_16x16x32_bf16 v[120:123], v[136:139], v[144:147], v[120:123]
	s_waitcnt lgkmcnt(5)
	v_mfma_f32_16x16x32_bf16 v[108:111], v[128:131], v[170:173], v[108:111]
	v_mfma_f32_16x16x32_bf16 v[104:107], v[136:139], v[170:173], v[104:107]
	s_waitcnt lgkmcnt(3)
	v_mfma_f32_16x16x32_bf16 v[92:95], v[128:131], v[178:181], v[92:95]
	v_mfma_f32_16x16x32_bf16 v[88:91], v[136:139], v[178:181], v[88:91]
	s_waitcnt lgkmcnt(1)
	v_mfma_f32_16x16x32_bf16 v[76:79], v[128:131], v[194:197], v[76:79]
	v_mfma_f32_16x16x32_bf16 v[72:75], v[136:139], v[194:197], v[72:75]
	v_mfma_f32_16x16x32_bf16 v[124:127], v[132:135], v[148:151], v[124:127]
	v_mfma_f32_16x16x32_bf16 v[120:123], v[140:143], v[148:151], v[120:123]
	v_mfma_f32_16x16x32_bf16 v[108:111], v[132:135], v[174:177], v[108:111]
	v_mfma_f32_16x16x32_bf16 v[104:107], v[140:143], v[174:177], v[104:107]
	v_mfma_f32_16x16x32_bf16 v[92:95], v[132:135], v[182:185], v[92:95]
	v_mfma_f32_16x16x32_bf16 v[88:91], v[140:143], v[182:185], v[88:91]
	s_waitcnt lgkmcnt(0)
	v_mfma_f32_16x16x32_bf16 v[76:79], v[132:135], v[198:201], v[76:79]
	v_mfma_f32_16x16x32_bf16 v[72:75], v[140:143], v[198:201], v[72:75]
	s_barrier
	s_add_i32 s47, s40, s29
	v_lshl_add_u64 v[186:187], s[22:23], 0, v[156:157]
	s_mov_b32 m0, s47
	ds_read_b128 v[202:205], v192
	ds_read_b128 v[206:209], v192 offset:1024
	ds_read_b128 v[210:213], v192 offset:2048
	ds_read_b128 v[214:217], v192 offset:3072
	global_load_lds_dwordx4 v[186:187], off
	v_lshl_add_u64 v[218:219], s[22:23], 0, v[160:161]
	s_add_i32 m0, s47, 0x2000
	s_nop 0
	global_load_lds_dwordx4 v[218:219], off
	s_barrier
; #define PG8_STAGE(bufoff, gbase, voff) do { _Pragma("unroll") for (int _i = 0; _i < 2; ++_i) \
;         __builtin_amdgcn_global_load_lds((const unsigned*)((const char*)(gbase) + (voff)[_i]), (LAS unsigned*)(lds + (bufoff) + ldsw + _i * 8192), 16, 0, 0); } while (0)
; #define PG8_LDA(dst, b, h) do { _Pragma("unroll") for (int m = 0; m < 4; ++m) _Pragma("unroll") for (int k = 0; k < 2; ++k) dst[m][k] = *(const LAS bf16x8*)(lds + PG8_SA(b, h) + aoff + m * 2048 + k * 1024); } while (0)
; #define PG8_LDB(dst, b, h) do { _Pragma("unroll") for (int n = 0; n < 2; ++n) _Pragma("unroll") for (int k = 0; k < 2; ++k) dst[n][k] = *(const LAS bf16x8*)(lds + PG8_SB(b, h) + boff + n * 2048 + k * 1024); } while (0)
; #define PG8_MMA(ai, bj, At, Bt) do { __builtin_amdgcn_s_setprio(1); _Pragma("unroll") for (int m = 0; m < 4; ++m) _Pragma("unroll") for (int n = 0; n < 2; ++n) _Pragma("unroll") for (int k = 0; k < 2; ++k) \
;         acc[ai][bj][m][n] = __builtin_amdgcn_mfma_f32_16x16x32_bf16(Bt[n][k], At[m][k], acc[ai][bj][m][n], 0, 0, 0); __builtin_amdgcn_s_setprio(0); } while (0)
; #define PG8_WAIT_V(n) asm volatile("s_waitcnt vmcnt(" #n ")" ::: "memory")
; #define PG8_WAIT_L(n) asm volatile("s_waitcnt lgkmcnt(" #n ")" ::: "memory")
; #define PG8_BAR __builtin_amdgcn_s_barrier()
; #define PG8_SCHED __builtin_amdgcn_sched_barrier(0)
; template <class Epi>
; __device__ __forceinline__ void gemm_phase(LAS unsigned char* lds, const Gemm g, const StaticOrder& S, const Epi& E) {
;     ...
;             PG8_BAR; PG8_WAIT_L(0); PG8_MMA(0, 1, At, B1); PG8_BAR;
;             PG8_LDA(At, 0, 1); PG8_STAGE(PG8_SA(0, 0), a2, voffA);
;             PG8_BAR; PG8_WAIT_L(0); PG8_MMA(1, 0, At, B0); PG8_BAR; PG8_SCHED;
;             PG8_STAGE(PG8_SB(0, 1), b2 + hstepB, voffB);
;             PG8_WAIT_V(6); PG8_BAR; PG8_MMA(1, 1, At, B1); PG8_BAR;
;             PG8_LDB(B0, 1, 0); PG8_SCHED; PG8_LDA(At, 1, 0); PG8_STAGE(PG8_SA(0, 1), a2 + hstepA, voffA);
;             PG8_WAIT_L(8); PG8_BAR; PG8_WAIT_L(0); PG8_MMA(0, 0, At, B0); PG8_BAR; PG8_SCHED;
	s_waitcnt lgkmcnt(3)
	v_mfma_f32_16x16x32_bf16 v[116:119], v[202:205], v[144:147], v[116:119]
	s_waitcnt lgkmcnt(1)
	v_mfma_f32_16x16x32_bf16 v[112:115], v[210:213], v[144:147], v[112:115]
	v_mfma_f32_16x16x32_bf16 v[100:103], v[202:205], v[170:173], v[100:103]
	v_mfma_f32_16x16x32_bf16 v[96:99], v[210:213], v[170:173], v[96:99]
	v_mfma_f32_16x16x32_bf16 v[84:87], v[202:205], v[178:181], v[84:87]
	v_mfma_f32_16x16x32_bf16 v[80:83], v[210:213], v[178:181], v[80:83]
	v_mfma_f32_16x16x32_bf16 v[68:71], v[202:205], v[194:197], v[68:71]
	v_mfma_f32_16x16x32_bf16 v[64:67], v[210:213], v[194:197], v[64:67]
	v_mfma_f32_16x16x32_bf16 v[116:119], v[206:209], v[148:151], v[116:119]
	s_waitcnt lgkmcnt(0)
	v_mfma_f32_16x16x32_bf16 v[112:115], v[214:217], v[148:151], v[112:115]
	v_mfma_f32_16x16x32_bf16 v[100:103], v[206:209], v[174:177], v[100:103]
	v_mfma_f32_16x16x32_bf16 v[96:99], v[214:217], v[174:177], v[96:99]
	v_mfma_f32_16x16x32_bf16 v[84:87], v[206:209], v[182:185], v[84:87]
	v_mfma_f32_16x16x32_bf16 v[80:83], v[214:217], v[182:185], v[80:83]
	v_mfma_f32_16x16x32_bf16 v[68:71], v[206:209], v[198:201], v[68:71]
	v_mfma_f32_16x16x32_bf16 v[64:67], v[214:217], v[198:201], v[64:67]
	s_mov_b32 m0, s9
	v_lshl_add_u64 v[220:221], s[24:25], 0, v[154:155]
	s_barrier
	ds_read_b128 v[144:147], v191 offset:16384
	ds_read_b128 v[148:151], v191 offset:17408
	ds_read_b128 v[170:173], v191 offset:18432
	ds_read_b128 v[174:177], v191 offset:19456
	ds_read_b128 v[178:181], v191 offset:20480
	ds_read_b128 v[182:185], v191 offset:21504
	ds_read_b128 v[194:197], v191 offset:22528
	ds_read_b128 v[198:201], v191 offset:23552
	global_load_lds_dwordx4 v[220:221], off
	v_lshl_add_u64 v[222:223], s[24:25], 0, v[158:159]
	s_mov_b32 m0, s30
	s_nop 0
	global_load_lds_dwordx4 v[222:223], off
	s_barrier
	s_waitcnt lgkmcnt(7)
	v_mfma_f32_16x16x32_bf16 v[60:63], v[128:131], v[144:147], v[60:63]
	v_mfma_f32_16x16x32_bf16 v[56:59], v[136:139], v[144:147], v[56:59]
	s_waitcnt lgkmcnt(5)
	v_mfma_f32_16x16x32_bf16 v[44:47], v[128:131], v[170:173], v[44:47]
	v_mfma_f32_16x16x32_bf16 v[40:43], v[136:139], v[170:173], v[40:43]
	s_waitcnt lgkmcnt(3)
	v_mfma_f32_16x16x32_bf16 v[28:31], v[128:131], v[178:181], v[28:31]
	v_mfma_f32_16x16x32_bf16 v[24:27], v[136:139], v[178:181], v[24:27]
	s_waitcnt lgkmcnt(1)
	v_mfma_f32_16x16x32_bf16 v[12:15], v[128:131], v[194:197], v[12:15]
	v_mfma_f32_16x16x32_bf16 v[8:11], v[136:139], v[194:197], v[8:11]
	v_mfma_f32_16x16x32_bf16 v[60:63], v[132:135], v[148:151], v[60:63]
	v_mfma_f32_16x16x32_bf16 v[56:59], v[140:143], v[148:151], v[56:59]
	v_mfma_f32_16x16x32_bf16 v[44:47], v[132:135], v[174:177], v[44:47]
	v_mfma_f32_16x16x32_bf16 v[40:43], v[140:143], v[174:177], v[40:43]
	v_mfma_f32_16x16x32_bf16 v[28:31], v[132:135], v[182:185], v[28:31]
	v_mfma_f32_16x16x32_bf16 v[24:27], v[140:143], v[182:185], v[24:27]
	s_waitcnt lgkmcnt(0)
	v_mfma_f32_16x16x32_bf16 v[12:15], v[132:135], v[198:201], v[12:15]
	v_mfma_f32_16x16x32_bf16 v[8:11], v[140:143], v[198:201], v[8:11]
	s_barrier
	s_add_u32 s48, s22, 0x40000
	s_addc_u32 s49, s23, 0
	s_add_i32 s47, s41, s29
	v_lshl_add_u64 v[128:129], s[48:49], 0, v[156:157]
	s_mov_b32 m0, s47
	s_nop 0
	global_load_lds_dwordx4 v[128:129], off
	v_lshl_add_u64 v[128:129], s[48:49], 0, v[160:161]
	s_add_i32 m0, s47, 0x2000
	s_nop 0
	global_load_lds_dwordx4 v[128:129], off
	s_waitcnt vmcnt(6)
	s_barrier
	v_mfma_f32_16x16x32_bf16 v[52:55], v[202:205], v[144:147], v[52:55]
	v_mfma_f32_16x16x32_bf16 v[48:51], v[210:213], v[144:147], v[48:51]
	v_mfma_f32_16x16x32_bf16 v[36:39], v[202:205], v[170:173], v[36:39]
	v_mfma_f32_16x16x32_bf16 v[32:35], v[210:213], v[170:173], v[32:35]
	v_mfma_f32_16x16x32_bf16 v[20:23], v[202:205], v[178:181], v[20:23]
	v_mfma_f32_16x16x32_bf16 v[16:19], v[210:213], v[178:181], v[16:19]
	v_mfma_f32_16x16x32_bf16 v[4:7], v[202:205], v[194:197], v[4:7]
	v_mfma_f32_16x16x32_bf16 v[0:3], v[210:213], v[194:197], v[0:3]
	v_mfma_f32_16x16x32_bf16 v[52:55], v[206:209], v[148:151], v[52:55]
	v_mfma_f32_16x16x32_bf16 v[48:51], v[214:217], v[148:151], v[48:51]
	v_mfma_f32_16x16x32_bf16 v[36:39], v[206:209], v[174:177], v[36:39]
	v_mfma_f32_16x16x32_bf16 v[32:35], v[214:217], v[174:177], v[32:35]
	v_mfma_f32_16x16x32_bf16 v[20:23], v[206:209], v[182:185], v[20:23]
	v_mfma_f32_16x16x32_bf16 v[16:19], v[214:217], v[182:185], v[16:19]
	v_mfma_f32_16x16x32_bf16 v[4:7], v[206:209], v[198:201], v[4:7]
	v_mfma_f32_16x16x32_bf16 v[0:3], v[214:217], v[198:201], v[0:3]
	s_add_i32 s47, 0, 0x18000
	v_add_u32_e32 v140, s47, v188
	s_barrier
	ds_read_b128 v[128:131], v140
	ds_read_b128 v[132:135], v140 offset:1024
	ds_read_b128 v[136:139], v140 offset:2048
	ds_read_b128 v[140:143], v140 offset:3072
	s_add_u32 s24, s24, 0x140000
	s_addc_u32 s25, s25, 0
	s_mov_b32 m0, s31
	v_lshl_add_u64 v[202:203], s[24:25], 0, v[154:155]
	ds_read_b128 v[144:147], v191 offset:32768
	ds_read_b128 v[148:151], v191 offset:33792
	ds_read_b128 v[170:173], v191 offset:34816
	ds_read_b128 v[174:177], v191 offset:35840
	ds_read_b128 v[178:181], v191 offset:36864
	ds_read_b128 v[182:185], v191 offset:37888
	ds_read_b128 v[194:197], v191 offset:38912
	ds_read_b128 v[198:201], v191 offset:39936
	global_load_lds_dwordx4 v[202:203], off
	v_lshl_add_u64 v[202:203], s[24:25], 0, v[158:159]
	s_mov_b32 m0, s34
	s_nop 0
	global_load_lds_dwordx4 v[202:203], off
	s_waitcnt lgkmcnt(8)
	s_barrier
; #define PG8_STAGE(bufoff, gbase, voff) do { _Pragma("unroll") for (int _i = 0; _i < 2; ++_i) \
;         __builtin_amdgcn_global_load_lds((const unsigned*)((const char*)(gbase) + (voff)[_i]), (LAS unsigned*)(lds + (bufoff) + ldsw + _i * 8192), 16, 0, 0); } while (0)
; #define PG8_LDA(dst, b, h) do { _Pragma("unroll") for (int m = 0; m < 4; ++m) _Pragma("unroll") for (int k = 0; k < 2; ++k) dst[m][k] = *(const LAS bf16x8*)(lds + PG8_SA(b, h) + aoff + m * 2048 + k * 1024); } while (0)
; #define PG8_LDB(dst, b, h) do { _Pragma("unroll") for (int n = 0; n < 2; ++n) _Pragma("unroll") for (int k = 0; k < 2; ++k) dst[n][k] = *(const LAS bf16x8*)(lds + PG8_SB(b, h) + boff + n * 2048 + k * 1024); } while (0)
; #define PG8_MMA(ai, bj, At, Bt) do { __builtin_amdgcn_s_setprio(1); _Pragma("unroll") for (int m = 0; m < 4; ++m) _Pragma("unroll") for (int n = 0; n < 2; ++n) _Pragma("unroll") for (int k = 0; k < 2; ++k) \
;         acc[ai][bj][m][n] = __builtin_amdgcn_mfma_f32_16x16x32_bf16(Bt[n][k], At[m][k], acc[ai][bj][m][n], 0, 0, 0); __builtin_amdgcn_s_setprio(0); } while (0)
; #define PG8_WAIT_V(n) asm volatile("s_waitcnt vmcnt(" #n ")" ::: "memory")
; #define PG8_WAIT_L(n) asm volatile("s_waitcnt lgkmcnt(" #n ")" ::: "memory")
; #define PG8_BAR __builtin_amdgcn_s_barrier()
; #define PG8_SCHED __builtin_amdgcn_sched_barrier(0)
; template <class Epi>
; __device__ __forceinline__ void gemm_phase(LAS unsigned char* lds, const Gemm g, const StaticOrder& S, const Epi& E) {
;     ...
;             PG8_WAIT_L(8); PG8_BAR; PG8_WAIT_L(0); PG8_MMA(0, 0, At, B0); PG8_BAR; PG8_SCHED;
;             PG8_LDB(B1, 1, 1); PG8_STAGE(PG8_SB(1, 0), b3, voffB);
;             PG8_BAR; PG8_WAIT_L(0); PG8_MMA(0, 1, At, B1); PG8_BAR;
;             PG8_LDA(At, 1, 1); PG8_STAGE(PG8_SA(1, 0), a3, voffA);
;             PG8_BAR; PG8_WAIT_L(0); PG8_MMA(1, 0, At, B0); PG8_BAR; PG8_SCHED;
;             PG8_STAGE(PG8_SB(1, 1), b3 + hstepB, voffB);
;             PG8_WAIT_V(6); PG8_BAR; PG8_MMA(1, 1, At, B1); PG8_BAR;
	s_waitcnt lgkmcnt(7)
	v_mfma_f32_16x16x32_bf16 v[124:127], v[128:131], v[144:147], v[124:127]
	v_mfma_f32_16x16x32_bf16 v[120:123], v[136:139], v[144:147], v[120:123]
	s_waitcnt lgkmcnt(5)
	v_mfma_f32_16x16x32_bf16 v[108:111], v[128:131], v[170:173], v[108:111]
	v_mfma_f32_16x16x32_bf16 v[104:107], v[136:139], v[170:173], v[104:107]
	s_waitcnt lgkmcnt(3)
	v_mfma_f32_16x16x32_bf16 v[92:95], v[128:131], v[178:181], v[92:95]
	v_mfma_f32_16x16x32_bf16 v[88:91], v[136:139], v[178:181], v[88:91]
	s_waitcnt lgkmcnt(1)
	v_mfma_f32_16x16x32_bf16 v[76:79], v[128:131], v[194:197], v[76:79]
	v_mfma_f32_16x16x32_bf16 v[72:75], v[136:139], v[194:197], v[72:75]
	v_mfma_f32_16x16x32_bf16 v[124:127], v[132:135], v[148:151], v[124:127]
	v_mfma_f32_16x16x32_bf16 v[120:123], v[140:143], v[148:151], v[120:123]
	v_mfma_f32_16x16x32_bf16 v[108:111], v[132:135], v[174:177], v[108:111]
	v_mfma_f32_16x16x32_bf16 v[104:107], v[140:143], v[174:177], v[104:107]
	v_mfma_f32_16x16x32_bf16 v[92:95], v[132:135], v[182:185], v[92:95]
	v_mfma_f32_16x16x32_bf16 v[88:91], v[140:143], v[182:185], v[88:91]
	s_waitcnt lgkmcnt(0)
	v_mfma_f32_16x16x32_bf16 v[76:79], v[132:135], v[198:201], v[76:79]
	v_mfma_f32_16x16x32_bf16 v[72:75], v[140:143], v[198:201], v[72:75]
	s_barrier
	s_add_i32 s24, 0, 0x1c000
	s_add_i32 s25, s47, s29
	v_add_u32_e32 v214, s24, v188
	v_lshl_add_u64 v[186:187], v[186:187], 0, s[14:15]
	s_mov_b32 m0, s25
	ds_read_b128 v[202:205], v214
	ds_read_b128 v[206:209], v214 offset:1024
	ds_read_b128 v[210:213], v214 offset:2048
	ds_read_b128 v[214:217], v214 offset:3072
	global_load_lds_dwordx4 v[186:187], off
	v_lshl_add_u64 v[186:187], v[218:219], 0, s[14:15]
	s_add_i32 m0, s25, 0x2000
	s_nop 0
	global_load_lds_dwordx4 v[186:187], off
	s_barrier
	s_waitcnt lgkmcnt(3)
	v_mfma_f32_16x16x32_bf16 v[116:119], v[202:205], v[144:147], v[116:119]
	s_waitcnt lgkmcnt(1)
	v_mfma_f32_16x16x32_bf16 v[112:115], v[210:213], v[144:147], v[112:115]
	v_mfma_f32_16x16x32_bf16 v[100:103], v[202:205], v[170:173], v[100:103]
	v_mfma_f32_16x16x32_bf16 v[96:99], v[210:213], v[170:173], v[96:99]
	v_mfma_f32_16x16x32_bf16 v[84:87], v[202:205], v[178:181], v[84:87]
	v_mfma_f32_16x16x32_bf16 v[80:83], v[210:213], v[178:181], v[80:83]
	v_mfma_f32_16x16x32_bf16 v[68:71], v[202:205], v[194:197], v[68:71]
	v_mfma_f32_16x16x32_bf16 v[64:67], v[210:213], v[194:197], v[64:67]
	v_mfma_f32_16x16x32_bf16 v[116:119], v[206:209], v[148:151], v[116:119]
	s_waitcnt lgkmcnt(0)
	v_mfma_f32_16x16x32_bf16 v[112:115], v[214:217], v[148:151], v[112:115]
	v_mfma_f32_16x16x32_bf16 v[100:103], v[206:209], v[174:177], v[100:103]
	v_mfma_f32_16x16x32_bf16 v[96:99], v[214:217], v[174:177], v[96:99]
	v_mfma_f32_16x16x32_bf16 v[84:87], v[206:209], v[182:185], v[84:87]
	v_mfma_f32_16x16x32_bf16 v[80:83], v[214:217], v[182:185], v[80:83]
	v_mfma_f32_16x16x32_bf16 v[68:71], v[206:209], v[198:201], v[68:71]
	v_mfma_f32_16x16x32_bf16 v[64:67], v[214:217], v[198:201], v[64:67]
	s_mov_b32 m0, s36
	v_lshl_add_u64 v[186:187], v[220:221], 0, s[14:15]
	s_barrier
	ds_read_b128 v[144:147], v191 offset:49152
	ds_read_b128 v[148:151], v191 offset:50176
	ds_read_b128 v[170:173], v191 offset:51200
	ds_read_b128 v[174:177], v191 offset:52224
	ds_read_b128 v[178:181], v191 offset:53248
	ds_read_b128 v[182:185], v191 offset:54272
	ds_read_b128 v[194:197], v191 offset:55296
	ds_read_b128 v[198:201], v191 offset:56320
	global_load_lds_dwordx4 v[186:187], off
	v_lshl_add_u64 v[186:187], v[222:223], 0, s[14:15]
	s_mov_b32 m0, s37
	s_nop 0
	global_load_lds_dwordx4 v[186:187], off
	s_barrier
	s_waitcnt lgkmcnt(7)
	v_mfma_f32_16x16x32_bf16 v[60:63], v[128:131], v[144:147], v[60:63]
	v_mfma_f32_16x16x32_bf16 v[56:59], v[136:139], v[144:147], v[56:59]
	s_waitcnt lgkmcnt(5)
	v_mfma_f32_16x16x32_bf16 v[44:47], v[128:131], v[170:173], v[44:47]
	v_mfma_f32_16x16x32_bf16 v[40:43], v[136:139], v[170:173], v[40:43]
	s_waitcnt lgkmcnt(3)
	v_mfma_f32_16x16x32_bf16 v[28:31], v[128:131], v[178:181], v[28:31]
	v_mfma_f32_16x16x32_bf16 v[24:27], v[136:139], v[178:181], v[24:27]
	s_waitcnt lgkmcnt(1)
	v_mfma_f32_16x16x32_bf16 v[12:15], v[128:131], v[194:197], v[12:15]
	v_mfma_f32_16x16x32_bf16 v[8:11], v[136:139], v[194:197], v[8:11]
	v_mfma_f32_16x16x32_bf16 v[60:63], v[132:135], v[148:151], v[60:63]
	v_mfma_f32_16x16x32_bf16 v[56:59], v[140:143], v[148:151], v[56:59]
	v_mfma_f32_16x16x32_bf16 v[44:47], v[132:135], v[174:177], v[44:47]
	v_mfma_f32_16x16x32_bf16 v[40:43], v[140:143], v[174:177], v[40:43]
	v_mfma_f32_16x16x32_bf16 v[28:31], v[132:135], v[182:185], v[28:31]
	v_mfma_f32_16x16x32_bf16 v[24:27], v[140:143], v[182:185], v[24:27]
	s_waitcnt lgkmcnt(0)
	v_mfma_f32_16x16x32_bf16 v[12:15], v[132:135], v[198:201], v[12:15]
	v_mfma_f32_16x16x32_bf16 v[8:11], v[140:143], v[198:201], v[8:11]
	s_barrier
	s_add_u32 s22, s22, 0x40080
	s_addc_u32 s23, s23, 0
	s_add_i32 s24, s24, s29
	v_lshl_add_u64 v[128:129], s[22:23], 0, v[156:157]
	s_mov_b32 m0, s24
	s_nop 0
	global_load_lds_dwordx4 v[128:129], off
	v_lshl_add_u64 v[128:129], s[22:23], 0, v[160:161]
	s_add_i32 m0, s24, 0x2000
	s_nop 0
	global_load_lds_dwordx4 v[128:129], off
	s_waitcnt vmcnt(6)
	s_barrier
; __device__ __forceinline__ unsigned pk2(float lo, float hi) { const f32x2 v = (f32x2){lo, hi}; const bf16x2_t b = __builtin_convertvector(v, bf16x2_t); return __builtin_bit_cast(unsigned, b); }
; __device__ __forceinline__ void unpack8(const u32x4 v, float* f) { f[0] = bf_lo(v.x); f[1] = bf_hi(v.x); f[2] = bf_lo(v.y); f[3] = bf_hi(v.y); f[4] = bf_lo(v.z); f[5] = bf_hi(v.z); f[6] = bf_lo(v.w); f[7] = bf_hi(v.w); }
; #define PG8_WAIT_V(n) asm volatile("s_waitcnt vmcnt(" #n ")" ::: "memory")
; #define PG8_BAR __builtin_amdgcn_s_barrier()
;     __device__ __forceinline__ void operator()(const f32x4 (&acc)[2][2][4][2], const Unit& u, int wr, int wc, int fr, int fq, const float (&)[8]) const {
;         const int row0 = u.pm * BM + wr * 64 + fr, col0 = u.pn * BM + wc * 32 + 8 * fq;
; #pragma unroll
;         for (int ai = 0; ai < 2; ++ai) {
;             u32x4 bv[4][2];
; #pragma unroll
;             for (int m = 0; m < 4; ++m)
; #pragma unroll
;                 for (int bj = 0; bj < 2; ++bj) bv[m][bj] = *(const u32x4*)(xb + (size_t)(row0 + ai * HALF + m * 16) * DM + col0 + bj * HALF);
; #pragma unroll
;             for (int m = 0; m < 4; ++m) { const int row = row0 + ai * HALF + m * 16; const size_t ro = (size_t)row * DM + col0; float s = 0.f;
; #pragma unroll
;                 for (int bj = 0; bj < 2; ++bj) { float b8[8]; unpack8(bv[m][bj], b8);
;                     const f32x4 v0 = (f32x4){b8[0], b8[1], b8[2], b8[3]} + acc[ai][bj][m][0], v1 = (f32x4){b8[4], b8[5], b8[6], b8[7]} + acc[ai][bj][m][1];
;                     s += v0[0] * v0[0] + v0[1] * v0[1] + v0[2] * v0[2] + v0[3] * v0[3] + v1[0] * v1[0] + v1[1] * v1[1] + v1[2] * v1[2] + v1[3] * v1[3];
;                     if (LAST) { *(f32x4*)(out + ro + bj * HALF) = v0; *(f32x4*)(out + ro + bj * HALF + 4) = v1; }
;                     else { u32x4 w; w.x = pk2(v0[0], v0[1]); w.y = pk2(v0[2], v0[3]); w.z = pk2(v1[0], v1[1]); w.w = pk2(v1[2], v1[3]); *(u32x4*)(xb + ro + bj * HALF) = w; } }
;                 s += __shfl_xor(s, 16); s += __shfl_xor(s, 32);
;                 if (fq == 0) ss[(size_t)row * 16 + u.pn * 4 + wc] = s; }
; template <class Epi>
; __device__ __forceinline__ void gemm_phase(LAS unsigned char* lds, const Gemm g, const StaticOrder& S, const Epi& E) {
;     ...
;             PG8_WAIT_V(6); PG8_BAR; PG8_MMA(1, 1, At, B1); PG8_BAR;
;         }
;         E(acc, cur, wr, wc, fr, fq, epre);
	v_mfma_f32_16x16x32_bf16 v[52:55], v[202:205], v[144:147], v[52:55]
	v_mfma_f32_16x16x32_bf16 v[48:51], v[210:213], v[144:147], v[48:51]
	v_mfma_f32_16x16x32_bf16 v[36:39], v[202:205], v[170:173], v[36:39]
	v_mfma_f32_16x16x32_bf16 v[32:35], v[210:213], v[170:173], v[32:35]
	v_mfma_f32_16x16x32_bf16 v[20:23], v[202:205], v[178:181], v[20:23]
	v_mfma_f32_16x16x32_bf16 v[16:19], v[210:213], v[178:181], v[16:19]
	v_mfma_f32_16x16x32_bf16 v[4:7], v[202:205], v[194:197], v[4:7]
	v_mfma_f32_16x16x32_bf16 v[0:3], v[210:213], v[194:197], v[0:3]
	v_mfma_f32_16x16x32_bf16 v[52:55], v[206:209], v[148:151], v[52:55]
	v_mfma_f32_16x16x32_bf16 v[48:51], v[214:217], v[148:151], v[48:51]
	v_mfma_f32_16x16x32_bf16 v[36:39], v[206:209], v[174:177], v[36:39]
	v_mfma_f32_16x16x32_bf16 v[32:35], v[214:217], v[174:177], v[32:35]
	v_mfma_f32_16x16x32_bf16 v[20:23], v[206:209], v[182:185], v[20:23]
	v_mfma_f32_16x16x32_bf16 v[16:19], v[214:217], v[182:185], v[16:19]
	v_mfma_f32_16x16x32_bf16 v[4:7], v[206:209], v[198:201], v[4:7]
	v_mfma_f32_16x16x32_bf16 v[0:3], v[214:217], v[198:201], v[0:3]
	s_add_i32 s46, s46, 2
	s_add_u32 s4, s4, 0x100
	s_addc_u32 s5, s5, 0
	s_add_u32 s44, s44, 0x100
	s_addc_u32 s45, s45, 0
	s_cmp_gt_u32 s46, 13
	s_barrier
	s_cbranch_scc0 .LBB0_1118
	v_lshl_or_b32 v170, s8, 8, v189
	v_lshl_add_u32 v172, s10, 8, v153
	v_ashrrev_i32_e32 v171, 31, v170
	v_lshlrev_b64 v[204:205], 1, v[170:171]
	v_ashrrev_i32_e32 v173, 31, v172
	v_lshl_add_u64 v[174:175], s[76:77], 0, v[204:205]
	v_lshlrev_b64 v[206:207], 11, v[172:173]
	v_lshl_add_u64 v[128:129], v[174:175], 0, v[206:207]
	global_load_dwordx4 v[196:199], v[128:129], off
	global_load_dwordx4 v[200:203], v[128:129], off offset:256
	v_or_b32_e32 v184, 16, v172
	v_or_b32_e32 v180, 32, v172
	v_or_b32_e32 v176, 48, v172
	v_ashrrev_i32_e32 v185, 31, v184
	v_ashrrev_i32_e32 v181, 31, v180
	v_ashrrev_i32_e32 v177, 31, v176
	v_lshlrev_b64 v[186:187], 11, v[184:185]
	v_lshlrev_b64 v[182:183], 11, v[180:181]
	v_lshlrev_b64 v[178:179], 11, v[176:177]
	v_lshl_add_u64 v[128:129], v[174:175], 0, v[186:187]
	v_lshl_add_u64 v[130:131], v[174:175], 0, v[182:183]
	v_lshl_add_u64 v[194:195], v[174:175], 0, v[178:179]
	global_load_dwordx4 v[148:151], v[128:129], off
	global_load_dwordx4 v[144:147], v[128:129], off offset:256
	global_load_dwordx4 v[140:143], v[130:131], off
	global_load_dwordx4 v[136:139], v[130:131], off offset:256
	global_load_dwordx4 v[132:135], v[194:195], off
	s_nop 0
	global_load_dwordx4 v[128:131], v[194:195], off offset:256
	v_add_u32_e32 v226, 0x80, v172
	v_ashrrev_i32_e32 v227, 31, v226
	v_lshlrev_b64 v[226:227], 11, v[226:227]
	v_lshl_add_u64 v[226:227], v[174:175], 0, v[226:227]
	global_load_dwordx4 v[216:219], v[226:227], off
	global_load_dwordx4 v[220:223], v[226:227], off offset:256
	v_add_u32_e32 v226, 0x90, v172
	v_ashrrev_i32_e32 v227, 31, v226
	v_lshlrev_b64 v[226:227], 11, v[226:227]
	v_lshl_add_u64 v[226:227], v[174:175], 0, v[226:227]
	global_load_dwordx4 v[228:231], v[226:227], off
	global_load_dwordx4 v[232:235], v[226:227], off offset:256
	v_add_u32_e32 v226, 0xa0, v172
	v_ashrrev_i32_e32 v227, 31, v226
	v_lshlrev_b64 v[226:227], 11, v[226:227]
	v_lshl_add_u64 v[226:227], v[174:175], 0, v[226:227]
	global_load_dwordx4 v[236:239], v[226:227], off
	global_load_dwordx4 v[240:243], v[226:227], off offset:256
	v_add_u32_e32 v226, 0xb0, v172
	v_ashrrev_i32_e32 v227, 31, v226
	v_lshlrev_b64 v[226:227], 11, v[226:227]
	v_lshl_add_u64 v[226:227], v[174:175], 0, v[226:227]
	global_load_dwordx4 v[244:247], v[226:227], off
	global_load_dwordx4 v[252:255], v[226:227], off offset:256
	v_and_b32_e32 v195, 64, v193
	v_xor_b32_e32 v194, 16, v193
	v_add_u32_e32 v195, 64, v195
	v_xor_b32_e32 v208, 32, v193
	v_cmp_lt_i32_e32 vcc, v194, v195
	s_waitcnt vmcnt(15)
	v_and_b32_e32 v209, 0xffff0000, v196
	v_cndmask_b32_e32 v194, v193, v194, vcc
	v_cmp_lt_i32_e32 vcc, v208, v195
	v_lshlrev_b32_e32 v195, 2, v194
	s_waitcnt vmcnt(14)
	v_lshlrev_b32_e32 v212, 16, v200
	v_cndmask_b32_e32 v208, v193, v208, vcc
	v_lshlrev_b32_e32 v194, 2, v208
	v_lshlrev_b32_e32 v208, 16, v196
	v_and_b32_e32 v213, 0xffff0000, v200
	v_lshlrev_b32_e32 v210, 16, v198
	v_and_b32_e32 v211, 0xffff0000, v198
	v_lshlrev_b32_e32 v198, 16, v199
	v_and_b32_e32 v199, 0xffff0000, v199
	v_lshlrev_b32_e32 v200, 16, v201
	v_and_b32_e32 v201, 0xffff0000, v201
	v_lshlrev_b32_e32 v214, 16, v202
	v_and_b32_e32 v215, 0xffff0000, v202
	v_pk_add_f32 v[124:125], v[124:125], v[208:209]
	v_pk_add_f32 v[116:117], v[116:117], v[212:213]
	v_lshlrev_b32_e32 v196, 16, v197
	v_and_b32_e32 v197, 0xffff0000, v197
	v_pk_add_f32 v[122:123], v[122:123], v[198:199]
	v_pk_add_f32 v[118:119], v[118:119], v[200:201]
	v_pk_add_f32 v[198:199], v[112:113], v[214:215]
	v_mul_f32_e32 v200, v125, v125
	v_cvt_pk_bf16_f32 v112, v124, v125
	v_mul_f32_e32 v125, v117, v117
	v_pk_add_f32 v[126:127], v[126:127], v[196:197]
	v_fmac_f32_e32 v200, v124, v124
	v_fmac_f32_e32 v125, v116, v116
	v_fmac_f32_e32 v200, v126, v126
	v_fmac_f32_e32 v125, v118, v118
	v_pk_add_f32 v[120:121], v[120:121], v[210:211]
	v_fmac_f32_e32 v200, v127, v127
	v_fmac_f32_e32 v125, v119, v119
	v_lshlrev_b32_e32 v202, 16, v203
	v_and_b32_e32 v203, 0xffff0000, v203
	v_fmac_f32_e32 v200, v120, v120
	v_fmac_f32_e32 v125, v198, v198
	v_pk_add_f32 v[196:197], v[114:115], v[202:203]
	v_fmac_f32_e32 v200, v121, v121
	v_fmac_f32_e32 v125, v199, v199
	v_fmac_f32_e32 v200, v122, v122
	v_fmac_f32_e32 v125, v196, v196
	v_fmac_f32_e32 v200, v123, v123
	v_fmac_f32_e32 v125, v197, v197
	v_cvt_pk_bf16_f32 v115, v122, v123
	v_add_f32_e32 v122, v200, v125
	ds_bpermute_b32 v123, v195, v122
	v_cvt_pk_bf16_f32 v114, v120, v121
	v_lshl_add_u64 v[120:121], s[76:77], 0, v[206:207]
	v_cvt_pk_bf16_f32 v113, v126, v127
	v_lshl_add_u64 v[120:121], v[120:121], 0, v[204:205]
	global_store_dwordx4 v[120:121], v[112:115], off
	s_waitcnt lgkmcnt(0)
	s_nop 0
	v_add_f32_e32 v112, v122, v123
	ds_bpermute_b32 v113, v194, v112
	v_cvt_pk_bf16_f32 v114, v116, v117
	v_cvt_pk_bf16_f32 v115, v118, v119
	v_cvt_pk_bf16_f32 v116, v198, v199
	v_cvt_pk_bf16_f32 v117, v196, v197
	global_store_dwordx4 v[120:121], v[114:117], off offset:256
	s_and_saveexec_b64 s[4:5], s[0:1]
	s_cbranch_execz .LBB0_1121
	s_waitcnt lgkmcnt(0)
	v_add_f32_e32 v114, v112, v113
	s_lshl_b32 s22, s8, 2
	v_lshlrev_b64 v[112:113], 6, v[172:173]
	s_ashr_i32 s23, s22, 31
	v_lshl_add_u64 v[112:113], s[12:13], 0, v[112:113]
	v_lshl_add_u64 v[112:113], s[22:23], 2, v[112:113]
	s_lshl_b32 s10, s35, 2
	v_lshl_add_u64 v[112:113], v[112:113], 0, s[10:11]
	global_store_dword v[112:113], v114, off

; #define PG8_STAGE(bufoff, gbase, voff) do { _Pragma("unroll") for (int _i = 0; _i < 2; ++_i) \
;         __builtin_amdgcn_global_load_lds((const unsigned*)((const char*)(gbase) + (voff)[_i]), (LAS unsigned*)(lds + (bufoff) + ldsw + _i * 8192), 16, 0, 0); } while (0)
; #define PG8_LDA(dst, b, h) do { _Pragma("unroll") for (int m = 0; m < 4; ++m) _Pragma("unroll") for (int k = 0; k < 2; ++k) dst[m][k] = *(const LAS bf16x8*)(lds + PG8_SA(b, h) + aoff + m * 2048 + k * 1024); } while (0)
; #define PG8_LDB(dst, b, h) do { _Pragma("unroll") for (int n = 0; n < 2; ++n) _Pragma("unroll") for (int k = 0; k < 2; ++k) dst[n][k] = *(const LAS bf16x8*)(lds + PG8_SB(b, h) + boff + n * 2048 + k * 1024); } while (0)
; #define PG8_MMA(ai, bj, At, Bt) do { __builtin_amdgcn_s_setprio(1); _Pragma("unroll") for (int m = 0; m < 4; ++m) _Pragma("unroll") for (int n = 0; n < 2; ++n) _Pragma("unroll") for (int k = 0; k < 2; ++k) \
;         acc[ai][bj][m][n] = __builtin_amdgcn_mfma_f32_16x16x32_bf16(Bt[n][k], At[m][k], acc[ai][bj][m][n], 0, 0, 0); __builtin_amdgcn_s_setprio(0); } while (0)
; #define PG8_BAR __builtin_amdgcn_s_barrier()
; template <class Epi>
; __device__ __forceinline__ void gemm_phase(LAS unsigned char* lds, const Gemm g, const StaticOrder& S, const Epi& E) {
;     ...
;         const bool has_next = S.next(ui + 1, nxt);
;         const char* nA = has_next ? (const char*)g.A + (size_t)nxt.pm * tstepA : cA; const char* nB = has_next ? (const char*)g.Bt + (size_t)nxt.pn * tstepB : cB;
;         for (int t = 0; t < nt; t += 2) {
;             const bool last = (t == nt - 2);
;             const char* a1 = cA + (size_t)(t + 1) * kstep;
;             const char* a2 = last ? nA : cA + (size_t)(t + 2) * kstep; const char* b2 = last ? nB : cB + (size_t)(t + 2) * kstep;
;             const char* a3 = a2 + kstep; const char* b3 = b2 + kstep;
;             if (last) E.pre(cur, wr, fr, epre);
;             PG8_LDB(B0, 0, 0); PG8_SCHED; PG8_LDA(At, 0, 0); PG8_STAGE(PG8_SA(1, 1), a1 + hstepA, voffA);
;             PG8_WAIT_L(8); PG8_BAR; PG8_WAIT_L(0); PG8_MMA(0, 0, At, B0); PG8_BAR; PG8_SCHED;
;             PG8_LDB(B1, 0, 1); PG8_STAGE(PG8_SB(0, 0), b2, voffB);
;             PG8_BAR; PG8_WAIT_L(0); PG8_MMA(0, 1, At, B1); PG8_BAR;
;             PG8_LDA(At, 0, 1); PG8_STAGE(PG8_SA(0, 0), a2, voffA);
;             PG8_BAR; PG8_WAIT_L(0); PG8_MMA(1, 0, At, B0); PG8_BAR; PG8_SCHED;
.LBB0_1203:
	s_ashr_i32 s13, s12, 31
	v_cmp_lt_i64_e32 vcc, s[14:15], v[142:143]
	s_lshl_b64 s[14:15], s[12:13], 19
	s_add_u32 s14, s76, s14
	s_addc_u32 s15, s77, s15
	s_and_b64 s[16:17], vcc, exec
	s_cselect_b32 s13, s15, s21
	s_cselect_b32 s41, s14, s20
	s_ashr_i32 s11, s10, 31
	s_lshl_b64 s[16:17], s[10:11], 19
	s_add_u32 s16, s26, s16
	s_addc_u32 s17, s27, s17
	s_and_b64 s[24:25], vcc, exec
	s_cselect_b32 s11, s17, s23
	s_cselect_b32 s42, s16, s22
	s_add_u32 s20, s20, 0x40080
	s_addc_u32 s21, s21, 0
	s_add_u32 s43, s22, 0x100
	s_addc_u32 s44, s23, 0
	s_mov_b32 s45, -2
	ds_read_b128 v[146:149], v176
	ds_read_b128 v[154:157], v176 offset:1024
	ds_read_b128 v[158:161], v176 offset:2048
	ds_read_b128 v[162:165], v176 offset:3072
	s_add_u32 s22, s20, 0xfffc0080
	s_addc_u32 s23, s21, -1
	s_cmp_eq_u32 s45, 12
	s_cselect_b32 s25, s13, s23
	s_cselect_b32 s24, s41, s22
	s_cselect_b32 s23, s11, s44
	s_cselect_b32 s22, s42, s43
	v_lshl_add_u64 v[150:151], s[20:21], 0, v[138:139]
	s_add_i32 m0, s19, 0xc000
	ds_read_b128 v[166:169], v177
	ds_read_b128 v[170:173], v177 offset:1024
	ds_read_b128 v[180:183], v177 offset:2048
	ds_read_b128 v[184:187], v177 offset:3072
	ds_read_b128 v[188:191], v177 offset:4096
	ds_read_b128 v[192:195], v177 offset:5120
	ds_read_b128 v[196:199], v177 offset:6144
	ds_read_b128 v[200:203], v177 offset:7168
	global_load_lds_dwordx4 v[150:151], off
	v_lshl_add_u64 v[150:151], s[20:21], 0, v[140:141]
	s_add_i32 m0, s19, 0xe000
	s_nop 0
	global_load_lds_dwordx4 v[150:151], off
	s_waitcnt lgkmcnt(8)
	s_barrier
	s_waitcnt lgkmcnt(7)
	v_mfma_f32_16x16x32_bf16 v[124:127], v[146:149], v[166:169], 0
	v_mfma_f32_16x16x32_bf16 v[120:123], v[158:161], v[166:169], 0
	s_waitcnt lgkmcnt(5)
	v_mfma_f32_16x16x32_bf16 v[108:111], v[146:149], v[180:183], 0
	v_mfma_f32_16x16x32_bf16 v[104:107], v[158:161], v[180:183], 0
	s_waitcnt lgkmcnt(3)
	v_mfma_f32_16x16x32_bf16 v[92:95], v[146:149], v[188:191], 0
	v_mfma_f32_16x16x32_bf16 v[88:91], v[158:161], v[188:191], 0
	s_waitcnt lgkmcnt(1)
	v_mfma_f32_16x16x32_bf16 v[76:79], v[146:149], v[196:199], 0
	v_mfma_f32_16x16x32_bf16 v[72:75], v[158:161], v[196:199], 0
	v_mfma_f32_16x16x32_bf16 v[124:127], v[154:157], v[170:173], v[124:127]
	v_mfma_f32_16x16x32_bf16 v[120:123], v[162:165], v[170:173], v[120:123]
	v_mfma_f32_16x16x32_bf16 v[108:111], v[154:157], v[184:187], v[108:111]
	v_mfma_f32_16x16x32_bf16 v[104:107], v[162:165], v[184:187], v[104:107]
	v_mfma_f32_16x16x32_bf16 v[92:95], v[154:157], v[192:195], v[92:95]
	v_mfma_f32_16x16x32_bf16 v[88:91], v[162:165], v[192:195], v[88:91]
	s_waitcnt lgkmcnt(0)
	v_mfma_f32_16x16x32_bf16 v[76:79], v[154:157], v[200:203], v[76:79]
	v_mfma_f32_16x16x32_bf16 v[72:75], v[162:165], v[200:203], v[72:75]
	s_barrier
	s_add_i32 s46, s37, s28
	v_lshl_add_u64 v[150:151], s[22:23], 0, v[130:131]
	s_mov_b32 m0, s46
	ds_read_b128 v[204:207], v178
	ds_read_b128 v[208:211], v178 offset:1024
	ds_read_b128 v[212:215], v178 offset:2048
	ds_read_b128 v[216:219], v178 offset:3072
	global_load_lds_dwordx4 v[150:151], off
	v_lshl_add_u64 v[220:221], s[22:23], 0, v[134:135]
	s_add_i32 m0, s46, 0x2000
	s_nop 0
	global_load_lds_dwordx4 v[220:221], off
	s_barrier
	s_waitcnt lgkmcnt(3)
	v_mfma_f32_16x16x32_bf16 v[116:119], v[204:207], v[166:169], 0
	s_waitcnt lgkmcnt(1)
	v_mfma_f32_16x16x32_bf16 v[112:115], v[212:215], v[166:169], 0
	v_mfma_f32_16x16x32_bf16 v[100:103], v[204:207], v[180:183], 0
	v_mfma_f32_16x16x32_bf16 v[96:99], v[212:215], v[180:183], 0
	v_mfma_f32_16x16x32_bf16 v[84:87], v[204:207], v[188:191], 0
	v_mfma_f32_16x16x32_bf16 v[80:83], v[212:215], v[188:191], 0
	v_mfma_f32_16x16x32_bf16 v[68:71], v[204:207], v[196:199], 0
	v_mfma_f32_16x16x32_bf16 v[64:67], v[212:215], v[196:199], 0
	v_mfma_f32_16x16x32_bf16 v[116:119], v[208:211], v[170:173], v[116:119]
	s_waitcnt lgkmcnt(0)
	v_mfma_f32_16x16x32_bf16 v[112:115], v[216:219], v[170:173], v[112:115]
	v_mfma_f32_16x16x32_bf16 v[100:103], v[208:211], v[184:187], v[100:103]
	v_mfma_f32_16x16x32_bf16 v[96:99], v[216:219], v[184:187], v[96:99]
	v_mfma_f32_16x16x32_bf16 v[84:87], v[208:211], v[192:195], v[84:87]
	v_mfma_f32_16x16x32_bf16 v[80:83], v[216:219], v[192:195], v[80:83]
	v_mfma_f32_16x16x32_bf16 v[68:71], v[208:211], v[200:203], v[68:71]
	v_mfma_f32_16x16x32_bf16 v[64:67], v[216:219], v[200:203], v[64:67]
	s_mov_b32 m0, s19
	v_lshl_add_u64 v[222:223], s[24:25], 0, v[128:129]
	s_barrier
	ds_read_b128 v[166:169], v177 offset:16384
	ds_read_b128 v[170:173], v177 offset:17408
	ds_read_b128 v[180:183], v177 offset:18432
	ds_read_b128 v[184:187], v177 offset:19456
	ds_read_b128 v[188:191], v177 offset:20480
	ds_read_b128 v[192:195], v177 offset:21504
	ds_read_b128 v[196:199], v177 offset:22528
	ds_read_b128 v[200:203], v177 offset:23552
	global_load_lds_dwordx4 v[222:223], off
	v_lshl_add_u64 v[224:225], s[24:25], 0, v[132:133]
	s_mov_b32 m0, s29
	s_nop 0
	global_load_lds_dwordx4 v[224:225], off
	s_barrier
	s_waitcnt lgkmcnt(7)
	v_mfma_f32_16x16x32_bf16 v[60:63], v[146:149], v[166:169], 0
	v_mfma_f32_16x16x32_bf16 v[56:59], v[158:161], v[166:169], 0
	s_waitcnt lgkmcnt(5)
	v_mfma_f32_16x16x32_bf16 v[44:47], v[146:149], v[180:183], 0
	v_mfma_f32_16x16x32_bf16 v[40:43], v[158:161], v[180:183], 0
	s_waitcnt lgkmcnt(3)
	v_mfma_f32_16x16x32_bf16 v[28:31], v[146:149], v[188:191], 0
	v_mfma_f32_16x16x32_bf16 v[24:27], v[158:161], v[188:191], 0
	s_waitcnt lgkmcnt(1)
	v_mfma_f32_16x16x32_bf16 v[12:15], v[146:149], v[196:199], 0
	v_mfma_f32_16x16x32_bf16 v[8:11], v[158:161], v[196:199], 0
	v_mfma_f32_16x16x32_bf16 v[60:63], v[154:157], v[170:173], v[60:63]
	v_mfma_f32_16x16x32_bf16 v[56:59], v[162:165], v[170:173], v[56:59]
	v_mfma_f32_16x16x32_bf16 v[44:47], v[154:157], v[184:187], v[44:47]
	v_mfma_f32_16x16x32_bf16 v[40:43], v[162:165], v[184:187], v[40:43]
	v_mfma_f32_16x16x32_bf16 v[28:31], v[154:157], v[192:195], v[28:31]
	v_mfma_f32_16x16x32_bf16 v[24:27], v[162:165], v[192:195], v[24:27]
	s_waitcnt lgkmcnt(0)
	v_mfma_f32_16x16x32_bf16 v[12:15], v[154:157], v[200:203], v[12:15]
	v_mfma_f32_16x16x32_bf16 v[8:11], v[162:165], v[200:203], v[8:11]
	s_barrier
; #define PG8_STAGE(bufoff, gbase, voff) do { _Pragma("unroll") for (int _i = 0; _i < 2; ++_i) \
;         __builtin_amdgcn_global_load_lds((const unsigned*)((const char*)(gbase) + (voff)[_i]), (LAS unsigned*)(lds + (bufoff) + ldsw + _i * 8192), 16, 0, 0); } while (0)
; #define PG8_LDA(dst, b, h) do { _Pragma("unroll") for (int m = 0; m < 4; ++m) _Pragma("unroll") for (int k = 0; k < 2; ++k) dst[m][k] = *(const LAS bf16x8*)(lds + PG8_SA(b, h) + aoff + m * 2048 + k * 1024); } while (0)
; #define PG8_LDB(dst, b, h) do { _Pragma("unroll") for (int n = 0; n < 2; ++n) _Pragma("unroll") for (int k = 0; k < 2; ++k) dst[n][k] = *(const LAS bf16x8*)(lds + PG8_SB(b, h) + boff + n * 2048 + k * 1024); } while (0)
; #define PG8_MMA(ai, bj, At, Bt) do { __builtin_amdgcn_s_setprio(1); _Pragma("unroll") for (int m = 0; m < 4; ++m) _Pragma("unroll") for (int n = 0; n < 2; ++n) _Pragma("unroll") for (int k = 0; k < 2; ++k) \
;         acc[ai][bj][m][n] = __builtin_amdgcn_mfma_f32_16x16x32_bf16(Bt[n][k], At[m][k], acc[ai][bj][m][n], 0, 0, 0); __builtin_amdgcn_s_setprio(0); } while (0)
; #define PG8_WAIT_V(n) asm volatile("s_waitcnt vmcnt(" #n ")" ::: "memory")
; #define PG8_WAIT_L(n) asm volatile("s_waitcnt lgkmcnt(" #n ")" ::: "memory")
; #define PG8_BAR __builtin_amdgcn_s_barrier()
; #define PG8_SCHED __builtin_amdgcn_sched_barrier(0)
; template <class Epi>
; __device__ __forceinline__ void gemm_phase(LAS unsigned char* lds, const Gemm g, const StaticOrder& S, const Epi& E) {
;     ...
;             PG8_STAGE(PG8_SB(0, 1), b2 + hstepB, voffB);
;             PG8_WAIT_V(6); PG8_BAR; PG8_MMA(1, 1, At, B1); PG8_BAR;
;             PG8_LDB(B0, 1, 0); PG8_SCHED; PG8_LDA(At, 1, 0); PG8_STAGE(PG8_SA(0, 1), a2 + hstepA, voffA);
;             PG8_WAIT_L(8); PG8_BAR; PG8_WAIT_L(0); PG8_MMA(0, 0, At, B0); PG8_BAR; PG8_SCHED;
;             PG8_LDB(B1, 1, 1); PG8_STAGE(PG8_SB(1, 0), b3, voffB);
;             PG8_BAR; PG8_WAIT_L(0); PG8_MMA(0, 1, At, B1); PG8_BAR;
;             PG8_LDA(At, 1, 1); PG8_STAGE(PG8_SA(1, 0), a3, voffA);
;             PG8_BAR; PG8_WAIT_L(0); PG8_MMA(1, 0, At, B0); PG8_BAR; PG8_SCHED;
	s_add_u32 s46, s22, 0x40000
	s_addc_u32 s47, s23, 0
	s_add_i32 s48, s38, s28
	v_lshl_add_u64 v[146:147], s[46:47], 0, v[130:131]
	s_mov_b32 m0, s48
	s_nop 0
	global_load_lds_dwordx4 v[146:147], off
	v_lshl_add_u64 v[146:147], s[46:47], 0, v[134:135]
	s_add_i32 m0, s48, 0x2000
	s_nop 0
	global_load_lds_dwordx4 v[146:147], off
	s_waitcnt vmcnt(6)
	s_barrier
	v_mfma_f32_16x16x32_bf16 v[52:55], v[204:207], v[166:169], 0
	v_mfma_f32_16x16x32_bf16 v[48:51], v[212:215], v[166:169], 0
	v_mfma_f32_16x16x32_bf16 v[36:39], v[204:207], v[180:183], 0
	v_mfma_f32_16x16x32_bf16 v[32:35], v[212:215], v[180:183], 0
	v_mfma_f32_16x16x32_bf16 v[20:23], v[204:207], v[188:191], 0
	v_mfma_f32_16x16x32_bf16 v[16:19], v[212:215], v[188:191], 0
	v_mfma_f32_16x16x32_bf16 v[4:7], v[204:207], v[196:199], 0
	v_mfma_f32_16x16x32_bf16 v[0:3], v[212:215], v[196:199], 0
	v_mfma_f32_16x16x32_bf16 v[52:55], v[208:211], v[170:173], v[52:55]
	v_mfma_f32_16x16x32_bf16 v[48:51], v[216:219], v[170:173], v[48:51]
	v_mfma_f32_16x16x32_bf16 v[36:39], v[208:211], v[184:187], v[36:39]
	v_mfma_f32_16x16x32_bf16 v[32:35], v[216:219], v[184:187], v[32:35]
	v_mfma_f32_16x16x32_bf16 v[20:23], v[208:211], v[192:195], v[20:23]
	v_mfma_f32_16x16x32_bf16 v[16:19], v[216:219], v[192:195], v[16:19]
	v_mfma_f32_16x16x32_bf16 v[4:7], v[208:211], v[200:203], v[4:7]
	v_mfma_f32_16x16x32_bf16 v[0:3], v[216:219], v[200:203], v[0:3]
	s_add_i32 s46, 0, 0x18000
	v_add_u32_e32 v162, s46, v174
	s_barrier
	ds_read_b128 v[146:149], v162
	ds_read_b128 v[154:157], v162 offset:1024
	ds_read_b128 v[158:161], v162 offset:2048
	ds_read_b128 v[162:165], v162 offset:3072
	s_add_u32 s24, s24, 0x40000
	s_addc_u32 s25, s25, 0
	s_mov_b32 m0, s30
	v_lshl_add_u64 v[204:205], s[24:25], 0, v[128:129]
	ds_read_b128 v[166:169], v177 offset:32768
	ds_read_b128 v[170:173], v177 offset:33792
	ds_read_b128 v[180:183], v177 offset:34816
	ds_read_b128 v[184:187], v177 offset:35840
	ds_read_b128 v[188:191], v177 offset:36864
	ds_read_b128 v[192:195], v177 offset:37888
	ds_read_b128 v[196:199], v177 offset:38912
	ds_read_b128 v[200:203], v177 offset:39936
	global_load_lds_dwordx4 v[204:205], off
	v_lshl_add_u64 v[204:205], s[24:25], 0, v[132:133]
	s_mov_b32 m0, s31
	s_nop 0
	global_load_lds_dwordx4 v[204:205], off
	s_waitcnt lgkmcnt(8)
	s_barrier
	s_waitcnt lgkmcnt(7)
	v_mfma_f32_16x16x32_bf16 v[124:127], v[146:149], v[166:169], v[124:127]
	v_mfma_f32_16x16x32_bf16 v[120:123], v[158:161], v[166:169], v[120:123]
	s_waitcnt lgkmcnt(5)
	v_mfma_f32_16x16x32_bf16 v[108:111], v[146:149], v[180:183], v[108:111]
	v_mfma_f32_16x16x32_bf16 v[104:107], v[158:161], v[180:183], v[104:107]
	s_waitcnt lgkmcnt(3)
	v_mfma_f32_16x16x32_bf16 v[92:95], v[146:149], v[188:191], v[92:95]
	v_mfma_f32_16x16x32_bf16 v[88:91], v[158:161], v[188:191], v[88:91]
	s_waitcnt lgkmcnt(1)
	v_mfma_f32_16x16x32_bf16 v[76:79], v[146:149], v[196:199], v[76:79]
	v_mfma_f32_16x16x32_bf16 v[72:75], v[158:161], v[196:199], v[72:75]
	v_mfma_f32_16x16x32_bf16 v[124:127], v[154:157], v[170:173], v[124:127]
	v_mfma_f32_16x16x32_bf16 v[120:123], v[162:165], v[170:173], v[120:123]
	v_mfma_f32_16x16x32_bf16 v[108:111], v[154:157], v[184:187], v[108:111]
	v_mfma_f32_16x16x32_bf16 v[104:107], v[162:165], v[184:187], v[104:107]
	v_mfma_f32_16x16x32_bf16 v[92:95], v[154:157], v[192:195], v[92:95]
	v_mfma_f32_16x16x32_bf16 v[88:91], v[162:165], v[192:195], v[88:91]
	s_waitcnt lgkmcnt(0)
	v_mfma_f32_16x16x32_bf16 v[76:79], v[154:157], v[200:203], v[76:79]
	v_mfma_f32_16x16x32_bf16 v[72:75], v[162:165], v[200:203], v[72:75]
	s_barrier
	s_add_i32 s24, 0, 0x1c000
	s_add_i32 s25, s46, s28
	v_add_u32_e32 v216, s24, v174
	v_lshl_add_u64 v[150:151], v[150:151], 0, s[4:5]
	s_mov_b32 m0, s25
	ds_read_b128 v[204:207], v216
	ds_read_b128 v[208:211], v216 offset:1024
	ds_read_b128 v[212:215], v216 offset:2048
	ds_read_b128 v[216:219], v216 offset:3072
	global_load_lds_dwordx4 v[150:151], off
	v_lshl_add_u64 v[150:151], v[220:221], 0, s[4:5]
	s_add_i32 m0, s25, 0x2000
	s_nop 0
	global_load_lds_dwordx4 v[150:151], off
	s_barrier
	s_waitcnt lgkmcnt(3)
	v_mfma_f32_16x16x32_bf16 v[116:119], v[204:207], v[166:169], v[116:119]
	s_waitcnt lgkmcnt(1)
	v_mfma_f32_16x16x32_bf16 v[112:115], v[212:215], v[166:169], v[112:115]
	v_mfma_f32_16x16x32_bf16 v[100:103], v[204:207], v[180:183], v[100:103]
	v_mfma_f32_16x16x32_bf16 v[96:99], v[212:215], v[180:183], v[96:99]
	v_mfma_f32_16x16x32_bf16 v[84:87], v[204:207], v[188:191], v[84:87]
	v_mfma_f32_16x16x32_bf16 v[80:83], v[212:215], v[188:191], v[80:83]
	v_mfma_f32_16x16x32_bf16 v[68:71], v[204:207], v[196:199], v[68:71]
	v_mfma_f32_16x16x32_bf16 v[64:67], v[212:215], v[196:199], v[64:67]
	v_mfma_f32_16x16x32_bf16 v[116:119], v[208:211], v[170:173], v[116:119]
	s_waitcnt lgkmcnt(0)
	v_mfma_f32_16x16x32_bf16 v[112:115], v[216:219], v[170:173], v[112:115]
	v_mfma_f32_16x16x32_bf16 v[100:103], v[208:211], v[184:187], v[100:103]
	v_mfma_f32_16x16x32_bf16 v[96:99], v[216:219], v[184:187], v[96:99]
	v_mfma_f32_16x16x32_bf16 v[84:87], v[208:211], v[192:195], v[84:87]
	v_mfma_f32_16x16x32_bf16 v[80:83], v[216:219], v[192:195], v[80:83]
	v_mfma_f32_16x16x32_bf16 v[68:71], v[208:211], v[200:203], v[68:71]
	v_mfma_f32_16x16x32_bf16 v[64:67], v[216:219], v[200:203], v[64:67]
	s_mov_b32 m0, s34
	v_lshl_add_u64 v[150:151], v[222:223], 0, s[4:5]
	s_barrier
	ds_read_b128 v[166:169], v177 offset:49152
	ds_read_b128 v[170:173], v177 offset:50176
	ds_read_b128 v[180:183], v177 offset:51200
	ds_read_b128 v[184:187], v177 offset:52224
	ds_read_b128 v[188:191], v177 offset:53248
	ds_read_b128 v[192:195], v177 offset:54272
	ds_read_b128 v[196:199], v177 offset:55296
	ds_read_b128 v[200:203], v177 offset:56320
	global_load_lds_dwordx4 v[150:151], off
	v_lshl_add_u64 v[150:151], v[224:225], 0, s[4:5]
	s_mov_b32 m0, s35
	s_nop 0
	global_load_lds_dwordx4 v[150:151], off
	s_barrier
; #define PG8_STAGE(bufoff, gbase, voff) do { _Pragma("unroll") for (int _i = 0; _i < 2; ++_i) \
;         __builtin_amdgcn_global_load_lds((const unsigned*)((const char*)(gbase) + (voff)[_i]), (LAS unsigned*)(lds + (bufoff) + ldsw + _i * 8192), 16, 0, 0); } while (0)
; #define PG8_LDA(dst, b, h) do { _Pragma("unroll") for (int m = 0; m < 4; ++m) _Pragma("unroll") for (int k = 0; k < 2; ++k) dst[m][k] = *(const LAS bf16x8*)(lds + PG8_SA(b, h) + aoff + m * 2048 + k * 1024); } while (0)
; #define PG8_WAIT_V(n) asm volatile("s_waitcnt vmcnt(" #n ")" ::: "memory")
; template <class Epi>
; __device__ __forceinline__ void gemm_phase(LAS unsigned char* lds, const Gemm g, const StaticOrder& S, const Epi& E) {
;     ...
;         for (int t = 0; t < nt; t += 2) {
;             const bool last = (t == nt - 2);
;             const char* a1 = cA + (size_t)(t + 1) * kstep;
;             const char* a2 = last ? nA : cA + (size_t)(t + 2) * kstep; const char* b2 = last ? nB : cB + (size_t)(t + 2) * kstep;
;             const char* a3 = a2 + kstep; const char* b3 = b2 + kstep;
;             if (last) E.pre(cur, wr, fr, epre);
;             PG8_LDB(B0, 0, 0); PG8_SCHED; PG8_LDA(At, 0, 0); PG8_STAGE(PG8_SA(1, 1), a1 + hstepA, voffA);
;             PG8_WAIT_L(8); PG8_BAR; PG8_WAIT_L(0); PG8_MMA(0, 0, At, B0); PG8_BAR; PG8_SCHED;
;             PG8_LDB(B1, 0, 1); PG8_STAGE(PG8_SB(0, 0), b2, voffB);
;             PG8_BAR; PG8_WAIT_L(0); PG8_MMA(0, 1, At, B1); PG8_BAR;
;             PG8_LDA(At, 0, 1); PG8_STAGE(PG8_SA(0, 0), a2, voffA);
;             PG8_BAR; PG8_WAIT_L(0); PG8_MMA(1, 0, At, B0); PG8_BAR; PG8_SCHED;
;             PG8_STAGE(PG8_SB(0, 1), b2 + hstepB, voffB);
;             PG8_WAIT_V(6); PG8_BAR; PG8_MMA(1, 1, At, B1); PG8_BAR;
;             PG8_LDB(B0, 1, 0); PG8_SCHED; PG8_LDA(At, 1, 0); PG8_STAGE(PG8_SA(0, 1), a2 + hstepA, voffA);
;             PG8_WAIT_L(8); PG8_BAR; PG8_WAIT_L(0); PG8_MMA(0, 0, At, B0); PG8_BAR; PG8_SCHED;
;             PG8_LDB(B1, 1, 1); PG8_STAGE(PG8_SB(1, 0), b3, voffB);
;             PG8_BAR; PG8_WAIT_L(0); PG8_MMA(0, 1, At, B1); PG8_BAR;
;             PG8_LDA(At, 1, 1); PG8_STAGE(PG8_SA(1, 0), a3, voffA);
;             PG8_BAR; PG8_WAIT_L(0); PG8_MMA(1, 0, At, B0); PG8_BAR; PG8_SCHED;
;             PG8_STAGE(PG8_SB(1, 1), b3 + hstepB, voffB);
;             PG8_WAIT_V(6); PG8_BAR; PG8_MMA(1, 1, At, B1); PG8_BAR;
	s_waitcnt lgkmcnt(7)
	v_mfma_f32_16x16x32_bf16 v[60:63], v[146:149], v[166:169], v[60:63]
	v_mfma_f32_16x16x32_bf16 v[56:59], v[158:161], v[166:169], v[56:59]
	s_waitcnt lgkmcnt(5)
	v_mfma_f32_16x16x32_bf16 v[44:47], v[146:149], v[180:183], v[44:47]
	v_mfma_f32_16x16x32_bf16 v[40:43], v[158:161], v[180:183], v[40:43]
	s_waitcnt lgkmcnt(3)
	v_mfma_f32_16x16x32_bf16 v[28:31], v[146:149], v[188:191], v[28:31]
	v_mfma_f32_16x16x32_bf16 v[24:27], v[158:161], v[188:191], v[24:27]
	s_waitcnt lgkmcnt(1)
	v_mfma_f32_16x16x32_bf16 v[12:15], v[146:149], v[196:199], v[12:15]
	v_mfma_f32_16x16x32_bf16 v[8:11], v[158:161], v[196:199], v[8:11]
	v_mfma_f32_16x16x32_bf16 v[60:63], v[154:157], v[170:173], v[60:63]
	v_mfma_f32_16x16x32_bf16 v[56:59], v[162:165], v[170:173], v[56:59]
	v_mfma_f32_16x16x32_bf16 v[44:47], v[154:157], v[184:187], v[44:47]
	v_mfma_f32_16x16x32_bf16 v[40:43], v[162:165], v[184:187], v[40:43]
	v_mfma_f32_16x16x32_bf16 v[28:31], v[154:157], v[192:195], v[28:31]
	v_mfma_f32_16x16x32_bf16 v[24:27], v[162:165], v[192:195], v[24:27]
	s_waitcnt lgkmcnt(0)
	v_mfma_f32_16x16x32_bf16 v[12:15], v[154:157], v[200:203], v[12:15]
	v_mfma_f32_16x16x32_bf16 v[8:11], v[162:165], v[200:203], v[8:11]
	s_barrier
	s_add_u32 s22, s22, 0x40080
	s_addc_u32 s23, s23, 0
	s_add_i32 s24, s24, s28
	v_lshl_add_u64 v[146:147], s[22:23], 0, v[130:131]
	s_mov_b32 m0, s24
	s_nop 0
	global_load_lds_dwordx4 v[146:147], off
	v_lshl_add_u64 v[146:147], s[22:23], 0, v[134:135]
	s_add_i32 m0, s24, 0x2000
	s_nop 0
	global_load_lds_dwordx4 v[146:147], off
	s_waitcnt vmcnt(6)
	s_barrier
	v_mfma_f32_16x16x32_bf16 v[52:55], v[204:207], v[166:169], v[52:55]
	v_mfma_f32_16x16x32_bf16 v[48:51], v[212:215], v[166:169], v[48:51]
	v_mfma_f32_16x16x32_bf16 v[36:39], v[204:207], v[180:183], v[36:39]
	v_mfma_f32_16x16x32_bf16 v[32:35], v[212:215], v[180:183], v[32:35]
	v_mfma_f32_16x16x32_bf16 v[20:23], v[204:207], v[188:191], v[20:23]
	v_mfma_f32_16x16x32_bf16 v[16:19], v[212:215], v[188:191], v[16:19]
	v_mfma_f32_16x16x32_bf16 v[4:7], v[204:207], v[196:199], v[4:7]
	v_mfma_f32_16x16x32_bf16 v[0:3], v[212:215], v[196:199], v[0:3]
	v_mfma_f32_16x16x32_bf16 v[52:55], v[208:211], v[170:173], v[52:55]
	v_mfma_f32_16x16x32_bf16 v[48:51], v[216:219], v[170:173], v[48:51]
	v_mfma_f32_16x16x32_bf16 v[36:39], v[208:211], v[184:187], v[36:39]
	v_mfma_f32_16x16x32_bf16 v[32:35], v[216:219], v[184:187], v[32:35]
	v_mfma_f32_16x16x32_bf16 v[20:23], v[208:211], v[192:195], v[20:23]
	v_mfma_f32_16x16x32_bf16 v[16:19], v[216:219], v[192:195], v[16:19]
	v_mfma_f32_16x16x32_bf16 v[4:7], v[208:211], v[200:203], v[4:7]
	v_mfma_f32_16x16x32_bf16 v[0:3], v[216:219], v[200:203], v[0:3]
	s_add_i32 s45, s45, 2
	s_add_u32 s20, s20, 0x100
	s_addc_u32 s21, s21, 0
	s_add_u32 s43, s43, 0x100
	s_addc_u32 s44, s44, 0
	s_cmp_gt_u32 s45, 13
	s_barrier
.LBB0_1204:
	ds_read_b128 v[146:149], v176
	ds_read_b128 v[154:157], v176 offset:1024
	ds_read_b128 v[158:161], v176 offset:2048
	ds_read_b128 v[162:165], v176 offset:3072
	s_add_u32 s22, s20, 0xfffc0080
	s_addc_u32 s23, s21, -1
	s_cmp_eq_u32 s45, 12
	s_cselect_b32 s25, s13, s23
	s_cselect_b32 s24, s41, s22
	s_cselect_b32 s23, s11, s44
	s_cselect_b32 s22, s42, s43
	v_lshl_add_u64 v[150:151], s[20:21], 0, v[138:139]
	s_add_i32 m0, s19, 0xc000
	ds_read_b128 v[166:169], v177
	ds_read_b128 v[170:173], v177 offset:1024
	ds_read_b128 v[180:183], v177 offset:2048
	ds_read_b128 v[184:187], v177 offset:3072
	ds_read_b128 v[188:191], v177 offset:4096
	ds_read_b128 v[192:195], v177 offset:5120
	ds_read_b128 v[196:199], v177 offset:6144
	ds_read_b128 v[200:203], v177 offset:7168
	global_load_lds_dwordx4 v[150:151], off
	v_lshl_add_u64 v[150:151], s[20:21], 0, v[140:141]
	s_add_i32 m0, s19, 0xe000
	s_nop 0
	global_load_lds_dwordx4 v[150:151], off
	s_waitcnt lgkmcnt(8)
	s_barrier
	s_waitcnt lgkmcnt(7)
	v_mfma_f32_16x16x32_bf16 v[124:127], v[146:149], v[166:169], v[124:127]
	v_mfma_f32_16x16x32_bf16 v[120:123], v[158:161], v[166:169], v[120:123]
	s_waitcnt lgkmcnt(5)
	v_mfma_f32_16x16x32_bf16 v[108:111], v[146:149], v[180:183], v[108:111]
	v_mfma_f32_16x16x32_bf16 v[104:107], v[158:161], v[180:183], v[104:107]
	s_waitcnt lgkmcnt(3)
	v_mfma_f32_16x16x32_bf16 v[92:95], v[146:149], v[188:191], v[92:95]
	v_mfma_f32_16x16x32_bf16 v[88:91], v[158:161], v[188:191], v[88:91]
	s_waitcnt lgkmcnt(1)
	v_mfma_f32_16x16x32_bf16 v[76:79], v[146:149], v[196:199], v[76:79]
	v_mfma_f32_16x16x32_bf16 v[72:75], v[158:161], v[196:199], v[72:75]
	v_mfma_f32_16x16x32_bf16 v[124:127], v[154:157], v[170:173], v[124:127]
	v_mfma_f32_16x16x32_bf16 v[120:123], v[162:165], v[170:173], v[120:123]
	v_mfma_f32_16x16x32_bf16 v[108:111], v[154:157], v[184:187], v[108:111]
	v_mfma_f32_16x16x32_bf16 v[104:107], v[162:165], v[184:187], v[104:107]
	v_mfma_f32_16x16x32_bf16 v[92:95], v[154:157], v[192:195], v[92:95]
	v_mfma_f32_16x16x32_bf16 v[88:91], v[162:165], v[192:195], v[88:91]
	s_waitcnt lgkmcnt(0)
	v_mfma_f32_16x16x32_bf16 v[76:79], v[154:157], v[200:203], v[76:79]
	v_mfma_f32_16x16x32_bf16 v[72:75], v[162:165], v[200:203], v[72:75]
	s_barrier
	s_add_i32 s46, s37, s28
	v_lshl_add_u64 v[150:151], s[22:23], 0, v[130:131]
	s_mov_b32 m0, s46
	ds_read_b128 v[204:207], v178
	ds_read_b128 v[208:211], v178 offset:1024
	ds_read_b128 v[212:215], v178 offset:2048
	ds_read_b128 v[216:219], v178 offset:3072
	global_load_lds_dwordx4 v[150:151], off
	v_lshl_add_u64 v[220:221], s[22:23], 0, v[134:135]
	s_add_i32 m0, s46, 0x2000
	s_nop 0
	global_load_lds_dwordx4 v[220:221], off
	s_barrier
; #define PG8_STAGE(bufoff, gbase, voff) do { _Pragma("unroll") for (int _i = 0; _i < 2; ++_i) \
;         __builtin_amdgcn_global_load_lds((const unsigned*)((const char*)(gbase) + (voff)[_i]), (LAS unsigned*)(lds + (bufoff) + ldsw + _i * 8192), 16, 0, 0); } while (0)
; #define PG8_LDA(dst, b, h) do { _Pragma("unroll") for (int m = 0; m < 4; ++m) _Pragma("unroll") for (int k = 0; k < 2; ++k) dst[m][k] = *(const LAS bf16x8*)(lds + PG8_SA(b, h) + aoff + m * 2048 + k * 1024); } while (0)
; #define PG8_LDB(dst, b, h) do { _Pragma("unroll") for (int n = 0; n < 2; ++n) _Pragma("unroll") for (int k = 0; k < 2; ++k) dst[n][k] = *(const LAS bf16x8*)(lds + PG8_SB(b, h) + boff + n * 2048 + k * 1024); } while (0)
; #define PG8_MMA(ai, bj, At, Bt) do { __builtin_amdgcn_s_setprio(1); _Pragma("unroll") for (int m = 0; m < 4; ++m) _Pragma("unroll") for (int n = 0; n < 2; ++n) _Pragma("unroll") for (int k = 0; k < 2; ++k) \
;         acc[ai][bj][m][n] = __builtin_amdgcn_mfma_f32_16x16x32_bf16(Bt[n][k], At[m][k], acc[ai][bj][m][n], 0, 0, 0); __builtin_amdgcn_s_setprio(0); } while (0)
; #define PG8_WAIT_V(n) asm volatile("s_waitcnt vmcnt(" #n ")" ::: "memory")
; #define PG8_WAIT_L(n) asm volatile("s_waitcnt lgkmcnt(" #n ")" ::: "memory")
; #define PG8_BAR __builtin_amdgcn_s_barrier()
; #define PG8_SCHED __builtin_amdgcn_sched_barrier(0)
; template <class Epi>
; __device__ __forceinline__ void gemm_phase(LAS unsigned char* lds, const Gemm g, const StaticOrder& S, const Epi& E) {
;     ...
;             PG8_WAIT_L(8); PG8_BAR; PG8_WAIT_L(0); PG8_MMA(0, 0, At, B0); PG8_BAR; PG8_SCHED;
;             PG8_LDB(B1, 0, 1); PG8_STAGE(PG8_SB(0, 0), b2, voffB);
;             PG8_BAR; PG8_WAIT_L(0); PG8_MMA(0, 1, At, B1); PG8_BAR;
;             PG8_LDA(At, 0, 1); PG8_STAGE(PG8_SA(0, 0), a2, voffA);
;             PG8_BAR; PG8_WAIT_L(0); PG8_MMA(1, 0, At, B0); PG8_BAR; PG8_SCHED;
;             PG8_STAGE(PG8_SB(0, 1), b2 + hstepB, voffB);
;             PG8_WAIT_V(6); PG8_BAR; PG8_MMA(1, 1, At, B1); PG8_BAR;
;             PG8_LDB(B0, 1, 0); PG8_SCHED; PG8_LDA(At, 1, 0); PG8_STAGE(PG8_SA(0, 1), a2 + hstepA, voffA);
;             PG8_WAIT_L(8); PG8_BAR; PG8_WAIT_L(0); PG8_MMA(0, 0, At, B0); PG8_BAR; PG8_SCHED;
	s_waitcnt lgkmcnt(3)
	v_mfma_f32_16x16x32_bf16 v[116:119], v[204:207], v[166:169], v[116:119]
	s_waitcnt lgkmcnt(1)
	v_mfma_f32_16x16x32_bf16 v[112:115], v[212:215], v[166:169], v[112:115]
	v_mfma_f32_16x16x32_bf16 v[100:103], v[204:207], v[180:183], v[100:103]
	v_mfma_f32_16x16x32_bf16 v[96:99], v[212:215], v[180:183], v[96:99]
	v_mfma_f32_16x16x32_bf16 v[84:87], v[204:207], v[188:191], v[84:87]
	v_mfma_f32_16x16x32_bf16 v[80:83], v[212:215], v[188:191], v[80:83]
	v_mfma_f32_16x16x32_bf16 v[68:71], v[204:207], v[196:199], v[68:71]
	v_mfma_f32_16x16x32_bf16 v[64:67], v[212:215], v[196:199], v[64:67]
	v_mfma_f32_16x16x32_bf16 v[116:119], v[208:211], v[170:173], v[116:119]
	s_waitcnt lgkmcnt(0)
	v_mfma_f32_16x16x32_bf16 v[112:115], v[216:219], v[170:173], v[112:115]
	v_mfma_f32_16x16x32_bf16 v[100:103], v[208:211], v[184:187], v[100:103]
	v_mfma_f32_16x16x32_bf16 v[96:99], v[216:219], v[184:187], v[96:99]
	v_mfma_f32_16x16x32_bf16 v[84:87], v[208:211], v[192:195], v[84:87]
	v_mfma_f32_16x16x32_bf16 v[80:83], v[216:219], v[192:195], v[80:83]
	v_mfma_f32_16x16x32_bf16 v[68:71], v[208:211], v[200:203], v[68:71]
	v_mfma_f32_16x16x32_bf16 v[64:67], v[216:219], v[200:203], v[64:67]
	s_mov_b32 m0, s19
	v_lshl_add_u64 v[222:223], s[24:25], 0, v[128:129]
	s_barrier
	ds_read_b128 v[166:169], v177 offset:16384
	ds_read_b128 v[170:173], v177 offset:17408
	ds_read_b128 v[180:183], v177 offset:18432
	ds_read_b128 v[184:187], v177 offset:19456
	ds_read_b128 v[188:191], v177 offset:20480
	ds_read_b128 v[192:195], v177 offset:21504
	ds_read_b128 v[196:199], v177 offset:22528
	ds_read_b128 v[200:203], v177 offset:23552
	global_load_lds_dwordx4 v[222:223], off
	v_lshl_add_u64 v[224:225], s[24:25], 0, v[132:133]
	s_mov_b32 m0, s29
	s_nop 0
	global_load_lds_dwordx4 v[224:225], off
	s_barrier
	s_waitcnt lgkmcnt(7)
	v_mfma_f32_16x16x32_bf16 v[60:63], v[146:149], v[166:169], v[60:63]
	v_mfma_f32_16x16x32_bf16 v[56:59], v[158:161], v[166:169], v[56:59]
	s_waitcnt lgkmcnt(5)
	v_mfma_f32_16x16x32_bf16 v[44:47], v[146:149], v[180:183], v[44:47]
	v_mfma_f32_16x16x32_bf16 v[40:43], v[158:161], v[180:183], v[40:43]
	s_waitcnt lgkmcnt(3)
	v_mfma_f32_16x16x32_bf16 v[28:31], v[146:149], v[188:191], v[28:31]
	v_mfma_f32_16x16x32_bf16 v[24:27], v[158:161], v[188:191], v[24:27]
	s_waitcnt lgkmcnt(1)
	v_mfma_f32_16x16x32_bf16 v[12:15], v[146:149], v[196:199], v[12:15]
	v_mfma_f32_16x16x32_bf16 v[8:11], v[158:161], v[196:199], v[8:11]
	v_mfma_f32_16x16x32_bf16 v[60:63], v[154:157], v[170:173], v[60:63]
	v_mfma_f32_16x16x32_bf16 v[56:59], v[162:165], v[170:173], v[56:59]
	v_mfma_f32_16x16x32_bf16 v[44:47], v[154:157], v[184:187], v[44:47]
	v_mfma_f32_16x16x32_bf16 v[40:43], v[162:165], v[184:187], v[40:43]
	v_mfma_f32_16x16x32_bf16 v[28:31], v[154:157], v[192:195], v[28:31]
	v_mfma_f32_16x16x32_bf16 v[24:27], v[162:165], v[192:195], v[24:27]
	s_waitcnt lgkmcnt(0)
	v_mfma_f32_16x16x32_bf16 v[12:15], v[154:157], v[200:203], v[12:15]
	v_mfma_f32_16x16x32_bf16 v[8:11], v[162:165], v[200:203], v[8:11]
	s_barrier
	s_add_u32 s46, s22, 0x40000
	s_addc_u32 s47, s23, 0
	s_add_i32 s48, s38, s28
	v_lshl_add_u64 v[146:147], s[46:47], 0, v[130:131]
	s_mov_b32 m0, s48
	s_nop 0
	global_load_lds_dwordx4 v[146:147], off
	v_lshl_add_u64 v[146:147], s[46:47], 0, v[134:135]
	s_add_i32 m0, s48, 0x2000
	s_nop 0
	global_load_lds_dwordx4 v[146:147], off
	s_waitcnt vmcnt(6)
	s_barrier
	v_mfma_f32_16x16x32_bf16 v[52:55], v[204:207], v[166:169], v[52:55]
	v_mfma_f32_16x16x32_bf16 v[48:51], v[212:215], v[166:169], v[48:51]
	v_mfma_f32_16x16x32_bf16 v[36:39], v[204:207], v[180:183], v[36:39]
	v_mfma_f32_16x16x32_bf16 v[32:35], v[212:215], v[180:183], v[32:35]
	v_mfma_f32_16x16x32_bf16 v[20:23], v[204:207], v[188:191], v[20:23]
	v_mfma_f32_16x16x32_bf16 v[16:19], v[212:215], v[188:191], v[16:19]
	v_mfma_f32_16x16x32_bf16 v[4:7], v[204:207], v[196:199], v[4:7]
	v_mfma_f32_16x16x32_bf16 v[0:3], v[212:215], v[196:199], v[0:3]
	v_mfma_f32_16x16x32_bf16 v[52:55], v[208:211], v[170:173], v[52:55]
	v_mfma_f32_16x16x32_bf16 v[48:51], v[216:219], v[170:173], v[48:51]
	v_mfma_f32_16x16x32_bf16 v[36:39], v[208:211], v[184:187], v[36:39]
	v_mfma_f32_16x16x32_bf16 v[32:35], v[216:219], v[184:187], v[32:35]
	v_mfma_f32_16x16x32_bf16 v[20:23], v[208:211], v[192:195], v[20:23]
	v_mfma_f32_16x16x32_bf16 v[16:19], v[216:219], v[192:195], v[16:19]
	v_mfma_f32_16x16x32_bf16 v[4:7], v[208:211], v[200:203], v[4:7]
	v_mfma_f32_16x16x32_bf16 v[0:3], v[216:219], v[200:203], v[0:3]
	s_add_i32 s46, 0, 0x18000
	v_add_u32_e32 v162, s46, v174
	s_barrier
	ds_read_b128 v[146:149], v162
	ds_read_b128 v[154:157], v162 offset:1024
	ds_read_b128 v[158:161], v162 offset:2048
	ds_read_b128 v[162:165], v162 offset:3072
	s_add_u32 s24, s24, 0x40000
	s_addc_u32 s25, s25, 0
	s_mov_b32 m0, s30
	v_lshl_add_u64 v[204:205], s[24:25], 0, v[128:129]
	ds_read_b128 v[166:169], v177 offset:32768
	ds_read_b128 v[170:173], v177 offset:33792
	ds_read_b128 v[180:183], v177 offset:34816
	ds_read_b128 v[184:187], v177 offset:35840
	ds_read_b128 v[188:191], v177 offset:36864
	ds_read_b128 v[192:195], v177 offset:37888
	ds_read_b128 v[196:199], v177 offset:38912
	ds_read_b128 v[200:203], v177 offset:39936
	global_load_lds_dwordx4 v[204:205], off
	v_lshl_add_u64 v[204:205], s[24:25], 0, v[132:133]
	s_mov_b32 m0, s31
	s_nop 0
	global_load_lds_dwordx4 v[204:205], off
	s_waitcnt lgkmcnt(8)
	s_barrier
; #define PG8_STAGE(bufoff, gbase, voff) do { _Pragma("unroll") for (int _i = 0; _i < 2; ++_i) \
;         __builtin_amdgcn_global_load_lds((const unsigned*)((const char*)(gbase) + (voff)[_i]), (LAS unsigned*)(lds + (bufoff) + ldsw + _i * 8192), 16, 0, 0); } while (0)
; #define PG8_LDA(dst, b, h) do { _Pragma("unroll") for (int m = 0; m < 4; ++m) _Pragma("unroll") for (int k = 0; k < 2; ++k) dst[m][k] = *(const LAS bf16x8*)(lds + PG8_SA(b, h) + aoff + m * 2048 + k * 1024); } while (0)
; #define PG8_LDB(dst, b, h) do { _Pragma("unroll") for (int n = 0; n < 2; ++n) _Pragma("unroll") for (int k = 0; k < 2; ++k) dst[n][k] = *(const LAS bf16x8*)(lds + PG8_SB(b, h) + boff + n * 2048 + k * 1024); } while (0)
; #define PG8_MMA(ai, bj, At, Bt) do { __builtin_amdgcn_s_setprio(1); _Pragma("unroll") for (int m = 0; m < 4; ++m) _Pragma("unroll") for (int n = 0; n < 2; ++n) _Pragma("unroll") for (int k = 0; k < 2; ++k) \
;         acc[ai][bj][m][n] = __builtin_amdgcn_mfma_f32_16x16x32_bf16(Bt[n][k], At[m][k], acc[ai][bj][m][n], 0, 0, 0); __builtin_amdgcn_s_setprio(0); } while (0)
; #define PG8_WAIT_V(n) asm volatile("s_waitcnt vmcnt(" #n ")" ::: "memory")
; #define PG8_WAIT_L(n) asm volatile("s_waitcnt lgkmcnt(" #n ")" ::: "memory")
; #define PG8_BAR __builtin_amdgcn_s_barrier()
; #define PG8_SCHED __builtin_amdgcn_sched_barrier(0)
; template <class Epi>
; __device__ __forceinline__ void gemm_phase(LAS unsigned char* lds, const Gemm g, const StaticOrder& S, const Epi& E) {
;     ...
;             PG8_WAIT_L(8); PG8_BAR; PG8_WAIT_L(0); PG8_MMA(0, 0, At, B0); PG8_BAR; PG8_SCHED;
;             PG8_LDB(B1, 1, 1); PG8_STAGE(PG8_SB(1, 0), b3, voffB);
;             PG8_BAR; PG8_WAIT_L(0); PG8_MMA(0, 1, At, B1); PG8_BAR;
;             PG8_LDA(At, 1, 1); PG8_STAGE(PG8_SA(1, 0), a3, voffA);
;             PG8_BAR; PG8_WAIT_L(0); PG8_MMA(1, 0, At, B0); PG8_BAR; PG8_SCHED;
;             PG8_STAGE(PG8_SB(1, 1), b3 + hstepB, voffB);
;             PG8_WAIT_V(6); PG8_BAR; PG8_MMA(1, 1, At, B1); PG8_BAR;
	s_waitcnt lgkmcnt(7)
	v_mfma_f32_16x16x32_bf16 v[124:127], v[146:149], v[166:169], v[124:127]
	v_mfma_f32_16x16x32_bf16 v[120:123], v[158:161], v[166:169], v[120:123]
	s_waitcnt lgkmcnt(5)
	v_mfma_f32_16x16x32_bf16 v[108:111], v[146:149], v[180:183], v[108:111]
	v_mfma_f32_16x16x32_bf16 v[104:107], v[158:161], v[180:183], v[104:107]
	s_waitcnt lgkmcnt(3)
	v_mfma_f32_16x16x32_bf16 v[92:95], v[146:149], v[188:191], v[92:95]
	v_mfma_f32_16x16x32_bf16 v[88:91], v[158:161], v[188:191], v[88:91]
	s_waitcnt lgkmcnt(1)
	v_mfma_f32_16x16x32_bf16 v[76:79], v[146:149], v[196:199], v[76:79]
	v_mfma_f32_16x16x32_bf16 v[72:75], v[158:161], v[196:199], v[72:75]
	v_mfma_f32_16x16x32_bf16 v[124:127], v[154:157], v[170:173], v[124:127]
	v_mfma_f32_16x16x32_bf16 v[120:123], v[162:165], v[170:173], v[120:123]
	v_mfma_f32_16x16x32_bf16 v[108:111], v[154:157], v[184:187], v[108:111]
	v_mfma_f32_16x16x32_bf16 v[104:107], v[162:165], v[184:187], v[104:107]
	v_mfma_f32_16x16x32_bf16 v[92:95], v[154:157], v[192:195], v[92:95]
	v_mfma_f32_16x16x32_bf16 v[88:91], v[162:165], v[192:195], v[88:91]
	s_waitcnt lgkmcnt(0)
	v_mfma_f32_16x16x32_bf16 v[76:79], v[154:157], v[200:203], v[76:79]
	v_mfma_f32_16x16x32_bf16 v[72:75], v[162:165], v[200:203], v[72:75]
	s_barrier
	s_add_i32 s24, 0, 0x1c000
	s_add_i32 s25, s46, s28
	v_add_u32_e32 v216, s24, v174
	v_lshl_add_u64 v[150:151], v[150:151], 0, s[4:5]
	s_mov_b32 m0, s25
	ds_read_b128 v[204:207], v216
	ds_read_b128 v[208:211], v216 offset:1024
	ds_read_b128 v[212:215], v216 offset:2048
	ds_read_b128 v[216:219], v216 offset:3072
	global_load_lds_dwordx4 v[150:151], off
	v_lshl_add_u64 v[150:151], v[220:221], 0, s[4:5]
	s_add_i32 m0, s25, 0x2000
	s_nop 0
	global_load_lds_dwordx4 v[150:151], off
	s_barrier
	s_waitcnt lgkmcnt(3)
	v_mfma_f32_16x16x32_bf16 v[116:119], v[204:207], v[166:169], v[116:119]
	s_waitcnt lgkmcnt(1)
	v_mfma_f32_16x16x32_bf16 v[112:115], v[212:215], v[166:169], v[112:115]
	v_mfma_f32_16x16x32_bf16 v[100:103], v[204:207], v[180:183], v[100:103]
	v_mfma_f32_16x16x32_bf16 v[96:99], v[212:215], v[180:183], v[96:99]
	v_mfma_f32_16x16x32_bf16 v[84:87], v[204:207], v[188:191], v[84:87]
	v_mfma_f32_16x16x32_bf16 v[80:83], v[212:215], v[188:191], v[80:83]
	v_mfma_f32_16x16x32_bf16 v[68:71], v[204:207], v[196:199], v[68:71]
	v_mfma_f32_16x16x32_bf16 v[64:67], v[212:215], v[196:199], v[64:67]
	v_mfma_f32_16x16x32_bf16 v[116:119], v[208:211], v[170:173], v[116:119]
	s_waitcnt lgkmcnt(0)
	v_mfma_f32_16x16x32_bf16 v[112:115], v[216:219], v[170:173], v[112:115]
	v_mfma_f32_16x16x32_bf16 v[100:103], v[208:211], v[184:187], v[100:103]
	v_mfma_f32_16x16x32_bf16 v[96:99], v[216:219], v[184:187], v[96:99]
	v_mfma_f32_16x16x32_bf16 v[84:87], v[208:211], v[192:195], v[84:87]
	v_mfma_f32_16x16x32_bf16 v[80:83], v[216:219], v[192:195], v[80:83]
	v_mfma_f32_16x16x32_bf16 v[68:71], v[208:211], v[200:203], v[68:71]
	v_mfma_f32_16x16x32_bf16 v[64:67], v[216:219], v[200:203], v[64:67]
	s_mov_b32 m0, s34
	v_lshl_add_u64 v[150:151], v[222:223], 0, s[4:5]
	s_barrier
	ds_read_b128 v[166:169], v177 offset:49152
	ds_read_b128 v[170:173], v177 offset:50176
	ds_read_b128 v[180:183], v177 offset:51200
	ds_read_b128 v[184:187], v177 offset:52224
	ds_read_b128 v[188:191], v177 offset:53248
	ds_read_b128 v[192:195], v177 offset:54272
	ds_read_b128 v[196:199], v177 offset:55296
	ds_read_b128 v[200:203], v177 offset:56320
	global_load_lds_dwordx4 v[150:151], off
	v_lshl_add_u64 v[150:151], v[224:225], 0, s[4:5]
	s_mov_b32 m0, s35
	s_nop 0
	global_load_lds_dwordx4 v[150:151], off
	s_barrier
	s_waitcnt lgkmcnt(7)
	v_mfma_f32_16x16x32_bf16 v[60:63], v[146:149], v[166:169], v[60:63]
	v_mfma_f32_16x16x32_bf16 v[56:59], v[158:161], v[166:169], v[56:59]
	s_waitcnt lgkmcnt(5)
	v_mfma_f32_16x16x32_bf16 v[44:47], v[146:149], v[180:183], v[44:47]
	v_mfma_f32_16x16x32_bf16 v[40:43], v[158:161], v[180:183], v[40:43]
	s_waitcnt lgkmcnt(3)
	v_mfma_f32_16x16x32_bf16 v[28:31], v[146:149], v[188:191], v[28:31]
	v_mfma_f32_16x16x32_bf16 v[24:27], v[158:161], v[188:191], v[24:27]
	s_waitcnt lgkmcnt(1)
	v_mfma_f32_16x16x32_bf16 v[12:15], v[146:149], v[196:199], v[12:15]
	v_mfma_f32_16x16x32_bf16 v[8:11], v[158:161], v[196:199], v[8:11]
	v_mfma_f32_16x16x32_bf16 v[60:63], v[154:157], v[170:173], v[60:63]
	v_mfma_f32_16x16x32_bf16 v[56:59], v[162:165], v[170:173], v[56:59]
	v_mfma_f32_16x16x32_bf16 v[44:47], v[154:157], v[184:187], v[44:47]
	v_mfma_f32_16x16x32_bf16 v[40:43], v[162:165], v[184:187], v[40:43]
	v_mfma_f32_16x16x32_bf16 v[28:31], v[154:157], v[192:195], v[28:31]
	v_mfma_f32_16x16x32_bf16 v[24:27], v[162:165], v[192:195], v[24:27]
	s_waitcnt lgkmcnt(0)
	v_mfma_f32_16x16x32_bf16 v[12:15], v[154:157], v[200:203], v[12:15]
	v_mfma_f32_16x16x32_bf16 v[8:11], v[162:165], v[200:203], v[8:11]
	s_barrier
	s_add_u32 s22, s22, 0x40080
	s_addc_u32 s23, s23, 0
	s_add_i32 s24, s24, s28
	v_lshl_add_u64 v[146:147], s[22:23], 0, v[130:131]
	s_mov_b32 m0, s24
	s_nop 0
	global_load_lds_dwordx4 v[146:147], off
	v_lshl_add_u64 v[146:147], s[22:23], 0, v[134:135]
	s_add_i32 m0, s24, 0x2000
	s_nop 0
	global_load_lds_dwordx4 v[146:147], off
	s_waitcnt vmcnt(6)
	s_barrier
; __device__ __forceinline__ unsigned pk2(float lo, float hi) { const f32x2 v = (f32x2){lo, hi}; const bf16x2_t b = __builtin_convertvector(v, bf16x2_t); return __builtin_bit_cast(unsigned, b); }
; #define PG8_MMA(ai, bj, At, Bt) do { __builtin_amdgcn_s_setprio(1); _Pragma("unroll") for (int m = 0; m < 4; ++m) _Pragma("unroll") for (int n = 0; n < 2; ++n) _Pragma("unroll") for (int k = 0; k < 2; ++k) \
;         acc[ai][bj][m][n] = __builtin_amdgcn_mfma_f32_16x16x32_bf16(Bt[n][k], At[m][k], acc[ai][bj][m][n], 0, 0, 0); __builtin_amdgcn_s_setprio(0); } while (0)
; #define PG8_WAIT_V(n) asm volatile("s_waitcnt vmcnt(" #n ")" ::: "memory")
; #define PG8_BAR __builtin_amdgcn_s_barrier()
;     __device__ __forceinline__ void operator()(const f32x4 (&acc)[2][2][4][2], const Unit& u, int wr, int wc, int fr, int fq, const float (&)[8]) const {
;     ...
;         const int col0 = u.pn * BM + wc * 32 + 8 * fq;
; #pragma unroll
;         for (int ai = 0; ai < 2; ++ai)
; #pragma unroll
;             for (int m = 0; m < 4; ++m) { const int row = row0 + ai * HALF + m * 16; const float rs = rsqrtf(ep[ai * 4 + m] * (1.0f / 1024.0f) + EPS);
;                 u16* rowp = O + (size_t)row * ldc + col0;
; #pragma unroll
;                 for (int bj = 0; bj < 2; ++bj) { f32x4 v0 = acc[ai][bj][m][0] * rs, v1 = acc[ai][bj][m][1] * rs;
;                     if (ACT == 1) {
; #pragma unroll
;                         for (int j = 0; j < 4; ++j) { const float a0 = fmaxf(v0[j], 0.f), a1 = fmaxf(v1[j], 0.f); v0[j] = a0 * a0; v1[j] = a1 * a1; } }
;                     u32x4 w; w.x = pk2(v0[0], v0[1]); w.y = pk2(v0[2], v0[3]); w.z = pk2(v1[0], v1[1]); w.w = pk2(v1[2], v1[3]);
;                     *(u32x4*)(rowp + bj * HALF) = w; } }
; template <class Epi>
; __device__ __forceinline__ void gemm_phase(LAS unsigned char* lds, const Gemm g, const StaticOrder& S, const Epi& E) {
;     ...
;             PG8_WAIT_V(6); PG8_BAR; PG8_MMA(1, 1, At, B1); PG8_BAR;
;         }
	v_mfma_f32_16x16x32_bf16 v[52:55], v[204:207], v[166:169], v[52:55]
	v_mfma_f32_16x16x32_bf16 v[48:51], v[212:215], v[166:169], v[48:51]
	v_mfma_f32_16x16x32_bf16 v[36:39], v[204:207], v[180:183], v[36:39]
	v_mfma_f32_16x16x32_bf16 v[32:35], v[212:215], v[180:183], v[32:35]
	v_mfma_f32_16x16x32_bf16 v[20:23], v[204:207], v[188:191], v[20:23]
	v_mfma_f32_16x16x32_bf16 v[16:19], v[212:215], v[188:191], v[16:19]
	v_mfma_f32_16x16x32_bf16 v[4:7], v[204:207], v[196:199], v[4:7]
	v_mfma_f32_16x16x32_bf16 v[0:3], v[212:215], v[196:199], v[0:3]
	v_mfma_f32_16x16x32_bf16 v[52:55], v[208:211], v[170:173], v[52:55]
	v_mfma_f32_16x16x32_bf16 v[48:51], v[216:219], v[170:173], v[48:51]
	v_mfma_f32_16x16x32_bf16 v[36:39], v[208:211], v[184:187], v[36:39]
	v_mfma_f32_16x16x32_bf16 v[32:35], v[216:219], v[184:187], v[32:35]
	v_mfma_f32_16x16x32_bf16 v[20:23], v[208:211], v[192:195], v[20:23]
	v_mfma_f32_16x16x32_bf16 v[16:19], v[216:219], v[192:195], v[16:19]
	v_mfma_f32_16x16x32_bf16 v[4:7], v[208:211], v[200:203], v[4:7]
	v_mfma_f32_16x16x32_bf16 v[0:3], v[216:219], v[200:203], v[0:3]
	s_add_i32 s45, s45, 2
	s_add_u32 s20, s20, 0x100
	s_addc_u32 s21, s21, 0
	s_add_u32 s43, s43, 0x100
	s_addc_u32 s44, s44, 0
	s_cmp_gt_u32 s45, 13
	s_barrier
	s_cbranch_scc0 .LBB0_1204
	s_bfe_u32 vcc_lo, s18, 0x20003
	s_lshl_b32 vcc_lo, vcc_lo, 10
	s_add_i32 vcc_lo, vcc_lo, 0x20010
	v_lshl_add_u32 v236, v153, 2, vcc_lo
	ds_read_b32 v228, v236
	ds_read_b32 v229, v236 offset:64
	ds_read_b32 v230, v236 offset:128
	ds_read_b32 v231, v236 offset:192
	ds_read_b32 v232, v236 offset:512
	ds_read_b32 v233, v236 offset:576
	ds_read_b32 v234, v236 offset:640
	ds_read_b32 v235, v236 offset:704
	s_waitcnt lgkmcnt(0)
	v_lshl_add_u32 v148, s18, 8, v153
	v_ashrrev_i32_e32 v149, 31, v148
	v_or_b32_e32 v172, 16, v148
	v_ashrrev_i32_e32 v173, 31, v172
	v_or_b32_e32 v168, 32, v148
	v_or_b32_e32 v164, 48, v148
	v_ashrrev_i32_e32 v169, 31, v168
	v_ashrrev_i32_e32 v165, 31, v164
	v_add_u32_e32 v162, 0x80, v148
	v_add_u32_e32 v156, 0x90, v148
	v_ashrrev_i32_e32 v163, 31, v162
	v_ashrrev_i32_e32 v157, 31, v156
	v_add_u32_e32 v150, 0xa0, v148
	v_ashrrev_i32_e32 v151, 31, v150
	v_add_u32_e32 v146, 0xb0, v148
	v_ashrrev_i32_e32 v147, 31, v146
	v_lshl_or_b32 v166, s40, 8, v175
	v_ashrrev_i32_e32 v167, 31, v166
	v_lshlrev_b64 v[170:171], 13, v[148:149]
	v_lshlrev_b64 v[148:149], 1, v[166:167]
	v_lshl_add_u64 v[166:167], s[96:97], 0, v[170:171]
	v_lshl_add_u64 v[210:211], v[166:167], 0, v[148:149]
	s_mov_b32 s40, s10
	s_mov_b32 s18, s12
	s_mov_b64 s[22:23], s[16:17]
	s_mov_b64 s[20:21], s[14:15]
	s_waitcnt vmcnt(8)
	s_waitcnt lgkmcnt(0)
	s_waitcnt lgkmcnt(0)
	v_mov_b32_e32 v182, v228
	v_pk_mul_f32 v[120:121], v[120:121], v[182:183] op_sel_hi:[1,0]
	v_pk_mul_f32 v[126:127], v[126:127], v[182:183] op_sel_hi:[1,0]
	v_pk_mul_f32 v[124:125], v[124:125], v[182:183] op_sel_hi:[1,0]
	v_pk_mul_f32 v[122:123], v[122:123], v[182:183] op_sel_hi:[1,0]
	v_max_f32_e32 v120, 0, v120
	v_max_f32_e32 v121, 0, v121
	v_max_f32_e32 v124, 0, v124
	v_max_f32_e32 v125, 0, v125
	v_pk_mul_f32 v[188:189], v[120:121], v[120:121]
	v_max_f32_e32 v120, 0, v126
	v_max_f32_e32 v122, 0, v122
	v_max_f32_e32 v121, 0, v127
	v_max_f32_e32 v123, 0, v123
	v_pk_mul_f32 v[124:125], v[124:125], v[124:125]
	v_pk_mul_f32 v[126:127], v[120:121], v[120:121]
	v_pk_mul_f32 v[192:193], v[122:123], v[122:123]
	v_pk_mul_f32 v[114:115], v[114:115], v[182:183] op_sel_hi:[1,0]
	v_cvt_pk_bf16_f32 v120, v124, v125
	v_cvt_pk_bf16_f32 v121, v126, v127
	v_cvt_pk_bf16_f32 v122, v188, v189
	v_cvt_pk_bf16_f32 v123, v192, v193
	v_pk_mul_f32 v[116:117], v[116:117], v[182:183] op_sel_hi:[1,0]
	v_pk_mul_f32 v[112:113], v[112:113], v[182:183] op_sel_hi:[1,0]
	v_max_f32_e32 v114, 0, v114
	v_max_f32_e32 v115, 0, v115
	global_store_dwordx4 v[210:211], v[120:123], off
	v_pk_mul_f32 v[118:119], v[118:119], v[182:183] op_sel_hi:[1,0]
	v_max_f32_e32 v116, 0, v116
	v_max_f32_e32 v112, 0, v112
	v_max_f32_e32 v117, 0, v117
	v_max_f32_e32 v113, 0, v113
	v_pk_mul_f32 v[122:123], v[114:115], v[114:115]
	v_pk_mul_f32 v[116:117], v[116:117], v[116:117]
	v_pk_mul_f32 v[120:121], v[112:113], v[112:113]
	v_max_f32_e32 v112, 0, v118
	v_max_f32_e32 v113, 0, v119
	v_pk_mul_f32 v[118:119], v[112:113], v[112:113]
	v_cvt_pk_bf16_f32 v112, v116, v117
	v_cvt_pk_bf16_f32 v113, v118, v119
	v_cvt_pk_bf16_f32 v114, v120, v121
	v_cvt_pk_bf16_f32 v115, v122, v123
	global_store_dwordx4 v[210:211], v[112:115], off offset:256
	s_nop 1
	v_mov_b32_e32 v112, v229
	v_pk_mul_f32 v[104:105], v[104:105], v[112:113] op_sel_hi:[1,0]
	v_pk_mul_f32 v[110:111], v[110:111], v[112:113] op_sel_hi:[1,0]
	v_pk_mul_f32 v[108:109], v[108:109], v[112:113] op_sel_hi:[1,0]
	v_pk_mul_f32 v[106:107], v[106:107], v[112:113] op_sel_hi:[1,0]
	v_max_f32_e32 v104, 0, v104
	v_max_f32_e32 v105, 0, v105
	v_lshlrev_b64 v[114:115], 13, v[172:173]
	v_max_f32_e32 v108, 0, v108
	v_max_f32_e32 v109, 0, v109
	v_pk_mul_f32 v[116:117], v[104:105], v[104:105]
	v_max_f32_e32 v104, 0, v110
	v_max_f32_e32 v106, 0, v106
	v_max_f32_e32 v105, 0, v111
	v_max_f32_e32 v107, 0, v107
	v_lshl_add_u64 v[114:115], s[96:97], 0, v[114:115]
	v_pk_mul_f32 v[108:109], v[108:109], v[108:109]
	v_pk_mul_f32 v[110:111], v[104:105], v[104:105]
	v_pk_mul_f32 v[118:119], v[106:107], v[106:107]
	v_pk_mul_f32 v[96:97], v[96:97], v[112:113] op_sel_hi:[1,0]
	v_lshl_add_u64 v[114:115], v[114:115], 0, v[148:149]
	v_cvt_pk_bf16_f32 v104, v108, v109
	v_cvt_pk_bf16_f32 v105, v110, v111
	v_cvt_pk_bf16_f32 v106, v116, v117
	v_cvt_pk_bf16_f32 v107, v118, v119
	v_pk_mul_f32 v[102:103], v[102:103], v[112:113] op_sel_hi:[1,0]
	v_max_f32_e32 v96, 0, v96
	v_max_f32_e32 v97, 0, v97
	global_store_dwordx4 v[114:115], v[104:107], off
	v_pk_mul_f32 v[100:101], v[100:101], v[112:113] op_sel_hi:[1,0]
	v_pk_mul_f32 v[98:99], v[98:99], v[112:113] op_sel_hi:[1,0]
	v_pk_mul_f32 v[104:105], v[96:97], v[96:97]
	v_max_f32_e32 v96, 0, v102
	v_max_f32_e32 v97, 0, v103
	v_max_f32_e32 v100, 0, v100
	v_max_f32_e32 v101, 0, v101
	v_pk_mul_f32 v[100:101], v[100:101], v[100:101]
	v_pk_mul_f32 v[108:109], v[96:97], v[96:97]
	v_cvt_pk_bf16_f32 v96, v100, v101
	s_waitcnt lgkmcnt(0)
; __device__ __forceinline__ unsigned pk2(float lo, float hi) { const f32x2 v = (f32x2){lo, hi}; const bf16x2_t b = __builtin_convertvector(v, bf16x2_t); return __builtin_bit_cast(unsigned, b); }
;     __device__ __forceinline__ void operator()(const f32x4 (&acc)[2][2][4][2], const Unit& u, int wr, int wc, int fr, int fq, const float (&)[8]) const {
;     ...
;         const int col0 = u.pn * BM + wc * 32 + 8 * fq;
; #pragma unroll
;         for (int ai = 0; ai < 2; ++ai)
; #pragma unroll
;             for (int m = 0; m < 4; ++m) { const int row = row0 + ai * HALF + m * 16; const float rs = rsqrtf(ep[ai * 4 + m] * (1.0f / 1024.0f) + EPS);
;                 u16* rowp = O + (size_t)row * ldc + col0;
; #pragma unroll
;                 for (int bj = 0; bj < 2; ++bj) { f32x4 v0 = acc[ai][bj][m][0] * rs, v1 = acc[ai][bj][m][1] * rs;
;                     if (ACT == 1) {
; #pragma unroll
;                         for (int j = 0; j < 4; ++j) { const float a0 = fmaxf(v0[j], 0.f), a1 = fmaxf(v1[j], 0.f); v0[j] = a0 * a0; v1[j] = a1 * a1; } }
;                     u32x4 w; w.x = pk2(v0[0], v0[1]); w.y = pk2(v0[2], v0[3]); w.z = pk2(v1[0], v1[1]); w.w = pk2(v1[2], v1[3]);
;                     *(u32x4*)(rowp + bj * HALF) = w; } }
	v_max_f32_e32 v98, 0, v98
	v_max_f32_e32 v99, 0, v99
	v_pk_mul_f32 v[110:111], v[98:99], v[98:99]
	v_cvt_pk_bf16_f32 v97, v108, v109
	v_cvt_pk_bf16_f32 v98, v104, v105
	v_cvt_pk_bf16_f32 v99, v110, v111
	global_store_dwordx4 v[114:115], v[96:99], off offset:256
	s_waitcnt lgkmcnt(0)
	s_nop 0
	s_nop 0
	s_nop 0
	s_nop 1
	v_lshlrev_b64 v[98:99], 13, v[168:169]
	v_lshl_add_u64 v[98:99], s[96:97], 0, v[98:99]
	v_lshl_add_u64 v[98:99], v[98:99], 0, v[148:149]
	v_mov_b32_e32 v100, v230
	v_pk_mul_f32 v[88:89], v[88:89], v[100:101] op_sel_hi:[1,0]
	v_pk_mul_f32 v[94:95], v[94:95], v[100:101] op_sel_hi:[1,0]
	v_pk_mul_f32 v[92:93], v[92:93], v[100:101] op_sel_hi:[1,0]
	v_pk_mul_f32 v[90:91], v[90:91], v[100:101] op_sel_hi:[1,0]
	v_max_f32_e32 v88, 0, v88
	v_max_f32_e32 v89, 0, v89
	v_max_f32_e32 v92, 0, v92
	v_max_f32_e32 v93, 0, v93
	v_pk_mul_f32 v[102:103], v[88:89], v[88:89]
	v_max_f32_e32 v88, 0, v94
	v_max_f32_e32 v90, 0, v90
	v_max_f32_e32 v89, 0, v95
	v_max_f32_e32 v91, 0, v91
	v_pk_mul_f32 v[92:93], v[92:93], v[92:93]
	v_pk_mul_f32 v[94:95], v[88:89], v[88:89]
	v_pk_mul_f32 v[104:105], v[90:91], v[90:91]
	v_pk_mul_f32 v[82:83], v[82:83], v[100:101] op_sel_hi:[1,0]
	v_cvt_pk_bf16_f32 v88, v92, v93
	v_cvt_pk_bf16_f32 v89, v94, v95
	v_cvt_pk_bf16_f32 v90, v102, v103
	v_cvt_pk_bf16_f32 v91, v104, v105
	v_pk_mul_f32 v[84:85], v[84:85], v[100:101] op_sel_hi:[1,0]
	v_pk_mul_f32 v[80:81], v[80:81], v[100:101] op_sel_hi:[1,0]
	v_max_f32_e32 v82, 0, v82
	v_max_f32_e32 v83, 0, v83
	global_store_dwordx4 v[98:99], v[88:91], off
	v_pk_mul_f32 v[86:87], v[86:87], v[100:101] op_sel_hi:[1,0]
	v_max_f32_e32 v84, 0, v84
	v_max_f32_e32 v80, 0, v80
	v_max_f32_e32 v85, 0, v85
	v_max_f32_e32 v81, 0, v81
	v_pk_mul_f32 v[90:91], v[82:83], v[82:83]
	v_pk_mul_f32 v[84:85], v[84:85], v[84:85]
	v_pk_mul_f32 v[88:89], v[80:81], v[80:81]
	v_max_f32_e32 v80, 0, v86
	v_max_f32_e32 v81, 0, v87
	v_pk_mul_f32 v[86:87], v[80:81], v[80:81]
	v_cvt_pk_bf16_f32 v80, v84, v85
	v_cvt_pk_bf16_f32 v81, v86, v87
	v_cvt_pk_bf16_f32 v82, v88, v89
	v_cvt_pk_bf16_f32 v83, v90, v91
	global_store_dwordx4 v[98:99], v[80:83], off offset:256
	s_nop 1
	v_mov_b32_e32 v80, v231
	v_pk_mul_f32 v[72:73], v[72:73], v[80:81] op_sel_hi:[1,0]
	v_pk_mul_f32 v[78:79], v[78:79], v[80:81] op_sel_hi:[1,0]
	v_pk_mul_f32 v[76:77], v[76:77], v[80:81] op_sel_hi:[1,0]
	v_pk_mul_f32 v[74:75], v[74:75], v[80:81] op_sel_hi:[1,0]
	v_max_f32_e32 v72, 0, v72
	v_max_f32_e32 v73, 0, v73
	v_lshlrev_b64 v[82:83], 13, v[164:165]
	v_max_f32_e32 v76, 0, v76
	v_max_f32_e32 v77, 0, v77
	v_pk_mul_f32 v[84:85], v[72:73], v[72:73]
	v_max_f32_e32 v72, 0, v78
	v_max_f32_e32 v74, 0, v74
	v_max_f32_e32 v73, 0, v79
	v_max_f32_e32 v75, 0, v75
	v_lshl_add_u64 v[82:83], s[96:97], 0, v[82:83]
	v_pk_mul_f32 v[76:77], v[76:77], v[76:77]
	v_pk_mul_f32 v[78:79], v[72:73], v[72:73]
	v_pk_mul_f32 v[86:87], v[74:75], v[74:75]
	v_pk_mul_f32 v[64:65], v[64:65], v[80:81] op_sel_hi:[1,0]
	v_lshl_add_u64 v[82:83], v[82:83], 0, v[148:149]
	v_cvt_pk_bf16_f32 v72, v76, v77
	v_cvt_pk_bf16_f32 v73, v78, v79
	v_cvt_pk_bf16_f32 v74, v84, v85
	v_cvt_pk_bf16_f32 v75, v86, v87
	v_pk_mul_f32 v[70:71], v[70:71], v[80:81] op_sel_hi:[1,0]
	v_max_f32_e32 v64, 0, v64
	v_max_f32_e32 v65, 0, v65
	global_store_dwordx4 v[82:83], v[72:75], off
	v_pk_mul_f32 v[68:69], v[68:69], v[80:81] op_sel_hi:[1,0]
	v_pk_mul_f32 v[66:67], v[66:67], v[80:81] op_sel_hi:[1,0]
	v_pk_mul_f32 v[72:73], v[64:65], v[64:65]
	v_max_f32_e32 v64, 0, v70
	v_max_f32_e32 v65, 0, v71
	v_max_f32_e32 v68, 0, v68
	v_max_f32_e32 v69, 0, v69
	v_pk_mul_f32 v[68:69], v[68:69], v[68:69]
	v_pk_mul_f32 v[76:77], v[64:65], v[64:65]
	v_cvt_pk_bf16_f32 v64, v68, v69
	s_waitcnt lgkmcnt(0)
	v_max_f32_e32 v66, 0, v66
	v_max_f32_e32 v67, 0, v67
	v_pk_mul_f32 v[78:79], v[66:67], v[66:67]
	v_cvt_pk_bf16_f32 v65, v76, v77
	v_cvt_pk_bf16_f32 v66, v72, v73
	v_cvt_pk_bf16_f32 v67, v78, v79
	global_store_dwordx4 v[82:83], v[64:67], off offset:256
	s_waitcnt lgkmcnt(0)
	s_nop 0
	s_nop 0
	s_nop 0
	s_nop 1
	v_lshlrev_b64 v[66:67], 13, v[162:163]
	v_lshl_add_u64 v[66:67], s[96:97], 0, v[66:67]
	v_lshl_add_u64 v[66:67], v[66:67], 0, v[148:149]
	v_mov_b32_e32 v68, v232
	v_pk_mul_f32 v[56:57], v[56:57], v[68:69] op_sel_hi:[1,0]
	v_pk_mul_f32 v[62:63], v[62:63], v[68:69] op_sel_hi:[1,0]
	v_pk_mul_f32 v[60:61], v[60:61], v[68:69] op_sel_hi:[1,0]
	v_pk_mul_f32 v[58:59], v[58:59], v[68:69] op_sel_hi:[1,0]
	v_max_f32_e32 v56, 0, v56
	v_max_f32_e32 v57, 0, v57
	v_max_f32_e32 v60, 0, v60
	v_max_f32_e32 v61, 0, v61
	v_pk_mul_f32 v[70:71], v[56:57], v[56:57]
	v_max_f32_e32 v56, 0, v62
	v_max_f32_e32 v58, 0, v58
	v_max_f32_e32 v57, 0, v63
	v_max_f32_e32 v59, 0, v59
	v_pk_mul_f32 v[60:61], v[60:61], v[60:61]
	v_pk_mul_f32 v[62:63], v[56:57], v[56:57]
	v_pk_mul_f32 v[72:73], v[58:59], v[58:59]
	v_pk_mul_f32 v[50:51], v[50:51], v[68:69] op_sel_hi:[1,0]
	v_cvt_pk_bf16_f32 v56, v60, v61
	v_cvt_pk_bf16_f32 v57, v62, v63
	v_cvt_pk_bf16_f32 v58, v70, v71
	v_cvt_pk_bf16_f32 v59, v72, v73
	v_pk_mul_f32 v[52:53], v[52:53], v[68:69] op_sel_hi:[1,0]
	v_pk_mul_f32 v[48:49], v[48:49], v[68:69] op_sel_hi:[1,0]
	v_max_f32_e32 v50, 0, v50
	v_max_f32_e32 v51, 0, v51
	global_store_dwordx4 v[66:67], v[56:59], off
	v_pk_mul_f32 v[54:55], v[54:55], v[68:69] op_sel_hi:[1,0]
	v_max_f32_e32 v52, 0, v52
	v_max_f32_e32 v48, 0, v48
	v_max_f32_e32 v53, 0, v53
	v_max_f32_e32 v49, 0, v49
	v_pk_mul_f32 v[58:59], v[50:51], v[50:51]
	v_pk_mul_f32 v[52:53], v[52:53], v[52:53]
	v_pk_mul_f32 v[56:57], v[48:49], v[48:49]
	v_max_f32_e32 v48, 0, v54
	v_max_f32_e32 v49, 0, v55
	v_pk_mul_f32 v[54:55], v[48:49], v[48:49]
	v_cvt_pk_bf16_f32 v48, v52, v53
; __device__ __forceinline__ unsigned pk2(float lo, float hi) { const f32x2 v = (f32x2){lo, hi}; const bf16x2_t b = __builtin_convertvector(v, bf16x2_t); return __builtin_bit_cast(unsigned, b); }
; #define PG8_WAIT_V(n) asm volatile("s_waitcnt vmcnt(" #n ")" ::: "memory")
; #define PG8_BAR __builtin_amdgcn_s_barrier()
;     __device__ __forceinline__ void operator()(const f32x4 (&acc)[2][2][4][2], const Unit& u, int wr, int wc, int fr, int fq, const float (&)[8]) const {
;     ...
;             for (int m = 0; m < 4; ++m) { const int row = row0 + ai * HALF + m * 16; const float rs = rsqrtf(ep[ai * 4 + m] * (1.0f / 1024.0f) + EPS);
;                 u16* rowp = O + (size_t)row * ldc + col0;
; #pragma unroll
;                 for (int bj = 0; bj < 2; ++bj) { f32x4 v0 = acc[ai][bj][m][0] * rs, v1 = acc[ai][bj][m][1] * rs;
;                     if (ACT == 1) {
; #pragma unroll
;                         for (int j = 0; j < 4; ++j) { const float a0 = fmaxf(v0[j], 0.f), a1 = fmaxf(v1[j], 0.f); v0[j] = a0 * a0; v1[j] = a1 * a1; } }
;                     u32x4 w; w.x = pk2(v0[0], v0[1]); w.y = pk2(v0[2], v0[3]); w.z = pk2(v1[0], v1[1]); w.w = pk2(v1[2], v1[3]);
;                     *(u32x4*)(rowp + bj * HALF) = w; } }
; template <class Epi>
; __device__ __forceinline__ void gemm_phase(LAS unsigned char* lds, const Gemm g, const StaticOrder& S, const Epi& E) {
;     ...
;         E(acc, cur, wr, wc, fr, fq, epre);
;         if (!has_next) break;
; #pragma unroll
;         for (int a = 0; a < 2; ++a)
; #pragma unroll
;             for (int b = 0; b < 2; ++b)
; #pragma unroll
;                 for (int m = 0; m < 4; ++m)
; #pragma unroll
;                     for (int n = 0; n < 2; ++n) acc[a][b][m][n] = (f32x4){0.f, 0.f, 0.f, 0.f};
;         cur = nxt; cA = nA; cB = nB; ++ui;
;     }
;     PG8_WAIT_V(0);
;     if (wr == 0) PG8_BAR;
;     PG8_BAR;
	v_cvt_pk_bf16_f32 v49, v54, v55
	v_cvt_pk_bf16_f32 v50, v56, v57
	v_cvt_pk_bf16_f32 v51, v58, v59
	global_store_dwordx4 v[66:67], v[48:51], off offset:256
	s_nop 1
	v_mov_b32_e32 v48, v233
	v_pk_mul_f32 v[40:41], v[40:41], v[48:49] op_sel_hi:[1,0]
	v_pk_mul_f32 v[46:47], v[46:47], v[48:49] op_sel_hi:[1,0]
	v_pk_mul_f32 v[44:45], v[44:45], v[48:49] op_sel_hi:[1,0]
	v_pk_mul_f32 v[42:43], v[42:43], v[48:49] op_sel_hi:[1,0]
	v_max_f32_e32 v40, 0, v40
	v_max_f32_e32 v41, 0, v41
	v_lshlrev_b64 v[50:51], 13, v[156:157]
	v_max_f32_e32 v44, 0, v44
	v_max_f32_e32 v45, 0, v45
	v_pk_mul_f32 v[52:53], v[40:41], v[40:41]
	v_max_f32_e32 v40, 0, v46
	v_max_f32_e32 v42, 0, v42
	v_max_f32_e32 v41, 0, v47
	v_max_f32_e32 v43, 0, v43
	v_lshl_add_u64 v[50:51], s[96:97], 0, v[50:51]
	v_pk_mul_f32 v[44:45], v[44:45], v[44:45]
	v_pk_mul_f32 v[46:47], v[40:41], v[40:41]
	v_pk_mul_f32 v[54:55], v[42:43], v[42:43]
	v_pk_mul_f32 v[32:33], v[32:33], v[48:49] op_sel_hi:[1,0]
	v_lshl_add_u64 v[50:51], v[50:51], 0, v[148:149]
	v_cvt_pk_bf16_f32 v40, v44, v45
	v_cvt_pk_bf16_f32 v41, v46, v47
	v_cvt_pk_bf16_f32 v42, v52, v53
	v_cvt_pk_bf16_f32 v43, v54, v55
	v_pk_mul_f32 v[38:39], v[38:39], v[48:49] op_sel_hi:[1,0]
	v_max_f32_e32 v32, 0, v32
	v_max_f32_e32 v33, 0, v33
	global_store_dwordx4 v[50:51], v[40:43], off
	v_pk_mul_f32 v[36:37], v[36:37], v[48:49] op_sel_hi:[1,0]
	v_pk_mul_f32 v[34:35], v[34:35], v[48:49] op_sel_hi:[1,0]
	v_pk_mul_f32 v[40:41], v[32:33], v[32:33]
	v_max_f32_e32 v32, 0, v38
	v_max_f32_e32 v33, 0, v39
	v_max_f32_e32 v36, 0, v36
	v_max_f32_e32 v37, 0, v37
	v_pk_mul_f32 v[36:37], v[36:37], v[36:37]
	v_pk_mul_f32 v[44:45], v[32:33], v[32:33]
	v_cvt_pk_bf16_f32 v32, v36, v37
	s_waitcnt lgkmcnt(0)
	v_max_f32_e32 v34, 0, v34
	v_max_f32_e32 v35, 0, v35
	v_pk_mul_f32 v[46:47], v[34:35], v[34:35]
	v_cvt_pk_bf16_f32 v33, v44, v45
	v_cvt_pk_bf16_f32 v34, v40, v41
	v_cvt_pk_bf16_f32 v35, v46, v47
	global_store_dwordx4 v[50:51], v[32:35], off offset:256
	s_waitcnt lgkmcnt(0)
	s_nop 0
	s_nop 0
	s_nop 0
	s_nop 1
	v_lshlrev_b64 v[34:35], 13, v[150:151]
	v_lshl_add_u64 v[34:35], s[96:97], 0, v[34:35]
	v_lshl_add_u64 v[34:35], v[34:35], 0, v[148:149]
	v_mov_b32_e32 v36, v234
	v_pk_mul_f32 v[24:25], v[24:25], v[36:37] op_sel_hi:[1,0]
	v_pk_mul_f32 v[30:31], v[30:31], v[36:37] op_sel_hi:[1,0]
	v_pk_mul_f32 v[28:29], v[28:29], v[36:37] op_sel_hi:[1,0]
	v_pk_mul_f32 v[26:27], v[26:27], v[36:37] op_sel_hi:[1,0]
	v_max_f32_e32 v24, 0, v24
	v_max_f32_e32 v25, 0, v25
	v_max_f32_e32 v28, 0, v28
	v_max_f32_e32 v29, 0, v29
	v_pk_mul_f32 v[38:39], v[24:25], v[24:25]
	v_max_f32_e32 v24, 0, v30
	v_max_f32_e32 v26, 0, v26
	v_max_f32_e32 v25, 0, v31
	v_max_f32_e32 v27, 0, v27
	v_pk_mul_f32 v[28:29], v[28:29], v[28:29]
	v_pk_mul_f32 v[30:31], v[24:25], v[24:25]
	v_pk_mul_f32 v[40:41], v[26:27], v[26:27]
	v_pk_mul_f32 v[18:19], v[18:19], v[36:37] op_sel_hi:[1,0]
	v_cvt_pk_bf16_f32 v24, v28, v29
	v_cvt_pk_bf16_f32 v25, v30, v31
	v_cvt_pk_bf16_f32 v26, v38, v39
	v_cvt_pk_bf16_f32 v27, v40, v41
	v_pk_mul_f32 v[20:21], v[20:21], v[36:37] op_sel_hi:[1,0]
	v_pk_mul_f32 v[16:17], v[16:17], v[36:37] op_sel_hi:[1,0]
	v_max_f32_e32 v18, 0, v18
	v_max_f32_e32 v19, 0, v19
	global_store_dwordx4 v[34:35], v[24:27], off
	v_pk_mul_f32 v[22:23], v[22:23], v[36:37] op_sel_hi:[1,0]
	v_max_f32_e32 v20, 0, v20
	v_max_f32_e32 v16, 0, v16
	v_max_f32_e32 v21, 0, v21
	v_max_f32_e32 v17, 0, v17
	v_pk_mul_f32 v[26:27], v[18:19], v[18:19]
	v_pk_mul_f32 v[20:21], v[20:21], v[20:21]
	v_pk_mul_f32 v[24:25], v[16:17], v[16:17]
	v_max_f32_e32 v16, 0, v22
	v_max_f32_e32 v17, 0, v23
	v_pk_mul_f32 v[22:23], v[16:17], v[16:17]
	v_cvt_pk_bf16_f32 v16, v20, v21
	v_cvt_pk_bf16_f32 v17, v22, v23
	v_cvt_pk_bf16_f32 v18, v24, v25
	v_cvt_pk_bf16_f32 v19, v26, v27
	global_store_dwordx4 v[34:35], v[16:19], off offset:256
	s_nop 1
	v_mov_b32_e32 v16, v235
	v_pk_mul_f32 v[8:9], v[8:9], v[16:17] op_sel_hi:[1,0]
	v_pk_mul_f32 v[14:15], v[14:15], v[16:17] op_sel_hi:[1,0]
	v_pk_mul_f32 v[12:13], v[12:13], v[16:17] op_sel_hi:[1,0]
	v_pk_mul_f32 v[10:11], v[10:11], v[16:17] op_sel_hi:[1,0]
	v_max_f32_e32 v8, 0, v8
	v_max_f32_e32 v9, 0, v9
	v_lshlrev_b64 v[18:19], 13, v[146:147]
	v_max_f32_e32 v12, 0, v12
	v_max_f32_e32 v13, 0, v13
	v_pk_mul_f32 v[20:21], v[8:9], v[8:9]
	v_max_f32_e32 v8, 0, v14
	v_max_f32_e32 v10, 0, v10
	v_max_f32_e32 v9, 0, v15
	v_max_f32_e32 v11, 0, v11
	v_lshl_add_u64 v[18:19], s[96:97], 0, v[18:19]
	v_pk_mul_f32 v[12:13], v[12:13], v[12:13]
	v_pk_mul_f32 v[14:15], v[8:9], v[8:9]
	v_pk_mul_f32 v[22:23], v[10:11], v[10:11]
	v_pk_mul_f32 v[0:1], v[0:1], v[16:17] op_sel_hi:[1,0]
	v_lshl_add_u64 v[18:19], v[18:19], 0, v[148:149]
	v_cvt_pk_bf16_f32 v8, v12, v13
	v_cvt_pk_bf16_f32 v9, v14, v15
	v_cvt_pk_bf16_f32 v10, v20, v21
	v_cvt_pk_bf16_f32 v11, v22, v23
	v_pk_mul_f32 v[6:7], v[6:7], v[16:17] op_sel_hi:[1,0]
	v_pk_mul_f32 v[4:5], v[4:5], v[16:17] op_sel_hi:[1,0]
	v_pk_mul_f32 v[2:3], v[2:3], v[16:17] op_sel_hi:[1,0]
	v_max_f32_e32 v0, 0, v0
	v_max_f32_e32 v1, 0, v1
	global_store_dwordx4 v[18:19], v[8:11], off
	v_max_f32_e32 v4, 0, v4
	v_max_f32_e32 v5, 0, v5
	v_pk_mul_f32 v[8:9], v[0:1], v[0:1]
	v_max_f32_e32 v0, 0, v6
	v_max_f32_e32 v2, 0, v2
	v_max_f32_e32 v1, 0, v7
	v_max_f32_e32 v3, 0, v3
	v_pk_mul_f32 v[4:5], v[4:5], v[4:5]
	v_pk_mul_f32 v[6:7], v[0:1], v[0:1]
	v_pk_mul_f32 v[10:11], v[2:3], v[2:3]
	v_cvt_pk_bf16_f32 v0, v4, v5
	v_cvt_pk_bf16_f32 v1, v6, v7
	v_cvt_pk_bf16_f32 v2, v8, v9
	v_cvt_pk_bf16_f32 v3, v10, v11
	s_and_b64 vcc, exec, s[0:1]
	global_store_dwordx4 v[18:19], v[0:3], off offset:256
	s_cbranch_vccz .LBB0_1197
	s_waitcnt vmcnt(0)
	s_cmpk_gt_u32 s7, 0xff
	s_cbranch_scc1 .LBB0_1208
	s_barrier

; #define PG8_STAGE(bufoff, gbase, voff) do { _Pragma("unroll") for (int _i = 0; _i < 2; ++_i) \
;         __builtin_amdgcn_global_load_lds((const unsigned*)((const char*)(gbase) + (voff)[_i]), (LAS unsigned*)(lds + (bufoff) + ldsw + _i * 8192), 16, 0, 0); } while (0)
; #define PG8_LDA(dst, b, h) do { _Pragma("unroll") for (int m = 0; m < 4; ++m) _Pragma("unroll") for (int k = 0; k < 2; ++k) dst[m][k] = *(const LAS bf16x8*)(lds + PG8_SA(b, h) + aoff + m * 2048 + k * 1024); } while (0)
; #define PG8_LDB(dst, b, h) do { _Pragma("unroll") for (int n = 0; n < 2; ++n) _Pragma("unroll") for (int k = 0; k < 2; ++k) dst[n][k] = *(const LAS bf16x8*)(lds + PG8_SB(b, h) + boff + n * 2048 + k * 1024); } while (0)
; #define PG8_WAIT_V(n) asm volatile("s_waitcnt vmcnt(" #n ")" ::: "memory")
; #define PG8_WAIT_L(n) asm volatile("s_waitcnt lgkmcnt(" #n ")" ::: "memory")
; #define PG8_BAR __builtin_amdgcn_s_barrier()
; #define PG8_SCHED __builtin_amdgcn_sched_barrier(0)
; template <class Epi>
; __device__ __forceinline__ void gemm_phase(LAS unsigned char* lds, const Gemm g, const StaticOrder& S, const Epi& E) {
;     ...
;         const bool has_next = S.next(ui + 1, nxt);
;         const char* nA = has_next ? (const char*)g.A + (size_t)nxt.pm * tstepA : cA; const char* nB = has_next ? (const char*)g.Bt + (size_t)nxt.pn * tstepB : cB;
;         for (int t = 0; t < nt; t += 2) {
;             const bool last = (t == nt - 2);
;             const char* a1 = cA + (size_t)(t + 1) * kstep;
;             const char* a2 = last ? nA : cA + (size_t)(t + 2) * kstep; const char* b2 = last ? nB : cB + (size_t)(t + 2) * kstep;
;             const char* a3 = a2 + kstep; const char* b3 = b2 + kstep;
;             if (last) E.pre(cur, wr, fr, epre);
;             PG8_LDB(B0, 0, 0); PG8_SCHED; PG8_LDA(At, 0, 0); PG8_STAGE(PG8_SA(1, 1), a1 + hstepA, voffA);
;             PG8_WAIT_L(8); PG8_BAR; PG8_WAIT_L(0); PG8_MMA(0, 0, At, B0); PG8_BAR; PG8_SCHED;
;             PG8_LDB(B1, 0, 1); PG8_STAGE(PG8_SB(0, 0), b2, voffB);
;             PG8_BAR; PG8_WAIT_L(0); PG8_MMA(0, 1, At, B1); PG8_BAR;
;             PG8_LDA(At, 0, 1); PG8_STAGE(PG8_SA(0, 0), a2, voffA);
;             PG8_BAR; PG8_WAIT_L(0); PG8_MMA(1, 0, At, B0); PG8_BAR; PG8_SCHED;
;             PG8_STAGE(PG8_SB(0, 1), b2 + hstepB, voffB);
;             PG8_WAIT_V(6); PG8_BAR; PG8_MMA(1, 1, At, B1); PG8_BAR;
.LBB0_1277:
	s_ashr_i32 s17, s16, 31
	v_cmp_lt_i64_e32 vcc, s[18:19], v[166:167]
	s_lshl_b64 s[18:19], s[16:17], 21
	s_add_u32 s18, s96, s18
	s_addc_u32 s19, s97, s19
	s_and_b64 s[20:21], vcc, exec
	s_cselect_b32 s17, s19, s23
	s_cselect_b32 s44, s18, s22
	s_ashr_i32 s15, s14, 31
	s_lshl_b64 s[20:21], s[14:15], 21
	s_add_u32 s20, s29, s20
	s_addc_u32 s21, s30, s21
	s_and_b64 s[26:27], vcc, exec
	s_cselect_b32 s15, s21, s25
	s_cselect_b32 s45, s20, s24
	s_add_u32 s22, s22, 0x100080
	s_addc_u32 s23, s23, 0
	s_add_u32 s46, s24, 0x100
	s_addc_u32 s47, s25, 0
	s_mov_b32 s48, -2
	s_waitcnt lgkmcnt(0)
	ds_read_b128 v[128:131], v190
	ds_read_b128 v[132:135], v190 offset:1024
	ds_read_b128 v[136:139], v190 offset:2048
	ds_read_b128 v[140:143], v190 offset:3072
	s_add_u32 s24, s22, 0xfff00080
	s_addc_u32 s25, s23, -1
	s_cmp_eq_u32 s48, 60
	s_cselect_b32 s27, s17, s25
	s_cselect_b32 s26, s44, s24
	s_cselect_b32 s25, s15, s47
	s_cselect_b32 s24, s45, s46
	v_lshl_add_u64 v[186:187], s[22:23], 0, v[162:163]
	s_add_i32 m0, s7, 0xc000
	ds_read_b128 v[144:147], v191
	ds_read_b128 v[148:151], v191 offset:1024
	ds_read_b128 v[170:173], v191 offset:2048
	ds_read_b128 v[174:177], v191 offset:3072
	ds_read_b128 v[178:181], v191 offset:4096
	ds_read_b128 v[182:185], v191 offset:5120
	ds_read_b128 v[194:197], v191 offset:6144
	ds_read_b128 v[198:201], v191 offset:7168
	global_load_lds_dwordx4 v[186:187], off
	v_lshl_add_u64 v[186:187], s[22:23], 0, v[164:165]
	s_add_i32 m0, s7, 0xe000
	s_nop 0
	global_load_lds_dwordx4 v[186:187], off
	s_waitcnt lgkmcnt(8)
	s_barrier
	s_waitcnt lgkmcnt(7)
	v_mfma_f32_16x16x32_bf16 v[124:127], v[128:131], v[144:147], 0
	v_mfma_f32_16x16x32_bf16 v[120:123], v[136:139], v[144:147], 0
	s_waitcnt lgkmcnt(5)
	v_mfma_f32_16x16x32_bf16 v[108:111], v[128:131], v[170:173], 0
	v_mfma_f32_16x16x32_bf16 v[104:107], v[136:139], v[170:173], 0
	s_waitcnt lgkmcnt(3)
	v_mfma_f32_16x16x32_bf16 v[92:95], v[128:131], v[178:181], 0
	v_mfma_f32_16x16x32_bf16 v[88:91], v[136:139], v[178:181], 0
	s_waitcnt lgkmcnt(1)
	v_mfma_f32_16x16x32_bf16 v[76:79], v[128:131], v[194:197], 0
	v_mfma_f32_16x16x32_bf16 v[72:75], v[136:139], v[194:197], 0
	v_mfma_f32_16x16x32_bf16 v[124:127], v[132:135], v[148:151], v[124:127]
	v_mfma_f32_16x16x32_bf16 v[120:123], v[140:143], v[148:151], v[120:123]
	v_mfma_f32_16x16x32_bf16 v[108:111], v[132:135], v[174:177], v[108:111]
	v_mfma_f32_16x16x32_bf16 v[104:107], v[140:143], v[174:177], v[104:107]
	v_mfma_f32_16x16x32_bf16 v[92:95], v[132:135], v[182:185], v[92:95]
	v_mfma_f32_16x16x32_bf16 v[88:91], v[140:143], v[182:185], v[88:91]
	s_waitcnt lgkmcnt(0)
	v_mfma_f32_16x16x32_bf16 v[76:79], v[132:135], v[198:201], v[76:79]
	v_mfma_f32_16x16x32_bf16 v[72:75], v[140:143], v[198:201], v[72:75]
	s_barrier
	s_add_i32 s49, s42, s31
	v_lshl_add_u64 v[186:187], s[24:25], 0, v[156:157]
	s_mov_b32 m0, s49
	ds_read_b128 v[202:205], v192
	ds_read_b128 v[206:209], v192 offset:1024
	ds_read_b128 v[210:213], v192 offset:2048
	ds_read_b128 v[214:217], v192 offset:3072
	global_load_lds_dwordx4 v[186:187], off
	v_lshl_add_u64 v[218:219], s[24:25], 0, v[160:161]
	s_add_i32 m0, s49, 0x2000
	s_nop 0
	global_load_lds_dwordx4 v[218:219], off
	s_barrier
	s_waitcnt lgkmcnt(3)
	v_mfma_f32_16x16x32_bf16 v[116:119], v[202:205], v[144:147], 0
	s_waitcnt lgkmcnt(1)
	v_mfma_f32_16x16x32_bf16 v[112:115], v[210:213], v[144:147], 0
	v_mfma_f32_16x16x32_bf16 v[100:103], v[202:205], v[170:173], 0
	v_mfma_f32_16x16x32_bf16 v[96:99], v[210:213], v[170:173], 0
	v_mfma_f32_16x16x32_bf16 v[84:87], v[202:205], v[178:181], 0
	v_mfma_f32_16x16x32_bf16 v[80:83], v[210:213], v[178:181], 0
	v_mfma_f32_16x16x32_bf16 v[68:71], v[202:205], v[194:197], 0
	v_mfma_f32_16x16x32_bf16 v[64:67], v[210:213], v[194:197], 0
	v_mfma_f32_16x16x32_bf16 v[116:119], v[206:209], v[148:151], v[116:119]
	s_waitcnt lgkmcnt(0)
	v_mfma_f32_16x16x32_bf16 v[112:115], v[214:217], v[148:151], v[112:115]
	v_mfma_f32_16x16x32_bf16 v[100:103], v[206:209], v[174:177], v[100:103]
	v_mfma_f32_16x16x32_bf16 v[96:99], v[214:217], v[174:177], v[96:99]
	v_mfma_f32_16x16x32_bf16 v[84:87], v[206:209], v[182:185], v[84:87]
	v_mfma_f32_16x16x32_bf16 v[80:83], v[214:217], v[182:185], v[80:83]
	v_mfma_f32_16x16x32_bf16 v[68:71], v[206:209], v[198:201], v[68:71]
	v_mfma_f32_16x16x32_bf16 v[64:67], v[214:217], v[198:201], v[64:67]
	s_mov_b32 m0, s7
	v_lshl_add_u64 v[220:221], s[26:27], 0, v[154:155]
	s_barrier
	ds_read_b128 v[144:147], v191 offset:16384
	ds_read_b128 v[148:151], v191 offset:17408
	ds_read_b128 v[170:173], v191 offset:18432
	ds_read_b128 v[174:177], v191 offset:19456
	ds_read_b128 v[178:181], v191 offset:20480
	ds_read_b128 v[182:185], v191 offset:21504
	ds_read_b128 v[194:197], v191 offset:22528
	ds_read_b128 v[198:201], v191 offset:23552
	global_load_lds_dwordx4 v[220:221], off
	v_lshl_add_u64 v[222:223], s[26:27], 0, v[158:159]
	s_mov_b32 m0, s34
	s_nop 0
	global_load_lds_dwordx4 v[222:223], off
	s_barrier
	s_waitcnt lgkmcnt(7)
	v_mfma_f32_16x16x32_bf16 v[60:63], v[128:131], v[144:147], 0
	v_mfma_f32_16x16x32_bf16 v[56:59], v[136:139], v[144:147], 0
	s_waitcnt lgkmcnt(5)
	v_mfma_f32_16x16x32_bf16 v[44:47], v[128:131], v[170:173], 0
	v_mfma_f32_16x16x32_bf16 v[40:43], v[136:139], v[170:173], 0
	s_waitcnt lgkmcnt(3)
	v_mfma_f32_16x16x32_bf16 v[28:31], v[128:131], v[178:181], 0
	v_mfma_f32_16x16x32_bf16 v[24:27], v[136:139], v[178:181], 0
	s_waitcnt lgkmcnt(1)
	v_mfma_f32_16x16x32_bf16 v[12:15], v[128:131], v[194:197], 0
	v_mfma_f32_16x16x32_bf16 v[8:11], v[136:139], v[194:197], 0
	v_mfma_f32_16x16x32_bf16 v[60:63], v[132:135], v[148:151], v[60:63]
	v_mfma_f32_16x16x32_bf16 v[56:59], v[140:143], v[148:151], v[56:59]
	v_mfma_f32_16x16x32_bf16 v[44:47], v[132:135], v[174:177], v[44:47]
	v_mfma_f32_16x16x32_bf16 v[40:43], v[140:143], v[174:177], v[40:43]
	v_mfma_f32_16x16x32_bf16 v[28:31], v[132:135], v[182:185], v[28:31]
	v_mfma_f32_16x16x32_bf16 v[24:27], v[140:143], v[182:185], v[24:27]
	s_waitcnt lgkmcnt(0)
	v_mfma_f32_16x16x32_bf16 v[12:15], v[132:135], v[198:201], v[12:15]
	v_mfma_f32_16x16x32_bf16 v[8:11], v[140:143], v[198:201], v[8:11]
	s_barrier
; #define PG8_STAGE(bufoff, gbase, voff) do { _Pragma("unroll") for (int _i = 0; _i < 2; ++_i) \
;         __builtin_amdgcn_global_load_lds((const unsigned*)((const char*)(gbase) + (voff)[_i]), (LAS unsigned*)(lds + (bufoff) + ldsw + _i * 8192), 16, 0, 0); } while (0)
; #define PG8_LDA(dst, b, h) do { _Pragma("unroll") for (int m = 0; m < 4; ++m) _Pragma("unroll") for (int k = 0; k < 2; ++k) dst[m][k] = *(const LAS bf16x8*)(lds + PG8_SA(b, h) + aoff + m * 2048 + k * 1024); } while (0)
; #define PG8_LDB(dst, b, h) do { _Pragma("unroll") for (int n = 0; n < 2; ++n) _Pragma("unroll") for (int k = 0; k < 2; ++k) dst[n][k] = *(const LAS bf16x8*)(lds + PG8_SB(b, h) + boff + n * 2048 + k * 1024); } while (0)
; #define PG8_MMA(ai, bj, At, Bt) do { __builtin_amdgcn_s_setprio(1); _Pragma("unroll") for (int m = 0; m < 4; ++m) _Pragma("unroll") for (int n = 0; n < 2; ++n) _Pragma("unroll") for (int k = 0; k < 2; ++k) \
;         acc[ai][bj][m][n] = __builtin_amdgcn_mfma_f32_16x16x32_bf16(Bt[n][k], At[m][k], acc[ai][bj][m][n], 0, 0, 0); __builtin_amdgcn_s_setprio(0); } while (0)
; #define PG8_WAIT_V(n) asm volatile("s_waitcnt vmcnt(" #n ")" ::: "memory")
; #define PG8_WAIT_L(n) asm volatile("s_waitcnt lgkmcnt(" #n ")" ::: "memory")
; #define PG8_BAR __builtin_amdgcn_s_barrier()
; #define PG8_SCHED __builtin_amdgcn_sched_barrier(0)
; template <class Epi>
; __device__ __forceinline__ void gemm_phase(LAS unsigned char* lds, const Gemm g, const StaticOrder& S, const Epi& E) {
;     ...
;             PG8_WAIT_V(6); PG8_BAR; PG8_MMA(1, 1, At, B1); PG8_BAR;
;             PG8_LDB(B0, 1, 0); PG8_SCHED; PG8_LDA(At, 1, 0); PG8_STAGE(PG8_SA(0, 1), a2 + hstepA, voffA);
;             PG8_WAIT_L(8); PG8_BAR; PG8_WAIT_L(0); PG8_MMA(0, 0, At, B0); PG8_BAR; PG8_SCHED;
;             PG8_LDB(B1, 1, 1); PG8_STAGE(PG8_SB(1, 0), b3, voffB);
;             PG8_BAR; PG8_WAIT_L(0); PG8_MMA(0, 1, At, B1); PG8_BAR;
;             PG8_LDA(At, 1, 1); PG8_STAGE(PG8_SA(1, 0), a3, voffA);
;             PG8_BAR; PG8_WAIT_L(0); PG8_MMA(1, 0, At, B0); PG8_BAR; PG8_SCHED;
;             PG8_STAGE(PG8_SB(1, 1), b3 + hstepB, voffB);
;             PG8_WAIT_V(6); PG8_BAR; PG8_MMA(1, 1, At, B1); PG8_BAR;
	s_add_u32 s50, s24, 0x100000
	s_addc_u32 s51, s25, 0
	s_add_i32 s49, s43, s31
	v_lshl_add_u64 v[128:129], s[50:51], 0, v[156:157]
	s_mov_b32 m0, s49
	s_nop 0
	global_load_lds_dwordx4 v[128:129], off
	v_lshl_add_u64 v[128:129], s[50:51], 0, v[160:161]
	s_add_i32 m0, s49, 0x2000
	s_nop 0
	global_load_lds_dwordx4 v[128:129], off
	s_waitcnt vmcnt(6)
	s_barrier
	v_mfma_f32_16x16x32_bf16 v[52:55], v[202:205], v[144:147], 0
	v_mfma_f32_16x16x32_bf16 v[48:51], v[210:213], v[144:147], 0
	v_mfma_f32_16x16x32_bf16 v[36:39], v[202:205], v[170:173], 0
	v_mfma_f32_16x16x32_bf16 v[32:35], v[210:213], v[170:173], 0
	v_mfma_f32_16x16x32_bf16 v[20:23], v[202:205], v[178:181], 0
	v_mfma_f32_16x16x32_bf16 v[16:19], v[210:213], v[178:181], 0
	v_mfma_f32_16x16x32_bf16 v[4:7], v[202:205], v[194:197], 0
	v_mfma_f32_16x16x32_bf16 v[0:3], v[210:213], v[194:197], 0
	v_mfma_f32_16x16x32_bf16 v[52:55], v[206:209], v[148:151], v[52:55]
	v_mfma_f32_16x16x32_bf16 v[48:51], v[214:217], v[148:151], v[48:51]
	v_mfma_f32_16x16x32_bf16 v[36:39], v[206:209], v[174:177], v[36:39]
	v_mfma_f32_16x16x32_bf16 v[32:35], v[214:217], v[174:177], v[32:35]
	v_mfma_f32_16x16x32_bf16 v[20:23], v[206:209], v[182:185], v[20:23]
	v_mfma_f32_16x16x32_bf16 v[16:19], v[214:217], v[182:185], v[16:19]
	v_mfma_f32_16x16x32_bf16 v[4:7], v[206:209], v[198:201], v[4:7]
	v_mfma_f32_16x16x32_bf16 v[0:3], v[214:217], v[198:201], v[0:3]
	s_add_i32 s49, 0, 0x18000
	v_add_u32_e32 v140, s49, v188
	s_barrier
	ds_read_b128 v[128:131], v140
	ds_read_b128 v[132:135], v140 offset:1024
	ds_read_b128 v[136:139], v140 offset:2048
	ds_read_b128 v[140:143], v140 offset:3072
	s_add_u32 s26, s26, 0x100000
	s_addc_u32 s27, s27, 0
	s_mov_b32 m0, s35
	v_lshl_add_u64 v[202:203], s[26:27], 0, v[154:155]
	ds_read_b128 v[144:147], v191 offset:32768
	ds_read_b128 v[148:151], v191 offset:33792
	ds_read_b128 v[170:173], v191 offset:34816
	ds_read_b128 v[174:177], v191 offset:35840
	ds_read_b128 v[178:181], v191 offset:36864
	ds_read_b128 v[182:185], v191 offset:37888
	ds_read_b128 v[194:197], v191 offset:38912
	ds_read_b128 v[198:201], v191 offset:39936
	global_load_lds_dwordx4 v[202:203], off
	v_lshl_add_u64 v[202:203], s[26:27], 0, v[158:159]
	s_mov_b32 m0, s36
	s_nop 0
	global_load_lds_dwordx4 v[202:203], off
	s_waitcnt lgkmcnt(8)
	s_barrier
	s_waitcnt lgkmcnt(7)
	v_mfma_f32_16x16x32_bf16 v[124:127], v[128:131], v[144:147], v[124:127]
	v_mfma_f32_16x16x32_bf16 v[120:123], v[136:139], v[144:147], v[120:123]
	s_waitcnt lgkmcnt(5)
	v_mfma_f32_16x16x32_bf16 v[108:111], v[128:131], v[170:173], v[108:111]
	v_mfma_f32_16x16x32_bf16 v[104:107], v[136:139], v[170:173], v[104:107]
	s_waitcnt lgkmcnt(3)
	v_mfma_f32_16x16x32_bf16 v[92:95], v[128:131], v[178:181], v[92:95]
	v_mfma_f32_16x16x32_bf16 v[88:91], v[136:139], v[178:181], v[88:91]
	s_waitcnt lgkmcnt(1)
	v_mfma_f32_16x16x32_bf16 v[76:79], v[128:131], v[194:197], v[76:79]
	v_mfma_f32_16x16x32_bf16 v[72:75], v[136:139], v[194:197], v[72:75]
	v_mfma_f32_16x16x32_bf16 v[124:127], v[132:135], v[148:151], v[124:127]
	v_mfma_f32_16x16x32_bf16 v[120:123], v[140:143], v[148:151], v[120:123]
	v_mfma_f32_16x16x32_bf16 v[108:111], v[132:135], v[174:177], v[108:111]
	v_mfma_f32_16x16x32_bf16 v[104:107], v[140:143], v[174:177], v[104:107]
	v_mfma_f32_16x16x32_bf16 v[92:95], v[132:135], v[182:185], v[92:95]
	v_mfma_f32_16x16x32_bf16 v[88:91], v[140:143], v[182:185], v[88:91]
	s_waitcnt lgkmcnt(0)
	v_mfma_f32_16x16x32_bf16 v[76:79], v[132:135], v[198:201], v[76:79]
	v_mfma_f32_16x16x32_bf16 v[72:75], v[140:143], v[198:201], v[72:75]
	s_barrier
	s_add_i32 s26, 0, 0x1c000
	s_add_i32 s27, s49, s31
	v_add_u32_e32 v214, s26, v188
	v_lshl_add_u64 v[186:187], v[186:187], 0, s[12:13]
	s_mov_b32 m0, s27
	ds_read_b128 v[202:205], v214
	ds_read_b128 v[206:209], v214 offset:1024
	ds_read_b128 v[210:213], v214 offset:2048
	ds_read_b128 v[214:217], v214 offset:3072
	global_load_lds_dwordx4 v[186:187], off
	v_lshl_add_u64 v[186:187], v[218:219], 0, s[12:13]
	s_add_i32 m0, s27, 0x2000
	s_nop 0
	global_load_lds_dwordx4 v[186:187], off
	s_barrier
	s_waitcnt lgkmcnt(3)
	v_mfma_f32_16x16x32_bf16 v[116:119], v[202:205], v[144:147], v[116:119]
	s_waitcnt lgkmcnt(1)
	v_mfma_f32_16x16x32_bf16 v[112:115], v[210:213], v[144:147], v[112:115]
	v_mfma_f32_16x16x32_bf16 v[100:103], v[202:205], v[170:173], v[100:103]
	v_mfma_f32_16x16x32_bf16 v[96:99], v[210:213], v[170:173], v[96:99]
	v_mfma_f32_16x16x32_bf16 v[84:87], v[202:205], v[178:181], v[84:87]
	v_mfma_f32_16x16x32_bf16 v[80:83], v[210:213], v[178:181], v[80:83]
	v_mfma_f32_16x16x32_bf16 v[68:71], v[202:205], v[194:197], v[68:71]
	v_mfma_f32_16x16x32_bf16 v[64:67], v[210:213], v[194:197], v[64:67]
	v_mfma_f32_16x16x32_bf16 v[116:119], v[206:209], v[148:151], v[116:119]
	s_waitcnt lgkmcnt(0)
	v_mfma_f32_16x16x32_bf16 v[112:115], v[214:217], v[148:151], v[112:115]
	v_mfma_f32_16x16x32_bf16 v[100:103], v[206:209], v[174:177], v[100:103]
	v_mfma_f32_16x16x32_bf16 v[96:99], v[214:217], v[174:177], v[96:99]
	v_mfma_f32_16x16x32_bf16 v[84:87], v[206:209], v[182:185], v[84:87]
	v_mfma_f32_16x16x32_bf16 v[80:83], v[214:217], v[182:185], v[80:83]
	v_mfma_f32_16x16x32_bf16 v[68:71], v[206:209], v[198:201], v[68:71]
	v_mfma_f32_16x16x32_bf16 v[64:67], v[214:217], v[198:201], v[64:67]
	s_mov_b32 m0, s38
	v_lshl_add_u64 v[186:187], v[220:221], 0, s[12:13]
	s_barrier
	ds_read_b128 v[144:147], v191 offset:49152
	ds_read_b128 v[148:151], v191 offset:50176
	ds_read_b128 v[170:173], v191 offset:51200
	ds_read_b128 v[174:177], v191 offset:52224
	ds_read_b128 v[178:181], v191 offset:53248
	ds_read_b128 v[182:185], v191 offset:54272
	ds_read_b128 v[194:197], v191 offset:55296
	ds_read_b128 v[198:201], v191 offset:56320
	global_load_lds_dwordx4 v[186:187], off
	v_lshl_add_u64 v[186:187], v[222:223], 0, s[12:13]
	s_mov_b32 m0, s39
	s_nop 0
	global_load_lds_dwordx4 v[186:187], off
	s_barrier
; #define PG8_STAGE(bufoff, gbase, voff) do { _Pragma("unroll") for (int _i = 0; _i < 2; ++_i) \
;         __builtin_amdgcn_global_load_lds((const unsigned*)((const char*)(gbase) + (voff)[_i]), (LAS unsigned*)(lds + (bufoff) + ldsw + _i * 8192), 16, 0, 0); } while (0)
; #define PG8_LDA(dst, b, h) do { _Pragma("unroll") for (int m = 0; m < 4; ++m) _Pragma("unroll") for (int k = 0; k < 2; ++k) dst[m][k] = *(const LAS bf16x8*)(lds + PG8_SA(b, h) + aoff + m * 2048 + k * 1024); } while (0)
; #define PG8_LDB(dst, b, h) do { _Pragma("unroll") for (int n = 0; n < 2; ++n) _Pragma("unroll") for (int k = 0; k < 2; ++k) dst[n][k] = *(const LAS bf16x8*)(lds + PG8_SB(b, h) + boff + n * 2048 + k * 1024); } while (0)
; #define PG8_WAIT_V(n) asm volatile("s_waitcnt vmcnt(" #n ")" ::: "memory")
; #define PG8_WAIT_L(n) asm volatile("s_waitcnt lgkmcnt(" #n ")" ::: "memory")
; #define PG8_BAR __builtin_amdgcn_s_barrier()
; #define PG8_SCHED __builtin_amdgcn_sched_barrier(0)
; template <class Epi>
; __device__ __forceinline__ void gemm_phase(LAS unsigned char* lds, const Gemm g, const StaticOrder& S, const Epi& E) {
;     ...
;         for (int t = 0; t < nt; t += 2) {
;             const bool last = (t == nt - 2);
;             const char* a1 = cA + (size_t)(t + 1) * kstep;
;             const char* a2 = last ? nA : cA + (size_t)(t + 2) * kstep; const char* b2 = last ? nB : cB + (size_t)(t + 2) * kstep;
;             const char* a3 = a2 + kstep; const char* b3 = b2 + kstep;
;             if (last) E.pre(cur, wr, fr, epre);
;             PG8_LDB(B0, 0, 0); PG8_SCHED; PG8_LDA(At, 0, 0); PG8_STAGE(PG8_SA(1, 1), a1 + hstepA, voffA);
;             PG8_WAIT_L(8); PG8_BAR; PG8_WAIT_L(0); PG8_MMA(0, 0, At, B0); PG8_BAR; PG8_SCHED;
;             PG8_LDB(B1, 0, 1); PG8_STAGE(PG8_SB(0, 0), b2, voffB);
;             PG8_BAR; PG8_WAIT_L(0); PG8_MMA(0, 1, At, B1); PG8_BAR;
;             PG8_LDA(At, 0, 1); PG8_STAGE(PG8_SA(0, 0), a2, voffA);
;             PG8_BAR; PG8_WAIT_L(0); PG8_MMA(1, 0, At, B0); PG8_BAR; PG8_SCHED;
;             PG8_STAGE(PG8_SB(0, 1), b2 + hstepB, voffB);
;             PG8_WAIT_V(6); PG8_BAR; PG8_MMA(1, 1, At, B1); PG8_BAR;
;             PG8_LDB(B0, 1, 0); PG8_SCHED; PG8_LDA(At, 1, 0); PG8_STAGE(PG8_SA(0, 1), a2 + hstepA, voffA);
;             PG8_WAIT_L(8); PG8_BAR; PG8_WAIT_L(0); PG8_MMA(0, 0, At, B0); PG8_BAR; PG8_SCHED;
	s_waitcnt lgkmcnt(7)
	v_mfma_f32_16x16x32_bf16 v[60:63], v[128:131], v[144:147], v[60:63]
	v_mfma_f32_16x16x32_bf16 v[56:59], v[136:139], v[144:147], v[56:59]
	s_waitcnt lgkmcnt(5)
	v_mfma_f32_16x16x32_bf16 v[44:47], v[128:131], v[170:173], v[44:47]
	v_mfma_f32_16x16x32_bf16 v[40:43], v[136:139], v[170:173], v[40:43]
	s_waitcnt lgkmcnt(3)
	v_mfma_f32_16x16x32_bf16 v[28:31], v[128:131], v[178:181], v[28:31]
	v_mfma_f32_16x16x32_bf16 v[24:27], v[136:139], v[178:181], v[24:27]
	s_waitcnt lgkmcnt(1)
	v_mfma_f32_16x16x32_bf16 v[12:15], v[128:131], v[194:197], v[12:15]
	v_mfma_f32_16x16x32_bf16 v[8:11], v[136:139], v[194:197], v[8:11]
	v_mfma_f32_16x16x32_bf16 v[60:63], v[132:135], v[148:151], v[60:63]
	v_mfma_f32_16x16x32_bf16 v[56:59], v[140:143], v[148:151], v[56:59]
	v_mfma_f32_16x16x32_bf16 v[44:47], v[132:135], v[174:177], v[44:47]
	v_mfma_f32_16x16x32_bf16 v[40:43], v[140:143], v[174:177], v[40:43]
	v_mfma_f32_16x16x32_bf16 v[28:31], v[132:135], v[182:185], v[28:31]
	v_mfma_f32_16x16x32_bf16 v[24:27], v[140:143], v[182:185], v[24:27]
	s_waitcnt lgkmcnt(0)
	v_mfma_f32_16x16x32_bf16 v[12:15], v[132:135], v[198:201], v[12:15]
	v_mfma_f32_16x16x32_bf16 v[8:11], v[140:143], v[198:201], v[8:11]
	s_barrier
	s_add_u32 s24, s24, 0x100080
	s_addc_u32 s25, s25, 0
	s_add_i32 s26, s26, s31
	v_lshl_add_u64 v[128:129], s[24:25], 0, v[156:157]
	s_mov_b32 m0, s26
	s_nop 0
	global_load_lds_dwordx4 v[128:129], off
	v_lshl_add_u64 v[128:129], s[24:25], 0, v[160:161]
	s_add_i32 m0, s26, 0x2000
	s_nop 0
	global_load_lds_dwordx4 v[128:129], off
	s_waitcnt vmcnt(6)
	s_barrier
	v_mfma_f32_16x16x32_bf16 v[52:55], v[202:205], v[144:147], v[52:55]
	v_mfma_f32_16x16x32_bf16 v[48:51], v[210:213], v[144:147], v[48:51]
	v_mfma_f32_16x16x32_bf16 v[36:39], v[202:205], v[170:173], v[36:39]
	v_mfma_f32_16x16x32_bf16 v[32:35], v[210:213], v[170:173], v[32:35]
	v_mfma_f32_16x16x32_bf16 v[20:23], v[202:205], v[178:181], v[20:23]
	v_mfma_f32_16x16x32_bf16 v[16:19], v[210:213], v[178:181], v[16:19]
	v_mfma_f32_16x16x32_bf16 v[4:7], v[202:205], v[194:197], v[4:7]
	v_mfma_f32_16x16x32_bf16 v[0:3], v[210:213], v[194:197], v[0:3]
	v_mfma_f32_16x16x32_bf16 v[52:55], v[206:209], v[148:151], v[52:55]
	v_mfma_f32_16x16x32_bf16 v[48:51], v[214:217], v[148:151], v[48:51]
	v_mfma_f32_16x16x32_bf16 v[36:39], v[206:209], v[174:177], v[36:39]
	v_mfma_f32_16x16x32_bf16 v[32:35], v[214:217], v[174:177], v[32:35]
	v_mfma_f32_16x16x32_bf16 v[20:23], v[206:209], v[182:185], v[20:23]
	v_mfma_f32_16x16x32_bf16 v[16:19], v[214:217], v[182:185], v[16:19]
	v_mfma_f32_16x16x32_bf16 v[4:7], v[206:209], v[198:201], v[4:7]
	v_mfma_f32_16x16x32_bf16 v[0:3], v[214:217], v[198:201], v[0:3]
	s_add_i32 s48, s48, 2
	s_add_u32 s22, s22, 0x100
	s_addc_u32 s23, s23, 0
	s_add_u32 s46, s46, 0x100
	s_addc_u32 s47, s47, 0
	s_cmp_gt_u32 s48, 61
	s_barrier
.LBB0_1278:
	ds_read_b128 v[128:131], v190
	ds_read_b128 v[132:135], v190 offset:1024
	ds_read_b128 v[136:139], v190 offset:2048
	ds_read_b128 v[140:143], v190 offset:3072
	s_add_u32 s24, s22, 0xfff00080
	s_addc_u32 s25, s23, -1
	s_cmp_eq_u32 s48, 60
	s_cselect_b32 s27, s17, s25
	s_cselect_b32 s26, s44, s24
	s_cselect_b32 s25, s15, s47
	s_cselect_b32 s24, s45, s46
	v_lshl_add_u64 v[186:187], s[22:23], 0, v[162:163]
	s_add_i32 m0, s7, 0xc000
	ds_read_b128 v[144:147], v191
	ds_read_b128 v[148:151], v191 offset:1024
	ds_read_b128 v[170:173], v191 offset:2048
	ds_read_b128 v[174:177], v191 offset:3072
	ds_read_b128 v[178:181], v191 offset:4096
	ds_read_b128 v[182:185], v191 offset:5120
	ds_read_b128 v[194:197], v191 offset:6144
	ds_read_b128 v[198:201], v191 offset:7168
	global_load_lds_dwordx4 v[186:187], off
	v_lshl_add_u64 v[186:187], s[22:23], 0, v[164:165]
	s_add_i32 m0, s7, 0xe000
	s_nop 0
	global_load_lds_dwordx4 v[186:187], off
	s_waitcnt lgkmcnt(8)
	s_barrier
	s_waitcnt lgkmcnt(7)
	v_mfma_f32_16x16x32_bf16 v[124:127], v[128:131], v[144:147], v[124:127]
	v_mfma_f32_16x16x32_bf16 v[120:123], v[136:139], v[144:147], v[120:123]
	s_waitcnt lgkmcnt(5)
	v_mfma_f32_16x16x32_bf16 v[108:111], v[128:131], v[170:173], v[108:111]
	v_mfma_f32_16x16x32_bf16 v[104:107], v[136:139], v[170:173], v[104:107]
	s_waitcnt lgkmcnt(3)
	v_mfma_f32_16x16x32_bf16 v[92:95], v[128:131], v[178:181], v[92:95]
	v_mfma_f32_16x16x32_bf16 v[88:91], v[136:139], v[178:181], v[88:91]
	s_waitcnt lgkmcnt(1)
	v_mfma_f32_16x16x32_bf16 v[76:79], v[128:131], v[194:197], v[76:79]
	v_mfma_f32_16x16x32_bf16 v[72:75], v[136:139], v[194:197], v[72:75]
	v_mfma_f32_16x16x32_bf16 v[124:127], v[132:135], v[148:151], v[124:127]
	v_mfma_f32_16x16x32_bf16 v[120:123], v[140:143], v[148:151], v[120:123]
	v_mfma_f32_16x16x32_bf16 v[108:111], v[132:135], v[174:177], v[108:111]
	v_mfma_f32_16x16x32_bf16 v[104:107], v[140:143], v[174:177], v[104:107]
	v_mfma_f32_16x16x32_bf16 v[92:95], v[132:135], v[182:185], v[92:95]
	v_mfma_f32_16x16x32_bf16 v[88:91], v[140:143], v[182:185], v[88:91]
	s_waitcnt lgkmcnt(0)
	v_mfma_f32_16x16x32_bf16 v[76:79], v[132:135], v[198:201], v[76:79]
	v_mfma_f32_16x16x32_bf16 v[72:75], v[140:143], v[198:201], v[72:75]
	s_barrier
	s_add_i32 s49, s42, s31
	v_lshl_add_u64 v[186:187], s[24:25], 0, v[156:157]
	s_mov_b32 m0, s49
	ds_read_b128 v[202:205], v192
	ds_read_b128 v[206:209], v192 offset:1024
	ds_read_b128 v[210:213], v192 offset:2048
	ds_read_b128 v[214:217], v192 offset:3072
	global_load_lds_dwordx4 v[186:187], off
	v_lshl_add_u64 v[218:219], s[24:25], 0, v[160:161]
	s_add_i32 m0, s49, 0x2000
	s_nop 0
	global_load_lds_dwordx4 v[218:219], off
	s_barrier
; #define PG8_STAGE(bufoff, gbase, voff) do { _Pragma("unroll") for (int _i = 0; _i < 2; ++_i) \
;         __builtin_amdgcn_global_load_lds((const unsigned*)((const char*)(gbase) + (voff)[_i]), (LAS unsigned*)(lds + (bufoff) + ldsw + _i * 8192), 16, 0, 0); } while (0)
; #define PG8_LDA(dst, b, h) do { _Pragma("unroll") for (int m = 0; m < 4; ++m) _Pragma("unroll") for (int k = 0; k < 2; ++k) dst[m][k] = *(const LAS bf16x8*)(lds + PG8_SA(b, h) + aoff + m * 2048 + k * 1024); } while (0)
; #define PG8_LDB(dst, b, h) do { _Pragma("unroll") for (int n = 0; n < 2; ++n) _Pragma("unroll") for (int k = 0; k < 2; ++k) dst[n][k] = *(const LAS bf16x8*)(lds + PG8_SB(b, h) + boff + n * 2048 + k * 1024); } while (0)
; #define PG8_MMA(ai, bj, At, Bt) do { __builtin_amdgcn_s_setprio(1); _Pragma("unroll") for (int m = 0; m < 4; ++m) _Pragma("unroll") for (int n = 0; n < 2; ++n) _Pragma("unroll") for (int k = 0; k < 2; ++k) \
;         acc[ai][bj][m][n] = __builtin_amdgcn_mfma_f32_16x16x32_bf16(Bt[n][k], At[m][k], acc[ai][bj][m][n], 0, 0, 0); __builtin_amdgcn_s_setprio(0); } while (0)
; #define PG8_WAIT_V(n) asm volatile("s_waitcnt vmcnt(" #n ")" ::: "memory")
; #define PG8_WAIT_L(n) asm volatile("s_waitcnt lgkmcnt(" #n ")" ::: "memory")
; #define PG8_BAR __builtin_amdgcn_s_barrier()
; #define PG8_SCHED __builtin_amdgcn_sched_barrier(0)
; template <class Epi>
; __device__ __forceinline__ void gemm_phase(LAS unsigned char* lds, const Gemm g, const StaticOrder& S, const Epi& E) {
;     ...
;             PG8_WAIT_L(8); PG8_BAR; PG8_WAIT_L(0); PG8_MMA(0, 0, At, B0); PG8_BAR; PG8_SCHED;
;             PG8_LDB(B1, 0, 1); PG8_STAGE(PG8_SB(0, 0), b2, voffB);
;             PG8_BAR; PG8_WAIT_L(0); PG8_MMA(0, 1, At, B1); PG8_BAR;
;             PG8_LDA(At, 0, 1); PG8_STAGE(PG8_SA(0, 0), a2, voffA);
;             PG8_BAR; PG8_WAIT_L(0); PG8_MMA(1, 0, At, B0); PG8_BAR; PG8_SCHED;
;             PG8_STAGE(PG8_SB(0, 1), b2 + hstepB, voffB);
;             PG8_WAIT_V(6); PG8_BAR; PG8_MMA(1, 1, At, B1); PG8_BAR;
;             PG8_LDB(B0, 1, 0); PG8_SCHED; PG8_LDA(At, 1, 0); PG8_STAGE(PG8_SA(0, 1), a2 + hstepA, voffA);
;             PG8_WAIT_L(8); PG8_BAR; PG8_WAIT_L(0); PG8_MMA(0, 0, At, B0); PG8_BAR; PG8_SCHED;
	s_waitcnt lgkmcnt(3)
	v_mfma_f32_16x16x32_bf16 v[116:119], v[202:205], v[144:147], v[116:119]
	s_waitcnt lgkmcnt(1)
	v_mfma_f32_16x16x32_bf16 v[112:115], v[210:213], v[144:147], v[112:115]
	v_mfma_f32_16x16x32_bf16 v[100:103], v[202:205], v[170:173], v[100:103]
	v_mfma_f32_16x16x32_bf16 v[96:99], v[210:213], v[170:173], v[96:99]
	v_mfma_f32_16x16x32_bf16 v[84:87], v[202:205], v[178:181], v[84:87]
	v_mfma_f32_16x16x32_bf16 v[80:83], v[210:213], v[178:181], v[80:83]
	v_mfma_f32_16x16x32_bf16 v[68:71], v[202:205], v[194:197], v[68:71]
	v_mfma_f32_16x16x32_bf16 v[64:67], v[210:213], v[194:197], v[64:67]
	v_mfma_f32_16x16x32_bf16 v[116:119], v[206:209], v[148:151], v[116:119]
	s_waitcnt lgkmcnt(0)
	v_mfma_f32_16x16x32_bf16 v[112:115], v[214:217], v[148:151], v[112:115]
	v_mfma_f32_16x16x32_bf16 v[100:103], v[206:209], v[174:177], v[100:103]
	v_mfma_f32_16x16x32_bf16 v[96:99], v[214:217], v[174:177], v[96:99]
	v_mfma_f32_16x16x32_bf16 v[84:87], v[206:209], v[182:185], v[84:87]
	v_mfma_f32_16x16x32_bf16 v[80:83], v[214:217], v[182:185], v[80:83]
	v_mfma_f32_16x16x32_bf16 v[68:71], v[206:209], v[198:201], v[68:71]
	v_mfma_f32_16x16x32_bf16 v[64:67], v[214:217], v[198:201], v[64:67]
	s_mov_b32 m0, s7
	v_lshl_add_u64 v[220:221], s[26:27], 0, v[154:155]
	s_barrier
	ds_read_b128 v[144:147], v191 offset:16384
	ds_read_b128 v[148:151], v191 offset:17408
	ds_read_b128 v[170:173], v191 offset:18432
	ds_read_b128 v[174:177], v191 offset:19456
	ds_read_b128 v[178:181], v191 offset:20480
	ds_read_b128 v[182:185], v191 offset:21504
	ds_read_b128 v[194:197], v191 offset:22528
	ds_read_b128 v[198:201], v191 offset:23552
	global_load_lds_dwordx4 v[220:221], off
	v_lshl_add_u64 v[222:223], s[26:27], 0, v[158:159]
	s_mov_b32 m0, s34
	s_nop 0
	global_load_lds_dwordx4 v[222:223], off
	s_barrier
	s_waitcnt lgkmcnt(7)
	v_mfma_f32_16x16x32_bf16 v[60:63], v[128:131], v[144:147], v[60:63]
	v_mfma_f32_16x16x32_bf16 v[56:59], v[136:139], v[144:147], v[56:59]
	s_waitcnt lgkmcnt(5)
	v_mfma_f32_16x16x32_bf16 v[44:47], v[128:131], v[170:173], v[44:47]
	v_mfma_f32_16x16x32_bf16 v[40:43], v[136:139], v[170:173], v[40:43]
	s_waitcnt lgkmcnt(3)
	v_mfma_f32_16x16x32_bf16 v[28:31], v[128:131], v[178:181], v[28:31]
	v_mfma_f32_16x16x32_bf16 v[24:27], v[136:139], v[178:181], v[24:27]
	s_waitcnt lgkmcnt(1)
	v_mfma_f32_16x16x32_bf16 v[12:15], v[128:131], v[194:197], v[12:15]
	v_mfma_f32_16x16x32_bf16 v[8:11], v[136:139], v[194:197], v[8:11]
	v_mfma_f32_16x16x32_bf16 v[60:63], v[132:135], v[148:151], v[60:63]
	v_mfma_f32_16x16x32_bf16 v[56:59], v[140:143], v[148:151], v[56:59]
	v_mfma_f32_16x16x32_bf16 v[44:47], v[132:135], v[174:177], v[44:47]
	v_mfma_f32_16x16x32_bf16 v[40:43], v[140:143], v[174:177], v[40:43]
	v_mfma_f32_16x16x32_bf16 v[28:31], v[132:135], v[182:185], v[28:31]
	v_mfma_f32_16x16x32_bf16 v[24:27], v[140:143], v[182:185], v[24:27]
	s_waitcnt lgkmcnt(0)
	v_mfma_f32_16x16x32_bf16 v[12:15], v[132:135], v[198:201], v[12:15]
	v_mfma_f32_16x16x32_bf16 v[8:11], v[140:143], v[198:201], v[8:11]
	s_barrier
	s_add_u32 s50, s24, 0x100000
	s_addc_u32 s51, s25, 0
	s_add_i32 s49, s43, s31
	v_lshl_add_u64 v[128:129], s[50:51], 0, v[156:157]
	s_mov_b32 m0, s49
	s_nop 0
	global_load_lds_dwordx4 v[128:129], off
	v_lshl_add_u64 v[128:129], s[50:51], 0, v[160:161]
	s_add_i32 m0, s49, 0x2000
	s_nop 0
	global_load_lds_dwordx4 v[128:129], off
	s_waitcnt vmcnt(6)
	s_barrier
	v_mfma_f32_16x16x32_bf16 v[52:55], v[202:205], v[144:147], v[52:55]
	v_mfma_f32_16x16x32_bf16 v[48:51], v[210:213], v[144:147], v[48:51]
	v_mfma_f32_16x16x32_bf16 v[36:39], v[202:205], v[170:173], v[36:39]
	v_mfma_f32_16x16x32_bf16 v[32:35], v[210:213], v[170:173], v[32:35]
	v_mfma_f32_16x16x32_bf16 v[20:23], v[202:205], v[178:181], v[20:23]
	v_mfma_f32_16x16x32_bf16 v[16:19], v[210:213], v[178:181], v[16:19]
	v_mfma_f32_16x16x32_bf16 v[4:7], v[202:205], v[194:197], v[4:7]
	v_mfma_f32_16x16x32_bf16 v[0:3], v[210:213], v[194:197], v[0:3]
	v_mfma_f32_16x16x32_bf16 v[52:55], v[206:209], v[148:151], v[52:55]
	v_mfma_f32_16x16x32_bf16 v[48:51], v[214:217], v[148:151], v[48:51]
	v_mfma_f32_16x16x32_bf16 v[36:39], v[206:209], v[174:177], v[36:39]
	v_mfma_f32_16x16x32_bf16 v[32:35], v[214:217], v[174:177], v[32:35]
	v_mfma_f32_16x16x32_bf16 v[20:23], v[206:209], v[182:185], v[20:23]
	v_mfma_f32_16x16x32_bf16 v[16:19], v[214:217], v[182:185], v[16:19]
	v_mfma_f32_16x16x32_bf16 v[4:7], v[206:209], v[198:201], v[4:7]
	v_mfma_f32_16x16x32_bf16 v[0:3], v[214:217], v[198:201], v[0:3]
	s_add_i32 s49, 0, 0x18000
	v_add_u32_e32 v140, s49, v188
	s_barrier
	ds_read_b128 v[128:131], v140
	ds_read_b128 v[132:135], v140 offset:1024
	ds_read_b128 v[136:139], v140 offset:2048
	ds_read_b128 v[140:143], v140 offset:3072
	s_add_u32 s26, s26, 0x100000
	s_addc_u32 s27, s27, 0
	s_mov_b32 m0, s35
	v_lshl_add_u64 v[202:203], s[26:27], 0, v[154:155]
	ds_read_b128 v[144:147], v191 offset:32768
	ds_read_b128 v[148:151], v191 offset:33792
	ds_read_b128 v[170:173], v191 offset:34816
	ds_read_b128 v[174:177], v191 offset:35840
	ds_read_b128 v[178:181], v191 offset:36864
	ds_read_b128 v[182:185], v191 offset:37888
	ds_read_b128 v[194:197], v191 offset:38912
	ds_read_b128 v[198:201], v191 offset:39936
	global_load_lds_dwordx4 v[202:203], off
	v_lshl_add_u64 v[202:203], s[26:27], 0, v[158:159]
	s_mov_b32 m0, s36
	s_nop 0
	global_load_lds_dwordx4 v[202:203], off
	s_waitcnt lgkmcnt(8)
	s_barrier
; #define PG8_STAGE(bufoff, gbase, voff) do { _Pragma("unroll") for (int _i = 0; _i < 2; ++_i) \
;         __builtin_amdgcn_global_load_lds((const unsigned*)((const char*)(gbase) + (voff)[_i]), (LAS unsigned*)(lds + (bufoff) + ldsw + _i * 8192), 16, 0, 0); } while (0)
; #define PG8_LDA(dst, b, h) do { _Pragma("unroll") for (int m = 0; m < 4; ++m) _Pragma("unroll") for (int k = 0; k < 2; ++k) dst[m][k] = *(const LAS bf16x8*)(lds + PG8_SA(b, h) + aoff + m * 2048 + k * 1024); } while (0)
; #define PG8_LDB(dst, b, h) do { _Pragma("unroll") for (int n = 0; n < 2; ++n) _Pragma("unroll") for (int k = 0; k < 2; ++k) dst[n][k] = *(const LAS bf16x8*)(lds + PG8_SB(b, h) + boff + n * 2048 + k * 1024); } while (0)
; #define PG8_MMA(ai, bj, At, Bt) do { __builtin_amdgcn_s_setprio(1); _Pragma("unroll") for (int m = 0; m < 4; ++m) _Pragma("unroll") for (int n = 0; n < 2; ++n) _Pragma("unroll") for (int k = 0; k < 2; ++k) \
;         acc[ai][bj][m][n] = __builtin_amdgcn_mfma_f32_16x16x32_bf16(Bt[n][k], At[m][k], acc[ai][bj][m][n], 0, 0, 0); __builtin_amdgcn_s_setprio(0); } while (0)
; #define PG8_WAIT_V(n) asm volatile("s_waitcnt vmcnt(" #n ")" ::: "memory")
; #define PG8_WAIT_L(n) asm volatile("s_waitcnt lgkmcnt(" #n ")" ::: "memory")
; #define PG8_BAR __builtin_amdgcn_s_barrier()
; #define PG8_SCHED __builtin_amdgcn_sched_barrier(0)
; template <class Epi>
; __device__ __forceinline__ void gemm_phase(LAS unsigned char* lds, const Gemm g, const StaticOrder& S, const Epi& E) {
;     ...
;             PG8_WAIT_V(6); PG8_BAR; PG8_MMA(1, 1, At, B1); PG8_BAR;
;             PG8_LDB(B0, 1, 0); PG8_SCHED; PG8_LDA(At, 1, 0); PG8_STAGE(PG8_SA(0, 1), a2 + hstepA, voffA);
;             PG8_WAIT_L(8); PG8_BAR; PG8_WAIT_L(0); PG8_MMA(0, 0, At, B0); PG8_BAR; PG8_SCHED;
;             PG8_LDB(B1, 1, 1); PG8_STAGE(PG8_SB(1, 0), b3, voffB);
;             PG8_BAR; PG8_WAIT_L(0); PG8_MMA(0, 1, At, B1); PG8_BAR;
;             PG8_LDA(At, 1, 1); PG8_STAGE(PG8_SA(1, 0), a3, voffA);
;             PG8_BAR; PG8_WAIT_L(0); PG8_MMA(1, 0, At, B0); PG8_BAR; PG8_SCHED;
;             PG8_STAGE(PG8_SB(1, 1), b3 + hstepB, voffB);
;             PG8_WAIT_V(6); PG8_BAR; PG8_MMA(1, 1, At, B1); PG8_BAR;
	s_waitcnt lgkmcnt(7)
	v_mfma_f32_16x16x32_bf16 v[124:127], v[128:131], v[144:147], v[124:127]
	v_mfma_f32_16x16x32_bf16 v[120:123], v[136:139], v[144:147], v[120:123]
	s_waitcnt lgkmcnt(5)
	v_mfma_f32_16x16x32_bf16 v[108:111], v[128:131], v[170:173], v[108:111]
	v_mfma_f32_16x16x32_bf16 v[104:107], v[136:139], v[170:173], v[104:107]
	s_waitcnt lgkmcnt(3)
	v_mfma_f32_16x16x32_bf16 v[92:95], v[128:131], v[178:181], v[92:95]
	v_mfma_f32_16x16x32_bf16 v[88:91], v[136:139], v[178:181], v[88:91]
	s_waitcnt lgkmcnt(1)
	v_mfma_f32_16x16x32_bf16 v[76:79], v[128:131], v[194:197], v[76:79]
	v_mfma_f32_16x16x32_bf16 v[72:75], v[136:139], v[194:197], v[72:75]
	v_mfma_f32_16x16x32_bf16 v[124:127], v[132:135], v[148:151], v[124:127]
	v_mfma_f32_16x16x32_bf16 v[120:123], v[140:143], v[148:151], v[120:123]
	v_mfma_f32_16x16x32_bf16 v[108:111], v[132:135], v[174:177], v[108:111]
	v_mfma_f32_16x16x32_bf16 v[104:107], v[140:143], v[174:177], v[104:107]
	v_mfma_f32_16x16x32_bf16 v[92:95], v[132:135], v[182:185], v[92:95]
	v_mfma_f32_16x16x32_bf16 v[88:91], v[140:143], v[182:185], v[88:91]
	s_waitcnt lgkmcnt(0)
	v_mfma_f32_16x16x32_bf16 v[76:79], v[132:135], v[198:201], v[76:79]
	v_mfma_f32_16x16x32_bf16 v[72:75], v[140:143], v[198:201], v[72:75]
	s_barrier
	s_add_i32 s26, 0, 0x1c000
	s_add_i32 s27, s49, s31
	v_add_u32_e32 v214, s26, v188
	v_lshl_add_u64 v[186:187], v[186:187], 0, s[12:13]
	s_mov_b32 m0, s27
	ds_read_b128 v[202:205], v214
	ds_read_b128 v[206:209], v214 offset:1024
	ds_read_b128 v[210:213], v214 offset:2048
	ds_read_b128 v[214:217], v214 offset:3072
	global_load_lds_dwordx4 v[186:187], off
	v_lshl_add_u64 v[186:187], v[218:219], 0, s[12:13]
	s_add_i32 m0, s27, 0x2000
	s_nop 0
	global_load_lds_dwordx4 v[186:187], off
	s_barrier
	s_waitcnt lgkmcnt(3)
	v_mfma_f32_16x16x32_bf16 v[116:119], v[202:205], v[144:147], v[116:119]
	s_waitcnt lgkmcnt(1)
	v_mfma_f32_16x16x32_bf16 v[112:115], v[210:213], v[144:147], v[112:115]
	v_mfma_f32_16x16x32_bf16 v[100:103], v[202:205], v[170:173], v[100:103]
	v_mfma_f32_16x16x32_bf16 v[96:99], v[210:213], v[170:173], v[96:99]
	v_mfma_f32_16x16x32_bf16 v[84:87], v[202:205], v[178:181], v[84:87]
	v_mfma_f32_16x16x32_bf16 v[80:83], v[210:213], v[178:181], v[80:83]
	v_mfma_f32_16x16x32_bf16 v[68:71], v[202:205], v[194:197], v[68:71]
	v_mfma_f32_16x16x32_bf16 v[64:67], v[210:213], v[194:197], v[64:67]
	v_mfma_f32_16x16x32_bf16 v[116:119], v[206:209], v[148:151], v[116:119]
	s_waitcnt lgkmcnt(0)
	v_mfma_f32_16x16x32_bf16 v[112:115], v[214:217], v[148:151], v[112:115]
	v_mfma_f32_16x16x32_bf16 v[100:103], v[206:209], v[174:177], v[100:103]
	v_mfma_f32_16x16x32_bf16 v[96:99], v[214:217], v[174:177], v[96:99]
	v_mfma_f32_16x16x32_bf16 v[84:87], v[206:209], v[182:185], v[84:87]
	v_mfma_f32_16x16x32_bf16 v[80:83], v[214:217], v[182:185], v[80:83]
	v_mfma_f32_16x16x32_bf16 v[68:71], v[206:209], v[198:201], v[68:71]
	v_mfma_f32_16x16x32_bf16 v[64:67], v[214:217], v[198:201], v[64:67]
	s_mov_b32 m0, s38
	v_lshl_add_u64 v[186:187], v[220:221], 0, s[12:13]
	s_barrier
	ds_read_b128 v[144:147], v191 offset:49152
	ds_read_b128 v[148:151], v191 offset:50176
	ds_read_b128 v[170:173], v191 offset:51200
	ds_read_b128 v[174:177], v191 offset:52224
	ds_read_b128 v[178:181], v191 offset:53248
	ds_read_b128 v[182:185], v191 offset:54272
	ds_read_b128 v[194:197], v191 offset:55296
	ds_read_b128 v[198:201], v191 offset:56320
	global_load_lds_dwordx4 v[186:187], off
	v_lshl_add_u64 v[186:187], v[222:223], 0, s[12:13]
	s_mov_b32 m0, s39
	s_nop 0
	global_load_lds_dwordx4 v[186:187], off
	s_barrier
	s_waitcnt lgkmcnt(7)
	v_mfma_f32_16x16x32_bf16 v[60:63], v[128:131], v[144:147], v[60:63]
	v_mfma_f32_16x16x32_bf16 v[56:59], v[136:139], v[144:147], v[56:59]
	s_waitcnt lgkmcnt(5)
	v_mfma_f32_16x16x32_bf16 v[44:47], v[128:131], v[170:173], v[44:47]
	v_mfma_f32_16x16x32_bf16 v[40:43], v[136:139], v[170:173], v[40:43]
	s_waitcnt lgkmcnt(3)
	v_mfma_f32_16x16x32_bf16 v[28:31], v[128:131], v[178:181], v[28:31]
	v_mfma_f32_16x16x32_bf16 v[24:27], v[136:139], v[178:181], v[24:27]
	s_waitcnt lgkmcnt(1)
	v_mfma_f32_16x16x32_bf16 v[12:15], v[128:131], v[194:197], v[12:15]
	v_mfma_f32_16x16x32_bf16 v[8:11], v[136:139], v[194:197], v[8:11]
	v_mfma_f32_16x16x32_bf16 v[60:63], v[132:135], v[148:151], v[60:63]
	v_mfma_f32_16x16x32_bf16 v[56:59], v[140:143], v[148:151], v[56:59]
	v_mfma_f32_16x16x32_bf16 v[44:47], v[132:135], v[174:177], v[44:47]
	v_mfma_f32_16x16x32_bf16 v[40:43], v[140:143], v[174:177], v[40:43]
	v_mfma_f32_16x16x32_bf16 v[28:31], v[132:135], v[182:185], v[28:31]
	v_mfma_f32_16x16x32_bf16 v[24:27], v[140:143], v[182:185], v[24:27]
	s_waitcnt lgkmcnt(0)
	v_mfma_f32_16x16x32_bf16 v[12:15], v[132:135], v[198:201], v[12:15]
	v_mfma_f32_16x16x32_bf16 v[8:11], v[140:143], v[198:201], v[8:11]
	s_barrier
	s_add_u32 s24, s24, 0x100080
	s_addc_u32 s25, s25, 0
	s_add_i32 s26, s26, s31
	v_lshl_add_u64 v[128:129], s[24:25], 0, v[156:157]
	s_mov_b32 m0, s26
	s_nop 0
	global_load_lds_dwordx4 v[128:129], off
	v_lshl_add_u64 v[128:129], s[24:25], 0, v[160:161]
	s_add_i32 m0, s26, 0x2000
	s_nop 0
	global_load_lds_dwordx4 v[128:129], off
	s_waitcnt vmcnt(6)
	s_barrier
; __device__ __forceinline__ unsigned pk2(float lo, float hi) { const f32x2 v = (f32x2){lo, hi}; const bf16x2_t b = __builtin_convertvector(v, bf16x2_t); return __builtin_bit_cast(unsigned, b); }
; __device__ __forceinline__ void unpack8(const u32x4 v, float* f) { f[0] = bf_lo(v.x); f[1] = bf_hi(v.x); f[2] = bf_lo(v.y); f[3] = bf_hi(v.y); f[4] = bf_lo(v.z); f[5] = bf_hi(v.z); f[6] = bf_lo(v.w); f[7] = bf_hi(v.w); }
; #define PG8_WAIT_V(n) asm volatile("s_waitcnt vmcnt(" #n ")" ::: "memory")
; #define PG8_BAR __builtin_amdgcn_s_barrier()
;     __device__ __forceinline__ void operator()(const f32x4 (&acc)[2][2][4][2], const Unit& u, int wr, int wc, int fr, int fq, const float (&)[8]) const {
;         const int row0 = u.pm * BM + wr * 64 + fr, col0 = u.pn * BM + wc * 32 + 8 * fq;
; #pragma unroll
;         for (int ai = 0; ai < 2; ++ai) {
;             u32x4 bv[4][2];
; #pragma unroll
;             for (int m = 0; m < 4; ++m)
; #pragma unroll
;                 for (int bj = 0; bj < 2; ++bj) bv[m][bj] = *(const u32x4*)(xb + (size_t)(row0 + ai * HALF + m * 16) * DM + col0 + bj * HALF);
; #pragma unroll
;             for (int m = 0; m < 4; ++m) { const int row = row0 + ai * HALF + m * 16; const size_t ro = (size_t)row * DM + col0; float s = 0.f;
; #pragma unroll
;                 for (int bj = 0; bj < 2; ++bj) { float b8[8]; unpack8(bv[m][bj], b8);
;                     const f32x4 v0 = (f32x4){b8[0], b8[1], b8[2], b8[3]} + acc[ai][bj][m][0], v1 = (f32x4){b8[4], b8[5], b8[6], b8[7]} + acc[ai][bj][m][1];
;                     s += v0[0] * v0[0] + v0[1] * v0[1] + v0[2] * v0[2] + v0[3] * v0[3] + v1[0] * v1[0] + v1[1] * v1[1] + v1[2] * v1[2] + v1[3] * v1[3];
;                     if (LAST) { *(f32x4*)(out + ro + bj * HALF) = v0; *(f32x4*)(out + ro + bj * HALF + 4) = v1; }
;                     else { u32x4 w; w.x = pk2(v0[0], v0[1]); w.y = pk2(v0[2], v0[3]); w.z = pk2(v1[0], v1[1]); w.w = pk2(v1[2], v1[3]); *(u32x4*)(xb + ro + bj * HALF) = w; } }
;                 s += __shfl_xor(s, 16); s += __shfl_xor(s, 32);
;                 if (fq == 0) ss[(size_t)row * 16 + u.pn * 4 + wc] = s; }
; template <class Epi>
; __device__ __forceinline__ void gemm_phase(LAS unsigned char* lds, const Gemm g, const StaticOrder& S, const Epi& E) {
;     ...
;             PG8_WAIT_V(6); PG8_BAR; PG8_MMA(1, 1, At, B1); PG8_BAR;
;         }
	v_mfma_f32_16x16x32_bf16 v[52:55], v[202:205], v[144:147], v[52:55]
	v_mfma_f32_16x16x32_bf16 v[48:51], v[210:213], v[144:147], v[48:51]
	v_mfma_f32_16x16x32_bf16 v[36:39], v[202:205], v[170:173], v[36:39]
	v_mfma_f32_16x16x32_bf16 v[32:35], v[210:213], v[170:173], v[32:35]
	v_mfma_f32_16x16x32_bf16 v[20:23], v[202:205], v[178:181], v[20:23]
	v_mfma_f32_16x16x32_bf16 v[16:19], v[210:213], v[178:181], v[16:19]
	v_mfma_f32_16x16x32_bf16 v[4:7], v[202:205], v[194:197], v[4:7]
	v_mfma_f32_16x16x32_bf16 v[0:3], v[210:213], v[194:197], v[0:3]
	v_mfma_f32_16x16x32_bf16 v[52:55], v[206:209], v[148:151], v[52:55]
	v_mfma_f32_16x16x32_bf16 v[48:51], v[214:217], v[148:151], v[48:51]
	v_mfma_f32_16x16x32_bf16 v[36:39], v[206:209], v[174:177], v[36:39]
	v_mfma_f32_16x16x32_bf16 v[32:35], v[214:217], v[174:177], v[32:35]
	v_mfma_f32_16x16x32_bf16 v[20:23], v[206:209], v[182:185], v[20:23]
	v_mfma_f32_16x16x32_bf16 v[16:19], v[214:217], v[182:185], v[16:19]
	v_mfma_f32_16x16x32_bf16 v[4:7], v[206:209], v[198:201], v[4:7]
	v_mfma_f32_16x16x32_bf16 v[0:3], v[214:217], v[198:201], v[0:3]
	s_add_i32 s48, s48, 2
	s_add_u32 s22, s22, 0x100
	s_addc_u32 s23, s23, 0
	s_add_u32 s46, s46, 0x100
	s_addc_u32 s47, s47, 0
	s_cmp_gt_u32 s48, 61
	s_barrier
	s_cbranch_scc0 .LBB0_1278
	v_lshl_or_b32 v170, s6, 8, v189
	v_lshl_add_u32 v172, s8, 8, v153
	v_ashrrev_i32_e32 v171, 31, v170
	v_lshlrev_b64 v[204:205], 1, v[170:171]
	v_ashrrev_i32_e32 v173, 31, v172
	v_lshl_add_u64 v[174:175], s[76:77], 0, v[204:205]
	v_lshlrev_b64 v[206:207], 11, v[172:173]
	v_lshl_add_u64 v[128:129], v[174:175], 0, v[206:207]
	global_load_dwordx4 v[196:199], v[128:129], off
	global_load_dwordx4 v[200:203], v[128:129], off offset:256
	v_or_b32_e32 v184, 16, v172
	v_or_b32_e32 v180, 32, v172
	v_or_b32_e32 v176, 48, v172
	v_ashrrev_i32_e32 v185, 31, v184
	v_ashrrev_i32_e32 v181, 31, v180
	v_ashrrev_i32_e32 v177, 31, v176
	v_lshlrev_b64 v[186:187], 11, v[184:185]
	v_lshlrev_b64 v[182:183], 11, v[180:181]
	v_lshlrev_b64 v[178:179], 11, v[176:177]
	v_lshl_add_u64 v[128:129], v[174:175], 0, v[186:187]
	v_lshl_add_u64 v[130:131], v[174:175], 0, v[182:183]
	v_lshl_add_u64 v[194:195], v[174:175], 0, v[178:179]
	global_load_dwordx4 v[148:151], v[128:129], off
	global_load_dwordx4 v[144:147], v[128:129], off offset:256
	global_load_dwordx4 v[140:143], v[130:131], off
	global_load_dwordx4 v[136:139], v[130:131], off offset:256
	global_load_dwordx4 v[132:135], v[194:195], off
	s_nop 0
	global_load_dwordx4 v[128:131], v[194:195], off offset:256
	v_add_u32_e32 v226, 0x80, v172
	v_ashrrev_i32_e32 v227, 31, v226
	v_lshlrev_b64 v[226:227], 11, v[226:227]
	v_lshl_add_u64 v[226:227], v[174:175], 0, v[226:227]
	global_load_dwordx4 v[216:219], v[226:227], off
	global_load_dwordx4 v[220:223], v[226:227], off offset:256
	v_add_u32_e32 v226, 0x90, v172
	v_ashrrev_i32_e32 v227, 31, v226
	v_lshlrev_b64 v[226:227], 11, v[226:227]
	v_lshl_add_u64 v[226:227], v[174:175], 0, v[226:227]
	global_load_dwordx4 v[228:231], v[226:227], off
	global_load_dwordx4 v[232:235], v[226:227], off offset:256
	v_add_u32_e32 v226, 0xa0, v172
	v_ashrrev_i32_e32 v227, 31, v226
	v_lshlrev_b64 v[226:227], 11, v[226:227]
	v_lshl_add_u64 v[226:227], v[174:175], 0, v[226:227]
	global_load_dwordx4 v[236:239], v[226:227], off
	global_load_dwordx4 v[240:243], v[226:227], off offset:256
	v_add_u32_e32 v226, 0xb0, v172
	v_ashrrev_i32_e32 v227, 31, v226
	v_lshlrev_b64 v[226:227], 11, v[226:227]
	v_lshl_add_u64 v[226:227], v[174:175], 0, v[226:227]
	global_load_dwordx4 v[244:247], v[226:227], off
	global_load_dwordx4 v[252:255], v[226:227], off offset:256
	v_and_b32_e32 v195, 64, v193
	v_xor_b32_e32 v194, 16, v193
	v_add_u32_e32 v195, 64, v195
	v_xor_b32_e32 v208, 32, v193
	v_cmp_lt_i32_e32 vcc, v194, v195
	s_waitcnt vmcnt(15)
	v_and_b32_e32 v209, 0xffff0000, v196
	v_cndmask_b32_e32 v194, v193, v194, vcc
	v_cmp_lt_i32_e32 vcc, v208, v195
	v_lshlrev_b32_e32 v195, 2, v194
	s_waitcnt vmcnt(14)
	v_lshlrev_b32_e32 v212, 16, v200
	v_cndmask_b32_e32 v208, v193, v208, vcc
	v_lshlrev_b32_e32 v194, 2, v208
	v_lshlrev_b32_e32 v208, 16, v196
	v_and_b32_e32 v213, 0xffff0000, v200
	v_lshlrev_b32_e32 v210, 16, v198
	v_and_b32_e32 v211, 0xffff0000, v198
	v_lshlrev_b32_e32 v198, 16, v199
	v_and_b32_e32 v199, 0xffff0000, v199
	v_lshlrev_b32_e32 v200, 16, v201
	v_and_b32_e32 v201, 0xffff0000, v201
	v_lshlrev_b32_e32 v214, 16, v202
	v_and_b32_e32 v215, 0xffff0000, v202
	v_pk_add_f32 v[124:125], v[124:125], v[208:209]
	v_pk_add_f32 v[116:117], v[116:117], v[212:213]
	v_lshlrev_b32_e32 v196, 16, v197
	v_and_b32_e32 v197, 0xffff0000, v197
	v_pk_add_f32 v[122:123], v[122:123], v[198:199]
	v_pk_add_f32 v[118:119], v[118:119], v[200:201]
	v_pk_add_f32 v[198:199], v[112:113], v[214:215]
	v_mul_f32_e32 v200, v125, v125
	v_cvt_pk_bf16_f32 v112, v124, v125
	v_mul_f32_e32 v125, v117, v117
	v_pk_add_f32 v[126:127], v[126:127], v[196:197]
	v_fmac_f32_e32 v200, v124, v124
	v_fmac_f32_e32 v125, v116, v116
	v_fmac_f32_e32 v200, v126, v126
	v_fmac_f32_e32 v125, v118, v118
	v_pk_add_f32 v[120:121], v[120:121], v[210:211]
	v_fmac_f32_e32 v200, v127, v127
	v_fmac_f32_e32 v125, v119, v119
	v_lshlrev_b32_e32 v202, 16, v203
	v_and_b32_e32 v203, 0xffff0000, v203
	v_fmac_f32_e32 v200, v120, v120
	v_fmac_f32_e32 v125, v198, v198
	v_pk_add_f32 v[196:197], v[114:115], v[202:203]
	v_fmac_f32_e32 v200, v121, v121
	v_fmac_f32_e32 v125, v199, v199
	v_fmac_f32_e32 v200, v122, v122
	v_fmac_f32_e32 v125, v196, v196
	v_fmac_f32_e32 v200, v123, v123
	v_fmac_f32_e32 v125, v197, v197
	v_cvt_pk_bf16_f32 v115, v122, v123
	v_add_f32_e32 v122, v200, v125
	ds_bpermute_b32 v123, v195, v122
	v_cvt_pk_bf16_f32 v114, v120, v121
	v_lshl_add_u64 v[120:121], s[76:77], 0, v[206:207]
	v_cvt_pk_bf16_f32 v113, v126, v127
	v_lshl_add_u64 v[120:121], v[120:121], 0, v[204:205]
	global_store_dwordx4 v[120:121], v[112:115], off
	s_waitcnt lgkmcnt(0)
	s_nop 0
	v_add_f32_e32 v112, v122, v123
	ds_bpermute_b32 v113, v194, v112
	v_cvt_pk_bf16_f32 v114, v116, v117
	v_cvt_pk_bf16_f32 v115, v118, v119
	v_cvt_pk_bf16_f32 v116, v198, v199
	v_cvt_pk_bf16_f32 v117, v196, v197
	global_store_dwordx4 v[120:121], v[114:117], off offset:256
	s_and_saveexec_b64 s[22:23], s[0:1]
	s_cbranch_execz .LBB0_1281
	s_waitcnt lgkmcnt(0)
	v_add_f32_e32 v114, v112, v113
	s_lshl_b32 s24, s6, 2
	v_lshlrev_b64 v[112:113], 6, v[172:173]
	s_ashr_i32 s25, s24, 31
	v_lshl_add_u64 v[112:113], s[10:11], 0, v[112:113]
	v_lshl_add_u64 v[112:113], s[24:25], 2, v[112:113]
	s_lshl_b32 s8, s37, 2
	v_lshl_add_u64 v[112:113], v[112:113], 0, s[8:9]
	global_store_dword v[112:113], v114, off
